# speedup vs baseline: 1.0011x; 1.0011x over previous
; #define STAGE(P,BASE,LD,br,kt) do{long _g=(long)(br)*(LD)+(long)(kt)*BK; \
;     _Pragma("unroll") for(int _i=0;_i<2;++_i){int _b=tid*16+_i*8192;int _r,_c;stage_rc(_b,_r,_c); \
;       __builtin_amdgcn_global_load_lds((const unsigned*)((BASE)+_g+(long)_r*(LD)+_c), \
;         (unsigned*)((char*)(P)+_b),16,0,0);}}while(0)
; #define STAGE(P,BASE,LD,br,kt) do{long _g=(long)(br)*(LD)+(long)(kt)*BK; \
;     _Pragma("unroll") for(int _i=0;_i<2;++_i){int _b=tid*16+_i*8192;int _r,_c;stage_rc(_b,_r,_c); \
;       __builtin_amdgcn_global_load_lds((const unsigned*)((BASE)+_g+(long)_r*(LD)+_c), \
;         (unsigned*)((char*)(P)+_b),16,0,0);}}while(0)
; #define LDA(dst,b,h) _Pragma("unroll") for(int m=0;m<4;++m) _Pragma("unroll") for(int k=0;k<2;++k) \
;     dst[m][k]=*reinterpret_cast<const bf16x8*>((char*)SA(b,h)+lds_byte(wr*64+m*16+fr,k*32+fq*8))
; #define LDB(dst,b,h) _Pragma("unroll") for(int n=0;n<2;++n) _Pragma("unroll") for(int k=0;k<2;++k) \
;     dst[n][k]=*reinterpret_cast<const bf16x8*>((char*)SB(b,h)+lds_byte(wc*32+n*16+fr,k*32+fq*8))
; #define MMA(ai,bj,At_,Bt_) do{__builtin_amdgcn_s_setprio(1); \
;     _Pragma("unroll") for(int m=0;m<4;++m) _Pragma("unroll") for(int n=0;n<2;++n) _Pragma("unroll") for(int k=0;k<2;++k) \
;       acc[ai][bj][m][n]=__builtin_amdgcn_mfma_f32_16x16x32_bf16(Bt_[n][k],At_[m][k],acc[ai][bj][m][n],0,0,0); \
;     __builtin_amdgcn_s_setprio(0);}while(0)
; #define WAIT_L(n) asm volatile("s_waitcnt lgkmcnt(" #n ")":::"memory")
; #define BAR __builtin_amdgcn_s_barrier()
; #define SCHED __builtin_amdgcn_sched_barrier(0)
; DEVINL void gemm8_mainloop(const u16* A, long lda, const u16* Bt, long ldb, int K, int brow, int bcol, f32x4 (&acc)[2][2][4][2], char* smem, int tid) {
;     ...
;     LDB(B0,0,0); SCHED; LDA(At,0,0); STAGE(SA(1,1),A,lda,brow+HALF,t+1);
;     WAIT_L(8); BAR; WAIT_L(0); MMA(0,0,At,B0); BAR; SCHED;
;     LDB(B1,0,1); STAGE(SB(0,0),Bt,ldb,bcol,t+2);
;     BAR; WAIT_L(0); MMA(0,1,At,B1); BAR;
;     LDA(At,0,1); STAGE(SA(0,0),A,lda,brow,t+2);
;     BAR; WAIT_L(0); MMA(1,0,At,B0); BAR; SCHED;
.LBB0_269:
	ds_read_b128 v[170:173], v161
	ds_read_b128 v[180:183], v161 offset:1024
	ds_read_b128 v[184:187], v161 offset:2048
	ds_read_b128 v[188:191], v161 offset:3072
	v_add_u32_e32 v178, 0xc000, v128
	v_lshl_add_u64 v[244:245], s[94:95], 0, v[148:149]
	v_readfirstlane_b32 s3, v178
	v_add_u32_e32 v179, 0xe000, v128
	v_add_u32_e32 v174, s41, v160
	v_add_u32_e32 v175, s45, v160
	v_add_u32_e32 v177, s47, v160
	v_lshl_add_u64 v[162:163], v[244:245], 0, s[12:13]
	s_mov_b32 m0, s3
	v_lshl_add_u64 v[246:247], s[94:95], 0, v[150:151]
	v_readfirstlane_b32 s3, v179
	ds_read_b128 v[192:195], v131
	ds_read_b128 v[196:199], v131 offset:1024
	ds_read_b128 v[200:203], v174
	ds_read_b128 v[204:207], v174 offset:1024
	ds_read_b128 v[208:211], v175
	ds_read_b128 v[212:215], v175 offset:1024
	ds_read_b128 v[216:219], v177
	ds_read_b128 v[220:223], v177 offset:1024
	global_load_lds_dwordx4 v[162:163], off
	v_lshl_add_u64 v[162:163], v[246:247], 0, s[12:13]
	s_mov_b32 m0, s3
	s_nop 0
	global_load_lds_dwordx4 v[162:163], off
	s_waitcnt lgkmcnt(8)
	s_barrier
	s_waitcnt lgkmcnt(0)
	v_mfma_f32_16x16x32_bf16 v[124:127], v[170:173], v[192:195], v[124:127]
	v_mfma_f32_16x16x32_bf16 v[120:123], v[184:187], v[192:195], v[120:123]
	v_mfma_f32_16x16x32_bf16 v[116:119], v[170:173], v[200:203], v[116:119]
	v_mfma_f32_16x16x32_bf16 v[112:115], v[184:187], v[200:203], v[112:115]
	v_mfma_f32_16x16x32_bf16 v[108:111], v[170:173], v[208:211], v[108:111]
	v_mfma_f32_16x16x32_bf16 v[104:107], v[184:187], v[208:211], v[104:107]
	v_mfma_f32_16x16x32_bf16 v[100:103], v[170:173], v[216:219], v[100:103]
	v_mfma_f32_16x16x32_bf16 v[96:99], v[184:187], v[216:219], v[96:99]
	v_mfma_f32_16x16x32_bf16 v[124:127], v[180:183], v[196:199], v[124:127]
	v_mfma_f32_16x16x32_bf16 v[120:123], v[188:191], v[196:199], v[120:123]
	v_mfma_f32_16x16x32_bf16 v[116:119], v[180:183], v[204:207], v[116:119]
	v_mfma_f32_16x16x32_bf16 v[112:115], v[188:191], v[204:207], v[112:115]
	v_mfma_f32_16x16x32_bf16 v[108:111], v[180:183], v[212:215], v[108:111]
	v_mfma_f32_16x16x32_bf16 v[104:107], v[188:191], v[212:215], v[104:107]
	v_mfma_f32_16x16x32_bf16 v[100:103], v[180:183], v[220:223], v[100:103]
	v_mfma_f32_16x16x32_bf16 v[96:99], v[188:191], v[220:223], v[96:99]
	s_barrier
	v_add_u32_e32 v162, s31, v153
	v_lshl_add_u64 v[248:249], s[94:95], 0, v[144:145]
	v_readfirstlane_b32 s3, v162
	v_add_u32_e32 v163, 0x2000, v162
	v_lshl_add_u64 v[240:241], v[248:249], 0, s[14:15]
	s_mov_b32 m0, s3
	v_lshl_add_u64 v[250:251], s[94:95], 0, v[146:147]
	v_readfirstlane_b32 s3, v163
	ds_read_b128 v[224:227], v158
	ds_read_b128 v[228:231], v158 offset:1024
	ds_read_b128 v[232:235], v158 offset:2048
	ds_read_b128 v[236:239], v158 offset:3072
	global_load_lds_dwordx4 v[240:241], off
	v_lshl_add_u64 v[240:241], v[250:251], 0, s[14:15]
	s_mov_b32 m0, s3
	s_nop 0
	global_load_lds_dwordx4 v[240:241], off
	s_barrier
	s_waitcnt lgkmcnt(0)
	v_mfma_f32_16x16x32_bf16 v[92:95], v[224:227], v[192:195], v[92:95]
	v_mfma_f32_16x16x32_bf16 v[88:91], v[232:235], v[192:195], v[88:91]
	v_mfma_f32_16x16x32_bf16 v[84:87], v[224:227], v[200:203], v[84:87]
	v_mfma_f32_16x16x32_bf16 v[80:83], v[232:235], v[200:203], v[80:83]
	v_mfma_f32_16x16x32_bf16 v[76:79], v[224:227], v[208:211], v[76:79]
	v_mfma_f32_16x16x32_bf16 v[72:75], v[232:235], v[208:211], v[72:75]
	v_mfma_f32_16x16x32_bf16 v[68:71], v[224:227], v[216:219], v[68:71]
	v_mfma_f32_16x16x32_bf16 v[64:67], v[232:235], v[216:219], v[64:67]
	v_mfma_f32_16x16x32_bf16 v[92:95], v[228:231], v[196:199], v[92:95]
	v_mfma_f32_16x16x32_bf16 v[88:91], v[236:239], v[196:199], v[88:91]
	v_mfma_f32_16x16x32_bf16 v[84:87], v[228:231], v[204:207], v[84:87]
	v_mfma_f32_16x16x32_bf16 v[80:83], v[236:239], v[204:207], v[80:83]
	v_mfma_f32_16x16x32_bf16 v[76:79], v[228:231], v[212:215], v[76:79]
	v_mfma_f32_16x16x32_bf16 v[72:75], v[236:239], v[212:215], v[72:75]
	v_mfma_f32_16x16x32_bf16 v[68:71], v[228:231], v[220:223], v[68:71]
	v_mfma_f32_16x16x32_bf16 v[64:67], v[236:239], v[220:223], v[64:67]
	v_readfirstlane_b32 s3, v128
	v_add_u32_e32 v169, 0x2000, v128
	v_lshl_add_u64 v[240:241], v[244:245], 0, s[16:17]
	s_mov_b32 m0, s3
	v_readfirstlane_b32 s3, v169
	s_barrier
	ds_read_b128 v[192:195], v131 offset:16384
	ds_read_b128 v[196:199], v131 offset:17408
	ds_read_b128 v[200:203], v174 offset:16384
	ds_read_b128 v[204:207], v174 offset:17408
	ds_read_b128 v[208:211], v175 offset:16384
	ds_read_b128 v[212:215], v175 offset:17408
	ds_read_b128 v[216:219], v177 offset:16384
	ds_read_b128 v[220:223], v177 offset:17408
	global_load_lds_dwordx4 v[240:241], off
	v_lshl_add_u64 v[240:241], v[246:247], 0, s[16:17]
	s_mov_b32 m0, s3
	s_nop 0
	global_load_lds_dwordx4 v[240:241], off
	s_barrier
	s_waitcnt lgkmcnt(0)
	v_mfma_f32_16x16x32_bf16 v[60:63], v[170:173], v[192:195], v[60:63]
	v_mfma_f32_16x16x32_bf16 v[56:59], v[184:187], v[192:195], v[56:59]
	v_mfma_f32_16x16x32_bf16 v[52:55], v[170:173], v[200:203], v[52:55]
	v_mfma_f32_16x16x32_bf16 v[48:51], v[184:187], v[200:203], v[48:51]
	v_mfma_f32_16x16x32_bf16 v[44:47], v[170:173], v[208:211], v[44:47]
	v_mfma_f32_16x16x32_bf16 v[40:43], v[184:187], v[208:211], v[40:43]
	v_mfma_f32_16x16x32_bf16 v[36:39], v[170:173], v[216:219], v[36:39]
	v_mfma_f32_16x16x32_bf16 v[32:35], v[184:187], v[216:219], v[32:35]
	v_mfma_f32_16x16x32_bf16 v[60:63], v[180:183], v[196:199], v[60:63]
	v_mfma_f32_16x16x32_bf16 v[56:59], v[188:191], v[196:199], v[56:59]
	v_mfma_f32_16x16x32_bf16 v[52:55], v[180:183], v[204:207], v[52:55]
	v_mfma_f32_16x16x32_bf16 v[48:51], v[188:191], v[204:207], v[48:51]
	v_mfma_f32_16x16x32_bf16 v[44:47], v[180:183], v[212:215], v[44:47]
	v_mfma_f32_16x16x32_bf16 v[40:43], v[188:191], v[212:215], v[40:43]
	v_mfma_f32_16x16x32_bf16 v[36:39], v[180:183], v[220:223], v[36:39]
	v_mfma_f32_16x16x32_bf16 v[32:35], v[188:191], v[220:223], v[32:35]
	s_barrier
; #define STAGE(P,BASE,LD,br,kt) do{long _g=(long)(br)*(LD)+(long)(kt)*BK; \
;     _Pragma("unroll") for(int _i=0;_i<2;++_i){int _b=tid*16+_i*8192;int _r,_c;stage_rc(_b,_r,_c); \
;       __builtin_amdgcn_global_load_lds((const unsigned*)((BASE)+_g+(long)_r*(LD)+_c), \
;         (unsigned*)((char*)(P)+_b),16,0,0);}}while(0)
; #define STAGE(P,BASE,LD,br,kt) do{long _g=(long)(br)*(LD)+(long)(kt)*BK; \
;     _Pragma("unroll") for(int _i=0;_i<2;++_i){int _b=tid*16+_i*8192;int _r,_c;stage_rc(_b,_r,_c); \
;       __builtin_amdgcn_global_load_lds((const unsigned*)((BASE)+_g+(long)_r*(LD)+_c), \
;         (unsigned*)((char*)(P)+_b),16,0,0);}}while(0)
; #define LDA(dst,b,h) _Pragma("unroll") for(int m=0;m<4;++m) _Pragma("unroll") for(int k=0;k<2;++k) \
;     dst[m][k]=*reinterpret_cast<const bf16x8*>((char*)SA(b,h)+lds_byte(wr*64+m*16+fr,k*32+fq*8))
; #define LDB(dst,b,h) _Pragma("unroll") for(int n=0;n<2;++n) _Pragma("unroll") for(int k=0;k<2;++k) \
;     dst[n][k]=*reinterpret_cast<const bf16x8*>((char*)SB(b,h)+lds_byte(wc*32+n*16+fr,k*32+fq*8))
; #define MMA(ai,bj,At_,Bt_) do{__builtin_amdgcn_s_setprio(1); \
;     _Pragma("unroll") for(int m=0;m<4;++m) _Pragma("unroll") for(int n=0;n<2;++n) _Pragma("unroll") for(int k=0;k<2;++k) \
;       acc[ai][bj][m][n]=__builtin_amdgcn_mfma_f32_16x16x32_bf16(Bt_[n][k],At_[m][k],acc[ai][bj][m][n],0,0,0); \
;     __builtin_amdgcn_s_setprio(0);}while(0)
; #define WAIT_V(n) asm volatile("s_waitcnt vmcnt(" #n ")":::"memory")
; #define WAIT_L(n) asm volatile("s_waitcnt lgkmcnt(" #n ")":::"memory")
; #define BAR __builtin_amdgcn_s_barrier()
; #define SCHED __builtin_amdgcn_sched_barrier(0)
; DEVINL void gemm8_mainloop(const u16* A, long lda, const u16* Bt, long ldb, int K, int brow, int bcol, f32x4 (&acc)[2][2][4][2], char* smem, int tid) {
;     ...
;     STAGE(SB(0,1),Bt,ldb,bcol+HALF,t+2);
;     WAIT_V(6); BAR; MMA(1,1,At,B1); BAR;
;     LDB(B0,1,0); SCHED; LDA(At,1,0); STAGE(SA(0,1),A,lda,brow+HALF,t+2);
;     WAIT_L(8); BAR; WAIT_L(0); MMA(0,0,At,B0); BAR; SCHED;
;     LDB(B1,1,1); STAGE(SB(1,0),Bt,ldb,bcol,t+3);
;     BAR; WAIT_L(0); MMA(0,1,At,B1); BAR;
;     LDA(At,1,1); STAGE(SA(1,0),A,lda,brow,t+3);
	v_add_u32_e32 v170, s33, v153
	v_add_u32_e32 v171, 0x2000, v170
	v_readfirstlane_b32 s3, v170
	v_lshl_add_u64 v[172:173], v[248:249], 0, s[18:19]
	s_mov_b32 m0, s3
	v_readfirstlane_b32 s3, v171
	global_load_lds_dwordx4 v[172:173], off
	v_lshl_add_u64 v[172:173], v[250:251], 0, s[18:19]
	s_mov_b32 m0, s3
	s_nop 0
	global_load_lds_dwordx4 v[172:173], off
	s_waitcnt vmcnt(6)
	s_barrier
	v_mfma_f32_16x16x32_bf16 v[28:31], v[224:227], v[192:195], v[28:31]
	v_mfma_f32_16x16x32_bf16 v[24:27], v[232:235], v[192:195], v[24:27]
	v_mfma_f32_16x16x32_bf16 v[20:23], v[224:227], v[200:203], v[20:23]
	v_mfma_f32_16x16x32_bf16 v[16:19], v[232:235], v[200:203], v[16:19]
	v_mfma_f32_16x16x32_bf16 v[12:15], v[224:227], v[208:211], v[12:15]
	v_mfma_f32_16x16x32_bf16 v[8:11], v[232:235], v[208:211], v[8:11]
	v_mfma_f32_16x16x32_bf16 v[4:7], v[224:227], v[216:219], v[4:7]
	v_mfma_f32_16x16x32_bf16 v[0:3], v[232:235], v[216:219], v[0:3]
	v_mfma_f32_16x16x32_bf16 v[28:31], v[228:231], v[196:199], v[28:31]
	v_mfma_f32_16x16x32_bf16 v[24:27], v[236:239], v[196:199], v[24:27]
	v_mfma_f32_16x16x32_bf16 v[20:23], v[228:231], v[204:207], v[20:23]
	v_mfma_f32_16x16x32_bf16 v[16:19], v[236:239], v[204:207], v[16:19]
	v_mfma_f32_16x16x32_bf16 v[12:15], v[228:231], v[212:215], v[12:15]
	v_mfma_f32_16x16x32_bf16 v[8:11], v[236:239], v[212:215], v[8:11]
	v_mfma_f32_16x16x32_bf16 v[4:7], v[228:231], v[220:223], v[4:7]
	v_mfma_f32_16x16x32_bf16 v[0:3], v[236:239], v[220:223], v[0:3]
	s_barrier
	ds_read_b128 v[180:183], v154
	ds_read_b128 v[184:187], v154 offset:1024
	ds_read_b128 v[188:191], v154 offset:2048
	ds_read_b128 v[192:195], v154 offset:3072
	v_add_u32_e32 v172, 0x4000, v128
	v_add_u32_e32 v173, 0x6000, v128
	v_readfirstlane_b32 s3, v172
	v_lshl_add_u64 v[228:229], v[244:245], 0, s[20:21]
	s_mov_b32 m0, s3
	v_readfirstlane_b32 s3, v173
	ds_read_b128 v[196:199], v131 offset:32768
	ds_read_b128 v[200:203], v131 offset:33792
	ds_read_b128 v[204:207], v174 offset:32768
	ds_read_b128 v[208:211], v174 offset:33792
	ds_read_b128 v[212:215], v175 offset:32768
	ds_read_b128 v[216:219], v175 offset:33792
	ds_read_b128 v[220:223], v177 offset:32768
	ds_read_b128 v[224:227], v177 offset:33792
	global_load_lds_dwordx4 v[228:229], off
	v_lshl_add_u64 v[228:229], v[246:247], 0, s[20:21]
	s_mov_b32 m0, s3
	s_nop 0
	global_load_lds_dwordx4 v[228:229], off
	s_waitcnt lgkmcnt(8)
	s_barrier
	s_waitcnt lgkmcnt(0)
	v_mfma_f32_16x16x32_bf16 v[124:127], v[180:183], v[196:199], v[124:127]
	v_mfma_f32_16x16x32_bf16 v[120:123], v[188:191], v[196:199], v[120:123]
	v_mfma_f32_16x16x32_bf16 v[116:119], v[180:183], v[204:207], v[116:119]
	v_mfma_f32_16x16x32_bf16 v[112:115], v[188:191], v[204:207], v[112:115]
	v_mfma_f32_16x16x32_bf16 v[108:111], v[180:183], v[212:215], v[108:111]
	v_mfma_f32_16x16x32_bf16 v[104:107], v[188:191], v[212:215], v[104:107]
	v_mfma_f32_16x16x32_bf16 v[100:103], v[180:183], v[220:223], v[100:103]
	v_mfma_f32_16x16x32_bf16 v[96:99], v[188:191], v[220:223], v[96:99]
	v_mfma_f32_16x16x32_bf16 v[124:127], v[184:187], v[200:203], v[124:127]
	v_mfma_f32_16x16x32_bf16 v[120:123], v[192:195], v[200:203], v[120:123]
	v_mfma_f32_16x16x32_bf16 v[116:119], v[184:187], v[208:211], v[116:119]
	v_mfma_f32_16x16x32_bf16 v[112:115], v[192:195], v[208:211], v[112:115]
	v_mfma_f32_16x16x32_bf16 v[108:111], v[184:187], v[216:219], v[108:111]
	v_mfma_f32_16x16x32_bf16 v[104:107], v[192:195], v[216:219], v[104:107]
	v_mfma_f32_16x16x32_bf16 v[100:103], v[184:187], v[224:227], v[100:103]
	v_mfma_f32_16x16x32_bf16 v[96:99], v[192:195], v[224:227], v[96:99]
	s_barrier
	v_readfirstlane_b32 s3, v155
	v_add_u32_e32 v165, 0x2000, v155
	v_lshl_add_u64 v[252:253], v[248:249], 0, s[22:23]
	s_mov_b32 m0, s3
	v_readfirstlane_b32 s3, v165
	ds_read_b128 v[228:231], v152
	ds_read_b128 v[232:235], v152 offset:1024
	ds_read_b128 v[236:239], v152 offset:2048
	ds_read_b128 v[240:243], v152 offset:3072
	global_load_lds_dwordx4 v[252:253], off
	v_lshl_add_u64 v[252:253], v[250:251], 0, s[22:23]
	s_mov_b32 m0, s3
	s_nop 0
	global_load_lds_dwordx4 v[252:253], off
	s_barrier
	s_waitcnt lgkmcnt(0)
	v_mfma_f32_16x16x32_bf16 v[92:95], v[228:231], v[196:199], v[92:95]
	v_mfma_f32_16x16x32_bf16 v[88:91], v[236:239], v[196:199], v[88:91]
	v_mfma_f32_16x16x32_bf16 v[84:87], v[228:231], v[204:207], v[84:87]
	v_mfma_f32_16x16x32_bf16 v[80:83], v[236:239], v[204:207], v[80:83]
	v_mfma_f32_16x16x32_bf16 v[76:79], v[228:231], v[212:215], v[76:79]
	v_mfma_f32_16x16x32_bf16 v[72:75], v[236:239], v[212:215], v[72:75]
	v_mfma_f32_16x16x32_bf16 v[68:71], v[228:231], v[220:223], v[68:71]
	v_mfma_f32_16x16x32_bf16 v[64:67], v[236:239], v[220:223], v[64:67]
	v_mfma_f32_16x16x32_bf16 v[92:95], v[232:235], v[200:203], v[92:95]
	v_mfma_f32_16x16x32_bf16 v[88:91], v[240:243], v[200:203], v[88:91]
	v_mfma_f32_16x16x32_bf16 v[84:87], v[232:235], v[208:211], v[84:87]
	v_mfma_f32_16x16x32_bf16 v[80:83], v[240:243], v[208:211], v[80:83]
	v_mfma_f32_16x16x32_bf16 v[76:79], v[232:235], v[216:219], v[76:79]
	v_mfma_f32_16x16x32_bf16 v[72:75], v[240:243], v[216:219], v[72:75]
	v_mfma_f32_16x16x32_bf16 v[68:71], v[232:235], v[224:227], v[68:71]
	v_mfma_f32_16x16x32_bf16 v[64:67], v[240:243], v[224:227], v[64:67]
	v_readfirstlane_b32 s3, v156
	v_lshl_add_u64 v[244:245], v[244:245], 0, s[24:25]
	s_mov_b32 m0, s3
	v_readfirstlane_b32 s3, v157
	s_barrier
	ds_read_b128 v[196:199], v131 offset:49152
	ds_read_b128 v[200:203], v131 offset:50176
	ds_read_b128 v[204:207], v174 offset:49152
	ds_read_b128 v[208:211], v174 offset:50176
	ds_read_b128 v[212:215], v175 offset:49152
	ds_read_b128 v[216:219], v175 offset:50176
	ds_read_b128 v[220:223], v177 offset:49152
	ds_read_b128 v[224:227], v177 offset:50176
	global_load_lds_dwordx4 v[244:245], off
	v_lshl_add_u64 v[244:245], v[246:247], 0, s[24:25]
	s_mov_b32 m0, s3
	s_nop 0
	global_load_lds_dwordx4 v[244:245], off
	s_barrier
; #define STAGE(P,BASE,LD,br,kt) do{long _g=(long)(br)*(LD)+(long)(kt)*BK; \
;     _Pragma("unroll") for(int _i=0;_i<2;++_i){int _b=tid*16+_i*8192;int _r,_c;stage_rc(_b,_r,_c); \
;       __builtin_amdgcn_global_load_lds((const unsigned*)((BASE)+_g+(long)_r*(LD)+_c), \
;         (unsigned*)((char*)(P)+_b),16,0,0);}}while(0)
; #define STAGE(P,BASE,LD,br,kt) do{long _g=(long)(br)*(LD)+(long)(kt)*BK; \
;     _Pragma("unroll") for(int _i=0;_i<2;++_i){int _b=tid*16+_i*8192;int _r,_c;stage_rc(_b,_r,_c); \
;       __builtin_amdgcn_global_load_lds((const unsigned*)((BASE)+_g+(long)_r*(LD)+_c), \
;         (unsigned*)((char*)(P)+_b),16,0,0);}}while(0)
; #define LDA(dst,b,h) _Pragma("unroll") for(int m=0;m<4;++m) _Pragma("unroll") for(int k=0;k<2;++k) \
;     dst[m][k]=*reinterpret_cast<const bf16x8*>((char*)SA(b,h)+lds_byte(wr*64+m*16+fr,k*32+fq*8))
; #define LDB(dst,b,h) _Pragma("unroll") for(int n=0;n<2;++n) _Pragma("unroll") for(int k=0;k<2;++k) \
;     dst[n][k]=*reinterpret_cast<const bf16x8*>((char*)SB(b,h)+lds_byte(wc*32+n*16+fr,k*32+fq*8))
; #define MMA(ai,bj,At_,Bt_) do{__builtin_amdgcn_s_setprio(1); \
;     _Pragma("unroll") for(int m=0;m<4;++m) _Pragma("unroll") for(int n=0;n<2;++n) _Pragma("unroll") for(int k=0;k<2;++k) \
;       acc[ai][bj][m][n]=__builtin_amdgcn_mfma_f32_16x16x32_bf16(Bt_[n][k],At_[m][k],acc[ai][bj][m][n],0,0,0); \
;     __builtin_amdgcn_s_setprio(0);}while(0)
; #define WAIT_V(n) asm volatile("s_waitcnt vmcnt(" #n ")":::"memory")
; #define WAIT_L(n) asm volatile("s_waitcnt lgkmcnt(" #n ")":::"memory")
; #define BAR __builtin_amdgcn_s_barrier()
; #define SCHED __builtin_amdgcn_sched_barrier(0)
; DEVINL void gemm8_mainloop(const u16* A, long lda, const u16* Bt, long ldb, int K, int brow, int bcol, f32x4 (&acc)[2][2][4][2], char* smem, int tid) {
;     ...
;     BAR; WAIT_L(0); MMA(1,0,At,B0); BAR; SCHED;
;     STAGE(SB(1,1),Bt,ldb,bcol+HALF,t+3);
;     WAIT_V(6); BAR; MMA(1,1,At,B1); BAR;
;   }
;   { LDB(B0,0,0); LDA(At,0,0); STAGE(SA(1,1),A,lda,brow+HALF,nt-1);
;     BAR; WAIT_L(0); MMA(0,0,At,B0); BAR;
;     LDB(B1,0,1); BAR; WAIT_L(0); MMA(0,1,At,B1); BAR;
	s_waitcnt lgkmcnt(0)
	v_mfma_f32_16x16x32_bf16 v[60:63], v[180:183], v[196:199], v[60:63]
	v_mfma_f32_16x16x32_bf16 v[56:59], v[188:191], v[196:199], v[56:59]
	v_mfma_f32_16x16x32_bf16 v[52:55], v[180:183], v[204:207], v[52:55]
	v_mfma_f32_16x16x32_bf16 v[48:51], v[188:191], v[204:207], v[48:51]
	v_mfma_f32_16x16x32_bf16 v[44:47], v[180:183], v[212:215], v[44:47]
	v_mfma_f32_16x16x32_bf16 v[40:43], v[188:191], v[212:215], v[40:43]
	v_mfma_f32_16x16x32_bf16 v[36:39], v[180:183], v[220:223], v[36:39]
	v_mfma_f32_16x16x32_bf16 v[32:35], v[188:191], v[220:223], v[32:35]
	v_mfma_f32_16x16x32_bf16 v[60:63], v[184:187], v[200:203], v[60:63]
	v_mfma_f32_16x16x32_bf16 v[56:59], v[192:195], v[200:203], v[56:59]
	v_mfma_f32_16x16x32_bf16 v[52:55], v[184:187], v[208:211], v[52:55]
	v_mfma_f32_16x16x32_bf16 v[48:51], v[192:195], v[208:211], v[48:51]
	v_mfma_f32_16x16x32_bf16 v[44:47], v[184:187], v[216:219], v[44:47]
	v_mfma_f32_16x16x32_bf16 v[40:43], v[192:195], v[216:219], v[40:43]
	v_mfma_f32_16x16x32_bf16 v[36:39], v[184:187], v[224:227], v[36:39]
	v_mfma_f32_16x16x32_bf16 v[32:35], v[192:195], v[224:227], v[32:35]
	s_barrier
	v_readfirstlane_b32 s3, v159
	v_add_u32_e32 v165, 0x2000, v159
	v_lshl_add_u64 v[180:181], v[248:249], 0, s[26:27]
	s_mov_b32 m0, s3
	v_readfirstlane_b32 s3, v165
	global_load_lds_dwordx4 v[180:181], off
	v_lshl_add_u64 v[180:181], v[250:251], 0, s[26:27]
	s_mov_b32 m0, s3
	s_nop 0
	global_load_lds_dwordx4 v[180:181], off
	s_waitcnt vmcnt(6)
	s_barrier
	v_mfma_f32_16x16x32_bf16 v[28:31], v[228:231], v[196:199], v[28:31]
	v_mfma_f32_16x16x32_bf16 v[24:27], v[236:239], v[196:199], v[24:27]
	v_mfma_f32_16x16x32_bf16 v[20:23], v[228:231], v[204:207], v[20:23]
	v_mfma_f32_16x16x32_bf16 v[16:19], v[236:239], v[204:207], v[16:19]
	v_mfma_f32_16x16x32_bf16 v[12:15], v[228:231], v[212:215], v[12:15]
	v_mfma_f32_16x16x32_bf16 v[8:11], v[236:239], v[212:215], v[8:11]
	v_mfma_f32_16x16x32_bf16 v[4:7], v[228:231], v[220:223], v[4:7]
	v_mfma_f32_16x16x32_bf16 v[0:3], v[236:239], v[220:223], v[0:3]
	v_mfma_f32_16x16x32_bf16 v[28:31], v[232:235], v[200:203], v[28:31]
	v_mfma_f32_16x16x32_bf16 v[24:27], v[240:243], v[200:203], v[24:27]
	v_mfma_f32_16x16x32_bf16 v[20:23], v[232:235], v[208:211], v[20:23]
	v_mfma_f32_16x16x32_bf16 v[16:19], v[240:243], v[208:211], v[16:19]
	v_mfma_f32_16x16x32_bf16 v[12:15], v[232:235], v[216:219], v[12:15]
	v_mfma_f32_16x16x32_bf16 v[8:11], v[240:243], v[216:219], v[8:11]
	v_mfma_f32_16x16x32_bf16 v[4:7], v[232:235], v[224:227], v[4:7]
	v_mfma_f32_16x16x32_bf16 v[0:3], v[240:243], v[224:227], v[0:3]
	s_add_i32 s2, s2, 2
	v_lshl_add_u64 v[144:145], v[144:145], 0, s[14:15]
	v_lshl_add_u64 v[146:147], v[146:147], 0, s[14:15]
	v_lshl_add_u64 v[148:149], v[148:149], 0, s[14:15]
	s_cmp_lt_u32 s2, 28
	v_lshl_add_u64 v[150:151], v[150:151], 0, s[14:15]
	s_barrier
	s_cbranch_scc1 .LBB0_269
	s_or_b32 s2, s40, 0x80
	s_ashr_i32 s3, s2, 31
	s_lshl_b64 s[2:3], s[2:3], 12
	s_add_u32 s2, s90, s2
	s_addc_u32 s3, s91, s3
	v_lshl_add_u64 v[156:157], v[136:137], 1, s[2:3]
	v_lshl_add_u64 v[140:141], v[140:141], 1, v[156:157]
	v_readfirstlane_b32 s41, v178
	v_lshl_add_u64 v[140:141], v[140:141], 0, s[28:29]
	s_mov_b32 m0, s41
	ds_read_b128 v[144:147], v161
	ds_read_b128 v[148:151], v161 offset:1024
	ds_read_b128 v[180:183], v161 offset:2048
	ds_read_b128 v[184:187], v161 offset:3072
	ds_read_b128 v[188:191], v131
	ds_read_b128 v[192:195], v131 offset:1024
	ds_read_b128 v[196:199], v174
	ds_read_b128 v[200:203], v174 offset:1024
	ds_read_b128 v[204:207], v175
	ds_read_b128 v[208:211], v175 offset:1024
	ds_read_b128 v[212:215], v177
	ds_read_b128 v[216:219], v177 offset:1024
	global_load_lds_dwordx4 v[140:141], off
	v_lshl_add_u64 v[140:141], v[138:139], 1, s[2:3]
	v_lshl_add_u64 v[140:141], v[142:143], 1, v[140:141]
	v_readfirstlane_b32 s2, v179
	v_lshl_add_u64 v[140:141], v[140:141], 0, s[28:29]
	s_mov_b32 m0, s2
	s_nop 0
	global_load_lds_dwordx4 v[140:141], off
	s_barrier
	s_waitcnt lgkmcnt(0)
	v_mfma_f32_16x16x32_bf16 v[124:127], v[144:147], v[188:191], v[124:127]
	v_mfma_f32_16x16x32_bf16 v[120:123], v[180:183], v[188:191], v[120:123]
	v_mfma_f32_16x16x32_bf16 v[108:111], v[144:147], v[204:207], v[108:111]
	v_mfma_f32_16x16x32_bf16 v[104:107], v[180:183], v[204:207], v[104:107]
	v_mfma_f32_16x16x32_bf16 v[124:127], v[148:151], v[192:195], v[124:127]
	v_mfma_f32_16x16x32_bf16 v[120:123], v[184:187], v[192:195], v[120:123]
	v_mfma_f32_16x16x32_bf16 v[116:119], v[144:147], v[196:199], v[116:119]
	v_mfma_f32_16x16x32_bf16 v[112:115], v[180:183], v[196:199], v[112:115]
	v_mfma_f32_16x16x32_bf16 v[108:111], v[148:151], v[208:211], v[108:111]
	v_mfma_f32_16x16x32_bf16 v[104:107], v[184:187], v[208:211], v[104:107]
	v_mfma_f32_16x16x32_bf16 v[100:103], v[144:147], v[212:215], v[100:103]
	v_mfma_f32_16x16x32_bf16 v[96:99], v[180:183], v[212:215], v[96:99]
	v_mfma_f32_16x16x32_bf16 v[140:143], v[148:151], v[200:203], v[116:119]
	v_mfma_f32_16x16x32_bf16 v[220:223], v[184:187], v[200:203], v[112:115]
	v_mfma_f32_16x16x32_bf16 v[224:227], v[148:151], v[216:219], v[100:103]
	v_mfma_f32_16x16x32_bf16 v[228:231], v[184:187], v[216:219], v[96:99]
	s_barrier
	s_nop 1
	s_nop 0
	ds_read_b128 v[96:99], v158
	ds_read_b128 v[100:103], v158 offset:1024
	ds_read_b128 v[112:115], v158 offset:2048
	ds_read_b128 v[116:119], v158 offset:3072
	s_barrier
; #define LDA(dst,b,h) _Pragma("unroll") for(int m=0;m<4;++m) _Pragma("unroll") for(int k=0;k<2;++k) \
;     dst[m][k]=*reinterpret_cast<const bf16x8*>((char*)SA(b,h)+lds_byte(wr*64+m*16+fr,k*32+fq*8))
; #define LDB(dst,b,h) _Pragma("unroll") for(int n=0;n<2;++n) _Pragma("unroll") for(int k=0;k<2;++k) \
;     dst[n][k]=*reinterpret_cast<const bf16x8*>((char*)SB(b,h)+lds_byte(wc*32+n*16+fr,k*32+fq*8))
; #define MMA(ai,bj,At_,Bt_) do{__builtin_amdgcn_s_setprio(1); \
;     _Pragma("unroll") for(int m=0;m<4;++m) _Pragma("unroll") for(int n=0;n<2;++n) _Pragma("unroll") for(int k=0;k<2;++k) \
;       acc[ai][bj][m][n]=__builtin_amdgcn_mfma_f32_16x16x32_bf16(Bt_[n][k],At_[m][k],acc[ai][bj][m][n],0,0,0); \
;     __builtin_amdgcn_s_setprio(0);}while(0)
; #define WAIT_V(n) asm volatile("s_waitcnt vmcnt(" #n ")":::"memory")
; #define WAIT_L(n) asm volatile("s_waitcnt lgkmcnt(" #n ")":::"memory")
; #define BAR __builtin_amdgcn_s_barrier()
; DEVINL void gemm8_mainloop(const u16* A, long lda, const u16* Bt, long ldb, int K, int brow, int bcol, f32x4 (&acc)[2][2][4][2], char* smem, int tid) {
;     ...
;     LDB(B1,0,1); BAR; WAIT_L(0); MMA(0,1,At,B1); BAR;
;     LDA(At,0,1); WAIT_V(4); BAR; WAIT_L(0); MMA(1,0,At,B0); MMA(1,1,At,B1); BAR; }
;   { LDB(B0,1,0); LDA(At,1,0); WAIT_V(2); BAR; WAIT_L(0); MMA(0,0,At,B0); BAR;
	s_waitcnt lgkmcnt(0)
	v_mfma_f32_16x16x32_bf16 v[92:95], v[96:99], v[188:191], v[92:95]
	v_mfma_f32_16x16x32_bf16 v[88:91], v[112:115], v[188:191], v[88:91]
	v_mfma_f32_16x16x32_bf16 v[76:79], v[96:99], v[204:207], v[76:79]
	v_mfma_f32_16x16x32_bf16 v[72:75], v[112:115], v[204:207], v[72:75]
	v_mfma_f32_16x16x32_bf16 v[92:95], v[100:103], v[192:195], v[92:95]
	v_mfma_f32_16x16x32_bf16 v[88:91], v[116:119], v[192:195], v[88:91]
	v_mfma_f32_16x16x32_bf16 v[84:87], v[96:99], v[196:199], v[84:87]
	v_mfma_f32_16x16x32_bf16 v[80:83], v[112:115], v[196:199], v[80:83]
	v_mfma_f32_16x16x32_bf16 v[76:79], v[100:103], v[208:211], v[76:79]
	v_mfma_f32_16x16x32_bf16 v[72:75], v[116:119], v[208:211], v[72:75]
	v_mfma_f32_16x16x32_bf16 v[68:71], v[96:99], v[212:215], v[68:71]
	v_mfma_f32_16x16x32_bf16 v[64:67], v[112:115], v[212:215], v[64:67]
	v_mfma_f32_16x16x32_bf16 v[156:159], v[100:103], v[200:203], v[84:87]
	v_mfma_f32_16x16x32_bf16 v[188:191], v[116:119], v[200:203], v[80:83]
	v_mfma_f32_16x16x32_bf16 v[192:195], v[100:103], v[216:219], v[68:71]
	v_mfma_f32_16x16x32_bf16 v[196:199], v[116:119], v[216:219], v[64:67]
	s_barrier
	s_nop 1
	s_nop 0
	ds_read_b128 v[64:67], v131 offset:16384
	ds_read_b128 v[68:71], v131 offset:17408
	ds_read_b128 v[80:83], v174 offset:16384
	ds_read_b128 v[84:87], v174 offset:17408
	ds_read_b128 v[200:203], v175 offset:16384
	ds_read_b128 v[204:207], v175 offset:17408
	ds_read_b128 v[208:211], v177 offset:16384
	ds_read_b128 v[212:215], v177 offset:17408
	s_waitcnt vmcnt(4)
	s_barrier
	s_waitcnt lgkmcnt(0)
	v_mfma_f32_16x16x32_bf16 v[60:63], v[144:147], v[64:67], v[60:63]
	v_mfma_f32_16x16x32_bf16 v[52:55], v[144:147], v[80:83], v[52:55]
	v_mfma_f32_16x16x32_bf16 v[44:47], v[144:147], v[200:203], v[44:47]
	v_mfma_f32_16x16x32_bf16 v[40:43], v[180:183], v[200:203], v[40:43]
	v_mfma_f32_16x16x32_bf16 v[60:63], v[148:151], v[68:71], v[60:63]
	v_mfma_f32_16x16x32_bf16 v[56:59], v[180:183], v[64:67], v[56:59]
	v_mfma_f32_16x16x32_bf16 v[52:55], v[148:151], v[84:87], v[52:55]
	v_mfma_f32_16x16x32_bf16 v[48:51], v[180:183], v[80:83], v[48:51]
	v_mfma_f32_16x16x32_bf16 v[44:47], v[148:151], v[204:207], v[44:47]
	v_mfma_f32_16x16x32_bf16 v[40:43], v[184:187], v[204:207], v[40:43]
	v_mfma_f32_16x16x32_bf16 v[36:39], v[144:147], v[208:211], v[36:39]
	v_mfma_f32_16x16x32_bf16 v[32:35], v[180:183], v[208:211], v[32:35]
	v_mfma_f32_16x16x32_bf16 v[216:219], v[184:187], v[68:71], v[56:59]
	v_mfma_f32_16x16x32_bf16 v[232:235], v[184:187], v[84:87], v[48:51]
	v_mfma_f32_16x16x32_bf16 v[144:147], v[148:151], v[212:215], v[36:39]
	v_mfma_f32_16x16x32_bf16 v[148:151], v[184:187], v[212:215], v[32:35]
	v_mfma_f32_16x16x32_bf16 v[28:31], v[96:99], v[64:67], v[28:31]
	v_mfma_f32_16x16x32_bf16 v[20:23], v[96:99], v[80:83], v[20:23]
	v_mfma_f32_16x16x32_bf16 v[12:15], v[96:99], v[200:203], v[12:15]
	v_mfma_f32_16x16x32_bf16 v[4:7], v[96:99], v[208:211], v[4:7]
	v_mfma_f32_16x16x32_bf16 v[28:31], v[100:103], v[68:71], v[28:31]
	v_mfma_f32_16x16x32_bf16 v[24:27], v[112:115], v[64:67], v[24:27]
	v_mfma_f32_16x16x32_bf16 v[20:23], v[100:103], v[84:87], v[20:23]
	v_mfma_f32_16x16x32_bf16 v[16:19], v[112:115], v[80:83], v[16:19]
	v_mfma_f32_16x16x32_bf16 v[12:15], v[100:103], v[204:207], v[12:15]
	v_mfma_f32_16x16x32_bf16 v[8:11], v[112:115], v[200:203], v[8:11]
	v_mfma_f32_16x16x32_bf16 v[4:7], v[100:103], v[212:215], v[4:7]
	v_mfma_f32_16x16x32_bf16 v[0:3], v[112:115], v[208:211], v[0:3]
	v_mfma_f32_16x16x32_bf16 v[178:181], v[116:119], v[68:71], v[24:27]
	v_mfma_f32_16x16x32_bf16 v[182:185], v[116:119], v[84:87], v[16:19]
	v_mfma_f32_16x16x32_bf16 v[200:203], v[116:119], v[204:207], v[8:11]
	v_mfma_f32_16x16x32_bf16 v[204:207], v[116:119], v[212:215], v[0:3]
	s_barrier
	s_nop 1
	s_nop 0
	ds_read_b128 v[0:3], v154
	ds_read_b128 v[8:11], v154 offset:1024
	ds_read_b128 v[208:211], v154 offset:2048
	ds_read_b128 v[212:215], v154 offset:3072
	ds_read_b128 v[16:19], v131 offset:32768
	ds_read_b128 v[24:27], v131 offset:33792
	ds_read_b128 v[32:35], v174 offset:32768
	ds_read_b128 v[36:39], v174 offset:33792
	ds_read_b128 v[48:51], v175 offset:32768
	ds_read_b128 v[56:59], v175 offset:33792
	ds_read_b128 v[236:239], v177 offset:32768
	ds_read_b128 v[240:243], v177 offset:33792
	s_waitcnt vmcnt(2)
	s_barrier
; #define LDA(dst,b,h) _Pragma("unroll") for(int m=0;m<4;++m) _Pragma("unroll") for(int k=0;k<2;++k) \
;     dst[m][k]=*reinterpret_cast<const bf16x8*>((char*)SA(b,h)+lds_byte(wr*64+m*16+fr,k*32+fq*8))
; #define LDB(dst,b,h) _Pragma("unroll") for(int n=0;n<2;++n) _Pragma("unroll") for(int k=0;k<2;++k) \
;     dst[n][k]=*reinterpret_cast<const bf16x8*>((char*)SB(b,h)+lds_byte(wc*32+n*16+fr,k*32+fq*8))
; #define MMA(ai,bj,At_,Bt_) do{__builtin_amdgcn_s_setprio(1); \
;     _Pragma("unroll") for(int m=0;m<4;++m) _Pragma("unroll") for(int n=0;n<2;++n) _Pragma("unroll") for(int k=0;k<2;++k) \
;       acc[ai][bj][m][n]=__builtin_amdgcn_mfma_f32_16x16x32_bf16(Bt_[n][k],At_[m][k],acc[ai][bj][m][n],0,0,0); \
;     __builtin_amdgcn_s_setprio(0);}while(0)
; #define WAIT_V(n) asm volatile("s_waitcnt vmcnt(" #n ")":::"memory")
; #define WAIT_L(n) asm volatile("s_waitcnt lgkmcnt(" #n ")":::"memory")
; #define BAR __builtin_amdgcn_s_barrier()
; DEVINL void gemm8_mainloop(const u16* A, long lda, const u16* Bt, long ldb, int K, int brow, int bcol, f32x4 (&acc)[2][2][4][2], char* smem, int tid) {
;     ...
;   { LDB(B0,1,0); LDA(At,1,0); WAIT_V(2); BAR; WAIT_L(0); MMA(0,0,At,B0); BAR;
;     LDB(B1,1,1); WAIT_V(0); BAR; WAIT_L(0); MMA(0,1,At,B1); BAR;
;     LDA(At,1,1); BAR; WAIT_L(0); MMA(1,0,At,B0); MMA(1,1,At,B1); BAR; }
;   if(wr==0)BAR;
	s_waitcnt lgkmcnt(0)
	v_mfma_f32_16x16x32_bf16 v[64:67], v[0:3], v[16:19], v[124:127]
	v_mfma_f32_16x16x32_bf16 v[116:119], v[8:11], v[24:27], v[64:67]
	v_mfma_f32_16x16x32_bf16 v[64:67], v[208:211], v[16:19], v[120:123]
	v_mfma_f32_16x16x32_bf16 v[112:115], v[212:215], v[24:27], v[64:67]
	v_mfma_f32_16x16x32_bf16 v[64:67], v[0:3], v[32:35], v[140:143]
	v_mfma_f32_16x16x32_bf16 v[100:103], v[8:11], v[36:39], v[64:67]
	v_mfma_f32_16x16x32_bf16 v[64:67], v[208:211], v[32:35], v[220:223]
	v_mfma_f32_16x16x32_bf16 v[96:99], v[212:215], v[36:39], v[64:67]
	v_mfma_f32_16x16x32_bf16 v[64:67], v[0:3], v[48:51], v[108:111]
	v_mfma_f32_16x16x32_bf16 v[84:87], v[8:11], v[56:59], v[64:67]
	v_mfma_f32_16x16x32_bf16 v[64:67], v[208:211], v[48:51], v[104:107]
	v_mfma_f32_16x16x32_bf16 v[80:83], v[212:215], v[56:59], v[64:67]
	v_mfma_f32_16x16x32_bf16 v[64:67], v[0:3], v[236:239], v[224:227]
	v_mfma_f32_16x16x32_bf16 v[68:71], v[8:11], v[240:243], v[64:67]
	v_mfma_f32_16x16x32_bf16 v[64:67], v[208:211], v[236:239], v[228:231]
	v_mfma_f32_16x16x32_bf16 v[64:67], v[212:215], v[240:243], v[64:67]
	s_barrier
	ds_read_b128 v[140:143], v152
	ds_read_b128 v[220:223], v152 offset:1024
	ds_read_b128 v[224:227], v152 offset:2048
	ds_read_b128 v[152:155], v152 offset:3072
	s_waitcnt vmcnt(0)
	s_barrier
	s_waitcnt lgkmcnt(0)
	v_mfma_f32_16x16x32_bf16 v[92:95], v[140:143], v[16:19], v[92:95]
	v_mfma_f32_16x16x32_bf16 v[16:19], v[224:227], v[16:19], v[88:91]
	v_mfma_f32_16x16x32_bf16 v[120:123], v[152:155], v[24:27], v[16:19]
	v_mfma_f32_16x16x32_bf16 v[16:19], v[140:143], v[32:35], v[156:159]
	v_mfma_f32_16x16x32_bf16 v[104:107], v[220:223], v[36:39], v[16:19]
	v_mfma_f32_16x16x32_bf16 v[16:19], v[224:227], v[32:35], v[188:191]
	v_mfma_f32_16x16x32_bf16 v[108:111], v[152:155], v[36:39], v[16:19]
	v_mfma_f32_16x16x32_bf16 v[16:19], v[140:143], v[48:51], v[76:79]
	v_mfma_f32_16x16x32_bf16 v[124:127], v[220:223], v[24:27], v[92:95]
	v_mfma_f32_16x16x32_bf16 v[92:95], v[220:223], v[56:59], v[16:19]
	v_mfma_f32_16x16x32_bf16 v[16:19], v[224:227], v[48:51], v[72:75]
	v_mfma_f32_16x16x32_bf16 v[88:91], v[152:155], v[56:59], v[16:19]
	v_mfma_f32_16x16x32_bf16 v[16:19], v[140:143], v[236:239], v[192:195]
	v_mfma_f32_16x16x32_bf16 v[72:75], v[220:223], v[240:243], v[16:19]
	v_mfma_f32_16x16x32_bf16 v[16:19], v[224:227], v[236:239], v[196:199]
	v_mfma_f32_16x16x32_bf16 v[76:79], v[152:155], v[240:243], v[16:19]
	s_barrier
	ds_read_b128 v[156:159], v131 offset:49152
	ds_read_b128 v[186:189], v131 offset:50176
	ds_read_b128 v[190:193], v174 offset:49152
	ds_read_b128 v[194:197], v174 offset:50176
	ds_read_b128 v[228:231], v175 offset:49152
	ds_read_b128 v[236:239], v175 offset:50176
	ds_read_b128 v[240:243], v177 offset:49152
	ds_read_b128 v[244:247], v177 offset:50176
	s_barrier
	s_waitcnt lgkmcnt(0)
	v_mfma_f32_16x16x32_bf16 v[16:19], v[0:3], v[156:159], v[60:63]
	v_mfma_f32_16x16x32_bf16 v[56:59], v[8:11], v[186:189], v[16:19]
	v_mfma_f32_16x16x32_bf16 v[16:19], v[208:211], v[156:159], v[216:219]
	v_mfma_f32_16x16x32_bf16 v[48:51], v[212:215], v[186:189], v[16:19]
	v_mfma_f32_16x16x32_bf16 v[16:19], v[0:3], v[190:193], v[52:55]
	v_mfma_f32_16x16x32_bf16 v[36:39], v[8:11], v[194:197], v[16:19]
	v_mfma_f32_16x16x32_bf16 v[16:19], v[208:211], v[190:193], v[232:235]
	v_mfma_f32_16x16x32_bf16 v[32:35], v[212:215], v[194:197], v[16:19]
	v_mfma_f32_16x16x32_bf16 v[16:19], v[0:3], v[228:231], v[44:47]
	v_mfma_f32_16x16x32_bf16 v[0:3], v[0:3], v[240:243], v[144:147]
	v_mfma_f32_16x16x32_bf16 v[24:27], v[8:11], v[236:239], v[16:19]
	v_mfma_f32_16x16x32_bf16 v[16:19], v[208:211], v[228:231], v[40:43]
	v_mfma_f32_16x16x32_bf16 v[8:11], v[8:11], v[244:247], v[0:3]
	v_mfma_f32_16x16x32_bf16 v[0:3], v[208:211], v[240:243], v[148:151]
	v_mfma_f32_16x16x32_bf16 v[16:19], v[212:215], v[236:239], v[16:19]
	v_mfma_f32_16x16x32_bf16 v[0:3], v[212:215], v[244:247], v[0:3]
	v_mfma_f32_16x16x32_bf16 v[28:31], v[140:143], v[156:159], v[28:31]
	v_mfma_f32_16x16x32_bf16 v[60:63], v[220:223], v[186:189], v[28:31]
	v_mfma_f32_16x16x32_bf16 v[28:31], v[224:227], v[156:159], v[178:181]
	v_mfma_f32_16x16x32_bf16 v[20:23], v[140:143], v[190:193], v[20:23]
	v_mfma_f32_16x16x32_bf16 v[12:15], v[140:143], v[228:231], v[12:15]
	v_mfma_f32_16x16x32_bf16 v[52:55], v[152:155], v[186:189], v[28:31]
	v_mfma_f32_16x16x32_bf16 v[40:43], v[220:223], v[194:197], v[20:23]
	v_mfma_f32_16x16x32_bf16 v[20:23], v[224:227], v[190:193], v[182:185]
	v_mfma_f32_16x16x32_bf16 v[28:31], v[220:223], v[236:239], v[12:15]
	v_mfma_f32_16x16x32_bf16 v[12:15], v[224:227], v[228:231], v[200:203]
	v_mfma_f32_16x16x32_bf16 v[4:7], v[140:143], v[240:243], v[4:7]
	v_mfma_f32_16x16x32_bf16 v[44:47], v[152:155], v[194:197], v[20:23]
	v_mfma_f32_16x16x32_bf16 v[20:23], v[152:155], v[236:239], v[12:15]
	v_mfma_f32_16x16x32_bf16 v[12:15], v[220:223], v[244:247], v[4:7]
	v_mfma_f32_16x16x32_bf16 v[4:7], v[224:227], v[240:243], v[204:207]
	v_mfma_f32_16x16x32_bf16 v[4:7], v[152:155], v[244:247], v[4:7]
	s_cmpk_gt_u32 s44, 0xff
	s_barrier
	s_cbranch_scc1 .LBB0_272
	s_barrier

; #define STAGE(P,BASE,LD,br,kt) do{long _g=(long)(br)*(LD)+(long)(kt)*BK; \
;     _Pragma("unroll") for(int _i=0;_i<2;++_i){int _b=tid*16+_i*8192;int _r,_c;stage_rc(_b,_r,_c); \
;       __builtin_amdgcn_global_load_lds((const unsigned*)((BASE)+_g+(long)_r*(LD)+_c), \
;         (unsigned*)((char*)(P)+_b),16,0,0);}}while(0)
; #define STAGE(P,BASE,LD,br,kt) do{long _g=(long)(br)*(LD)+(long)(kt)*BK; \
;     _Pragma("unroll") for(int _i=0;_i<2;++_i){int _b=tid*16+_i*8192;int _r,_c;stage_rc(_b,_r,_c); \
;       __builtin_amdgcn_global_load_lds((const unsigned*)((BASE)+_g+(long)_r*(LD)+_c), \
;         (unsigned*)((char*)(P)+_b),16,0,0);}}while(0)
; #define LDA(dst,b,h) _Pragma("unroll") for(int m=0;m<4;++m) _Pragma("unroll") for(int k=0;k<2;++k) \
;     dst[m][k]=*reinterpret_cast<const bf16x8*>((char*)SA(b,h)+lds_byte(wr*64+m*16+fr,k*32+fq*8))
; #define LDB(dst,b,h) _Pragma("unroll") for(int n=0;n<2;++n) _Pragma("unroll") for(int k=0;k<2;++k) \
;     dst[n][k]=*reinterpret_cast<const bf16x8*>((char*)SB(b,h)+lds_byte(wc*32+n*16+fr,k*32+fq*8))
; #define MMA(ai,bj,At_,Bt_) do{__builtin_amdgcn_s_setprio(1); \
;     _Pragma("unroll") for(int m=0;m<4;++m) _Pragma("unroll") for(int n=0;n<2;++n) _Pragma("unroll") for(int k=0;k<2;++k) \
;       acc[ai][bj][m][n]=__builtin_amdgcn_mfma_f32_16x16x32_bf16(Bt_[n][k],At_[m][k],acc[ai][bj][m][n],0,0,0); \
;     __builtin_amdgcn_s_setprio(0);}while(0)
; #define WAIT_L(n) asm volatile("s_waitcnt lgkmcnt(" #n ")":::"memory")
; #define BAR __builtin_amdgcn_s_barrier()
; #define SCHED __builtin_amdgcn_sched_barrier(0)
; DEVINL void gemm8_mainloop(const u16* A, long lda, const u16* Bt, long ldb, int K, int brow, int bcol, f32x4 (&acc)[2][2][4][2], char* smem, int tid) {
;     ...
;   for(int t=0;t<nt-2;t+=2){
;     LDB(B0,0,0); SCHED; LDA(At,0,0); STAGE(SA(1,1),A,lda,brow+HALF,t+1);
;     WAIT_L(8); BAR; WAIT_L(0); MMA(0,0,At,B0); BAR; SCHED;
;     LDB(B1,0,1); STAGE(SB(0,0),Bt,ldb,bcol,t+2);
;     BAR; WAIT_L(0); MMA(0,1,At,B1); BAR;
;     LDA(At,0,1); STAGE(SA(0,0),A,lda,brow,t+2);
;     BAR; WAIT_L(0); MMA(1,0,At,B0); BAR; SCHED;
.LBB0_849:
	ds_read_b128 v[178:181], v163
	ds_read_b128 v[182:185], v163 offset:1024
	ds_read_b128 v[186:189], v163 offset:2048
	ds_read_b128 v[190:193], v163 offset:3072
	v_add_u32_e32 v174, 0xc000, v152
	v_lshl_add_u64 v[242:243], s[94:95], 0, v[146:147]
	v_readfirstlane_b32 s27, v174
	v_add_u32_e32 v175, 0xe000, v152
	v_add_u32_e32 v171, s0, v162
	v_add_u32_e32 v172, s1, v162
	v_add_u32_e32 v173, s29, v162
	v_lshl_add_u64 v[164:165], v[242:243], 0, s[4:5]
	s_mov_b32 m0, s27
	v_lshl_add_u64 v[244:245], s[94:95], 0, v[148:149]
	v_readfirstlane_b32 s27, v175
	ds_read_b128 v[166:169], v153
	ds_read_b128 v[194:197], v153 offset:1024
	ds_read_b128 v[198:201], v171
	ds_read_b128 v[202:205], v171 offset:1024
	ds_read_b128 v[206:209], v172
	ds_read_b128 v[210:213], v172 offset:1024
	ds_read_b128 v[214:217], v173
	ds_read_b128 v[218:221], v173 offset:1024
	global_load_lds_dwordx4 v[164:165], off
	v_lshl_add_u64 v[164:165], v[244:245], 0, s[4:5]
	s_mov_b32 m0, s27
	s_nop 0
	global_load_lds_dwordx4 v[164:165], off
	s_waitcnt lgkmcnt(8)
	s_barrier
	s_waitcnt lgkmcnt(0)
	v_mfma_f32_16x16x32_bf16 v[124:127], v[178:181], v[166:169], v[124:127]
	v_mfma_f32_16x16x32_bf16 v[120:123], v[186:189], v[166:169], v[120:123]
	v_mfma_f32_16x16x32_bf16 v[116:119], v[178:181], v[198:201], v[116:119]
	v_mfma_f32_16x16x32_bf16 v[112:115], v[186:189], v[198:201], v[112:115]
	v_mfma_f32_16x16x32_bf16 v[108:111], v[178:181], v[206:209], v[108:111]
	v_mfma_f32_16x16x32_bf16 v[104:107], v[186:189], v[206:209], v[104:107]
	v_mfma_f32_16x16x32_bf16 v[100:103], v[178:181], v[214:217], v[100:103]
	v_mfma_f32_16x16x32_bf16 v[96:99], v[186:189], v[214:217], v[96:99]
	v_mfma_f32_16x16x32_bf16 v[124:127], v[182:185], v[194:197], v[124:127]
	v_mfma_f32_16x16x32_bf16 v[120:123], v[190:193], v[194:197], v[120:123]
	v_mfma_f32_16x16x32_bf16 v[116:119], v[182:185], v[202:205], v[116:119]
	v_mfma_f32_16x16x32_bf16 v[112:115], v[190:193], v[202:205], v[112:115]
	v_mfma_f32_16x16x32_bf16 v[108:111], v[182:185], v[210:213], v[108:111]
	v_mfma_f32_16x16x32_bf16 v[104:107], v[190:193], v[210:213], v[104:107]
	v_mfma_f32_16x16x32_bf16 v[100:103], v[182:185], v[218:221], v[100:103]
	v_mfma_f32_16x16x32_bf16 v[96:99], v[190:193], v[218:221], v[96:99]
	s_barrier
	v_add_u32_e32 v164, s33, v154
	v_lshl_add_u64 v[246:247], s[94:95], 0, v[142:143]
	v_readfirstlane_b32 s27, v164
	v_add_u32_e32 v165, 0x2000, v164
	v_lshl_add_u64 v[238:239], v[246:247], 0, s[6:7]
	s_mov_b32 m0, s27
	v_lshl_add_u64 v[248:249], s[94:95], 0, v[144:145]
	v_readfirstlane_b32 s27, v165
	ds_read_b128 v[222:225], v160
	ds_read_b128 v[226:229], v160 offset:1024
	ds_read_b128 v[230:233], v160 offset:2048
	ds_read_b128 v[234:237], v160 offset:3072
	global_load_lds_dwordx4 v[238:239], off
	v_lshl_add_u64 v[238:239], v[248:249], 0, s[6:7]
	s_mov_b32 m0, s27
	s_nop 0
	global_load_lds_dwordx4 v[238:239], off
	s_barrier
	s_waitcnt lgkmcnt(0)
	v_mfma_f32_16x16x32_bf16 v[92:95], v[222:225], v[166:169], v[92:95]
	v_mfma_f32_16x16x32_bf16 v[88:91], v[230:233], v[166:169], v[88:91]
	v_mfma_f32_16x16x32_bf16 v[84:87], v[222:225], v[198:201], v[84:87]
	v_mfma_f32_16x16x32_bf16 v[80:83], v[230:233], v[198:201], v[80:83]
	v_mfma_f32_16x16x32_bf16 v[76:79], v[222:225], v[206:209], v[76:79]
	v_mfma_f32_16x16x32_bf16 v[72:75], v[230:233], v[206:209], v[72:75]
	v_mfma_f32_16x16x32_bf16 v[68:71], v[222:225], v[214:217], v[68:71]
	v_mfma_f32_16x16x32_bf16 v[64:67], v[230:233], v[214:217], v[64:67]
	v_mfma_f32_16x16x32_bf16 v[92:95], v[226:229], v[194:197], v[92:95]
	v_mfma_f32_16x16x32_bf16 v[88:91], v[234:237], v[194:197], v[88:91]
	v_mfma_f32_16x16x32_bf16 v[84:87], v[226:229], v[202:205], v[84:87]
	v_mfma_f32_16x16x32_bf16 v[80:83], v[234:237], v[202:205], v[80:83]
	v_mfma_f32_16x16x32_bf16 v[76:79], v[226:229], v[210:213], v[76:79]
	v_mfma_f32_16x16x32_bf16 v[72:75], v[234:237], v[210:213], v[72:75]
	v_mfma_f32_16x16x32_bf16 v[68:71], v[226:229], v[218:221], v[68:71]
	v_mfma_f32_16x16x32_bf16 v[64:67], v[234:237], v[218:221], v[64:67]
	v_readfirstlane_b32 s27, v152
	v_lshl_add_u64 v[166:167], v[242:243], 0, s[8:9]
	s_mov_b32 m0, s27
	s_barrier
	ds_read_b128 v[194:197], v153 offset:16384
	ds_read_b128 v[198:201], v153 offset:17408
	ds_read_b128 v[202:205], v171 offset:16384
	ds_read_b128 v[206:209], v171 offset:17408
	ds_read_b128 v[210:213], v172 offset:16384
	ds_read_b128 v[214:217], v172 offset:17408
	ds_read_b128 v[218:221], v173 offset:16384
	ds_read_b128 v[238:241], v173 offset:17408
	global_load_lds_dwordx4 v[166:167], off
	v_add_u32_e32 v166, 0x2000, v152
	v_lshl_add_u64 v[168:169], v[244:245], 0, s[8:9]
	v_readfirstlane_b32 s27, v166
	s_mov_b32 m0, s27
	s_nop 0
	global_load_lds_dwordx4 v[168:169], off
	s_barrier
	s_waitcnt lgkmcnt(0)
	v_mfma_f32_16x16x32_bf16 v[60:63], v[178:181], v[194:197], v[60:63]
	v_mfma_f32_16x16x32_bf16 v[56:59], v[186:189], v[194:197], v[56:59]
	v_mfma_f32_16x16x32_bf16 v[52:55], v[178:181], v[202:205], v[52:55]
	v_mfma_f32_16x16x32_bf16 v[48:51], v[186:189], v[202:205], v[48:51]
	v_mfma_f32_16x16x32_bf16 v[44:47], v[178:181], v[210:213], v[44:47]
	v_mfma_f32_16x16x32_bf16 v[40:43], v[186:189], v[210:213], v[40:43]
	v_mfma_f32_16x16x32_bf16 v[36:39], v[178:181], v[218:221], v[36:39]
	v_mfma_f32_16x16x32_bf16 v[32:35], v[186:189], v[218:221], v[32:35]
	v_mfma_f32_16x16x32_bf16 v[60:63], v[182:185], v[198:201], v[60:63]
	v_mfma_f32_16x16x32_bf16 v[56:59], v[190:193], v[198:201], v[56:59]
	v_mfma_f32_16x16x32_bf16 v[52:55], v[182:185], v[206:209], v[52:55]
	v_mfma_f32_16x16x32_bf16 v[48:51], v[190:193], v[206:209], v[48:51]
	v_mfma_f32_16x16x32_bf16 v[44:47], v[182:185], v[214:217], v[44:47]
	v_mfma_f32_16x16x32_bf16 v[40:43], v[190:193], v[214:217], v[40:43]
	v_mfma_f32_16x16x32_bf16 v[36:39], v[182:185], v[238:241], v[36:39]
	v_mfma_f32_16x16x32_bf16 v[32:35], v[190:193], v[238:241], v[32:35]
	s_barrier
; #define STAGE(P,BASE,LD,br,kt) do{long _g=(long)(br)*(LD)+(long)(kt)*BK; \
;     _Pragma("unroll") for(int _i=0;_i<2;++_i){int _b=tid*16+_i*8192;int _r,_c;stage_rc(_b,_r,_c); \
;       __builtin_amdgcn_global_load_lds((const unsigned*)((BASE)+_g+(long)_r*(LD)+_c), \
;         (unsigned*)((char*)(P)+_b),16,0,0);}}while(0)
; #define STAGE(P,BASE,LD,br,kt) do{long _g=(long)(br)*(LD)+(long)(kt)*BK; \
;     _Pragma("unroll") for(int _i=0;_i<2;++_i){int _b=tid*16+_i*8192;int _r,_c;stage_rc(_b,_r,_c); \
;       __builtin_amdgcn_global_load_lds((const unsigned*)((BASE)+_g+(long)_r*(LD)+_c), \
;         (unsigned*)((char*)(P)+_b),16,0,0);}}while(0)
; #define LDA(dst,b,h) _Pragma("unroll") for(int m=0;m<4;++m) _Pragma("unroll") for(int k=0;k<2;++k) \
;     dst[m][k]=*reinterpret_cast<const bf16x8*>((char*)SA(b,h)+lds_byte(wr*64+m*16+fr,k*32+fq*8))
; #define LDB(dst,b,h) _Pragma("unroll") for(int n=0;n<2;++n) _Pragma("unroll") for(int k=0;k<2;++k) \
;     dst[n][k]=*reinterpret_cast<const bf16x8*>((char*)SB(b,h)+lds_byte(wc*32+n*16+fr,k*32+fq*8))
; #define MMA(ai,bj,At_,Bt_) do{__builtin_amdgcn_s_setprio(1); \
;     _Pragma("unroll") for(int m=0;m<4;++m) _Pragma("unroll") for(int n=0;n<2;++n) _Pragma("unroll") for(int k=0;k<2;++k) \
;       acc[ai][bj][m][n]=__builtin_amdgcn_mfma_f32_16x16x32_bf16(Bt_[n][k],At_[m][k],acc[ai][bj][m][n],0,0,0); \
;     __builtin_amdgcn_s_setprio(0);}while(0)
; #define WAIT_V(n) asm volatile("s_waitcnt vmcnt(" #n ")":::"memory")
; #define WAIT_L(n) asm volatile("s_waitcnt lgkmcnt(" #n ")":::"memory")
; #define BAR __builtin_amdgcn_s_barrier()
; #define SCHED __builtin_amdgcn_sched_barrier(0)
; DEVINL void gemm8_mainloop(const u16* A, long lda, const u16* Bt, long ldb, int K, int brow, int bcol, f32x4 (&acc)[2][2][4][2], char* smem, int tid) {
;     ...
;     STAGE(SB(0,1),Bt,ldb,bcol+HALF,t+2);
;     WAIT_V(6); BAR; MMA(1,1,At,B1); BAR;
;     LDB(B0,1,0); SCHED; LDA(At,1,0); STAGE(SA(0,1),A,lda,brow+HALF,t+2);
;     WAIT_L(8); BAR; WAIT_L(0); MMA(0,0,At,B0); BAR; SCHED;
;     LDB(B1,1,1); STAGE(SB(1,0),Bt,ldb,bcol,t+3);
;     BAR; WAIT_L(0); MMA(0,1,At,B1); BAR;
;     LDA(At,1,1); STAGE(SA(1,0),A,lda,brow,t+3);
	v_add_u32_e32 v167, s34, v154
	v_lshl_add_u64 v[168:169], v[246:247], 0, s[10:11]
	v_readfirstlane_b32 s27, v167
	s_mov_b32 m0, s27
	v_lshl_add_u64 v[178:179], v[248:249], 0, s[10:11]
	global_load_lds_dwordx4 v[168:169], off
	v_add_u32_e32 v168, 0x2000, v167
	s_nop 0
	v_readfirstlane_b32 s27, v168
	s_mov_b32 m0, s27
	s_nop 0
	global_load_lds_dwordx4 v[178:179], off
	s_waitcnt vmcnt(6)
	s_barrier
	v_mfma_f32_16x16x32_bf16 v[28:31], v[222:225], v[194:197], v[28:31]
	v_mfma_f32_16x16x32_bf16 v[24:27], v[230:233], v[194:197], v[24:27]
	v_mfma_f32_16x16x32_bf16 v[20:23], v[222:225], v[202:205], v[20:23]
	v_mfma_f32_16x16x32_bf16 v[16:19], v[230:233], v[202:205], v[16:19]
	v_mfma_f32_16x16x32_bf16 v[12:15], v[222:225], v[210:213], v[12:15]
	v_mfma_f32_16x16x32_bf16 v[8:11], v[230:233], v[210:213], v[8:11]
	v_mfma_f32_16x16x32_bf16 v[4:7], v[222:225], v[218:221], v[4:7]
	v_mfma_f32_16x16x32_bf16 v[0:3], v[230:233], v[218:221], v[0:3]
	v_mfma_f32_16x16x32_bf16 v[28:31], v[226:229], v[198:201], v[28:31]
	v_mfma_f32_16x16x32_bf16 v[24:27], v[234:237], v[198:201], v[24:27]
	v_mfma_f32_16x16x32_bf16 v[20:23], v[226:229], v[206:209], v[20:23]
	v_mfma_f32_16x16x32_bf16 v[16:19], v[234:237], v[206:209], v[16:19]
	v_mfma_f32_16x16x32_bf16 v[12:15], v[226:229], v[214:217], v[12:15]
	v_mfma_f32_16x16x32_bf16 v[8:11], v[234:237], v[214:217], v[8:11]
	v_mfma_f32_16x16x32_bf16 v[4:7], v[226:229], v[238:241], v[4:7]
	v_mfma_f32_16x16x32_bf16 v[0:3], v[234:237], v[238:241], v[0:3]
	s_barrier
	ds_read_b128 v[178:181], v157
	ds_read_b128 v[182:185], v157 offset:1024
	ds_read_b128 v[186:189], v157 offset:2048
	ds_read_b128 v[190:193], v157 offset:3072
	v_add_u32_e32 v169, 0x4000, v152
	v_add_u32_e32 v170, 0x6000, v152
	v_readfirstlane_b32 s27, v169
	v_lshl_add_u64 v[226:227], v[242:243], 0, s[12:13]
	s_mov_b32 m0, s27
	v_readfirstlane_b32 s27, v170
	ds_read_b128 v[194:197], v153 offset:32768
	ds_read_b128 v[198:201], v153 offset:33792
	ds_read_b128 v[202:205], v171 offset:32768
	ds_read_b128 v[206:209], v171 offset:33792
	ds_read_b128 v[210:213], v172 offset:32768
	ds_read_b128 v[214:217], v172 offset:33792
	ds_read_b128 v[218:221], v173 offset:32768
	ds_read_b128 v[222:225], v173 offset:33792
	global_load_lds_dwordx4 v[226:227], off
	v_lshl_add_u64 v[226:227], v[244:245], 0, s[12:13]
	s_mov_b32 m0, s27
	s_nop 0
	global_load_lds_dwordx4 v[226:227], off
	s_waitcnt lgkmcnt(8)
	s_barrier
	s_waitcnt lgkmcnt(0)
	v_mfma_f32_16x16x32_bf16 v[124:127], v[178:181], v[194:197], v[124:127]
	v_mfma_f32_16x16x32_bf16 v[120:123], v[186:189], v[194:197], v[120:123]
	v_mfma_f32_16x16x32_bf16 v[116:119], v[178:181], v[202:205], v[116:119]
	v_mfma_f32_16x16x32_bf16 v[112:115], v[186:189], v[202:205], v[112:115]
	v_mfma_f32_16x16x32_bf16 v[108:111], v[178:181], v[210:213], v[108:111]
	v_mfma_f32_16x16x32_bf16 v[104:107], v[186:189], v[210:213], v[104:107]
	v_mfma_f32_16x16x32_bf16 v[100:103], v[178:181], v[218:221], v[100:103]
	v_mfma_f32_16x16x32_bf16 v[96:99], v[186:189], v[218:221], v[96:99]
	v_mfma_f32_16x16x32_bf16 v[124:127], v[182:185], v[198:201], v[124:127]
	v_mfma_f32_16x16x32_bf16 v[120:123], v[190:193], v[198:201], v[120:123]
	v_mfma_f32_16x16x32_bf16 v[116:119], v[182:185], v[206:209], v[116:119]
	v_mfma_f32_16x16x32_bf16 v[112:115], v[190:193], v[206:209], v[112:115]
	v_mfma_f32_16x16x32_bf16 v[108:111], v[182:185], v[214:217], v[108:111]
	v_mfma_f32_16x16x32_bf16 v[104:107], v[190:193], v[214:217], v[104:107]
	v_mfma_f32_16x16x32_bf16 v[100:103], v[182:185], v[222:225], v[100:103]
	v_mfma_f32_16x16x32_bf16 v[96:99], v[190:193], v[222:225], v[96:99]
	s_barrier
	v_readfirstlane_b32 s27, v156
	v_add_u32_e32 v177, 0x2000, v156
	v_lshl_add_u64 v[250:251], v[246:247], 0, s[14:15]
	s_mov_b32 m0, s27
	v_readfirstlane_b32 s27, v177
	ds_read_b128 v[226:229], v155
	ds_read_b128 v[230:233], v155 offset:1024
	ds_read_b128 v[234:237], v155 offset:2048
	ds_read_b128 v[238:241], v155 offset:3072
	global_load_lds_dwordx4 v[250:251], off
	v_lshl_add_u64 v[250:251], v[248:249], 0, s[14:15]
	s_mov_b32 m0, s27
	s_nop 0
	global_load_lds_dwordx4 v[250:251], off
	s_barrier
	s_waitcnt lgkmcnt(0)
	v_mfma_f32_16x16x32_bf16 v[92:95], v[226:229], v[194:197], v[92:95]
	v_mfma_f32_16x16x32_bf16 v[88:91], v[234:237], v[194:197], v[88:91]
	v_mfma_f32_16x16x32_bf16 v[84:87], v[226:229], v[202:205], v[84:87]
	v_mfma_f32_16x16x32_bf16 v[80:83], v[234:237], v[202:205], v[80:83]
	v_mfma_f32_16x16x32_bf16 v[76:79], v[226:229], v[210:213], v[76:79]
	v_mfma_f32_16x16x32_bf16 v[72:75], v[234:237], v[210:213], v[72:75]
	v_mfma_f32_16x16x32_bf16 v[68:71], v[226:229], v[218:221], v[68:71]
	v_mfma_f32_16x16x32_bf16 v[64:67], v[234:237], v[218:221], v[64:67]
	v_mfma_f32_16x16x32_bf16 v[92:95], v[230:233], v[198:201], v[92:95]
	v_mfma_f32_16x16x32_bf16 v[88:91], v[238:241], v[198:201], v[88:91]
	v_mfma_f32_16x16x32_bf16 v[84:87], v[230:233], v[206:209], v[84:87]
	v_mfma_f32_16x16x32_bf16 v[80:83], v[238:241], v[206:209], v[80:83]
	v_mfma_f32_16x16x32_bf16 v[76:79], v[230:233], v[214:217], v[76:79]
	v_mfma_f32_16x16x32_bf16 v[72:75], v[238:241], v[214:217], v[72:75]
	v_mfma_f32_16x16x32_bf16 v[68:71], v[230:233], v[222:225], v[68:71]
	v_mfma_f32_16x16x32_bf16 v[64:67], v[238:241], v[222:225], v[64:67]
	v_readfirstlane_b32 s27, v158
	v_lshl_add_u64 v[242:243], v[242:243], 0, s[16:17]
	s_mov_b32 m0, s27
	v_readfirstlane_b32 s27, v159
	s_barrier
	ds_read_b128 v[194:197], v153 offset:49152
	ds_read_b128 v[198:201], v153 offset:50176
	ds_read_b128 v[202:205], v171 offset:49152
	ds_read_b128 v[206:209], v171 offset:50176
	ds_read_b128 v[210:213], v172 offset:49152
	ds_read_b128 v[214:217], v172 offset:50176
	ds_read_b128 v[218:221], v173 offset:49152
	ds_read_b128 v[222:225], v173 offset:50176
	global_load_lds_dwordx4 v[242:243], off
	v_lshl_add_u64 v[242:243], v[244:245], 0, s[16:17]
	s_mov_b32 m0, s27
	s_nop 0
	global_load_lds_dwordx4 v[242:243], off
	s_barrier
; #define STAGE(P,BASE,LD,br,kt) do{long _g=(long)(br)*(LD)+(long)(kt)*BK; \
;     _Pragma("unroll") for(int _i=0;_i<2;++_i){int _b=tid*16+_i*8192;int _r,_c;stage_rc(_b,_r,_c); \
;       __builtin_amdgcn_global_load_lds((const unsigned*)((BASE)+_g+(long)_r*(LD)+_c), \
;         (unsigned*)((char*)(P)+_b),16,0,0);}}while(0)
; #define STAGE(P,BASE,LD,br,kt) do{long _g=(long)(br)*(LD)+(long)(kt)*BK; \
;     _Pragma("unroll") for(int _i=0;_i<2;++_i){int _b=tid*16+_i*8192;int _r,_c;stage_rc(_b,_r,_c); \
;       __builtin_amdgcn_global_load_lds((const unsigned*)((BASE)+_g+(long)_r*(LD)+_c), \
;         (unsigned*)((char*)(P)+_b),16,0,0);}}while(0)
; #define LDA(dst,b,h) _Pragma("unroll") for(int m=0;m<4;++m) _Pragma("unroll") for(int k=0;k<2;++k) \
;     dst[m][k]=*reinterpret_cast<const bf16x8*>((char*)SA(b,h)+lds_byte(wr*64+m*16+fr,k*32+fq*8))
; #define LDB(dst,b,h) _Pragma("unroll") for(int n=0;n<2;++n) _Pragma("unroll") for(int k=0;k<2;++k) \
;     dst[n][k]=*reinterpret_cast<const bf16x8*>((char*)SB(b,h)+lds_byte(wc*32+n*16+fr,k*32+fq*8))
; #define MMA(ai,bj,At_,Bt_) do{__builtin_amdgcn_s_setprio(1); \
;     _Pragma("unroll") for(int m=0;m<4;++m) _Pragma("unroll") for(int n=0;n<2;++n) _Pragma("unroll") for(int k=0;k<2;++k) \
;       acc[ai][bj][m][n]=__builtin_amdgcn_mfma_f32_16x16x32_bf16(Bt_[n][k],At_[m][k],acc[ai][bj][m][n],0,0,0); \
;     __builtin_amdgcn_s_setprio(0);}while(0)
; #define WAIT_V(n) asm volatile("s_waitcnt vmcnt(" #n ")":::"memory")
; #define WAIT_L(n) asm volatile("s_waitcnt lgkmcnt(" #n ")":::"memory")
; #define BAR __builtin_amdgcn_s_barrier()
; #define SCHED __builtin_amdgcn_sched_barrier(0)
; DEVINL void gemm8_mainloop(const u16* A, long lda, const u16* Bt, long ldb, int K, int brow, int bcol, f32x4 (&acc)[2][2][4][2], char* smem, int tid) {
;     ...
;     BAR; WAIT_L(0); MMA(1,0,At,B0); BAR; SCHED;
;     STAGE(SB(1,1),Bt,ldb,bcol+HALF,t+3);
;     WAIT_V(6); BAR; MMA(1,1,At,B1); BAR;
;   }
;   { LDB(B0,0,0); LDA(At,0,0); STAGE(SA(1,1),A,lda,brow+HALF,nt-1);
;     BAR; WAIT_L(0); MMA(0,0,At,B0); BAR;
;     LDB(B1,0,1); BAR; WAIT_L(0); MMA(0,1,At,B1); BAR;
	s_waitcnt lgkmcnt(0)
	v_mfma_f32_16x16x32_bf16 v[60:63], v[178:181], v[194:197], v[60:63]
	v_mfma_f32_16x16x32_bf16 v[56:59], v[186:189], v[194:197], v[56:59]
	v_mfma_f32_16x16x32_bf16 v[52:55], v[178:181], v[202:205], v[52:55]
	v_mfma_f32_16x16x32_bf16 v[48:51], v[186:189], v[202:205], v[48:51]
	v_mfma_f32_16x16x32_bf16 v[44:47], v[178:181], v[210:213], v[44:47]
	v_mfma_f32_16x16x32_bf16 v[40:43], v[186:189], v[210:213], v[40:43]
	v_mfma_f32_16x16x32_bf16 v[36:39], v[178:181], v[218:221], v[36:39]
	v_mfma_f32_16x16x32_bf16 v[32:35], v[186:189], v[218:221], v[32:35]
	v_mfma_f32_16x16x32_bf16 v[60:63], v[182:185], v[198:201], v[60:63]
	v_mfma_f32_16x16x32_bf16 v[56:59], v[190:193], v[198:201], v[56:59]
	v_mfma_f32_16x16x32_bf16 v[52:55], v[182:185], v[206:209], v[52:55]
	v_mfma_f32_16x16x32_bf16 v[48:51], v[190:193], v[206:209], v[48:51]
	v_mfma_f32_16x16x32_bf16 v[44:47], v[182:185], v[214:217], v[44:47]
	v_mfma_f32_16x16x32_bf16 v[40:43], v[190:193], v[214:217], v[40:43]
	v_mfma_f32_16x16x32_bf16 v[36:39], v[182:185], v[222:225], v[36:39]
	v_mfma_f32_16x16x32_bf16 v[32:35], v[190:193], v[222:225], v[32:35]
	s_barrier
	v_readfirstlane_b32 s27, v161
	v_add_u32_e32 v177, 0x2000, v161
	v_lshl_add_u64 v[178:179], v[246:247], 0, s[18:19]
	s_mov_b32 m0, s27
	v_readfirstlane_b32 s27, v177
	global_load_lds_dwordx4 v[178:179], off
	v_lshl_add_u64 v[178:179], v[248:249], 0, s[18:19]
	s_mov_b32 m0, s27
	s_nop 0
	global_load_lds_dwordx4 v[178:179], off
	s_waitcnt vmcnt(6)
	s_barrier
	v_mfma_f32_16x16x32_bf16 v[28:31], v[226:229], v[194:197], v[28:31]
	v_mfma_f32_16x16x32_bf16 v[24:27], v[234:237], v[194:197], v[24:27]
	v_mfma_f32_16x16x32_bf16 v[20:23], v[226:229], v[202:205], v[20:23]
	v_mfma_f32_16x16x32_bf16 v[16:19], v[234:237], v[202:205], v[16:19]
	v_mfma_f32_16x16x32_bf16 v[12:15], v[226:229], v[210:213], v[12:15]
	v_mfma_f32_16x16x32_bf16 v[8:11], v[234:237], v[210:213], v[8:11]
	v_mfma_f32_16x16x32_bf16 v[4:7], v[226:229], v[218:221], v[4:7]
	v_mfma_f32_16x16x32_bf16 v[0:3], v[234:237], v[218:221], v[0:3]
	v_mfma_f32_16x16x32_bf16 v[28:31], v[230:233], v[198:201], v[28:31]
	v_mfma_f32_16x16x32_bf16 v[24:27], v[238:241], v[198:201], v[24:27]
	v_mfma_f32_16x16x32_bf16 v[20:23], v[230:233], v[206:209], v[20:23]
	v_mfma_f32_16x16x32_bf16 v[16:19], v[238:241], v[206:209], v[16:19]
	v_mfma_f32_16x16x32_bf16 v[12:15], v[230:233], v[214:217], v[12:15]
	v_mfma_f32_16x16x32_bf16 v[8:11], v[238:241], v[214:217], v[8:11]
	v_mfma_f32_16x16x32_bf16 v[4:7], v[230:233], v[222:225], v[4:7]
	v_mfma_f32_16x16x32_bf16 v[0:3], v[238:241], v[222:225], v[0:3]
	s_add_i32 s26, s26, 2
	v_lshl_add_u64 v[142:143], v[142:143], 0, s[20:21]
	v_lshl_add_u64 v[144:145], v[144:145], 0, s[20:21]
	v_lshl_add_u64 v[146:147], v[146:147], 0, s[20:21]
	s_cmp_lt_u32 s26, 28
	v_lshl_add_u64 v[148:149], v[148:149], 0, s[20:21]
	s_barrier
	s_cbranch_scc1 .LBB0_849
	s_or_b32 s0, s28, 0x80
	s_ashr_i32 s1, s0, 31
	s_lshl_b64 s[0:1], s[0:1], 12
	s_add_u32 s0, s58, s0
	s_addc_u32 s1, s59, s1
	v_lshl_add_u64 v[158:159], v[134:135], 1, s[0:1]
	v_lshl_add_u64 v[138:139], v[138:139], 1, v[158:159]
	v_readfirstlane_b32 s26, v174
	v_lshl_add_u64 v[138:139], v[138:139], 0, s[22:23]
	s_mov_b32 m0, s26
	ds_read_b128 v[142:145], v163
	ds_read_b128 v[146:149], v163 offset:1024
	ds_read_b128 v[178:181], v163 offset:2048
	ds_read_b128 v[182:185], v163 offset:3072
	ds_read_b128 v[186:189], v153
	ds_read_b128 v[190:193], v153 offset:1024
	ds_read_b128 v[194:197], v171
	ds_read_b128 v[198:201], v171 offset:1024
	ds_read_b128 v[202:205], v172
	ds_read_b128 v[206:209], v172 offset:1024
	ds_read_b128 v[210:213], v173
	ds_read_b128 v[214:217], v173 offset:1024
	global_load_lds_dwordx4 v[138:139], off
	v_lshl_add_u64 v[138:139], v[136:137], 1, s[0:1]
	v_lshl_add_u64 v[138:139], v[140:141], 1, v[138:139]
	v_readfirstlane_b32 s0, v175
	v_lshl_add_u64 v[138:139], v[138:139], 0, s[22:23]
	s_mov_b32 m0, s0
	s_nop 0
	global_load_lds_dwordx4 v[138:139], off
	s_barrier
	s_waitcnt lgkmcnt(0)
	v_mfma_f32_16x16x32_bf16 v[124:127], v[142:145], v[186:189], v[124:127]
	v_mfma_f32_16x16x32_bf16 v[120:123], v[178:181], v[186:189], v[120:123]
	v_mfma_f32_16x16x32_bf16 v[112:115], v[178:181], v[194:197], v[112:115]
	v_mfma_f32_16x16x32_bf16 v[104:107], v[178:181], v[202:205], v[104:107]
	v_mfma_f32_16x16x32_bf16 v[96:99], v[178:181], v[210:213], v[96:99]
	v_mfma_f32_16x16x32_bf16 v[124:127], v[146:149], v[190:193], v[124:127]
	v_mfma_f32_16x16x32_bf16 v[120:123], v[182:185], v[190:193], v[120:123]
	v_mfma_f32_16x16x32_bf16 v[116:119], v[142:145], v[194:197], v[116:119]
	v_mfma_f32_16x16x32_bf16 v[112:115], v[182:185], v[198:201], v[112:115]
	v_mfma_f32_16x16x32_bf16 v[108:111], v[142:145], v[202:205], v[108:111]
	v_mfma_f32_16x16x32_bf16 v[104:107], v[182:185], v[206:209], v[104:107]
	v_mfma_f32_16x16x32_bf16 v[100:103], v[142:145], v[210:213], v[100:103]
	v_mfma_f32_16x16x32_bf16 v[96:99], v[182:185], v[214:217], v[96:99]
	v_mfma_f32_16x16x32_bf16 v[138:141], v[146:149], v[198:201], v[116:119]
	v_mfma_f32_16x16x32_bf16 v[218:221], v[146:149], v[206:209], v[108:111]
	v_mfma_f32_16x16x32_bf16 v[222:225], v[146:149], v[214:217], v[100:103]
	s_barrier
	s_nop 1
	s_nop 0
	ds_read_b128 v[100:103], v160
	ds_read_b128 v[108:111], v160 offset:1024
	ds_read_b128 v[116:119], v160 offset:2048
	ds_read_b128 v[158:161], v160 offset:3072
	s_barrier
; #define LDA(dst,b,h) _Pragma("unroll") for(int m=0;m<4;++m) _Pragma("unroll") for(int k=0;k<2;++k) \
;     dst[m][k]=*reinterpret_cast<const bf16x8*>((char*)SA(b,h)+lds_byte(wr*64+m*16+fr,k*32+fq*8))
; #define LDB(dst,b,h) _Pragma("unroll") for(int n=0;n<2;++n) _Pragma("unroll") for(int k=0;k<2;++k) \
;     dst[n][k]=*reinterpret_cast<const bf16x8*>((char*)SB(b,h)+lds_byte(wc*32+n*16+fr,k*32+fq*8))
; #define MMA(ai,bj,At_,Bt_) do{__builtin_amdgcn_s_setprio(1); \
;     _Pragma("unroll") for(int m=0;m<4;++m) _Pragma("unroll") for(int n=0;n<2;++n) _Pragma("unroll") for(int k=0;k<2;++k) \
;       acc[ai][bj][m][n]=__builtin_amdgcn_mfma_f32_16x16x32_bf16(Bt_[n][k],At_[m][k],acc[ai][bj][m][n],0,0,0); \
;     __builtin_amdgcn_s_setprio(0);}while(0)
; #define WAIT_V(n) asm volatile("s_waitcnt vmcnt(" #n ")":::"memory")
; #define WAIT_L(n) asm volatile("s_waitcnt lgkmcnt(" #n ")":::"memory")
; #define BAR __builtin_amdgcn_s_barrier()
; DEVINL void gemm8_mainloop(const u16* A, long lda, const u16* Bt, long ldb, int K, int brow, int bcol, f32x4 (&acc)[2][2][4][2], char* smem, int tid) {
;     ...
;     LDB(B1,0,1); BAR; WAIT_L(0); MMA(0,1,At,B1); BAR;
;     LDA(At,0,1); WAIT_V(4); BAR; WAIT_L(0); MMA(1,0,At,B0); MMA(1,1,At,B1); BAR; }
;   { LDB(B0,1,0); LDA(At,1,0); WAIT_V(2); BAR; WAIT_L(0); MMA(0,0,At,B0); BAR;
	s_waitcnt lgkmcnt(0)
	v_mfma_f32_16x16x32_bf16 v[88:91], v[116:119], v[186:189], v[88:91]
	v_mfma_f32_16x16x32_bf16 v[80:83], v[116:119], v[194:197], v[80:83]
	v_mfma_f32_16x16x32_bf16 v[72:75], v[116:119], v[202:205], v[72:75]
	v_mfma_f32_16x16x32_bf16 v[64:67], v[116:119], v[210:213], v[64:67]
	v_mfma_f32_16x16x32_bf16 v[92:95], v[100:103], v[186:189], v[92:95]
	v_mfma_f32_16x16x32_bf16 v[88:91], v[158:161], v[190:193], v[88:91]
	v_mfma_f32_16x16x32_bf16 v[84:87], v[100:103], v[194:197], v[84:87]
	v_mfma_f32_16x16x32_bf16 v[80:83], v[158:161], v[198:201], v[80:83]
	v_mfma_f32_16x16x32_bf16 v[76:79], v[100:103], v[202:205], v[76:79]
	v_mfma_f32_16x16x32_bf16 v[72:75], v[158:161], v[206:209], v[72:75]
	v_mfma_f32_16x16x32_bf16 v[68:71], v[100:103], v[210:213], v[68:71]
	v_mfma_f32_16x16x32_bf16 v[64:67], v[158:161], v[214:217], v[64:67]
	v_mfma_f32_16x16x32_bf16 v[226:229], v[108:111], v[190:193], v[92:95]
	v_mfma_f32_16x16x32_bf16 v[186:189], v[108:111], v[198:201], v[84:87]
	v_mfma_f32_16x16x32_bf16 v[190:193], v[108:111], v[206:209], v[76:79]
	v_mfma_f32_16x16x32_bf16 v[194:197], v[108:111], v[214:217], v[68:71]
	s_barrier
	s_nop 0
	s_nop 0
	ds_read_b128 v[68:71], v153 offset:16384
	ds_read_b128 v[76:79], v153 offset:17408
	ds_read_b128 v[84:87], v171 offset:16384
	ds_read_b128 v[92:95], v171 offset:17408
	ds_read_b128 v[198:201], v172 offset:16384
	ds_read_b128 v[202:205], v172 offset:17408
	ds_read_b128 v[206:209], v173 offset:16384
	ds_read_b128 v[210:213], v173 offset:17408
	s_waitcnt vmcnt(4)
	s_barrier
	s_waitcnt lgkmcnt(0)
	v_mfma_f32_16x16x32_bf16 v[60:63], v[142:145], v[68:71], v[60:63]
	v_mfma_f32_16x16x32_bf16 v[56:59], v[178:181], v[68:71], v[56:59]
	v_mfma_f32_16x16x32_bf16 v[52:55], v[142:145], v[84:87], v[52:55]
	v_mfma_f32_16x16x32_bf16 v[48:51], v[178:181], v[84:87], v[48:51]
	v_mfma_f32_16x16x32_bf16 v[36:39], v[142:145], v[206:209], v[36:39]
	v_mfma_f32_16x16x32_bf16 v[32:35], v[178:181], v[206:209], v[32:35]
	v_mfma_f32_16x16x32_bf16 v[60:63], v[146:149], v[76:79], v[60:63]
	v_mfma_f32_16x16x32_bf16 v[56:59], v[182:185], v[76:79], v[56:59]
	v_mfma_f32_16x16x32_bf16 v[52:55], v[146:149], v[92:95], v[52:55]
	v_mfma_f32_16x16x32_bf16 v[48:51], v[182:185], v[92:95], v[48:51]
	v_mfma_f32_16x16x32_bf16 v[44:47], v[142:145], v[198:201], v[44:47]
	v_mfma_f32_16x16x32_bf16 v[40:43], v[178:181], v[198:201], v[40:43]
	v_mfma_f32_16x16x32_bf16 v[36:39], v[146:149], v[210:213], v[36:39]
	v_mfma_f32_16x16x32_bf16 v[32:35], v[182:185], v[210:213], v[32:35]
	v_mfma_f32_16x16x32_bf16 v[214:217], v[146:149], v[202:205], v[44:47]
	v_mfma_f32_16x16x32_bf16 v[230:233], v[182:185], v[202:205], v[40:43]
	v_mfma_f32_16x16x32_bf16 v[20:23], v[100:103], v[84:87], v[20:23]
	v_mfma_f32_16x16x32_bf16 v[16:19], v[116:119], v[84:87], v[16:19]
	v_mfma_f32_16x16x32_bf16 v[4:7], v[100:103], v[206:209], v[4:7]
	v_mfma_f32_16x16x32_bf16 v[0:3], v[116:119], v[206:209], v[0:3]
	v_mfma_f32_16x16x32_bf16 v[28:31], v[100:103], v[68:71], v[28:31]
	v_mfma_f32_16x16x32_bf16 v[24:27], v[116:119], v[68:71], v[24:27]
	v_mfma_f32_16x16x32_bf16 v[20:23], v[108:111], v[92:95], v[20:23]
	v_mfma_f32_16x16x32_bf16 v[16:19], v[158:161], v[92:95], v[16:19]
	v_mfma_f32_16x16x32_bf16 v[12:15], v[100:103], v[198:201], v[12:15]
	v_mfma_f32_16x16x32_bf16 v[8:11], v[116:119], v[198:201], v[8:11]
	v_mfma_f32_16x16x32_bf16 v[4:7], v[108:111], v[210:213], v[4:7]
	v_mfma_f32_16x16x32_bf16 v[0:3], v[158:161], v[210:213], v[0:3]
	v_mfma_f32_16x16x32_bf16 v[142:145], v[108:111], v[76:79], v[28:31]
	v_mfma_f32_16x16x32_bf16 v[146:149], v[158:161], v[76:79], v[24:27]
	v_mfma_f32_16x16x32_bf16 v[178:181], v[108:111], v[202:205], v[12:15]
	v_mfma_f32_16x16x32_bf16 v[182:185], v[158:161], v[202:205], v[8:11]
	s_barrier
	s_nop 0
	s_nop 0
	ds_read_b128 v[8:11], v157
	ds_read_b128 v[12:15], v157 offset:1024
	ds_read_b128 v[158:161], v157 offset:2048
	ds_read_b128 v[198:201], v157 offset:3072
	ds_read_b128 v[24:27], v153 offset:32768
	ds_read_b128 v[28:31], v153 offset:33792
	ds_read_b128 v[40:43], v171 offset:32768
	ds_read_b128 v[44:47], v171 offset:33792
	ds_read_b128 v[202:205], v172 offset:32768
	ds_read_b128 v[206:209], v172 offset:33792
	ds_read_b128 v[210:213], v173 offset:32768
	ds_read_b128 v[234:237], v173 offset:33792
	s_waitcnt vmcnt(2)
	s_barrier
; #define LDA(dst,b,h) _Pragma("unroll") for(int m=0;m<4;++m) _Pragma("unroll") for(int k=0;k<2;++k) \
;     dst[m][k]=*reinterpret_cast<const bf16x8*>((char*)SA(b,h)+lds_byte(wr*64+m*16+fr,k*32+fq*8))
; #define LDB(dst,b,h) _Pragma("unroll") for(int n=0;n<2;++n) _Pragma("unroll") for(int k=0;k<2;++k) \
;     dst[n][k]=*reinterpret_cast<const bf16x8*>((char*)SB(b,h)+lds_byte(wc*32+n*16+fr,k*32+fq*8))
; #define MMA(ai,bj,At_,Bt_) do{__builtin_amdgcn_s_setprio(1); \
;     _Pragma("unroll") for(int m=0;m<4;++m) _Pragma("unroll") for(int n=0;n<2;++n) _Pragma("unroll") for(int k=0;k<2;++k) \
;       acc[ai][bj][m][n]=__builtin_amdgcn_mfma_f32_16x16x32_bf16(Bt_[n][k],At_[m][k],acc[ai][bj][m][n],0,0,0); \
;     __builtin_amdgcn_s_setprio(0);}while(0)
; #define WAIT_V(n) asm volatile("s_waitcnt vmcnt(" #n ")":::"memory")
; #define WAIT_L(n) asm volatile("s_waitcnt lgkmcnt(" #n ")":::"memory")
; #define BAR __builtin_amdgcn_s_barrier()
; DEVINL void gemm8_mainloop(const u16* A, long lda, const u16* Bt, long ldb, int K, int brow, int bcol, f32x4 (&acc)[2][2][4][2], char* smem, int tid) {
;     ...
;   { LDB(B0,1,0); LDA(At,1,0); WAIT_V(2); BAR; WAIT_L(0); MMA(0,0,At,B0); BAR;
;     LDB(B1,1,1); WAIT_V(0); BAR; WAIT_L(0); MMA(0,1,At,B1); BAR;
;     LDA(At,1,1); BAR; WAIT_L(0); MMA(1,0,At,B0); MMA(1,1,At,B1); BAR; }
;   if(wr==0)BAR;
	s_waitcnt lgkmcnt(0)
	v_mfma_f32_16x16x32_bf16 v[68:71], v[8:11], v[24:27], v[124:127]
	v_mfma_f32_16x16x32_bf16 v[124:127], v[12:15], v[28:31], v[68:71]
	v_mfma_f32_16x16x32_bf16 v[68:71], v[158:161], v[24:27], v[120:123]
	v_mfma_f32_16x16x32_bf16 v[116:119], v[198:201], v[28:31], v[68:71]
	v_mfma_f32_16x16x32_bf16 v[68:71], v[8:11], v[40:43], v[138:141]
	v_mfma_f32_16x16x32_bf16 v[108:111], v[12:15], v[44:47], v[68:71]
	v_mfma_f32_16x16x32_bf16 v[68:71], v[158:161], v[40:43], v[112:115]
	v_mfma_f32_16x16x32_bf16 v[100:103], v[198:201], v[44:47], v[68:71]
	v_mfma_f32_16x16x32_bf16 v[68:71], v[8:11], v[202:205], v[218:221]
	v_mfma_f32_16x16x32_bf16 v[92:95], v[12:15], v[206:209], v[68:71]
	v_mfma_f32_16x16x32_bf16 v[68:71], v[158:161], v[202:205], v[104:107]
	v_mfma_f32_16x16x32_bf16 v[84:87], v[198:201], v[206:209], v[68:71]
	v_mfma_f32_16x16x32_bf16 v[68:71], v[8:11], v[210:213], v[222:225]
	v_mfma_f32_16x16x32_bf16 v[76:79], v[12:15], v[234:237], v[68:71]
	v_mfma_f32_16x16x32_bf16 v[68:71], v[158:161], v[210:213], v[96:99]
	v_mfma_f32_16x16x32_bf16 v[68:71], v[198:201], v[234:237], v[68:71]
	s_barrier
	ds_read_b128 v[138:141], v155
	ds_read_b128 v[218:221], v155 offset:1024
	ds_read_b128 v[222:225], v155 offset:2048
	ds_read_b128 v[154:157], v155 offset:3072
	s_waitcnt vmcnt(0)
	s_barrier
	s_waitcnt lgkmcnt(0)
	v_mfma_f32_16x16x32_bf16 v[96:99], v[138:141], v[24:27], v[226:229]
	v_mfma_f32_16x16x32_bf16 v[24:27], v[222:225], v[24:27], v[88:91]
	v_mfma_f32_16x16x32_bf16 v[112:115], v[154:157], v[28:31], v[24:27]
	v_mfma_f32_16x16x32_bf16 v[24:27], v[138:141], v[40:43], v[186:189]
	v_mfma_f32_16x16x32_bf16 v[104:107], v[218:221], v[44:47], v[24:27]
	v_mfma_f32_16x16x32_bf16 v[24:27], v[222:225], v[40:43], v[80:83]
	v_mfma_f32_16x16x32_bf16 v[120:123], v[218:221], v[28:31], v[96:99]
	v_mfma_f32_16x16x32_bf16 v[96:99], v[154:157], v[44:47], v[24:27]
	v_mfma_f32_16x16x32_bf16 v[24:27], v[138:141], v[202:205], v[190:193]
	v_mfma_f32_16x16x32_bf16 v[88:91], v[218:221], v[206:209], v[24:27]
	v_mfma_f32_16x16x32_bf16 v[24:27], v[222:225], v[202:205], v[72:75]
	v_mfma_f32_16x16x32_bf16 v[80:83], v[154:157], v[206:209], v[24:27]
	v_mfma_f32_16x16x32_bf16 v[24:27], v[138:141], v[210:213], v[194:197]
	v_mfma_f32_16x16x32_bf16 v[72:75], v[218:221], v[234:237], v[24:27]
	v_mfma_f32_16x16x32_bf16 v[24:27], v[222:225], v[210:213], v[64:67]
	v_mfma_f32_16x16x32_bf16 v[64:67], v[154:157], v[234:237], v[24:27]
	s_barrier
	ds_read_b128 v[186:189], v153 offset:49152
	ds_read_b128 v[190:193], v153 offset:50176
	ds_read_b128 v[194:197], v171 offset:49152
	ds_read_b128 v[202:205], v171 offset:50176
	ds_read_b128 v[206:209], v172 offset:49152
	ds_read_b128 v[210:213], v172 offset:50176
	ds_read_b128 v[226:229], v173 offset:49152
	ds_read_b128 v[172:175], v173 offset:50176
	s_barrier
	s_waitcnt lgkmcnt(0)
	v_mfma_f32_16x16x32_bf16 v[24:27], v[8:11], v[186:189], v[60:63]
	v_mfma_f32_16x16x32_bf16 v[60:63], v[12:15], v[190:193], v[24:27]
	v_mfma_f32_16x16x32_bf16 v[24:27], v[158:161], v[186:189], v[56:59]
	v_mfma_f32_16x16x32_bf16 v[56:59], v[198:201], v[190:193], v[24:27]
	v_mfma_f32_16x16x32_bf16 v[24:27], v[8:11], v[194:197], v[52:55]
	v_mfma_f32_16x16x32_bf16 v[44:47], v[12:15], v[202:205], v[24:27]
	v_mfma_f32_16x16x32_bf16 v[24:27], v[158:161], v[194:197], v[48:51]
	v_mfma_f32_16x16x32_bf16 v[40:43], v[198:201], v[202:205], v[24:27]
	v_mfma_f32_16x16x32_bf16 v[24:27], v[8:11], v[206:209], v[214:217]
	v_mfma_f32_16x16x32_bf16 v[8:11], v[8:11], v[226:229], v[36:39]
	v_mfma_f32_16x16x32_bf16 v[28:31], v[12:15], v[210:213], v[24:27]
	v_mfma_f32_16x16x32_bf16 v[24:27], v[158:161], v[206:209], v[230:233]
	v_mfma_f32_16x16x32_bf16 v[12:15], v[12:15], v[172:175], v[8:11]
	v_mfma_f32_16x16x32_bf16 v[8:11], v[158:161], v[226:229], v[32:35]
	v_mfma_f32_16x16x32_bf16 v[24:27], v[198:201], v[210:213], v[24:27]
	v_mfma_f32_16x16x32_bf16 v[8:11], v[198:201], v[172:175], v[8:11]
	v_mfma_f32_16x16x32_bf16 v[32:35], v[138:141], v[186:189], v[142:145]
	v_mfma_f32_16x16x32_bf16 v[52:55], v[218:221], v[190:193], v[32:35]
	v_mfma_f32_16x16x32_bf16 v[32:35], v[222:225], v[186:189], v[146:149]
	v_mfma_f32_16x16x32_bf16 v[16:19], v[222:225], v[194:197], v[16:19]
	v_mfma_f32_16x16x32_bf16 v[48:51], v[154:157], v[190:193], v[32:35]
	v_mfma_f32_16x16x32_bf16 v[20:23], v[138:141], v[194:197], v[20:23]
	v_mfma_f32_16x16x32_bf16 v[32:35], v[154:157], v[202:205], v[16:19]
	v_mfma_f32_16x16x32_bf16 v[16:19], v[138:141], v[206:209], v[178:181]
	v_mfma_f32_16x16x32_bf16 v[36:39], v[218:221], v[202:205], v[20:23]
	v_mfma_f32_16x16x32_bf16 v[20:23], v[218:221], v[210:213], v[16:19]
	v_mfma_f32_16x16x32_bf16 v[16:19], v[222:225], v[206:209], v[182:185]
	v_mfma_f32_16x16x32_bf16 v[4:7], v[138:141], v[226:229], v[4:7]
	v_mfma_f32_16x16x32_bf16 v[0:3], v[222:225], v[226:229], v[0:3]
	v_mfma_f32_16x16x32_bf16 v[16:19], v[154:157], v[210:213], v[16:19]
	v_mfma_f32_16x16x32_bf16 v[4:7], v[218:221], v[172:175], v[4:7]
	v_mfma_f32_16x16x32_bf16 v[0:3], v[154:157], v[172:175], v[0:3]
	s_cmpk_gt_u32 s31, 0xff
	s_barrier
	s_cbranch_scc1 .LBB0_852
	s_barrier

; #define STAGE(P,BASE,LD,br,kt) do{long _g=(long)(br)*(LD)+(long)(kt)*BK; \
;     _Pragma("unroll") for(int _i=0;_i<2;++_i){int _b=tid*16+_i*8192;int _r,_c;stage_rc(_b,_r,_c); \
;       __builtin_amdgcn_global_load_lds((const unsigned*)((BASE)+_g+(long)_r*(LD)+_c), \
;         (unsigned*)((char*)(P)+_b),16,0,0);}}while(0)
; #define STAGE(P,BASE,LD,br,kt) do{long _g=(long)(br)*(LD)+(long)(kt)*BK; \
;     _Pragma("unroll") for(int _i=0;_i<2;++_i){int _b=tid*16+_i*8192;int _r,_c;stage_rc(_b,_r,_c); \
;       __builtin_amdgcn_global_load_lds((const unsigned*)((BASE)+_g+(long)_r*(LD)+_c), \
;         (unsigned*)((char*)(P)+_b),16,0,0);}}while(0)
; #define LDA(dst,b,h) _Pragma("unroll") for(int m=0;m<4;++m) _Pragma("unroll") for(int k=0;k<2;++k) \
;     dst[m][k]=*reinterpret_cast<const bf16x8*>((char*)SA(b,h)+lds_byte(wr*64+m*16+fr,k*32+fq*8))
; #define LDB(dst,b,h) _Pragma("unroll") for(int n=0;n<2;++n) _Pragma("unroll") for(int k=0;k<2;++k) \
;     dst[n][k]=*reinterpret_cast<const bf16x8*>((char*)SB(b,h)+lds_byte(wc*32+n*16+fr,k*32+fq*8))
; #define MMA(ai,bj,At_,Bt_) do{__builtin_amdgcn_s_setprio(1); \
;     _Pragma("unroll") for(int m=0;m<4;++m) _Pragma("unroll") for(int n=0;n<2;++n) _Pragma("unroll") for(int k=0;k<2;++k) \
;       acc[ai][bj][m][n]=__builtin_amdgcn_mfma_f32_16x16x32_bf16(Bt_[n][k],At_[m][k],acc[ai][bj][m][n],0,0,0); \
;     __builtin_amdgcn_s_setprio(0);}while(0)
; #define WAIT_L(n) asm volatile("s_waitcnt lgkmcnt(" #n ")":::"memory")
; #define BAR __builtin_amdgcn_s_barrier()
; #define SCHED __builtin_amdgcn_sched_barrier(0)
; DEVINL void gemm8_mainloop(const u16* A, long lda, const u16* Bt, long ldb, int K, int brow, int bcol, f32x4 (&acc)[2][2][4][2], char* smem, int tid) {
;     ...
;   for(int t=0;t<nt-2;t+=2){
;     LDB(B0,0,0); SCHED; LDA(At,0,0); STAGE(SA(1,1),A,lda,brow+HALF,t+1);
;     WAIT_L(8); BAR; WAIT_L(0); MMA(0,0,At,B0); BAR; SCHED;
;     LDB(B1,0,1); STAGE(SB(0,0),Bt,ldb,bcol,t+2);
;     BAR; WAIT_L(0); MMA(0,1,At,B1); BAR;
;     LDA(At,0,1); STAGE(SA(0,0),A,lda,brow,t+2);
;     BAR; WAIT_L(0); MMA(1,0,At,B0); BAR; SCHED;
.LBB0_916:
	ds_read_b128 v[180:183], v165
	ds_read_b128 v[184:187], v165 offset:1024
	ds_read_b128 v[188:191], v165 offset:2048
	ds_read_b128 v[192:195], v165 offset:3072
	v_add_u32_e32 v177, 0xc000, v154
	v_lshl_add_u64 v[244:245], s[94:95], 0, v[146:147]
	v_readfirstlane_b32 s29, v177
	v_add_u32_e32 v178, 0xe000, v154
	v_add_u32_e32 v173, s1, v164
	v_add_u32_e32 v174, s25, v164
	v_add_u32_e32 v175, s37, v164
	v_lshl_add_u64 v[166:167], v[244:245], 0, s[4:5]
	s_mov_b32 m0, s29
	v_lshl_add_u64 v[246:247], s[94:95], 0, v[148:149]
	v_readfirstlane_b32 s29, v178
	ds_read_b128 v[168:171], v155
	ds_read_b128 v[196:199], v155 offset:1024
	ds_read_b128 v[200:203], v173
	ds_read_b128 v[204:207], v173 offset:1024
	ds_read_b128 v[208:211], v174
	ds_read_b128 v[212:215], v174 offset:1024
	ds_read_b128 v[216:219], v175
	ds_read_b128 v[220:223], v175 offset:1024
	global_load_lds_dwordx4 v[166:167], off
	v_lshl_add_u64 v[166:167], v[246:247], 0, s[4:5]
	s_mov_b32 m0, s29
	s_nop 0
	global_load_lds_dwordx4 v[166:167], off
	s_waitcnt lgkmcnt(8)
	s_barrier
	s_waitcnt lgkmcnt(0)
	v_mfma_f32_16x16x32_bf16 v[124:127], v[180:183], v[168:171], v[124:127]
	v_mfma_f32_16x16x32_bf16 v[120:123], v[188:191], v[168:171], v[120:123]
	v_mfma_f32_16x16x32_bf16 v[116:119], v[180:183], v[200:203], v[116:119]
	v_mfma_f32_16x16x32_bf16 v[112:115], v[188:191], v[200:203], v[112:115]
	v_mfma_f32_16x16x32_bf16 v[108:111], v[180:183], v[208:211], v[108:111]
	v_mfma_f32_16x16x32_bf16 v[104:107], v[188:191], v[208:211], v[104:107]
	v_mfma_f32_16x16x32_bf16 v[100:103], v[180:183], v[216:219], v[100:103]
	v_mfma_f32_16x16x32_bf16 v[96:99], v[188:191], v[216:219], v[96:99]
	v_mfma_f32_16x16x32_bf16 v[124:127], v[184:187], v[196:199], v[124:127]
	v_mfma_f32_16x16x32_bf16 v[120:123], v[192:195], v[196:199], v[120:123]
	v_mfma_f32_16x16x32_bf16 v[116:119], v[184:187], v[204:207], v[116:119]
	v_mfma_f32_16x16x32_bf16 v[112:115], v[192:195], v[204:207], v[112:115]
	v_mfma_f32_16x16x32_bf16 v[108:111], v[184:187], v[212:215], v[108:111]
	v_mfma_f32_16x16x32_bf16 v[104:107], v[192:195], v[212:215], v[104:107]
	v_mfma_f32_16x16x32_bf16 v[100:103], v[184:187], v[220:223], v[100:103]
	v_mfma_f32_16x16x32_bf16 v[96:99], v[192:195], v[220:223], v[96:99]
	s_barrier
	v_add_u32_e32 v166, s30, v157
	v_lshl_add_u64 v[248:249], s[94:95], 0, v[142:143]
	v_readfirstlane_b32 s29, v166
	v_add_u32_e32 v167, 0x2000, v166
	v_lshl_add_u64 v[240:241], v[248:249], 0, s[6:7]
	s_mov_b32 m0, s29
	v_lshl_add_u64 v[250:251], s[94:95], 0, v[144:145]
	v_readfirstlane_b32 s29, v167
	ds_read_b128 v[224:227], v162
	ds_read_b128 v[228:231], v162 offset:1024
	ds_read_b128 v[232:235], v162 offset:2048
	ds_read_b128 v[236:239], v162 offset:3072
	global_load_lds_dwordx4 v[240:241], off
	v_lshl_add_u64 v[240:241], v[250:251], 0, s[6:7]
	s_mov_b32 m0, s29
	s_nop 0
	global_load_lds_dwordx4 v[240:241], off
	s_barrier
	s_waitcnt lgkmcnt(0)
	v_mfma_f32_16x16x32_bf16 v[92:95], v[224:227], v[168:171], v[92:95]
	v_mfma_f32_16x16x32_bf16 v[88:91], v[232:235], v[168:171], v[88:91]
	v_mfma_f32_16x16x32_bf16 v[84:87], v[224:227], v[200:203], v[84:87]
	v_mfma_f32_16x16x32_bf16 v[80:83], v[232:235], v[200:203], v[80:83]
	v_mfma_f32_16x16x32_bf16 v[76:79], v[224:227], v[208:211], v[76:79]
	v_mfma_f32_16x16x32_bf16 v[72:75], v[232:235], v[208:211], v[72:75]
	v_mfma_f32_16x16x32_bf16 v[68:71], v[224:227], v[216:219], v[68:71]
	v_mfma_f32_16x16x32_bf16 v[64:67], v[232:235], v[216:219], v[64:67]
	v_mfma_f32_16x16x32_bf16 v[92:95], v[228:231], v[196:199], v[92:95]
	v_mfma_f32_16x16x32_bf16 v[88:91], v[236:239], v[196:199], v[88:91]
	v_mfma_f32_16x16x32_bf16 v[84:87], v[228:231], v[204:207], v[84:87]
	v_mfma_f32_16x16x32_bf16 v[80:83], v[236:239], v[204:207], v[80:83]
	v_mfma_f32_16x16x32_bf16 v[76:79], v[228:231], v[212:215], v[76:79]
	v_mfma_f32_16x16x32_bf16 v[72:75], v[236:239], v[212:215], v[72:75]
	v_mfma_f32_16x16x32_bf16 v[68:71], v[228:231], v[220:223], v[68:71]
	v_mfma_f32_16x16x32_bf16 v[64:67], v[236:239], v[220:223], v[64:67]
	v_readfirstlane_b32 s29, v154
	v_lshl_add_u64 v[168:169], v[244:245], 0, s[8:9]
	s_mov_b32 m0, s29
	s_barrier
	ds_read_b128 v[196:199], v155 offset:16384
	ds_read_b128 v[200:203], v155 offset:17408
	ds_read_b128 v[204:207], v173 offset:16384
	ds_read_b128 v[208:211], v173 offset:17408
	ds_read_b128 v[212:215], v174 offset:16384
	ds_read_b128 v[216:219], v174 offset:17408
	ds_read_b128 v[220:223], v175 offset:16384
	ds_read_b128 v[240:243], v175 offset:17408
	global_load_lds_dwordx4 v[168:169], off
	v_add_u32_e32 v168, 0x2000, v154
	v_lshl_add_u64 v[170:171], v[246:247], 0, s[8:9]
	v_readfirstlane_b32 s29, v168
	s_mov_b32 m0, s29
	s_nop 0
	global_load_lds_dwordx4 v[170:171], off
	s_barrier
	s_waitcnt lgkmcnt(0)
	v_mfma_f32_16x16x32_bf16 v[60:63], v[180:183], v[196:199], v[60:63]
	v_mfma_f32_16x16x32_bf16 v[56:59], v[188:191], v[196:199], v[56:59]
	v_mfma_f32_16x16x32_bf16 v[52:55], v[180:183], v[204:207], v[52:55]
	v_mfma_f32_16x16x32_bf16 v[48:51], v[188:191], v[204:207], v[48:51]
	v_mfma_f32_16x16x32_bf16 v[44:47], v[180:183], v[212:215], v[44:47]
	v_mfma_f32_16x16x32_bf16 v[40:43], v[188:191], v[212:215], v[40:43]
	v_mfma_f32_16x16x32_bf16 v[36:39], v[180:183], v[220:223], v[36:39]
	v_mfma_f32_16x16x32_bf16 v[32:35], v[188:191], v[220:223], v[32:35]
	v_mfma_f32_16x16x32_bf16 v[60:63], v[184:187], v[200:203], v[60:63]
	v_mfma_f32_16x16x32_bf16 v[56:59], v[192:195], v[200:203], v[56:59]
	v_mfma_f32_16x16x32_bf16 v[52:55], v[184:187], v[208:211], v[52:55]
	v_mfma_f32_16x16x32_bf16 v[48:51], v[192:195], v[208:211], v[48:51]
	v_mfma_f32_16x16x32_bf16 v[44:47], v[184:187], v[216:219], v[44:47]
	v_mfma_f32_16x16x32_bf16 v[40:43], v[192:195], v[216:219], v[40:43]
	v_mfma_f32_16x16x32_bf16 v[36:39], v[184:187], v[240:243], v[36:39]
	v_mfma_f32_16x16x32_bf16 v[32:35], v[192:195], v[240:243], v[32:35]
	s_barrier
; #define STAGE(P,BASE,LD,br,kt) do{long _g=(long)(br)*(LD)+(long)(kt)*BK; \
;     _Pragma("unroll") for(int _i=0;_i<2;++_i){int _b=tid*16+_i*8192;int _r,_c;stage_rc(_b,_r,_c); \
;       __builtin_amdgcn_global_load_lds((const unsigned*)((BASE)+_g+(long)_r*(LD)+_c), \
;         (unsigned*)((char*)(P)+_b),16,0,0);}}while(0)
; #define STAGE(P,BASE,LD,br,kt) do{long _g=(long)(br)*(LD)+(long)(kt)*BK; \
;     _Pragma("unroll") for(int _i=0;_i<2;++_i){int _b=tid*16+_i*8192;int _r,_c;stage_rc(_b,_r,_c); \
;       __builtin_amdgcn_global_load_lds((const unsigned*)((BASE)+_g+(long)_r*(LD)+_c), \
;         (unsigned*)((char*)(P)+_b),16,0,0);}}while(0)
; #define LDA(dst,b,h) _Pragma("unroll") for(int m=0;m<4;++m) _Pragma("unroll") for(int k=0;k<2;++k) \
;     dst[m][k]=*reinterpret_cast<const bf16x8*>((char*)SA(b,h)+lds_byte(wr*64+m*16+fr,k*32+fq*8))
; #define LDB(dst,b,h) _Pragma("unroll") for(int n=0;n<2;++n) _Pragma("unroll") for(int k=0;k<2;++k) \
;     dst[n][k]=*reinterpret_cast<const bf16x8*>((char*)SB(b,h)+lds_byte(wc*32+n*16+fr,k*32+fq*8))
; #define MMA(ai,bj,At_,Bt_) do{__builtin_amdgcn_s_setprio(1); \
;     _Pragma("unroll") for(int m=0;m<4;++m) _Pragma("unroll") for(int n=0;n<2;++n) _Pragma("unroll") for(int k=0;k<2;++k) \
;       acc[ai][bj][m][n]=__builtin_amdgcn_mfma_f32_16x16x32_bf16(Bt_[n][k],At_[m][k],acc[ai][bj][m][n],0,0,0); \
;     __builtin_amdgcn_s_setprio(0);}while(0)
; #define WAIT_V(n) asm volatile("s_waitcnt vmcnt(" #n ")":::"memory")
; #define WAIT_L(n) asm volatile("s_waitcnt lgkmcnt(" #n ")":::"memory")
; #define BAR __builtin_amdgcn_s_barrier()
; #define SCHED __builtin_amdgcn_sched_barrier(0)
; DEVINL void gemm8_mainloop(const u16* A, long lda, const u16* Bt, long ldb, int K, int brow, int bcol, f32x4 (&acc)[2][2][4][2], char* smem, int tid) {
;     ...
;     STAGE(SB(0,1),Bt,ldb,bcol+HALF,t+2);
;     WAIT_V(6); BAR; MMA(1,1,At,B1); BAR;
;     LDB(B0,1,0); SCHED; LDA(At,1,0); STAGE(SA(0,1),A,lda,brow+HALF,t+2);
;     WAIT_L(8); BAR; WAIT_L(0); MMA(0,0,At,B0); BAR; SCHED;
;     LDB(B1,1,1); STAGE(SB(1,0),Bt,ldb,bcol,t+3);
;     BAR; WAIT_L(0); MMA(0,1,At,B1); BAR;
;     LDA(At,1,1); STAGE(SA(1,0),A,lda,brow,t+3);
	v_add_u32_e32 v169, s31, v157
	v_lshl_add_u64 v[170:171], v[248:249], 0, s[10:11]
	v_readfirstlane_b32 s29, v169
	s_mov_b32 m0, s29
	v_lshl_add_u64 v[180:181], v[250:251], 0, s[10:11]
	global_load_lds_dwordx4 v[170:171], off
	v_add_u32_e32 v170, 0x2000, v169
	s_nop 0
	v_readfirstlane_b32 s29, v170
	s_mov_b32 m0, s29
	s_nop 0
	global_load_lds_dwordx4 v[180:181], off
	s_waitcnt vmcnt(6)
	s_barrier
	v_mfma_f32_16x16x32_bf16 v[28:31], v[224:227], v[196:199], v[28:31]
	v_mfma_f32_16x16x32_bf16 v[24:27], v[232:235], v[196:199], v[24:27]
	v_mfma_f32_16x16x32_bf16 v[20:23], v[224:227], v[204:207], v[20:23]
	v_mfma_f32_16x16x32_bf16 v[16:19], v[232:235], v[204:207], v[16:19]
	v_mfma_f32_16x16x32_bf16 v[12:15], v[224:227], v[212:215], v[12:15]
	v_mfma_f32_16x16x32_bf16 v[8:11], v[232:235], v[212:215], v[8:11]
	v_mfma_f32_16x16x32_bf16 v[4:7], v[224:227], v[220:223], v[4:7]
	v_mfma_f32_16x16x32_bf16 v[0:3], v[232:235], v[220:223], v[0:3]
	v_mfma_f32_16x16x32_bf16 v[28:31], v[228:231], v[200:203], v[28:31]
	v_mfma_f32_16x16x32_bf16 v[24:27], v[236:239], v[200:203], v[24:27]
	v_mfma_f32_16x16x32_bf16 v[20:23], v[228:231], v[208:211], v[20:23]
	v_mfma_f32_16x16x32_bf16 v[16:19], v[236:239], v[208:211], v[16:19]
	v_mfma_f32_16x16x32_bf16 v[12:15], v[228:231], v[216:219], v[12:15]
	v_mfma_f32_16x16x32_bf16 v[8:11], v[236:239], v[216:219], v[8:11]
	v_mfma_f32_16x16x32_bf16 v[4:7], v[228:231], v[240:243], v[4:7]
	v_mfma_f32_16x16x32_bf16 v[0:3], v[236:239], v[240:243], v[0:3]
	s_barrier
	ds_read_b128 v[180:183], v158
	ds_read_b128 v[184:187], v158 offset:1024
	ds_read_b128 v[188:191], v158 offset:2048
	ds_read_b128 v[192:195], v158 offset:3072
	v_add_u32_e32 v171, 0x4000, v154
	v_add_u32_e32 v172, 0x6000, v154
	v_readfirstlane_b32 s29, v171
	v_lshl_add_u64 v[228:229], v[244:245], 0, s[12:13]
	s_mov_b32 m0, s29
	v_readfirstlane_b32 s29, v172
	ds_read_b128 v[196:199], v155 offset:32768
	ds_read_b128 v[200:203], v155 offset:33792
	ds_read_b128 v[204:207], v173 offset:32768
	ds_read_b128 v[208:211], v173 offset:33792
	ds_read_b128 v[212:215], v174 offset:32768
	ds_read_b128 v[216:219], v174 offset:33792
	ds_read_b128 v[220:223], v175 offset:32768
	ds_read_b128 v[224:227], v175 offset:33792
	global_load_lds_dwordx4 v[228:229], off
	v_lshl_add_u64 v[228:229], v[246:247], 0, s[12:13]
	s_mov_b32 m0, s29
	s_nop 0
	global_load_lds_dwordx4 v[228:229], off
	s_waitcnt lgkmcnt(8)
	s_barrier
	s_waitcnt lgkmcnt(0)
	v_mfma_f32_16x16x32_bf16 v[124:127], v[180:183], v[196:199], v[124:127]
	v_mfma_f32_16x16x32_bf16 v[120:123], v[188:191], v[196:199], v[120:123]
	v_mfma_f32_16x16x32_bf16 v[116:119], v[180:183], v[204:207], v[116:119]
	v_mfma_f32_16x16x32_bf16 v[112:115], v[188:191], v[204:207], v[112:115]
	v_mfma_f32_16x16x32_bf16 v[108:111], v[180:183], v[212:215], v[108:111]
	v_mfma_f32_16x16x32_bf16 v[104:107], v[188:191], v[212:215], v[104:107]
	v_mfma_f32_16x16x32_bf16 v[100:103], v[180:183], v[220:223], v[100:103]
	v_mfma_f32_16x16x32_bf16 v[96:99], v[188:191], v[220:223], v[96:99]
	v_mfma_f32_16x16x32_bf16 v[124:127], v[184:187], v[200:203], v[124:127]
	v_mfma_f32_16x16x32_bf16 v[120:123], v[192:195], v[200:203], v[120:123]
	v_mfma_f32_16x16x32_bf16 v[116:119], v[184:187], v[208:211], v[116:119]
	v_mfma_f32_16x16x32_bf16 v[112:115], v[192:195], v[208:211], v[112:115]
	v_mfma_f32_16x16x32_bf16 v[108:111], v[184:187], v[216:219], v[108:111]
	v_mfma_f32_16x16x32_bf16 v[104:107], v[192:195], v[216:219], v[104:107]
	v_mfma_f32_16x16x32_bf16 v[100:103], v[184:187], v[224:227], v[100:103]
	v_mfma_f32_16x16x32_bf16 v[96:99], v[192:195], v[224:227], v[96:99]
	s_barrier
	v_readfirstlane_b32 s29, v159
	v_add_u32_e32 v179, 0x2000, v159
	v_lshl_add_u64 v[252:253], v[248:249], 0, s[14:15]
	s_mov_b32 m0, s29
	v_readfirstlane_b32 s29, v179
	ds_read_b128 v[228:231], v156
	ds_read_b128 v[232:235], v156 offset:1024
	ds_read_b128 v[236:239], v156 offset:2048
	ds_read_b128 v[240:243], v156 offset:3072
	global_load_lds_dwordx4 v[252:253], off
	v_lshl_add_u64 v[252:253], v[250:251], 0, s[14:15]
	s_mov_b32 m0, s29
	s_nop 0
	global_load_lds_dwordx4 v[252:253], off
	s_barrier
	s_waitcnt lgkmcnt(0)
	v_mfma_f32_16x16x32_bf16 v[92:95], v[228:231], v[196:199], v[92:95]
	v_mfma_f32_16x16x32_bf16 v[88:91], v[236:239], v[196:199], v[88:91]
	v_mfma_f32_16x16x32_bf16 v[84:87], v[228:231], v[204:207], v[84:87]
	v_mfma_f32_16x16x32_bf16 v[80:83], v[236:239], v[204:207], v[80:83]
	v_mfma_f32_16x16x32_bf16 v[76:79], v[228:231], v[212:215], v[76:79]
	v_mfma_f32_16x16x32_bf16 v[72:75], v[236:239], v[212:215], v[72:75]
	v_mfma_f32_16x16x32_bf16 v[68:71], v[228:231], v[220:223], v[68:71]
	v_mfma_f32_16x16x32_bf16 v[64:67], v[236:239], v[220:223], v[64:67]
	v_mfma_f32_16x16x32_bf16 v[92:95], v[232:235], v[200:203], v[92:95]
	v_mfma_f32_16x16x32_bf16 v[88:91], v[240:243], v[200:203], v[88:91]
	v_mfma_f32_16x16x32_bf16 v[84:87], v[232:235], v[208:211], v[84:87]
	v_mfma_f32_16x16x32_bf16 v[80:83], v[240:243], v[208:211], v[80:83]
	v_mfma_f32_16x16x32_bf16 v[76:79], v[232:235], v[216:219], v[76:79]
	v_mfma_f32_16x16x32_bf16 v[72:75], v[240:243], v[216:219], v[72:75]
	v_mfma_f32_16x16x32_bf16 v[68:71], v[232:235], v[224:227], v[68:71]
	v_mfma_f32_16x16x32_bf16 v[64:67], v[240:243], v[224:227], v[64:67]
	v_readfirstlane_b32 s29, v160
	v_lshl_add_u64 v[244:245], v[244:245], 0, s[16:17]
	s_mov_b32 m0, s29
	v_readfirstlane_b32 s29, v161
	s_barrier
	ds_read_b128 v[196:199], v155 offset:49152
	ds_read_b128 v[200:203], v155 offset:50176
	ds_read_b128 v[204:207], v173 offset:49152
	ds_read_b128 v[208:211], v173 offset:50176
	ds_read_b128 v[212:215], v174 offset:49152
	ds_read_b128 v[216:219], v174 offset:50176
	ds_read_b128 v[220:223], v175 offset:49152
	ds_read_b128 v[224:227], v175 offset:50176
	global_load_lds_dwordx4 v[244:245], off
	v_lshl_add_u64 v[244:245], v[246:247], 0, s[16:17]
	s_mov_b32 m0, s29
	s_nop 0
	global_load_lds_dwordx4 v[244:245], off
	s_barrier
; #define STAGE(P,BASE,LD,br,kt) do{long _g=(long)(br)*(LD)+(long)(kt)*BK; \
;     _Pragma("unroll") for(int _i=0;_i<2;++_i){int _b=tid*16+_i*8192;int _r,_c;stage_rc(_b,_r,_c); \
;       __builtin_amdgcn_global_load_lds((const unsigned*)((BASE)+_g+(long)_r*(LD)+_c), \
;         (unsigned*)((char*)(P)+_b),16,0,0);}}while(0)
; #define STAGE(P,BASE,LD,br,kt) do{long _g=(long)(br)*(LD)+(long)(kt)*BK; \
;     _Pragma("unroll") for(int _i=0;_i<2;++_i){int _b=tid*16+_i*8192;int _r,_c;stage_rc(_b,_r,_c); \
;       __builtin_amdgcn_global_load_lds((const unsigned*)((BASE)+_g+(long)_r*(LD)+_c), \
;         (unsigned*)((char*)(P)+_b),16,0,0);}}while(0)
; #define LDA(dst,b,h) _Pragma("unroll") for(int m=0;m<4;++m) _Pragma("unroll") for(int k=0;k<2;++k) \
;     dst[m][k]=*reinterpret_cast<const bf16x8*>((char*)SA(b,h)+lds_byte(wr*64+m*16+fr,k*32+fq*8))
; #define LDB(dst,b,h) _Pragma("unroll") for(int n=0;n<2;++n) _Pragma("unroll") for(int k=0;k<2;++k) \
;     dst[n][k]=*reinterpret_cast<const bf16x8*>((char*)SB(b,h)+lds_byte(wc*32+n*16+fr,k*32+fq*8))
; #define MMA(ai,bj,At_,Bt_) do{__builtin_amdgcn_s_setprio(1); \
;     _Pragma("unroll") for(int m=0;m<4;++m) _Pragma("unroll") for(int n=0;n<2;++n) _Pragma("unroll") for(int k=0;k<2;++k) \
;       acc[ai][bj][m][n]=__builtin_amdgcn_mfma_f32_16x16x32_bf16(Bt_[n][k],At_[m][k],acc[ai][bj][m][n],0,0,0); \
;     __builtin_amdgcn_s_setprio(0);}while(0)
; #define WAIT_V(n) asm volatile("s_waitcnt vmcnt(" #n ")":::"memory")
; #define WAIT_L(n) asm volatile("s_waitcnt lgkmcnt(" #n ")":::"memory")
; #define BAR __builtin_amdgcn_s_barrier()
; #define SCHED __builtin_amdgcn_sched_barrier(0)
; DEVINL void gemm8_mainloop(const u16* A, long lda, const u16* Bt, long ldb, int K, int brow, int bcol, f32x4 (&acc)[2][2][4][2], char* smem, int tid) {
;     ...
;     BAR; WAIT_L(0); MMA(1,0,At,B0); BAR; SCHED;
;     STAGE(SB(1,1),Bt,ldb,bcol+HALF,t+3);
;     WAIT_V(6); BAR; MMA(1,1,At,B1); BAR;
;   }
;   { LDB(B0,0,0); LDA(At,0,0); STAGE(SA(1,1),A,lda,brow+HALF,nt-1);
;     BAR; WAIT_L(0); MMA(0,0,At,B0); BAR;
;     LDB(B1,0,1); BAR; WAIT_L(0); MMA(0,1,At,B1); BAR;
	s_waitcnt lgkmcnt(0)
	v_mfma_f32_16x16x32_bf16 v[60:63], v[180:183], v[196:199], v[60:63]
	v_mfma_f32_16x16x32_bf16 v[56:59], v[188:191], v[196:199], v[56:59]
	v_mfma_f32_16x16x32_bf16 v[52:55], v[180:183], v[204:207], v[52:55]
	v_mfma_f32_16x16x32_bf16 v[48:51], v[188:191], v[204:207], v[48:51]
	v_mfma_f32_16x16x32_bf16 v[44:47], v[180:183], v[212:215], v[44:47]
	v_mfma_f32_16x16x32_bf16 v[40:43], v[188:191], v[212:215], v[40:43]
	v_mfma_f32_16x16x32_bf16 v[36:39], v[180:183], v[220:223], v[36:39]
	v_mfma_f32_16x16x32_bf16 v[32:35], v[188:191], v[220:223], v[32:35]
	v_mfma_f32_16x16x32_bf16 v[60:63], v[184:187], v[200:203], v[60:63]
	v_mfma_f32_16x16x32_bf16 v[56:59], v[192:195], v[200:203], v[56:59]
	v_mfma_f32_16x16x32_bf16 v[52:55], v[184:187], v[208:211], v[52:55]
	v_mfma_f32_16x16x32_bf16 v[48:51], v[192:195], v[208:211], v[48:51]
	v_mfma_f32_16x16x32_bf16 v[44:47], v[184:187], v[216:219], v[44:47]
	v_mfma_f32_16x16x32_bf16 v[40:43], v[192:195], v[216:219], v[40:43]
	v_mfma_f32_16x16x32_bf16 v[36:39], v[184:187], v[224:227], v[36:39]
	v_mfma_f32_16x16x32_bf16 v[32:35], v[192:195], v[224:227], v[32:35]
	s_barrier
	v_readfirstlane_b32 s29, v163
	v_add_u32_e32 v179, 0x2000, v163
	v_lshl_add_u64 v[180:181], v[248:249], 0, s[18:19]
	s_mov_b32 m0, s29
	v_readfirstlane_b32 s29, v179
	global_load_lds_dwordx4 v[180:181], off
	v_lshl_add_u64 v[180:181], v[250:251], 0, s[18:19]
	s_mov_b32 m0, s29
	s_nop 0
	global_load_lds_dwordx4 v[180:181], off
	s_waitcnt vmcnt(6)
	s_barrier
	v_mfma_f32_16x16x32_bf16 v[28:31], v[228:231], v[196:199], v[28:31]
	v_mfma_f32_16x16x32_bf16 v[24:27], v[236:239], v[196:199], v[24:27]
	v_mfma_f32_16x16x32_bf16 v[20:23], v[228:231], v[204:207], v[20:23]
	v_mfma_f32_16x16x32_bf16 v[16:19], v[236:239], v[204:207], v[16:19]
	v_mfma_f32_16x16x32_bf16 v[12:15], v[228:231], v[212:215], v[12:15]
	v_mfma_f32_16x16x32_bf16 v[8:11], v[236:239], v[212:215], v[8:11]
	v_mfma_f32_16x16x32_bf16 v[4:7], v[228:231], v[220:223], v[4:7]
	v_mfma_f32_16x16x32_bf16 v[0:3], v[236:239], v[220:223], v[0:3]
	v_mfma_f32_16x16x32_bf16 v[28:31], v[232:235], v[200:203], v[28:31]
	v_mfma_f32_16x16x32_bf16 v[24:27], v[240:243], v[200:203], v[24:27]
	v_mfma_f32_16x16x32_bf16 v[20:23], v[232:235], v[208:211], v[20:23]
	v_mfma_f32_16x16x32_bf16 v[16:19], v[240:243], v[208:211], v[16:19]
	v_mfma_f32_16x16x32_bf16 v[12:15], v[232:235], v[216:219], v[12:15]
	v_mfma_f32_16x16x32_bf16 v[8:11], v[240:243], v[216:219], v[8:11]
	v_mfma_f32_16x16x32_bf16 v[4:7], v[232:235], v[224:227], v[4:7]
	v_mfma_f32_16x16x32_bf16 v[0:3], v[240:243], v[224:227], v[0:3]
	s_add_i32 s28, s28, 2
	v_lshl_add_u64 v[142:143], v[142:143], 0, s[20:21]
	v_lshl_add_u64 v[144:145], v[144:145], 0, s[20:21]
	v_lshl_add_u64 v[146:147], v[146:147], 0, s[20:21]
	s_cmp_lt_u32 s28, 28
	v_lshl_add_u64 v[148:149], v[148:149], 0, s[20:21]
	s_barrier
	s_cbranch_scc1 .LBB0_916
	s_or_b32 s28, s24, 0x80
	s_ashr_i32 s29, s28, 31
	s_lshl_b64 s[28:29], s[28:29], 12
	s_add_u32 s28, s90, s28
	s_addc_u32 s29, s91, s29
	v_lshl_add_u64 v[160:161], v[134:135], 1, s[28:29]
	v_lshl_add_u64 v[138:139], v[138:139], 1, v[160:161]
	v_readfirstlane_b32 s1, v177
	v_lshl_add_u64 v[138:139], v[138:139], 0, s[22:23]
	s_mov_b32 m0, s1
	ds_read_b128 v[142:145], v165
	ds_read_b128 v[146:149], v165 offset:1024
	ds_read_b128 v[180:183], v165 offset:2048
	ds_read_b128 v[184:187], v165 offset:3072
	ds_read_b128 v[188:191], v155
	ds_read_b128 v[192:195], v155 offset:1024
	ds_read_b128 v[196:199], v173
	ds_read_b128 v[200:203], v173 offset:1024
	ds_read_b128 v[204:207], v174
	ds_read_b128 v[208:211], v174 offset:1024
	ds_read_b128 v[212:215], v175
	ds_read_b128 v[216:219], v175 offset:1024
	global_load_lds_dwordx4 v[138:139], off
	v_lshl_add_u64 v[138:139], v[136:137], 1, s[28:29]
	v_lshl_add_u64 v[138:139], v[140:141], 1, v[138:139]
	v_readfirstlane_b32 s1, v178
	v_lshl_add_u64 v[138:139], v[138:139], 0, s[22:23]
	s_mov_b32 m0, s1
	s_nop 0
	global_load_lds_dwordx4 v[138:139], off
	s_barrier
	s_waitcnt lgkmcnt(0)
	v_mfma_f32_16x16x32_bf16 v[124:127], v[142:145], v[188:191], v[124:127]
	v_mfma_f32_16x16x32_bf16 v[120:123], v[180:183], v[188:191], v[120:123]
	v_mfma_f32_16x16x32_bf16 v[116:119], v[142:145], v[196:199], v[116:119]
	v_mfma_f32_16x16x32_bf16 v[112:115], v[180:183], v[196:199], v[112:115]
	v_mfma_f32_16x16x32_bf16 v[104:107], v[180:183], v[204:207], v[104:107]
	v_mfma_f32_16x16x32_bf16 v[96:99], v[180:183], v[212:215], v[96:99]
	v_mfma_f32_16x16x32_bf16 v[124:127], v[146:149], v[192:195], v[124:127]
	v_mfma_f32_16x16x32_bf16 v[120:123], v[184:187], v[192:195], v[120:123]
	v_mfma_f32_16x16x32_bf16 v[116:119], v[146:149], v[200:203], v[116:119]
	v_mfma_f32_16x16x32_bf16 v[112:115], v[184:187], v[200:203], v[112:115]
	v_mfma_f32_16x16x32_bf16 v[108:111], v[142:145], v[204:207], v[108:111]
	v_mfma_f32_16x16x32_bf16 v[104:107], v[184:187], v[208:211], v[104:107]
	v_mfma_f32_16x16x32_bf16 v[100:103], v[142:145], v[212:215], v[100:103]
	v_mfma_f32_16x16x32_bf16 v[96:99], v[184:187], v[216:219], v[96:99]
	v_mfma_f32_16x16x32_bf16 v[138:141], v[146:149], v[208:211], v[108:111]
	v_mfma_f32_16x16x32_bf16 v[220:223], v[146:149], v[216:219], v[100:103]
	s_barrier
	s_nop 2
	s_nop 0
	ds_read_b128 v[100:103], v162
	ds_read_b128 v[108:111], v162 offset:1024
	ds_read_b128 v[224:227], v162 offset:2048
	ds_read_b128 v[160:163], v162 offset:3072
	s_barrier
; #define LDA(dst,b,h) _Pragma("unroll") for(int m=0;m<4;++m) _Pragma("unroll") for(int k=0;k<2;++k) \
;     dst[m][k]=*reinterpret_cast<const bf16x8*>((char*)SA(b,h)+lds_byte(wr*64+m*16+fr,k*32+fq*8))
; #define LDB(dst,b,h) _Pragma("unroll") for(int n=0;n<2;++n) _Pragma("unroll") for(int k=0;k<2;++k) \
;     dst[n][k]=*reinterpret_cast<const bf16x8*>((char*)SB(b,h)+lds_byte(wc*32+n*16+fr,k*32+fq*8))
; #define MMA(ai,bj,At_,Bt_) do{__builtin_amdgcn_s_setprio(1); \
;     _Pragma("unroll") for(int m=0;m<4;++m) _Pragma("unroll") for(int n=0;n<2;++n) _Pragma("unroll") for(int k=0;k<2;++k) \
;       acc[ai][bj][m][n]=__builtin_amdgcn_mfma_f32_16x16x32_bf16(Bt_[n][k],At_[m][k],acc[ai][bj][m][n],0,0,0); \
;     __builtin_amdgcn_s_setprio(0);}while(0)
; #define WAIT_V(n) asm volatile("s_waitcnt vmcnt(" #n ")":::"memory")
; #define WAIT_L(n) asm volatile("s_waitcnt lgkmcnt(" #n ")":::"memory")
; #define BAR __builtin_amdgcn_s_barrier()
; DEVINL void gemm8_mainloop(const u16* A, long lda, const u16* Bt, long ldb, int K, int brow, int bcol, f32x4 (&acc)[2][2][4][2], char* smem, int tid) {
;     ...
;     LDB(B1,0,1); BAR; WAIT_L(0); MMA(0,1,At,B1); BAR;
;     LDA(At,0,1); WAIT_V(4); BAR; WAIT_L(0); MMA(1,0,At,B0); MMA(1,1,At,B1); BAR; }
;   { LDB(B0,1,0); LDA(At,1,0); WAIT_V(2); BAR; WAIT_L(0); MMA(0,0,At,B0); BAR;
	s_waitcnt lgkmcnt(0)
	v_mfma_f32_16x16x32_bf16 v[88:91], v[224:227], v[188:191], v[88:91]
	v_mfma_f32_16x16x32_bf16 v[80:83], v[224:227], v[196:199], v[80:83]
	v_mfma_f32_16x16x32_bf16 v[72:75], v[224:227], v[204:207], v[72:75]
	v_mfma_f32_16x16x32_bf16 v[64:67], v[224:227], v[212:215], v[64:67]
	v_mfma_f32_16x16x32_bf16 v[92:95], v[100:103], v[188:191], v[92:95]
	v_mfma_f32_16x16x32_bf16 v[88:91], v[160:163], v[192:195], v[88:91]
	v_mfma_f32_16x16x32_bf16 v[84:87], v[100:103], v[196:199], v[84:87]
	v_mfma_f32_16x16x32_bf16 v[80:83], v[160:163], v[200:203], v[80:83]
	v_mfma_f32_16x16x32_bf16 v[76:79], v[100:103], v[204:207], v[76:79]
	v_mfma_f32_16x16x32_bf16 v[72:75], v[160:163], v[208:211], v[72:75]
	v_mfma_f32_16x16x32_bf16 v[68:71], v[100:103], v[212:215], v[68:71]
	v_mfma_f32_16x16x32_bf16 v[64:67], v[160:163], v[216:219], v[64:67]
	v_mfma_f32_16x16x32_bf16 v[228:231], v[108:111], v[192:195], v[92:95]
	v_mfma_f32_16x16x32_bf16 v[188:191], v[108:111], v[200:203], v[84:87]
	v_mfma_f32_16x16x32_bf16 v[192:195], v[108:111], v[208:211], v[76:79]
	v_mfma_f32_16x16x32_bf16 v[196:199], v[108:111], v[216:219], v[68:71]
	s_barrier
	s_nop 0
	s_nop 0
	ds_read_b128 v[68:71], v155 offset:16384
	ds_read_b128 v[76:79], v155 offset:17408
	ds_read_b128 v[84:87], v173 offset:16384
	ds_read_b128 v[92:95], v173 offset:17408
	ds_read_b128 v[200:203], v174 offset:16384
	ds_read_b128 v[204:207], v174 offset:17408
	ds_read_b128 v[208:211], v175 offset:16384
	ds_read_b128 v[212:215], v175 offset:17408
	s_waitcnt vmcnt(4)
	s_barrier
	s_waitcnt lgkmcnt(0)
	v_mfma_f32_16x16x32_bf16 v[60:63], v[142:145], v[68:71], v[60:63]
	v_mfma_f32_16x16x32_bf16 v[56:59], v[180:183], v[68:71], v[56:59]
	v_mfma_f32_16x16x32_bf16 v[48:51], v[180:183], v[84:87], v[48:51]
	v_mfma_f32_16x16x32_bf16 v[40:43], v[180:183], v[200:203], v[40:43]
	v_mfma_f32_16x16x32_bf16 v[32:35], v[180:183], v[208:211], v[32:35]
	v_mfma_f32_16x16x32_bf16 v[60:63], v[146:149], v[76:79], v[60:63]
	v_mfma_f32_16x16x32_bf16 v[56:59], v[184:187], v[76:79], v[56:59]
	v_mfma_f32_16x16x32_bf16 v[52:55], v[142:145], v[84:87], v[52:55]
	v_mfma_f32_16x16x32_bf16 v[48:51], v[184:187], v[92:95], v[48:51]
	v_mfma_f32_16x16x32_bf16 v[44:47], v[142:145], v[200:203], v[44:47]
	v_mfma_f32_16x16x32_bf16 v[40:43], v[184:187], v[204:207], v[40:43]
	v_mfma_f32_16x16x32_bf16 v[36:39], v[142:145], v[208:211], v[36:39]
	v_mfma_f32_16x16x32_bf16 v[32:35], v[184:187], v[212:215], v[32:35]
	v_mfma_f32_16x16x32_bf16 v[216:219], v[146:149], v[92:95], v[52:55]
	v_mfma_f32_16x16x32_bf16 v[232:235], v[146:149], v[204:207], v[44:47]
	v_mfma_f32_16x16x32_bf16 v[142:145], v[146:149], v[212:215], v[36:39]
	v_mfma_f32_16x16x32_bf16 v[24:27], v[224:227], v[68:71], v[24:27]
	v_mfma_f32_16x16x32_bf16 v[16:19], v[224:227], v[84:87], v[16:19]
	v_mfma_f32_16x16x32_bf16 v[4:7], v[100:103], v[208:211], v[4:7]
	v_mfma_f32_16x16x32_bf16 v[0:3], v[224:227], v[208:211], v[0:3]
	v_mfma_f32_16x16x32_bf16 v[28:31], v[100:103], v[68:71], v[28:31]
	v_mfma_f32_16x16x32_bf16 v[24:27], v[160:163], v[76:79], v[24:27]
	v_mfma_f32_16x16x32_bf16 v[20:23], v[100:103], v[84:87], v[20:23]
	v_mfma_f32_16x16x32_bf16 v[16:19], v[160:163], v[92:95], v[16:19]
	v_mfma_f32_16x16x32_bf16 v[12:15], v[100:103], v[200:203], v[12:15]
	v_mfma_f32_16x16x32_bf16 v[8:11], v[224:227], v[200:203], v[8:11]
	v_mfma_f32_16x16x32_bf16 v[4:7], v[108:111], v[212:215], v[4:7]
	v_mfma_f32_16x16x32_bf16 v[0:3], v[160:163], v[212:215], v[0:3]
	v_mfma_f32_16x16x32_bf16 v[146:149], v[108:111], v[76:79], v[28:31]
	v_mfma_f32_16x16x32_bf16 v[178:181], v[108:111], v[92:95], v[20:23]
	v_mfma_f32_16x16x32_bf16 v[182:185], v[108:111], v[204:207], v[12:15]
	v_mfma_f32_16x16x32_bf16 v[200:203], v[160:163], v[204:207], v[8:11]
	s_barrier
	s_nop 0
	s_nop 0
	ds_read_b128 v[8:11], v158
	ds_read_b128 v[12:15], v158 offset:1024
	ds_read_b128 v[160:163], v158 offset:2048
	ds_read_b128 v[204:207], v158 offset:3072
	ds_read_b128 v[20:23], v155 offset:32768
	ds_read_b128 v[28:31], v155 offset:33792
	ds_read_b128 v[36:39], v173 offset:32768
	ds_read_b128 v[44:47], v173 offset:33792
	ds_read_b128 v[52:55], v174 offset:32768
	ds_read_b128 v[208:211], v174 offset:33792
	ds_read_b128 v[212:215], v175 offset:32768
	ds_read_b128 v[224:227], v175 offset:33792
	s_waitcnt vmcnt(2)
	s_barrier
; #define LDA(dst,b,h) _Pragma("unroll") for(int m=0;m<4;++m) _Pragma("unroll") for(int k=0;k<2;++k) \
;     dst[m][k]=*reinterpret_cast<const bf16x8*>((char*)SA(b,h)+lds_byte(wr*64+m*16+fr,k*32+fq*8))
; #define LDB(dst,b,h) _Pragma("unroll") for(int n=0;n<2;++n) _Pragma("unroll") for(int k=0;k<2;++k) \
;     dst[n][k]=*reinterpret_cast<const bf16x8*>((char*)SB(b,h)+lds_byte(wc*32+n*16+fr,k*32+fq*8))
; #define MMA(ai,bj,At_,Bt_) do{__builtin_amdgcn_s_setprio(1); \
;     _Pragma("unroll") for(int m=0;m<4;++m) _Pragma("unroll") for(int n=0;n<2;++n) _Pragma("unroll") for(int k=0;k<2;++k) \
;       acc[ai][bj][m][n]=__builtin_amdgcn_mfma_f32_16x16x32_bf16(Bt_[n][k],At_[m][k],acc[ai][bj][m][n],0,0,0); \
;     __builtin_amdgcn_s_setprio(0);}while(0)
; #define WAIT_V(n) asm volatile("s_waitcnt vmcnt(" #n ")":::"memory")
; #define WAIT_L(n) asm volatile("s_waitcnt lgkmcnt(" #n ")":::"memory")
; #define BAR __builtin_amdgcn_s_barrier()
; DEVINL void gemm8_mainloop(const u16* A, long lda, const u16* Bt, long ldb, int K, int brow, int bcol, f32x4 (&acc)[2][2][4][2], char* smem, int tid) {
;     ...
;   { LDB(B0,1,0); LDA(At,1,0); WAIT_V(2); BAR; WAIT_L(0); MMA(0,0,At,B0); BAR;
;     LDB(B1,1,1); WAIT_V(0); BAR; WAIT_L(0); MMA(0,1,At,B1); BAR;
;     LDA(At,1,1); BAR; WAIT_L(0); MMA(1,0,At,B0); MMA(1,1,At,B1); BAR; }
;   if(wr==0)BAR;
	s_waitcnt lgkmcnt(0)
	v_mfma_f32_16x16x32_bf16 v[68:71], v[8:11], v[20:23], v[124:127]
	v_mfma_f32_16x16x32_bf16 v[124:127], v[12:15], v[28:31], v[68:71]
	v_mfma_f32_16x16x32_bf16 v[68:71], v[160:163], v[20:23], v[120:123]
	v_mfma_f32_16x16x32_bf16 v[120:123], v[204:207], v[28:31], v[68:71]
	v_mfma_f32_16x16x32_bf16 v[68:71], v[8:11], v[36:39], v[116:119]
	v_mfma_f32_16x16x32_bf16 v[108:111], v[12:15], v[44:47], v[68:71]
	v_mfma_f32_16x16x32_bf16 v[68:71], v[160:163], v[36:39], v[112:115]
	v_mfma_f32_16x16x32_bf16 v[100:103], v[204:207], v[44:47], v[68:71]
	v_mfma_f32_16x16x32_bf16 v[68:71], v[8:11], v[52:55], v[138:141]
	v_mfma_f32_16x16x32_bf16 v[92:95], v[12:15], v[208:211], v[68:71]
	v_mfma_f32_16x16x32_bf16 v[68:71], v[160:163], v[52:55], v[104:107]
	v_mfma_f32_16x16x32_bf16 v[84:87], v[204:207], v[208:211], v[68:71]
	v_mfma_f32_16x16x32_bf16 v[68:71], v[8:11], v[212:215], v[220:223]
	v_mfma_f32_16x16x32_bf16 v[76:79], v[12:15], v[224:227], v[68:71]
	v_mfma_f32_16x16x32_bf16 v[68:71], v[160:163], v[212:215], v[96:99]
	v_mfma_f32_16x16x32_bf16 v[68:71], v[204:207], v[224:227], v[68:71]
	s_barrier
	ds_read_b128 v[138:141], v156
	ds_read_b128 v[220:223], v156 offset:1024
	ds_read_b128 v[236:239], v156 offset:2048
	ds_read_b128 v[156:159], v156 offset:3072
	s_waitcnt vmcnt(0)
	s_barrier
	s_waitcnt lgkmcnt(0)
	v_mfma_f32_16x16x32_bf16 v[96:99], v[138:141], v[20:23], v[228:231]
	v_mfma_f32_16x16x32_bf16 v[20:23], v[236:239], v[20:23], v[88:91]
	v_mfma_f32_16x16x32_bf16 v[112:115], v[156:159], v[28:31], v[20:23]
	v_mfma_f32_16x16x32_bf16 v[20:23], v[138:141], v[36:39], v[188:191]
	v_mfma_f32_16x16x32_bf16 v[104:107], v[220:223], v[44:47], v[20:23]
	v_mfma_f32_16x16x32_bf16 v[20:23], v[236:239], v[36:39], v[80:83]
	v_mfma_f32_16x16x32_bf16 v[116:119], v[220:223], v[28:31], v[96:99]
	v_mfma_f32_16x16x32_bf16 v[96:99], v[156:159], v[44:47], v[20:23]
	v_mfma_f32_16x16x32_bf16 v[20:23], v[138:141], v[52:55], v[192:195]
	v_mfma_f32_16x16x32_bf16 v[88:91], v[220:223], v[208:211], v[20:23]
	v_mfma_f32_16x16x32_bf16 v[20:23], v[236:239], v[52:55], v[72:75]
	v_mfma_f32_16x16x32_bf16 v[80:83], v[156:159], v[208:211], v[20:23]
	v_mfma_f32_16x16x32_bf16 v[20:23], v[138:141], v[212:215], v[196:199]
	v_mfma_f32_16x16x32_bf16 v[72:75], v[220:223], v[224:227], v[20:23]
	v_mfma_f32_16x16x32_bf16 v[20:23], v[236:239], v[212:215], v[64:67]
	v_mfma_f32_16x16x32_bf16 v[64:67], v[156:159], v[224:227], v[20:23]
	s_barrier
	ds_read_b128 v[186:189], v155 offset:49152
	ds_read_b128 v[190:193], v155 offset:50176
	ds_read_b128 v[194:197], v173 offset:49152
	ds_read_b128 v[208:211], v173 offset:50176
	ds_read_b128 v[212:215], v174 offset:49152
	ds_read_b128 v[224:227], v174 offset:50176
	ds_read_b128 v[228:231], v175 offset:49152
	ds_read_b128 v[240:243], v175 offset:50176
	s_barrier
	s_waitcnt lgkmcnt(0)
	v_mfma_f32_16x16x32_bf16 v[20:23], v[8:11], v[186:189], v[60:63]
	v_mfma_f32_16x16x32_bf16 v[60:63], v[12:15], v[190:193], v[20:23]
	v_mfma_f32_16x16x32_bf16 v[20:23], v[160:163], v[186:189], v[56:59]
	v_mfma_f32_16x16x32_bf16 v[52:55], v[204:207], v[190:193], v[20:23]
	v_mfma_f32_16x16x32_bf16 v[20:23], v[8:11], v[194:197], v[216:219]
	v_mfma_f32_16x16x32_bf16 v[44:47], v[12:15], v[208:211], v[20:23]
	v_mfma_f32_16x16x32_bf16 v[20:23], v[160:163], v[194:197], v[48:51]
	v_mfma_f32_16x16x32_bf16 v[36:39], v[204:207], v[208:211], v[20:23]
	v_mfma_f32_16x16x32_bf16 v[20:23], v[8:11], v[212:215], v[232:235]
	v_mfma_f32_16x16x32_bf16 v[8:11], v[8:11], v[228:231], v[142:145]
	v_mfma_f32_16x16x32_bf16 v[28:31], v[12:15], v[224:227], v[20:23]
	v_mfma_f32_16x16x32_bf16 v[20:23], v[160:163], v[212:215], v[40:43]
	v_mfma_f32_16x16x32_bf16 v[12:15], v[12:15], v[240:243], v[8:11]
	v_mfma_f32_16x16x32_bf16 v[8:11], v[160:163], v[228:231], v[32:35]
	v_mfma_f32_16x16x32_bf16 v[20:23], v[204:207], v[224:227], v[20:23]
	v_mfma_f32_16x16x32_bf16 v[8:11], v[204:207], v[240:243], v[8:11]
	v_mfma_f32_16x16x32_bf16 v[32:35], v[138:141], v[186:189], v[146:149]
	v_mfma_f32_16x16x32_bf16 v[24:27], v[236:239], v[186:189], v[24:27]
	v_mfma_f32_16x16x32_bf16 v[16:19], v[236:239], v[194:197], v[16:19]
	v_mfma_f32_16x16x32_bf16 v[56:59], v[220:223], v[190:193], v[32:35]
	v_mfma_f32_16x16x32_bf16 v[48:51], v[156:159], v[190:193], v[24:27]
	v_mfma_f32_16x16x32_bf16 v[24:27], v[138:141], v[194:197], v[178:181]
	v_mfma_f32_16x16x32_bf16 v[32:35], v[156:159], v[208:211], v[16:19]
	v_mfma_f32_16x16x32_bf16 v[16:19], v[138:141], v[212:215], v[182:185]
	v_mfma_f32_16x16x32_bf16 v[40:43], v[220:223], v[208:211], v[24:27]
	v_mfma_f32_16x16x32_bf16 v[24:27], v[220:223], v[224:227], v[16:19]
	v_mfma_f32_16x16x32_bf16 v[16:19], v[236:239], v[212:215], v[200:203]
	v_mfma_f32_16x16x32_bf16 v[4:7], v[138:141], v[228:231], v[4:7]
	v_mfma_f32_16x16x32_bf16 v[0:3], v[236:239], v[228:231], v[0:3]
	v_mfma_f32_16x16x32_bf16 v[16:19], v[156:159], v[224:227], v[16:19]
	v_mfma_f32_16x16x32_bf16 v[4:7], v[220:223], v[240:243], v[4:7]
	v_mfma_f32_16x16x32_bf16 v[0:3], v[156:159], v[240:243], v[0:3]
	s_cmpk_gt_u32 s0, 0xff
	s_barrier
	s_cbranch_scc1 .LBB0_919
	s_barrier

; #define STAGE(P,BASE,LD,br,kt) do{long _g=(long)(br)*(LD)+(long)(kt)*BK; \
;     _Pragma("unroll") for(int _i=0;_i<2;++_i){int _b=tid*16+_i*8192;int _r,_c;stage_rc(_b,_r,_c); \
;       __builtin_amdgcn_global_load_lds((const unsigned*)((BASE)+_g+(long)_r*(LD)+_c), \
;         (unsigned*)((char*)(P)+_b),16,0,0);}}while(0)
; #define STAGE(P,BASE,LD,br,kt) do{long _g=(long)(br)*(LD)+(long)(kt)*BK; \
;     _Pragma("unroll") for(int _i=0;_i<2;++_i){int _b=tid*16+_i*8192;int _r,_c;stage_rc(_b,_r,_c); \
;       __builtin_amdgcn_global_load_lds((const unsigned*)((BASE)+_g+(long)_r*(LD)+_c), \
;         (unsigned*)((char*)(P)+_b),16,0,0);}}while(0)
; #define LDA(dst,b,h) _Pragma("unroll") for(int m=0;m<4;++m) _Pragma("unroll") for(int k=0;k<2;++k) \
;     dst[m][k]=*reinterpret_cast<const bf16x8*>((char*)SA(b,h)+lds_byte(wr*64+m*16+fr,k*32+fq*8))
; #define LDB(dst,b,h) _Pragma("unroll") for(int n=0;n<2;++n) _Pragma("unroll") for(int k=0;k<2;++k) \
;     dst[n][k]=*reinterpret_cast<const bf16x8*>((char*)SB(b,h)+lds_byte(wc*32+n*16+fr,k*32+fq*8))
; #define MMA(ai,bj,At_,Bt_) do{__builtin_amdgcn_s_setprio(1); \
;     _Pragma("unroll") for(int m=0;m<4;++m) _Pragma("unroll") for(int n=0;n<2;++n) _Pragma("unroll") for(int k=0;k<2;++k) \
;       acc[ai][bj][m][n]=__builtin_amdgcn_mfma_f32_16x16x32_bf16(Bt_[n][k],At_[m][k],acc[ai][bj][m][n],0,0,0); \
;     __builtin_amdgcn_s_setprio(0);}while(0)
; #define WAIT_L(n) asm volatile("s_waitcnt lgkmcnt(" #n ")":::"memory")
; #define BAR __builtin_amdgcn_s_barrier()
; #define SCHED __builtin_amdgcn_sched_barrier(0)
; DEVINL void gemm8_mainloop(const u16* A, long lda, const u16* Bt, long ldb, int K, int brow, int bcol, f32x4 (&acc)[2][2][4][2], char* smem, int tid) {
;     ...
;   for(int t=0;t<nt-2;t+=2){
;     LDB(B0,0,0); SCHED; LDA(At,0,0); STAGE(SA(1,1),A,lda,brow+HALF,t+1);
;     WAIT_L(8); BAR; WAIT_L(0); MMA(0,0,At,B0); BAR; SCHED;
;     LDB(B1,0,1); STAGE(SB(0,0),Bt,ldb,bcol,t+2);
;     BAR; WAIT_L(0); MMA(0,1,At,B1); BAR;
;     LDA(At,0,1); STAGE(SA(0,0),A,lda,brow,t+2);
;     BAR; WAIT_L(0); MMA(1,0,At,B0); BAR; SCHED;
.LBB0_965:
	ds_read_b128 v[178:181], v163
	ds_read_b128 v[182:185], v163 offset:1024
	ds_read_b128 v[186:189], v163 offset:2048
	ds_read_b128 v[190:193], v163 offset:3072
	v_add_u32_e32 v174, 0xc000, v152
	v_lshl_add_u64 v[242:243], s[94:95], 0, v[146:147]
	v_readfirstlane_b32 s25, v174
	v_add_u32_e32 v175, 0xe000, v152
	v_add_u32_e32 v171, s0, v162
	v_add_u32_e32 v172, s1, v162
	v_add_u32_e32 v173, s27, v162
	v_lshl_add_u64 v[164:165], v[242:243], 0, s[4:5]
	s_mov_b32 m0, s25
	v_lshl_add_u64 v[244:245], s[94:95], 0, v[148:149]
	v_readfirstlane_b32 s25, v175
	ds_read_b128 v[166:169], v153
	ds_read_b128 v[194:197], v153 offset:1024
	ds_read_b128 v[198:201], v171
	ds_read_b128 v[202:205], v171 offset:1024
	ds_read_b128 v[206:209], v172
	ds_read_b128 v[210:213], v172 offset:1024
	ds_read_b128 v[214:217], v173
	ds_read_b128 v[218:221], v173 offset:1024
	global_load_lds_dwordx4 v[164:165], off
	v_lshl_add_u64 v[164:165], v[244:245], 0, s[4:5]
	s_mov_b32 m0, s25
	s_nop 0
	global_load_lds_dwordx4 v[164:165], off
	s_waitcnt lgkmcnt(8)
	s_barrier
	s_waitcnt lgkmcnt(0)
	v_mfma_f32_16x16x32_bf16 v[124:127], v[178:181], v[166:169], v[124:127]
	v_mfma_f32_16x16x32_bf16 v[120:123], v[186:189], v[166:169], v[120:123]
	v_mfma_f32_16x16x32_bf16 v[116:119], v[178:181], v[198:201], v[116:119]
	v_mfma_f32_16x16x32_bf16 v[112:115], v[186:189], v[198:201], v[112:115]
	v_mfma_f32_16x16x32_bf16 v[108:111], v[178:181], v[206:209], v[108:111]
	v_mfma_f32_16x16x32_bf16 v[104:107], v[186:189], v[206:209], v[104:107]
	v_mfma_f32_16x16x32_bf16 v[100:103], v[178:181], v[214:217], v[100:103]
	v_mfma_f32_16x16x32_bf16 v[96:99], v[186:189], v[214:217], v[96:99]
	v_mfma_f32_16x16x32_bf16 v[124:127], v[182:185], v[194:197], v[124:127]
	v_mfma_f32_16x16x32_bf16 v[120:123], v[190:193], v[194:197], v[120:123]
	v_mfma_f32_16x16x32_bf16 v[116:119], v[182:185], v[202:205], v[116:119]
	v_mfma_f32_16x16x32_bf16 v[112:115], v[190:193], v[202:205], v[112:115]
	v_mfma_f32_16x16x32_bf16 v[108:111], v[182:185], v[210:213], v[108:111]
	v_mfma_f32_16x16x32_bf16 v[104:107], v[190:193], v[210:213], v[104:107]
	v_mfma_f32_16x16x32_bf16 v[100:103], v[182:185], v[218:221], v[100:103]
	v_mfma_f32_16x16x32_bf16 v[96:99], v[190:193], v[218:221], v[96:99]
	s_barrier
	v_add_u32_e32 v164, s30, v154
	v_lshl_add_u64 v[246:247], s[94:95], 0, v[142:143]
	v_readfirstlane_b32 s25, v164
	v_add_u32_e32 v165, 0x2000, v164
	v_lshl_add_u64 v[238:239], v[246:247], 0, s[6:7]
	s_mov_b32 m0, s25
	v_lshl_add_u64 v[248:249], s[94:95], 0, v[144:145]
	v_readfirstlane_b32 s25, v165
	ds_read_b128 v[222:225], v160
	ds_read_b128 v[226:229], v160 offset:1024
	ds_read_b128 v[230:233], v160 offset:2048
	ds_read_b128 v[234:237], v160 offset:3072
	global_load_lds_dwordx4 v[238:239], off
	v_lshl_add_u64 v[238:239], v[248:249], 0, s[6:7]
	s_mov_b32 m0, s25
	s_nop 0
	global_load_lds_dwordx4 v[238:239], off
	s_barrier
	s_waitcnt lgkmcnt(0)
	v_mfma_f32_16x16x32_bf16 v[92:95], v[222:225], v[166:169], v[92:95]
	v_mfma_f32_16x16x32_bf16 v[88:91], v[230:233], v[166:169], v[88:91]
	v_mfma_f32_16x16x32_bf16 v[84:87], v[222:225], v[198:201], v[84:87]
	v_mfma_f32_16x16x32_bf16 v[80:83], v[230:233], v[198:201], v[80:83]
	v_mfma_f32_16x16x32_bf16 v[76:79], v[222:225], v[206:209], v[76:79]
	v_mfma_f32_16x16x32_bf16 v[72:75], v[230:233], v[206:209], v[72:75]
	v_mfma_f32_16x16x32_bf16 v[68:71], v[222:225], v[214:217], v[68:71]
	v_mfma_f32_16x16x32_bf16 v[64:67], v[230:233], v[214:217], v[64:67]
	v_mfma_f32_16x16x32_bf16 v[92:95], v[226:229], v[194:197], v[92:95]
	v_mfma_f32_16x16x32_bf16 v[88:91], v[234:237], v[194:197], v[88:91]
	v_mfma_f32_16x16x32_bf16 v[84:87], v[226:229], v[202:205], v[84:87]
	v_mfma_f32_16x16x32_bf16 v[80:83], v[234:237], v[202:205], v[80:83]
	v_mfma_f32_16x16x32_bf16 v[76:79], v[226:229], v[210:213], v[76:79]
	v_mfma_f32_16x16x32_bf16 v[72:75], v[234:237], v[210:213], v[72:75]
	v_mfma_f32_16x16x32_bf16 v[68:71], v[226:229], v[218:221], v[68:71]
	v_mfma_f32_16x16x32_bf16 v[64:67], v[234:237], v[218:221], v[64:67]
	v_readfirstlane_b32 s25, v152
	v_lshl_add_u64 v[166:167], v[242:243], 0, s[8:9]
	s_mov_b32 m0, s25
	s_barrier
	ds_read_b128 v[194:197], v153 offset:16384
	ds_read_b128 v[198:201], v153 offset:17408
	ds_read_b128 v[202:205], v171 offset:16384
	ds_read_b128 v[206:209], v171 offset:17408
	ds_read_b128 v[210:213], v172 offset:16384
	ds_read_b128 v[214:217], v172 offset:17408
	ds_read_b128 v[218:221], v173 offset:16384
	ds_read_b128 v[238:241], v173 offset:17408
	global_load_lds_dwordx4 v[166:167], off
	v_add_u32_e32 v166, 0x2000, v152
	v_lshl_add_u64 v[168:169], v[244:245], 0, s[8:9]
	v_readfirstlane_b32 s25, v166
	s_mov_b32 m0, s25
	s_nop 0
	global_load_lds_dwordx4 v[168:169], off
	s_barrier
	s_waitcnt lgkmcnt(0)
	v_mfma_f32_16x16x32_bf16 v[60:63], v[178:181], v[194:197], v[60:63]
	v_mfma_f32_16x16x32_bf16 v[56:59], v[186:189], v[194:197], v[56:59]
	v_mfma_f32_16x16x32_bf16 v[52:55], v[178:181], v[202:205], v[52:55]
	v_mfma_f32_16x16x32_bf16 v[48:51], v[186:189], v[202:205], v[48:51]
	v_mfma_f32_16x16x32_bf16 v[44:47], v[178:181], v[210:213], v[44:47]
	v_mfma_f32_16x16x32_bf16 v[40:43], v[186:189], v[210:213], v[40:43]
	v_mfma_f32_16x16x32_bf16 v[36:39], v[178:181], v[218:221], v[36:39]
	v_mfma_f32_16x16x32_bf16 v[32:35], v[186:189], v[218:221], v[32:35]
	v_mfma_f32_16x16x32_bf16 v[60:63], v[182:185], v[198:201], v[60:63]
	v_mfma_f32_16x16x32_bf16 v[56:59], v[190:193], v[198:201], v[56:59]
	v_mfma_f32_16x16x32_bf16 v[52:55], v[182:185], v[206:209], v[52:55]
	v_mfma_f32_16x16x32_bf16 v[48:51], v[190:193], v[206:209], v[48:51]
	v_mfma_f32_16x16x32_bf16 v[44:47], v[182:185], v[214:217], v[44:47]
	v_mfma_f32_16x16x32_bf16 v[40:43], v[190:193], v[214:217], v[40:43]
	v_mfma_f32_16x16x32_bf16 v[36:39], v[182:185], v[238:241], v[36:39]
	v_mfma_f32_16x16x32_bf16 v[32:35], v[190:193], v[238:241], v[32:35]
	s_barrier
; #define STAGE(P,BASE,LD,br,kt) do{long _g=(long)(br)*(LD)+(long)(kt)*BK; \
;     _Pragma("unroll") for(int _i=0;_i<2;++_i){int _b=tid*16+_i*8192;int _r,_c;stage_rc(_b,_r,_c); \
;       __builtin_amdgcn_global_load_lds((const unsigned*)((BASE)+_g+(long)_r*(LD)+_c), \
;         (unsigned*)((char*)(P)+_b),16,0,0);}}while(0)
; #define STAGE(P,BASE,LD,br,kt) do{long _g=(long)(br)*(LD)+(long)(kt)*BK; \
;     _Pragma("unroll") for(int _i=0;_i<2;++_i){int _b=tid*16+_i*8192;int _r,_c;stage_rc(_b,_r,_c); \
;       __builtin_amdgcn_global_load_lds((const unsigned*)((BASE)+_g+(long)_r*(LD)+_c), \
;         (unsigned*)((char*)(P)+_b),16,0,0);}}while(0)
; #define LDA(dst,b,h) _Pragma("unroll") for(int m=0;m<4;++m) _Pragma("unroll") for(int k=0;k<2;++k) \
;     dst[m][k]=*reinterpret_cast<const bf16x8*>((char*)SA(b,h)+lds_byte(wr*64+m*16+fr,k*32+fq*8))
; #define LDB(dst,b,h) _Pragma("unroll") for(int n=0;n<2;++n) _Pragma("unroll") for(int k=0;k<2;++k) \
;     dst[n][k]=*reinterpret_cast<const bf16x8*>((char*)SB(b,h)+lds_byte(wc*32+n*16+fr,k*32+fq*8))
; #define MMA(ai,bj,At_,Bt_) do{__builtin_amdgcn_s_setprio(1); \
;     _Pragma("unroll") for(int m=0;m<4;++m) _Pragma("unroll") for(int n=0;n<2;++n) _Pragma("unroll") for(int k=0;k<2;++k) \
;       acc[ai][bj][m][n]=__builtin_amdgcn_mfma_f32_16x16x32_bf16(Bt_[n][k],At_[m][k],acc[ai][bj][m][n],0,0,0); \
;     __builtin_amdgcn_s_setprio(0);}while(0)
; #define WAIT_V(n) asm volatile("s_waitcnt vmcnt(" #n ")":::"memory")
; #define WAIT_L(n) asm volatile("s_waitcnt lgkmcnt(" #n ")":::"memory")
; #define BAR __builtin_amdgcn_s_barrier()
; #define SCHED __builtin_amdgcn_sched_barrier(0)
; DEVINL void gemm8_mainloop(const u16* A, long lda, const u16* Bt, long ldb, int K, int brow, int bcol, f32x4 (&acc)[2][2][4][2], char* smem, int tid) {
;     ...
;     STAGE(SB(0,1),Bt,ldb,bcol+HALF,t+2);
;     WAIT_V(6); BAR; MMA(1,1,At,B1); BAR;
;     LDB(B0,1,0); SCHED; LDA(At,1,0); STAGE(SA(0,1),A,lda,brow+HALF,t+2);
;     WAIT_L(8); BAR; WAIT_L(0); MMA(0,0,At,B0); BAR; SCHED;
;     LDB(B1,1,1); STAGE(SB(1,0),Bt,ldb,bcol,t+3);
;     BAR; WAIT_L(0); MMA(0,1,At,B1); BAR;
;     LDA(At,1,1); STAGE(SA(1,0),A,lda,brow,t+3);
	v_add_u32_e32 v167, s31, v154
	v_lshl_add_u64 v[168:169], v[246:247], 0, s[10:11]
	v_readfirstlane_b32 s25, v167
	s_mov_b32 m0, s25
	v_lshl_add_u64 v[178:179], v[248:249], 0, s[10:11]
	global_load_lds_dwordx4 v[168:169], off
	v_add_u32_e32 v168, 0x2000, v167
	s_nop 0
	v_readfirstlane_b32 s25, v168
	s_mov_b32 m0, s25
	s_nop 0
	global_load_lds_dwordx4 v[178:179], off
	s_waitcnt vmcnt(6)
	s_barrier
	v_mfma_f32_16x16x32_bf16 v[28:31], v[222:225], v[194:197], v[28:31]
	v_mfma_f32_16x16x32_bf16 v[24:27], v[230:233], v[194:197], v[24:27]
	v_mfma_f32_16x16x32_bf16 v[20:23], v[222:225], v[202:205], v[20:23]
	v_mfma_f32_16x16x32_bf16 v[16:19], v[230:233], v[202:205], v[16:19]
	v_mfma_f32_16x16x32_bf16 v[12:15], v[222:225], v[210:213], v[12:15]
	v_mfma_f32_16x16x32_bf16 v[8:11], v[230:233], v[210:213], v[8:11]
	v_mfma_f32_16x16x32_bf16 v[4:7], v[222:225], v[218:221], v[4:7]
	v_mfma_f32_16x16x32_bf16 v[0:3], v[230:233], v[218:221], v[0:3]
	v_mfma_f32_16x16x32_bf16 v[28:31], v[226:229], v[198:201], v[28:31]
	v_mfma_f32_16x16x32_bf16 v[24:27], v[234:237], v[198:201], v[24:27]
	v_mfma_f32_16x16x32_bf16 v[20:23], v[226:229], v[206:209], v[20:23]
	v_mfma_f32_16x16x32_bf16 v[16:19], v[234:237], v[206:209], v[16:19]
	v_mfma_f32_16x16x32_bf16 v[12:15], v[226:229], v[214:217], v[12:15]
	v_mfma_f32_16x16x32_bf16 v[8:11], v[234:237], v[214:217], v[8:11]
	v_mfma_f32_16x16x32_bf16 v[4:7], v[226:229], v[238:241], v[4:7]
	v_mfma_f32_16x16x32_bf16 v[0:3], v[234:237], v[238:241], v[0:3]
	s_barrier
	ds_read_b128 v[178:181], v157
	ds_read_b128 v[182:185], v157 offset:1024
	ds_read_b128 v[186:189], v157 offset:2048
	ds_read_b128 v[190:193], v157 offset:3072
	v_add_u32_e32 v169, 0x4000, v152
	v_add_u32_e32 v170, 0x6000, v152
	v_readfirstlane_b32 s25, v169
	v_lshl_add_u64 v[226:227], v[242:243], 0, s[12:13]
	s_mov_b32 m0, s25
	v_readfirstlane_b32 s25, v170
	ds_read_b128 v[194:197], v153 offset:32768
	ds_read_b128 v[198:201], v153 offset:33792
	ds_read_b128 v[202:205], v171 offset:32768
	ds_read_b128 v[206:209], v171 offset:33792
	ds_read_b128 v[210:213], v172 offset:32768
	ds_read_b128 v[214:217], v172 offset:33792
	ds_read_b128 v[218:221], v173 offset:32768
	ds_read_b128 v[222:225], v173 offset:33792
	global_load_lds_dwordx4 v[226:227], off
	v_lshl_add_u64 v[226:227], v[244:245], 0, s[12:13]
	s_mov_b32 m0, s25
	s_nop 0
	global_load_lds_dwordx4 v[226:227], off
	s_waitcnt lgkmcnt(8)
	s_barrier
	s_waitcnt lgkmcnt(0)
	v_mfma_f32_16x16x32_bf16 v[124:127], v[178:181], v[194:197], v[124:127]
	v_mfma_f32_16x16x32_bf16 v[120:123], v[186:189], v[194:197], v[120:123]
	v_mfma_f32_16x16x32_bf16 v[116:119], v[178:181], v[202:205], v[116:119]
	v_mfma_f32_16x16x32_bf16 v[112:115], v[186:189], v[202:205], v[112:115]
	v_mfma_f32_16x16x32_bf16 v[108:111], v[178:181], v[210:213], v[108:111]
	v_mfma_f32_16x16x32_bf16 v[104:107], v[186:189], v[210:213], v[104:107]
	v_mfma_f32_16x16x32_bf16 v[100:103], v[178:181], v[218:221], v[100:103]
	v_mfma_f32_16x16x32_bf16 v[96:99], v[186:189], v[218:221], v[96:99]
	v_mfma_f32_16x16x32_bf16 v[124:127], v[182:185], v[198:201], v[124:127]
	v_mfma_f32_16x16x32_bf16 v[120:123], v[190:193], v[198:201], v[120:123]
	v_mfma_f32_16x16x32_bf16 v[116:119], v[182:185], v[206:209], v[116:119]
	v_mfma_f32_16x16x32_bf16 v[112:115], v[190:193], v[206:209], v[112:115]
	v_mfma_f32_16x16x32_bf16 v[108:111], v[182:185], v[214:217], v[108:111]
	v_mfma_f32_16x16x32_bf16 v[104:107], v[190:193], v[214:217], v[104:107]
	v_mfma_f32_16x16x32_bf16 v[100:103], v[182:185], v[222:225], v[100:103]
	v_mfma_f32_16x16x32_bf16 v[96:99], v[190:193], v[222:225], v[96:99]
	s_barrier
	v_readfirstlane_b32 s25, v156
	v_add_u32_e32 v177, 0x2000, v156
	v_lshl_add_u64 v[250:251], v[246:247], 0, s[14:15]
	s_mov_b32 m0, s25
	v_readfirstlane_b32 s25, v177
	ds_read_b128 v[226:229], v155
	ds_read_b128 v[230:233], v155 offset:1024
	ds_read_b128 v[234:237], v155 offset:2048
	ds_read_b128 v[238:241], v155 offset:3072
	global_load_lds_dwordx4 v[250:251], off
	v_lshl_add_u64 v[250:251], v[248:249], 0, s[14:15]
	s_mov_b32 m0, s25
	s_nop 0
	global_load_lds_dwordx4 v[250:251], off
	s_barrier
	s_waitcnt lgkmcnt(0)
	v_mfma_f32_16x16x32_bf16 v[92:95], v[226:229], v[194:197], v[92:95]
	v_mfma_f32_16x16x32_bf16 v[88:91], v[234:237], v[194:197], v[88:91]
	v_mfma_f32_16x16x32_bf16 v[84:87], v[226:229], v[202:205], v[84:87]
	v_mfma_f32_16x16x32_bf16 v[80:83], v[234:237], v[202:205], v[80:83]
	v_mfma_f32_16x16x32_bf16 v[76:79], v[226:229], v[210:213], v[76:79]
	v_mfma_f32_16x16x32_bf16 v[72:75], v[234:237], v[210:213], v[72:75]
	v_mfma_f32_16x16x32_bf16 v[68:71], v[226:229], v[218:221], v[68:71]
	v_mfma_f32_16x16x32_bf16 v[64:67], v[234:237], v[218:221], v[64:67]
	v_mfma_f32_16x16x32_bf16 v[92:95], v[230:233], v[198:201], v[92:95]
	v_mfma_f32_16x16x32_bf16 v[88:91], v[238:241], v[198:201], v[88:91]
	v_mfma_f32_16x16x32_bf16 v[84:87], v[230:233], v[206:209], v[84:87]
	v_mfma_f32_16x16x32_bf16 v[80:83], v[238:241], v[206:209], v[80:83]
	v_mfma_f32_16x16x32_bf16 v[76:79], v[230:233], v[214:217], v[76:79]
	v_mfma_f32_16x16x32_bf16 v[72:75], v[238:241], v[214:217], v[72:75]
	v_mfma_f32_16x16x32_bf16 v[68:71], v[230:233], v[222:225], v[68:71]
	v_mfma_f32_16x16x32_bf16 v[64:67], v[238:241], v[222:225], v[64:67]
	v_readfirstlane_b32 s25, v158
	v_lshl_add_u64 v[242:243], v[242:243], 0, s[16:17]
	s_mov_b32 m0, s25
	v_readfirstlane_b32 s25, v159
	s_barrier
	ds_read_b128 v[194:197], v153 offset:49152
	ds_read_b128 v[198:201], v153 offset:50176
	ds_read_b128 v[202:205], v171 offset:49152
	ds_read_b128 v[206:209], v171 offset:50176
	ds_read_b128 v[210:213], v172 offset:49152
	ds_read_b128 v[214:217], v172 offset:50176
	ds_read_b128 v[218:221], v173 offset:49152
	ds_read_b128 v[222:225], v173 offset:50176
	global_load_lds_dwordx4 v[242:243], off
	v_lshl_add_u64 v[242:243], v[244:245], 0, s[16:17]
	s_mov_b32 m0, s25
	s_nop 0
	global_load_lds_dwordx4 v[242:243], off
	s_barrier
; #define STAGE(P,BASE,LD,br,kt) do{long _g=(long)(br)*(LD)+(long)(kt)*BK; \
;     _Pragma("unroll") for(int _i=0;_i<2;++_i){int _b=tid*16+_i*8192;int _r,_c;stage_rc(_b,_r,_c); \
;       __builtin_amdgcn_global_load_lds((const unsigned*)((BASE)+_g+(long)_r*(LD)+_c), \
;         (unsigned*)((char*)(P)+_b),16,0,0);}}while(0)
; #define STAGE(P,BASE,LD,br,kt) do{long _g=(long)(br)*(LD)+(long)(kt)*BK; \
;     _Pragma("unroll") for(int _i=0;_i<2;++_i){int _b=tid*16+_i*8192;int _r,_c;stage_rc(_b,_r,_c); \
;       __builtin_amdgcn_global_load_lds((const unsigned*)((BASE)+_g+(long)_r*(LD)+_c), \
;         (unsigned*)((char*)(P)+_b),16,0,0);}}while(0)
; #define LDA(dst,b,h) _Pragma("unroll") for(int m=0;m<4;++m) _Pragma("unroll") for(int k=0;k<2;++k) \
;     dst[m][k]=*reinterpret_cast<const bf16x8*>((char*)SA(b,h)+lds_byte(wr*64+m*16+fr,k*32+fq*8))
; #define LDB(dst,b,h) _Pragma("unroll") for(int n=0;n<2;++n) _Pragma("unroll") for(int k=0;k<2;++k) \
;     dst[n][k]=*reinterpret_cast<const bf16x8*>((char*)SB(b,h)+lds_byte(wc*32+n*16+fr,k*32+fq*8))
; #define MMA(ai,bj,At_,Bt_) do{__builtin_amdgcn_s_setprio(1); \
;     _Pragma("unroll") for(int m=0;m<4;++m) _Pragma("unroll") for(int n=0;n<2;++n) _Pragma("unroll") for(int k=0;k<2;++k) \
;       acc[ai][bj][m][n]=__builtin_amdgcn_mfma_f32_16x16x32_bf16(Bt_[n][k],At_[m][k],acc[ai][bj][m][n],0,0,0); \
;     __builtin_amdgcn_s_setprio(0);}while(0)
; #define WAIT_V(n) asm volatile("s_waitcnt vmcnt(" #n ")":::"memory")
; #define WAIT_L(n) asm volatile("s_waitcnt lgkmcnt(" #n ")":::"memory")
; #define BAR __builtin_amdgcn_s_barrier()
; #define SCHED __builtin_amdgcn_sched_barrier(0)
; DEVINL void gemm8_mainloop(const u16* A, long lda, const u16* Bt, long ldb, int K, int brow, int bcol, f32x4 (&acc)[2][2][4][2], char* smem, int tid) {
;     ...
;     BAR; WAIT_L(0); MMA(1,0,At,B0); BAR; SCHED;
;     STAGE(SB(1,1),Bt,ldb,bcol+HALF,t+3);
;     WAIT_V(6); BAR; MMA(1,1,At,B1); BAR;
;   }
;   { LDB(B0,0,0); LDA(At,0,0); STAGE(SA(1,1),A,lda,brow+HALF,nt-1);
;     BAR; WAIT_L(0); MMA(0,0,At,B0); BAR;
;     LDB(B1,0,1); BAR; WAIT_L(0); MMA(0,1,At,B1); BAR;
	s_waitcnt lgkmcnt(0)
	v_mfma_f32_16x16x32_bf16 v[60:63], v[178:181], v[194:197], v[60:63]
	v_mfma_f32_16x16x32_bf16 v[56:59], v[186:189], v[194:197], v[56:59]
	v_mfma_f32_16x16x32_bf16 v[52:55], v[178:181], v[202:205], v[52:55]
	v_mfma_f32_16x16x32_bf16 v[48:51], v[186:189], v[202:205], v[48:51]
	v_mfma_f32_16x16x32_bf16 v[44:47], v[178:181], v[210:213], v[44:47]
	v_mfma_f32_16x16x32_bf16 v[40:43], v[186:189], v[210:213], v[40:43]
	v_mfma_f32_16x16x32_bf16 v[36:39], v[178:181], v[218:221], v[36:39]
	v_mfma_f32_16x16x32_bf16 v[32:35], v[186:189], v[218:221], v[32:35]
	v_mfma_f32_16x16x32_bf16 v[60:63], v[182:185], v[198:201], v[60:63]
	v_mfma_f32_16x16x32_bf16 v[56:59], v[190:193], v[198:201], v[56:59]
	v_mfma_f32_16x16x32_bf16 v[52:55], v[182:185], v[206:209], v[52:55]
	v_mfma_f32_16x16x32_bf16 v[48:51], v[190:193], v[206:209], v[48:51]
	v_mfma_f32_16x16x32_bf16 v[44:47], v[182:185], v[214:217], v[44:47]
	v_mfma_f32_16x16x32_bf16 v[40:43], v[190:193], v[214:217], v[40:43]
	v_mfma_f32_16x16x32_bf16 v[36:39], v[182:185], v[222:225], v[36:39]
	v_mfma_f32_16x16x32_bf16 v[32:35], v[190:193], v[222:225], v[32:35]
	s_barrier
	v_readfirstlane_b32 s25, v161
	v_add_u32_e32 v177, 0x2000, v161
	v_lshl_add_u64 v[178:179], v[246:247], 0, s[18:19]
	s_mov_b32 m0, s25
	v_readfirstlane_b32 s25, v177
	global_load_lds_dwordx4 v[178:179], off
	v_lshl_add_u64 v[178:179], v[248:249], 0, s[18:19]
	s_mov_b32 m0, s25
	s_nop 0
	global_load_lds_dwordx4 v[178:179], off
	s_waitcnt vmcnt(6)
	s_barrier
	v_mfma_f32_16x16x32_bf16 v[28:31], v[226:229], v[194:197], v[28:31]
	v_mfma_f32_16x16x32_bf16 v[24:27], v[234:237], v[194:197], v[24:27]
	v_mfma_f32_16x16x32_bf16 v[20:23], v[226:229], v[202:205], v[20:23]
	v_mfma_f32_16x16x32_bf16 v[16:19], v[234:237], v[202:205], v[16:19]
	v_mfma_f32_16x16x32_bf16 v[12:15], v[226:229], v[210:213], v[12:15]
	v_mfma_f32_16x16x32_bf16 v[8:11], v[234:237], v[210:213], v[8:11]
	v_mfma_f32_16x16x32_bf16 v[4:7], v[226:229], v[218:221], v[4:7]
	v_mfma_f32_16x16x32_bf16 v[0:3], v[234:237], v[218:221], v[0:3]
	v_mfma_f32_16x16x32_bf16 v[28:31], v[230:233], v[198:201], v[28:31]
	v_mfma_f32_16x16x32_bf16 v[24:27], v[238:241], v[198:201], v[24:27]
	v_mfma_f32_16x16x32_bf16 v[20:23], v[230:233], v[206:209], v[20:23]
	v_mfma_f32_16x16x32_bf16 v[16:19], v[238:241], v[206:209], v[16:19]
	v_mfma_f32_16x16x32_bf16 v[12:15], v[230:233], v[214:217], v[12:15]
	v_mfma_f32_16x16x32_bf16 v[8:11], v[238:241], v[214:217], v[8:11]
	v_mfma_f32_16x16x32_bf16 v[4:7], v[230:233], v[222:225], v[4:7]
	v_mfma_f32_16x16x32_bf16 v[0:3], v[238:241], v[222:225], v[0:3]
	s_add_i32 s24, s24, 2
	v_lshl_add_u64 v[142:143], v[142:143], 0, s[20:21]
	v_lshl_add_u64 v[144:145], v[144:145], 0, s[20:21]
	v_lshl_add_u64 v[146:147], v[146:147], 0, s[20:21]
	s_cmpk_lt_u32 s24, 0x7c
	v_lshl_add_u64 v[148:149], v[148:149], 0, s[20:21]
	s_barrier
	s_cbranch_scc1 .LBB0_965
	s_or_b32 s0, s26, 0x80
	s_ashr_i32 s1, s0, 31
	s_lshl_b64 s[0:1], s[0:1], 14
	s_add_u32 s0, s62, s0
	s_addc_u32 s1, s63, s1
	s_add_u32 s0, s0, 0x3f80
	s_addc_u32 s1, s1, 0
	v_lshl_add_u64 v[158:159], v[134:135], 1, s[0:1]
	v_readfirstlane_b32 s24, v174
	v_lshl_add_u64 v[138:139], v[138:139], 1, v[158:159]
	s_mov_b32 m0, s24
	ds_read_b128 v[142:145], v163
	ds_read_b128 v[146:149], v163 offset:1024
	ds_read_b128 v[178:181], v163 offset:2048
	ds_read_b128 v[182:185], v163 offset:3072
	ds_read_b128 v[186:189], v153
	ds_read_b128 v[190:193], v153 offset:1024
	ds_read_b128 v[194:197], v171
	ds_read_b128 v[198:201], v171 offset:1024
	ds_read_b128 v[202:205], v172
	ds_read_b128 v[206:209], v172 offset:1024
	ds_read_b128 v[210:213], v173
	ds_read_b128 v[214:217], v173 offset:1024
	global_load_lds_dwordx4 v[138:139], off
	v_lshl_add_u64 v[138:139], v[136:137], 1, s[0:1]
	v_readfirstlane_b32 s0, v175
	v_lshl_add_u64 v[138:139], v[140:141], 1, v[138:139]
	s_mov_b32 m0, s0
	s_nop 0
	global_load_lds_dwordx4 v[138:139], off
	s_barrier
	s_waitcnt lgkmcnt(0)
	v_mfma_f32_16x16x32_bf16 v[124:127], v[142:145], v[186:189], v[124:127]
	v_mfma_f32_16x16x32_bf16 v[120:123], v[178:181], v[186:189], v[120:123]
	v_mfma_f32_16x16x32_bf16 v[116:119], v[142:145], v[194:197], v[116:119]
	v_mfma_f32_16x16x32_bf16 v[112:115], v[178:181], v[194:197], v[112:115]
	v_mfma_f32_16x16x32_bf16 v[100:103], v[142:145], v[210:213], v[100:103]
	v_mfma_f32_16x16x32_bf16 v[96:99], v[178:181], v[210:213], v[96:99]
	v_mfma_f32_16x16x32_bf16 v[124:127], v[146:149], v[190:193], v[124:127]
	v_mfma_f32_16x16x32_bf16 v[120:123], v[182:185], v[190:193], v[120:123]
	v_mfma_f32_16x16x32_bf16 v[116:119], v[146:149], v[198:201], v[116:119]
	v_mfma_f32_16x16x32_bf16 v[112:115], v[182:185], v[198:201], v[112:115]
	v_mfma_f32_16x16x32_bf16 v[108:111], v[142:145], v[202:205], v[108:111]
	v_mfma_f32_16x16x32_bf16 v[104:107], v[178:181], v[202:205], v[104:107]
	v_mfma_f32_16x16x32_bf16 v[100:103], v[146:149], v[214:217], v[100:103]
	v_mfma_f32_16x16x32_bf16 v[96:99], v[182:185], v[214:217], v[96:99]
	v_mfma_f32_16x16x32_bf16 v[138:141], v[146:149], v[206:209], v[108:111]
	v_mfma_f32_16x16x32_bf16 v[218:221], v[182:185], v[206:209], v[104:107]
	s_barrier
	s_nop 1
	s_nop 0
	ds_read_b128 v[104:107], v160
	ds_read_b128 v[108:111], v160 offset:1024
	ds_read_b128 v[222:225], v160 offset:2048
	ds_read_b128 v[158:161], v160 offset:3072
	s_barrier
; #define LDA(dst,b,h) _Pragma("unroll") for(int m=0;m<4;++m) _Pragma("unroll") for(int k=0;k<2;++k) \
;     dst[m][k]=*reinterpret_cast<const bf16x8*>((char*)SA(b,h)+lds_byte(wr*64+m*16+fr,k*32+fq*8))
; #define LDB(dst,b,h) _Pragma("unroll") for(int n=0;n<2;++n) _Pragma("unroll") for(int k=0;k<2;++k) \
;     dst[n][k]=*reinterpret_cast<const bf16x8*>((char*)SB(b,h)+lds_byte(wc*32+n*16+fr,k*32+fq*8))
; #define MMA(ai,bj,At_,Bt_) do{__builtin_amdgcn_s_setprio(1); \
;     _Pragma("unroll") for(int m=0;m<4;++m) _Pragma("unroll") for(int n=0;n<2;++n) _Pragma("unroll") for(int k=0;k<2;++k) \
;       acc[ai][bj][m][n]=__builtin_amdgcn_mfma_f32_16x16x32_bf16(Bt_[n][k],At_[m][k],acc[ai][bj][m][n],0,0,0); \
;     __builtin_amdgcn_s_setprio(0);}while(0)
; #define WAIT_V(n) asm volatile("s_waitcnt vmcnt(" #n ")":::"memory")
; #define WAIT_L(n) asm volatile("s_waitcnt lgkmcnt(" #n ")":::"memory")
; #define BAR __builtin_amdgcn_s_barrier()
; DEVINL void gemm8_mainloop(const u16* A, long lda, const u16* Bt, long ldb, int K, int brow, int bcol, f32x4 (&acc)[2][2][4][2], char* smem, int tid) {
;     ...
;     LDB(B1,0,1); BAR; WAIT_L(0); MMA(0,1,At,B1); BAR;
;     LDA(At,0,1); WAIT_V(4); BAR; WAIT_L(0); MMA(1,0,At,B0); MMA(1,1,At,B1); BAR; }
;   { LDB(B0,1,0); LDA(At,1,0); WAIT_V(2); BAR; WAIT_L(0); MMA(0,0,At,B0); BAR;
	s_waitcnt lgkmcnt(0)
	v_mfma_f32_16x16x32_bf16 v[84:87], v[104:107], v[194:197], v[84:87]
	v_mfma_f32_16x16x32_bf16 v[80:83], v[222:225], v[194:197], v[80:83]
	v_mfma_f32_16x16x32_bf16 v[68:71], v[104:107], v[210:213], v[68:71]
	v_mfma_f32_16x16x32_bf16 v[92:95], v[104:107], v[186:189], v[92:95]
	v_mfma_f32_16x16x32_bf16 v[88:91], v[222:225], v[186:189], v[88:91]
	v_mfma_f32_16x16x32_bf16 v[84:87], v[108:111], v[198:201], v[84:87]
	v_mfma_f32_16x16x32_bf16 v[80:83], v[158:161], v[198:201], v[80:83]
	v_mfma_f32_16x16x32_bf16 v[76:79], v[104:107], v[202:205], v[76:79]
	v_mfma_f32_16x16x32_bf16 v[72:75], v[222:225], v[202:205], v[72:75]
	v_mfma_f32_16x16x32_bf16 v[68:71], v[108:111], v[214:217], v[68:71]
	v_mfma_f32_16x16x32_bf16 v[64:67], v[222:225], v[210:213], v[64:67]
	v_mfma_f32_16x16x32_bf16 v[226:229], v[108:111], v[190:193], v[92:95]
	v_mfma_f32_16x16x32_bf16 v[186:189], v[158:161], v[190:193], v[88:91]
	v_mfma_f32_16x16x32_bf16 v[190:193], v[108:111], v[206:209], v[76:79]
	v_mfma_f32_16x16x32_bf16 v[194:197], v[158:161], v[206:209], v[72:75]
	v_mfma_f32_16x16x32_bf16 v[198:201], v[158:161], v[214:217], v[64:67]
	s_barrier
	s_nop 0
	s_nop 0
	ds_read_b128 v[64:67], v153 offset:16384
	ds_read_b128 v[72:75], v153 offset:17408
	ds_read_b128 v[76:79], v171 offset:16384
	ds_read_b128 v[88:91], v171 offset:17408
	ds_read_b128 v[92:95], v172 offset:16384
	ds_read_b128 v[202:205], v172 offset:17408
	ds_read_b128 v[206:209], v173 offset:16384
	ds_read_b128 v[210:213], v173 offset:17408
	s_waitcnt vmcnt(4)
	s_barrier
	s_waitcnt lgkmcnt(0)
	v_mfma_f32_16x16x32_bf16 v[60:63], v[142:145], v[64:67], v[60:63]
	v_mfma_f32_16x16x32_bf16 v[56:59], v[178:181], v[64:67], v[56:59]
	v_mfma_f32_16x16x32_bf16 v[52:55], v[142:145], v[76:79], v[52:55]
	v_mfma_f32_16x16x32_bf16 v[48:51], v[178:181], v[76:79], v[48:51]
	v_mfma_f32_16x16x32_bf16 v[36:39], v[142:145], v[206:209], v[36:39]
	v_mfma_f32_16x16x32_bf16 v[32:35], v[178:181], v[206:209], v[32:35]
	v_mfma_f32_16x16x32_bf16 v[60:63], v[146:149], v[72:75], v[60:63]
	v_mfma_f32_16x16x32_bf16 v[56:59], v[182:185], v[72:75], v[56:59]
	v_mfma_f32_16x16x32_bf16 v[52:55], v[146:149], v[88:91], v[52:55]
	v_mfma_f32_16x16x32_bf16 v[48:51], v[182:185], v[88:91], v[48:51]
	v_mfma_f32_16x16x32_bf16 v[44:47], v[142:145], v[92:95], v[44:47]
	v_mfma_f32_16x16x32_bf16 v[40:43], v[178:181], v[92:95], v[40:43]
	v_mfma_f32_16x16x32_bf16 v[36:39], v[146:149], v[210:213], v[36:39]
	v_mfma_f32_16x16x32_bf16 v[32:35], v[182:185], v[210:213], v[32:35]
	v_mfma_f32_16x16x32_bf16 v[214:217], v[146:149], v[202:205], v[44:47]
	v_mfma_f32_16x16x32_bf16 v[230:233], v[182:185], v[202:205], v[40:43]
	v_mfma_f32_16x16x32_bf16 v[20:23], v[104:107], v[76:79], v[20:23]
	v_mfma_f32_16x16x32_bf16 v[16:19], v[222:225], v[76:79], v[16:19]
	v_mfma_f32_16x16x32_bf16 v[4:7], v[104:107], v[206:209], v[4:7]
	v_mfma_f32_16x16x32_bf16 v[0:3], v[222:225], v[206:209], v[0:3]
	v_mfma_f32_16x16x32_bf16 v[28:31], v[104:107], v[64:67], v[28:31]
	v_mfma_f32_16x16x32_bf16 v[24:27], v[222:225], v[64:67], v[24:27]
	v_mfma_f32_16x16x32_bf16 v[20:23], v[108:111], v[88:91], v[20:23]
	v_mfma_f32_16x16x32_bf16 v[16:19], v[158:161], v[88:91], v[16:19]
	v_mfma_f32_16x16x32_bf16 v[12:15], v[104:107], v[92:95], v[12:15]
	v_mfma_f32_16x16x32_bf16 v[8:11], v[222:225], v[92:95], v[8:11]
	v_mfma_f32_16x16x32_bf16 v[4:7], v[108:111], v[210:213], v[4:7]
	v_mfma_f32_16x16x32_bf16 v[0:3], v[158:161], v[210:213], v[0:3]
	v_mfma_f32_16x16x32_bf16 v[142:145], v[108:111], v[72:75], v[28:31]
	v_mfma_f32_16x16x32_bf16 v[146:149], v[158:161], v[72:75], v[24:27]
	v_mfma_f32_16x16x32_bf16 v[178:181], v[108:111], v[202:205], v[12:15]
	v_mfma_f32_16x16x32_bf16 v[182:185], v[158:161], v[202:205], v[8:11]
	s_barrier
	s_nop 0
	s_nop 0
	ds_read_b128 v[8:11], v157
	ds_read_b128 v[12:15], v157 offset:1024
	ds_read_b128 v[158:161], v157 offset:2048
	ds_read_b128 v[202:205], v157 offset:3072
	ds_read_b128 v[24:27], v153 offset:32768
	ds_read_b128 v[28:31], v153 offset:33792
	ds_read_b128 v[40:43], v171 offset:32768
	ds_read_b128 v[44:47], v171 offset:33792
	ds_read_b128 v[64:67], v172 offset:32768
	ds_read_b128 v[206:209], v172 offset:33792
	ds_read_b128 v[210:213], v173 offset:32768
	ds_read_b128 v[222:225], v173 offset:33792
	s_waitcnt vmcnt(2)
	s_barrier
; #define LDA(dst,b,h) _Pragma("unroll") for(int m=0;m<4;++m) _Pragma("unroll") for(int k=0;k<2;++k) \
;     dst[m][k]=*reinterpret_cast<const bf16x8*>((char*)SA(b,h)+lds_byte(wr*64+m*16+fr,k*32+fq*8))
; #define LDB(dst,b,h) _Pragma("unroll") for(int n=0;n<2;++n) _Pragma("unroll") for(int k=0;k<2;++k) \
;     dst[n][k]=*reinterpret_cast<const bf16x8*>((char*)SB(b,h)+lds_byte(wc*32+n*16+fr,k*32+fq*8))
; #define MMA(ai,bj,At_,Bt_) do{__builtin_amdgcn_s_setprio(1); \
;     _Pragma("unroll") for(int m=0;m<4;++m) _Pragma("unroll") for(int n=0;n<2;++n) _Pragma("unroll") for(int k=0;k<2;++k) \
;       acc[ai][bj][m][n]=__builtin_amdgcn_mfma_f32_16x16x32_bf16(Bt_[n][k],At_[m][k],acc[ai][bj][m][n],0,0,0); \
;     __builtin_amdgcn_s_setprio(0);}while(0)
; #define WAIT_V(n) asm volatile("s_waitcnt vmcnt(" #n ")":::"memory")
; #define WAIT_L(n) asm volatile("s_waitcnt lgkmcnt(" #n ")":::"memory")
; #define BAR __builtin_amdgcn_s_barrier()
; DEVINL void gemm8_mainloop(const u16* A, long lda, const u16* Bt, long ldb, int K, int brow, int bcol, f32x4 (&acc)[2][2][4][2], char* smem, int tid) {
;     ...
;   { LDB(B0,1,0); LDA(At,1,0); WAIT_V(2); BAR; WAIT_L(0); MMA(0,0,At,B0); BAR;
;     LDB(B1,1,1); WAIT_V(0); BAR; WAIT_L(0); MMA(0,1,At,B1); BAR;
;     LDA(At,1,1); BAR; WAIT_L(0); MMA(1,0,At,B0); MMA(1,1,At,B1); BAR; }
;   if(wr==0)BAR;
	s_waitcnt lgkmcnt(0)
	v_mfma_f32_16x16x32_bf16 v[72:75], v[8:11], v[24:27], v[124:127]
	v_mfma_f32_16x16x32_bf16 v[124:127], v[12:15], v[28:31], v[72:75]
	v_mfma_f32_16x16x32_bf16 v[72:75], v[158:161], v[24:27], v[120:123]
	v_mfma_f32_16x16x32_bf16 v[120:123], v[202:205], v[28:31], v[72:75]
	v_mfma_f32_16x16x32_bf16 v[72:75], v[8:11], v[40:43], v[116:119]
	v_mfma_f32_16x16x32_bf16 v[108:111], v[12:15], v[44:47], v[72:75]
	v_mfma_f32_16x16x32_bf16 v[72:75], v[158:161], v[40:43], v[112:115]
	v_mfma_f32_16x16x32_bf16 v[104:107], v[202:205], v[44:47], v[72:75]
	v_mfma_f32_16x16x32_bf16 v[72:75], v[8:11], v[64:67], v[138:141]
	v_mfma_f32_16x16x32_bf16 v[92:95], v[12:15], v[206:209], v[72:75]
	v_mfma_f32_16x16x32_bf16 v[72:75], v[158:161], v[64:67], v[218:221]
	v_mfma_f32_16x16x32_bf16 v[88:91], v[202:205], v[206:209], v[72:75]
	v_mfma_f32_16x16x32_bf16 v[72:75], v[8:11], v[210:213], v[100:103]
	v_mfma_f32_16x16x32_bf16 v[76:79], v[12:15], v[222:225], v[72:75]
	v_mfma_f32_16x16x32_bf16 v[72:75], v[158:161], v[210:213], v[96:99]
	v_mfma_f32_16x16x32_bf16 v[72:75], v[202:205], v[222:225], v[72:75]
	s_barrier
	ds_read_b128 v[138:141], v155
	ds_read_b128 v[218:221], v155 offset:1024
	ds_read_b128 v[234:237], v155 offset:2048
	ds_read_b128 v[154:157], v155 offset:3072
	s_waitcnt vmcnt(0)
	s_barrier
	s_waitcnt lgkmcnt(0)
	v_mfma_f32_16x16x32_bf16 v[96:99], v[138:141], v[24:27], v[226:229]
	v_mfma_f32_16x16x32_bf16 v[24:27], v[234:237], v[24:27], v[186:189]
	v_mfma_f32_16x16x32_bf16 v[116:119], v[154:157], v[28:31], v[24:27]
	v_mfma_f32_16x16x32_bf16 v[24:27], v[138:141], v[40:43], v[84:87]
	v_mfma_f32_16x16x32_bf16 v[112:115], v[218:221], v[28:31], v[96:99]
	v_mfma_f32_16x16x32_bf16 v[96:99], v[218:221], v[44:47], v[24:27]
	v_mfma_f32_16x16x32_bf16 v[24:27], v[234:237], v[40:43], v[80:83]
	v_mfma_f32_16x16x32_bf16 v[100:103], v[154:157], v[44:47], v[24:27]
	v_mfma_f32_16x16x32_bf16 v[24:27], v[138:141], v[64:67], v[190:193]
	v_mfma_f32_16x16x32_bf16 v[80:83], v[218:221], v[206:209], v[24:27]
	v_mfma_f32_16x16x32_bf16 v[24:27], v[234:237], v[64:67], v[194:197]
	v_mfma_f32_16x16x32_bf16 v[84:87], v[154:157], v[206:209], v[24:27]
	v_mfma_f32_16x16x32_bf16 v[24:27], v[138:141], v[210:213], v[68:71]
	v_mfma_f32_16x16x32_bf16 v[64:67], v[218:221], v[222:225], v[24:27]
	v_mfma_f32_16x16x32_bf16 v[24:27], v[234:237], v[210:213], v[198:201]
	v_mfma_f32_16x16x32_bf16 v[68:71], v[154:157], v[222:225], v[24:27]
	s_barrier
	ds_read_b128 v[186:189], v153 offset:49152
	ds_read_b128 v[190:193], v153 offset:50176
	ds_read_b128 v[194:197], v171 offset:49152
	ds_read_b128 v[198:201], v171 offset:50176
	ds_read_b128 v[206:209], v172 offset:49152
	ds_read_b128 v[210:213], v172 offset:50176
	ds_read_b128 v[222:225], v173 offset:49152
	ds_read_b128 v[172:175], v173 offset:50176
	s_barrier
	s_waitcnt lgkmcnt(0)
	v_mfma_f32_16x16x32_bf16 v[24:27], v[8:11], v[186:189], v[60:63]
	v_mfma_f32_16x16x32_bf16 v[60:63], v[12:15], v[190:193], v[24:27]
	v_mfma_f32_16x16x32_bf16 v[24:27], v[158:161], v[186:189], v[56:59]
	v_mfma_f32_16x16x32_bf16 v[56:59], v[202:205], v[190:193], v[24:27]
	v_mfma_f32_16x16x32_bf16 v[24:27], v[8:11], v[194:197], v[52:55]
	v_mfma_f32_16x16x32_bf16 v[44:47], v[12:15], v[198:201], v[24:27]
	v_mfma_f32_16x16x32_bf16 v[24:27], v[158:161], v[194:197], v[48:51]
	v_mfma_f32_16x16x32_bf16 v[40:43], v[202:205], v[198:201], v[24:27]
	v_mfma_f32_16x16x32_bf16 v[24:27], v[8:11], v[206:209], v[214:217]
	v_mfma_f32_16x16x32_bf16 v[8:11], v[8:11], v[222:225], v[36:39]
	v_mfma_f32_16x16x32_bf16 v[28:31], v[12:15], v[210:213], v[24:27]
	v_mfma_f32_16x16x32_bf16 v[24:27], v[158:161], v[206:209], v[230:233]
	v_mfma_f32_16x16x32_bf16 v[12:15], v[12:15], v[172:175], v[8:11]
	v_mfma_f32_16x16x32_bf16 v[8:11], v[158:161], v[222:225], v[32:35]
	v_mfma_f32_16x16x32_bf16 v[24:27], v[202:205], v[210:213], v[24:27]
	v_mfma_f32_16x16x32_bf16 v[8:11], v[202:205], v[172:175], v[8:11]
	v_mfma_f32_16x16x32_bf16 v[32:35], v[138:141], v[186:189], v[142:145]
	v_mfma_f32_16x16x32_bf16 v[48:51], v[218:221], v[190:193], v[32:35]
	v_mfma_f32_16x16x32_bf16 v[32:35], v[234:237], v[186:189], v[146:149]
	v_mfma_f32_16x16x32_bf16 v[20:23], v[138:141], v[194:197], v[20:23]
	v_mfma_f32_16x16x32_bf16 v[16:19], v[234:237], v[194:197], v[16:19]
	v_mfma_f32_16x16x32_bf16 v[52:55], v[154:157], v[190:193], v[32:35]
	v_mfma_f32_16x16x32_bf16 v[32:35], v[218:221], v[198:201], v[20:23]
	v_mfma_f32_16x16x32_bf16 v[36:39], v[154:157], v[198:201], v[16:19]
	v_mfma_f32_16x16x32_bf16 v[16:19], v[138:141], v[206:209], v[178:181]
	v_mfma_f32_16x16x32_bf16 v[20:23], v[234:237], v[206:209], v[182:185]
	v_mfma_f32_16x16x32_bf16 v[4:7], v[138:141], v[222:225], v[4:7]
	v_mfma_f32_16x16x32_bf16 v[0:3], v[234:237], v[222:225], v[0:3]
	v_mfma_f32_16x16x32_bf16 v[16:19], v[218:221], v[210:213], v[16:19]
	v_mfma_f32_16x16x32_bf16 v[20:23], v[154:157], v[210:213], v[20:23]
	v_mfma_f32_16x16x32_bf16 v[4:7], v[218:221], v[172:175], v[4:7]
	v_mfma_f32_16x16x32_bf16 v[0:3], v[154:157], v[172:175], v[0:3]
	s_cmpk_gt_u32 s29, 0xff
	s_barrier
	s_cbranch_scc1 .LBB0_968
	s_barrier

; #define STAGE(P,BASE,LD,br,kt) do{long _g=(long)(br)*(LD)+(long)(kt)*BK; \
;     _Pragma("unroll") for(int _i=0;_i<2;++_i){int _b=tid*16+_i*8192;int _r,_c;stage_rc(_b,_r,_c); \
;       __builtin_amdgcn_global_load_lds((const unsigned*)((BASE)+_g+(long)_r*(LD)+_c), \
;         (unsigned*)((char*)(P)+_b),16,0,0);}}while(0)
; #define STAGE(P,BASE,LD,br,kt) do{long _g=(long)(br)*(LD)+(long)(kt)*BK; \
;     _Pragma("unroll") for(int _i=0;_i<2;++_i){int _b=tid*16+_i*8192;int _r,_c;stage_rc(_b,_r,_c); \
;       __builtin_amdgcn_global_load_lds((const unsigned*)((BASE)+_g+(long)_r*(LD)+_c), \
;         (unsigned*)((char*)(P)+_b),16,0,0);}}while(0)
; #define LDA(dst,b,h) _Pragma("unroll") for(int m=0;m<4;++m) _Pragma("unroll") for(int k=0;k<2;++k) \
;     dst[m][k]=*reinterpret_cast<const bf16x8*>((char*)SA(b,h)+lds_byte(wr*64+m*16+fr,k*32+fq*8))
; #define LDB(dst,b,h) _Pragma("unroll") for(int n=0;n<2;++n) _Pragma("unroll") for(int k=0;k<2;++k) \
;     dst[n][k]=*reinterpret_cast<const bf16x8*>((char*)SB(b,h)+lds_byte(wc*32+n*16+fr,k*32+fq*8))
; #define MMA(ai,bj,At_,Bt_) do{__builtin_amdgcn_s_setprio(1); \
;     _Pragma("unroll") for(int m=0;m<4;++m) _Pragma("unroll") for(int n=0;n<2;++n) _Pragma("unroll") for(int k=0;k<2;++k) \
;       acc[ai][bj][m][n]=__builtin_amdgcn_mfma_f32_16x16x32_bf16(Bt_[n][k],At_[m][k],acc[ai][bj][m][n],0,0,0); \
;     __builtin_amdgcn_s_setprio(0);}while(0)
; #define WAIT_L(n) asm volatile("s_waitcnt lgkmcnt(" #n ")":::"memory")
; #define BAR __builtin_amdgcn_s_barrier()
; #define SCHED __builtin_amdgcn_sched_barrier(0)
; DEVINL void gemm8_mainloop(const u16* A, long lda, const u16* Bt, long ldb, int K, int brow, int bcol, f32x4 (&acc)[2][2][4][2], char* smem, int tid) {
;     ...
;   for(int t=0;t<nt-2;t+=2){
;     LDB(B0,0,0); SCHED; LDA(At,0,0); STAGE(SA(1,1),A,lda,brow+HALF,t+1);
;     WAIT_L(8); BAR; WAIT_L(0); MMA(0,0,At,B0); BAR; SCHED;
;     LDB(B1,0,1); STAGE(SB(0,0),Bt,ldb,bcol,t+2);
;     BAR; WAIT_L(0); MMA(0,1,At,B1); BAR;
;     LDA(At,0,1); STAGE(SA(0,0),A,lda,brow,t+2);
;     BAR; WAIT_L(0); MMA(1,0,At,B0); BAR; SCHED;
.LBB0_1292:
	ds_read_b128 v[170:173], v161
	ds_read_b128 v[180:183], v161 offset:1024
	ds_read_b128 v[184:187], v161 offset:2048
	ds_read_b128 v[188:191], v161 offset:3072
	v_add_u32_e32 v178, 0xc000, v128
	v_lshl_add_u64 v[244:245], s[94:95], 0, v[148:149]
	v_readfirstlane_b32 s5, v178
	v_add_u32_e32 v179, 0xe000, v128
	v_add_u32_e32 v174, s1, v160
	v_add_u32_e32 v175, s37, v160
	v_add_u32_e32 v177, s40, v160
	v_lshl_add_u64 v[162:163], v[244:245], 0, s[8:9]
	s_mov_b32 m0, s5
	v_lshl_add_u64 v[246:247], s[94:95], 0, v[150:151]
	v_readfirstlane_b32 s5, v179
	ds_read_b128 v[192:195], v131
	ds_read_b128 v[196:199], v131 offset:1024
	ds_read_b128 v[200:203], v174
	ds_read_b128 v[204:207], v174 offset:1024
	ds_read_b128 v[208:211], v175
	ds_read_b128 v[212:215], v175 offset:1024
	ds_read_b128 v[216:219], v177
	ds_read_b128 v[220:223], v177 offset:1024
	global_load_lds_dwordx4 v[162:163], off
	v_lshl_add_u64 v[162:163], v[246:247], 0, s[8:9]
	s_mov_b32 m0, s5
	s_nop 0
	global_load_lds_dwordx4 v[162:163], off
	s_waitcnt lgkmcnt(8)
	s_barrier
	s_waitcnt lgkmcnt(0)
	v_mfma_f32_16x16x32_bf16 v[124:127], v[170:173], v[192:195], v[124:127]
	v_mfma_f32_16x16x32_bf16 v[120:123], v[184:187], v[192:195], v[120:123]
	v_mfma_f32_16x16x32_bf16 v[116:119], v[170:173], v[200:203], v[116:119]
	v_mfma_f32_16x16x32_bf16 v[112:115], v[184:187], v[200:203], v[112:115]
	v_mfma_f32_16x16x32_bf16 v[108:111], v[170:173], v[208:211], v[108:111]
	v_mfma_f32_16x16x32_bf16 v[104:107], v[184:187], v[208:211], v[104:107]
	v_mfma_f32_16x16x32_bf16 v[100:103], v[170:173], v[216:219], v[100:103]
	v_mfma_f32_16x16x32_bf16 v[96:99], v[184:187], v[216:219], v[96:99]
	v_mfma_f32_16x16x32_bf16 v[124:127], v[180:183], v[196:199], v[124:127]
	v_mfma_f32_16x16x32_bf16 v[120:123], v[188:191], v[196:199], v[120:123]
	v_mfma_f32_16x16x32_bf16 v[116:119], v[180:183], v[204:207], v[116:119]
	v_mfma_f32_16x16x32_bf16 v[112:115], v[188:191], v[204:207], v[112:115]
	v_mfma_f32_16x16x32_bf16 v[108:111], v[180:183], v[212:215], v[108:111]
	v_mfma_f32_16x16x32_bf16 v[104:107], v[188:191], v[212:215], v[104:107]
	v_mfma_f32_16x16x32_bf16 v[100:103], v[180:183], v[220:223], v[100:103]
	v_mfma_f32_16x16x32_bf16 v[96:99], v[188:191], v[220:223], v[96:99]
	s_barrier
	v_add_u32_e32 v162, s27, v153
	v_lshl_add_u64 v[248:249], s[94:95], 0, v[144:145]
	v_readfirstlane_b32 s5, v162
	v_add_u32_e32 v163, 0x2000, v162
	v_lshl_add_u64 v[240:241], v[248:249], 0, s[10:11]
	s_mov_b32 m0, s5
	v_lshl_add_u64 v[250:251], s[94:95], 0, v[146:147]
	v_readfirstlane_b32 s5, v163
	ds_read_b128 v[224:227], v158
	ds_read_b128 v[228:231], v158 offset:1024
	ds_read_b128 v[232:235], v158 offset:2048
	ds_read_b128 v[236:239], v158 offset:3072
	global_load_lds_dwordx4 v[240:241], off
	v_lshl_add_u64 v[240:241], v[250:251], 0, s[10:11]
	s_mov_b32 m0, s5
	s_nop 0
	global_load_lds_dwordx4 v[240:241], off
	s_barrier
	s_waitcnt lgkmcnt(0)
	v_mfma_f32_16x16x32_bf16 v[92:95], v[224:227], v[192:195], v[92:95]
	v_mfma_f32_16x16x32_bf16 v[88:91], v[232:235], v[192:195], v[88:91]
	v_mfma_f32_16x16x32_bf16 v[84:87], v[224:227], v[200:203], v[84:87]
	v_mfma_f32_16x16x32_bf16 v[80:83], v[232:235], v[200:203], v[80:83]
	v_mfma_f32_16x16x32_bf16 v[76:79], v[224:227], v[208:211], v[76:79]
	v_mfma_f32_16x16x32_bf16 v[72:75], v[232:235], v[208:211], v[72:75]
	v_mfma_f32_16x16x32_bf16 v[68:71], v[224:227], v[216:219], v[68:71]
	v_mfma_f32_16x16x32_bf16 v[64:67], v[232:235], v[216:219], v[64:67]
	v_mfma_f32_16x16x32_bf16 v[92:95], v[228:231], v[196:199], v[92:95]
	v_mfma_f32_16x16x32_bf16 v[88:91], v[236:239], v[196:199], v[88:91]
	v_mfma_f32_16x16x32_bf16 v[84:87], v[228:231], v[204:207], v[84:87]
	v_mfma_f32_16x16x32_bf16 v[80:83], v[236:239], v[204:207], v[80:83]
	v_mfma_f32_16x16x32_bf16 v[76:79], v[228:231], v[212:215], v[76:79]
	v_mfma_f32_16x16x32_bf16 v[72:75], v[236:239], v[212:215], v[72:75]
	v_mfma_f32_16x16x32_bf16 v[68:71], v[228:231], v[220:223], v[68:71]
	v_mfma_f32_16x16x32_bf16 v[64:67], v[236:239], v[220:223], v[64:67]
	v_readfirstlane_b32 s5, v128
	v_add_u32_e32 v169, 0x2000, v128
	v_lshl_add_u64 v[240:241], v[244:245], 0, s[12:13]
	s_mov_b32 m0, s5
	v_readfirstlane_b32 s5, v169
	s_barrier
	ds_read_b128 v[192:195], v131 offset:16384
	ds_read_b128 v[196:199], v131 offset:17408
	ds_read_b128 v[200:203], v174 offset:16384
	ds_read_b128 v[204:207], v174 offset:17408
	ds_read_b128 v[208:211], v175 offset:16384
	ds_read_b128 v[212:215], v175 offset:17408
	ds_read_b128 v[216:219], v177 offset:16384
	ds_read_b128 v[220:223], v177 offset:17408
	global_load_lds_dwordx4 v[240:241], off
	v_lshl_add_u64 v[240:241], v[246:247], 0, s[12:13]
	s_mov_b32 m0, s5
	s_nop 0
	global_load_lds_dwordx4 v[240:241], off
	s_barrier
	s_waitcnt lgkmcnt(0)
	v_mfma_f32_16x16x32_bf16 v[60:63], v[170:173], v[192:195], v[60:63]
	v_mfma_f32_16x16x32_bf16 v[56:59], v[184:187], v[192:195], v[56:59]
	v_mfma_f32_16x16x32_bf16 v[52:55], v[170:173], v[200:203], v[52:55]
	v_mfma_f32_16x16x32_bf16 v[48:51], v[184:187], v[200:203], v[48:51]
	v_mfma_f32_16x16x32_bf16 v[44:47], v[170:173], v[208:211], v[44:47]
	v_mfma_f32_16x16x32_bf16 v[40:43], v[184:187], v[208:211], v[40:43]
	v_mfma_f32_16x16x32_bf16 v[36:39], v[170:173], v[216:219], v[36:39]
	v_mfma_f32_16x16x32_bf16 v[32:35], v[184:187], v[216:219], v[32:35]
	v_mfma_f32_16x16x32_bf16 v[60:63], v[180:183], v[196:199], v[60:63]
	v_mfma_f32_16x16x32_bf16 v[56:59], v[188:191], v[196:199], v[56:59]
	v_mfma_f32_16x16x32_bf16 v[52:55], v[180:183], v[204:207], v[52:55]
	v_mfma_f32_16x16x32_bf16 v[48:51], v[188:191], v[204:207], v[48:51]
	v_mfma_f32_16x16x32_bf16 v[44:47], v[180:183], v[212:215], v[44:47]
	v_mfma_f32_16x16x32_bf16 v[40:43], v[188:191], v[212:215], v[40:43]
	v_mfma_f32_16x16x32_bf16 v[36:39], v[180:183], v[220:223], v[36:39]
	v_mfma_f32_16x16x32_bf16 v[32:35], v[188:191], v[220:223], v[32:35]
	s_barrier
; #define STAGE(P,BASE,LD,br,kt) do{long _g=(long)(br)*(LD)+(long)(kt)*BK; \
;     _Pragma("unroll") for(int _i=0;_i<2;++_i){int _b=tid*16+_i*8192;int _r,_c;stage_rc(_b,_r,_c); \
;       __builtin_amdgcn_global_load_lds((const unsigned*)((BASE)+_g+(long)_r*(LD)+_c), \
;         (unsigned*)((char*)(P)+_b),16,0,0);}}while(0)
; #define STAGE(P,BASE,LD,br,kt) do{long _g=(long)(br)*(LD)+(long)(kt)*BK; \
;     _Pragma("unroll") for(int _i=0;_i<2;++_i){int _b=tid*16+_i*8192;int _r,_c;stage_rc(_b,_r,_c); \
;       __builtin_amdgcn_global_load_lds((const unsigned*)((BASE)+_g+(long)_r*(LD)+_c), \
;         (unsigned*)((char*)(P)+_b),16,0,0);}}while(0)
; #define LDA(dst,b,h) _Pragma("unroll") for(int m=0;m<4;++m) _Pragma("unroll") for(int k=0;k<2;++k) \
;     dst[m][k]=*reinterpret_cast<const bf16x8*>((char*)SA(b,h)+lds_byte(wr*64+m*16+fr,k*32+fq*8))
; #define LDB(dst,b,h) _Pragma("unroll") for(int n=0;n<2;++n) _Pragma("unroll") for(int k=0;k<2;++k) \
;     dst[n][k]=*reinterpret_cast<const bf16x8*>((char*)SB(b,h)+lds_byte(wc*32+n*16+fr,k*32+fq*8))
; #define MMA(ai,bj,At_,Bt_) do{__builtin_amdgcn_s_setprio(1); \
;     _Pragma("unroll") for(int m=0;m<4;++m) _Pragma("unroll") for(int n=0;n<2;++n) _Pragma("unroll") for(int k=0;k<2;++k) \
;       acc[ai][bj][m][n]=__builtin_amdgcn_mfma_f32_16x16x32_bf16(Bt_[n][k],At_[m][k],acc[ai][bj][m][n],0,0,0); \
;     __builtin_amdgcn_s_setprio(0);}while(0)
; #define WAIT_V(n) asm volatile("s_waitcnt vmcnt(" #n ")":::"memory")
; #define WAIT_L(n) asm volatile("s_waitcnt lgkmcnt(" #n ")":::"memory")
; #define BAR __builtin_amdgcn_s_barrier()
; #define SCHED __builtin_amdgcn_sched_barrier(0)
; DEVINL void gemm8_mainloop(const u16* A, long lda, const u16* Bt, long ldb, int K, int brow, int bcol, f32x4 (&acc)[2][2][4][2], char* smem, int tid) {
;     ...
;     STAGE(SB(0,1),Bt,ldb,bcol+HALF,t+2);
;     WAIT_V(6); BAR; MMA(1,1,At,B1); BAR;
;     LDB(B0,1,0); SCHED; LDA(At,1,0); STAGE(SA(0,1),A,lda,brow+HALF,t+2);
;     WAIT_L(8); BAR; WAIT_L(0); MMA(0,0,At,B0); BAR; SCHED;
;     LDB(B1,1,1); STAGE(SB(1,0),Bt,ldb,bcol,t+3);
;     BAR; WAIT_L(0); MMA(0,1,At,B1); BAR;
;     LDA(At,1,1); STAGE(SA(1,0),A,lda,brow,t+3);
	v_add_u32_e32 v170, s29, v153
	v_add_u32_e32 v171, 0x2000, v170
	v_readfirstlane_b32 s5, v170
	v_lshl_add_u64 v[172:173], v[248:249], 0, s[14:15]
	s_mov_b32 m0, s5
	v_readfirstlane_b32 s5, v171
	global_load_lds_dwordx4 v[172:173], off
	v_lshl_add_u64 v[172:173], v[250:251], 0, s[14:15]
	s_mov_b32 m0, s5
	s_nop 0
	global_load_lds_dwordx4 v[172:173], off
	s_waitcnt vmcnt(6)
	s_barrier
	v_mfma_f32_16x16x32_bf16 v[28:31], v[224:227], v[192:195], v[28:31]
	v_mfma_f32_16x16x32_bf16 v[24:27], v[232:235], v[192:195], v[24:27]
	v_mfma_f32_16x16x32_bf16 v[20:23], v[224:227], v[200:203], v[20:23]
	v_mfma_f32_16x16x32_bf16 v[16:19], v[232:235], v[200:203], v[16:19]
	v_mfma_f32_16x16x32_bf16 v[12:15], v[224:227], v[208:211], v[12:15]
	v_mfma_f32_16x16x32_bf16 v[8:11], v[232:235], v[208:211], v[8:11]
	v_mfma_f32_16x16x32_bf16 v[4:7], v[224:227], v[216:219], v[4:7]
	v_mfma_f32_16x16x32_bf16 v[0:3], v[232:235], v[216:219], v[0:3]
	v_mfma_f32_16x16x32_bf16 v[28:31], v[228:231], v[196:199], v[28:31]
	v_mfma_f32_16x16x32_bf16 v[24:27], v[236:239], v[196:199], v[24:27]
	v_mfma_f32_16x16x32_bf16 v[20:23], v[228:231], v[204:207], v[20:23]
	v_mfma_f32_16x16x32_bf16 v[16:19], v[236:239], v[204:207], v[16:19]
	v_mfma_f32_16x16x32_bf16 v[12:15], v[228:231], v[212:215], v[12:15]
	v_mfma_f32_16x16x32_bf16 v[8:11], v[236:239], v[212:215], v[8:11]
	v_mfma_f32_16x16x32_bf16 v[4:7], v[228:231], v[220:223], v[4:7]
	v_mfma_f32_16x16x32_bf16 v[0:3], v[236:239], v[220:223], v[0:3]
	s_barrier
	ds_read_b128 v[180:183], v154
	ds_read_b128 v[184:187], v154 offset:1024
	ds_read_b128 v[188:191], v154 offset:2048
	ds_read_b128 v[192:195], v154 offset:3072
	v_add_u32_e32 v172, 0x4000, v128
	v_add_u32_e32 v173, 0x6000, v128
	v_readfirstlane_b32 s5, v172
	v_lshl_add_u64 v[228:229], v[244:245], 0, s[16:17]
	s_mov_b32 m0, s5
	v_readfirstlane_b32 s5, v173
	ds_read_b128 v[196:199], v131 offset:32768
	ds_read_b128 v[200:203], v131 offset:33792
	ds_read_b128 v[204:207], v174 offset:32768
	ds_read_b128 v[208:211], v174 offset:33792
	ds_read_b128 v[212:215], v175 offset:32768
	ds_read_b128 v[216:219], v175 offset:33792
	ds_read_b128 v[220:223], v177 offset:32768
	ds_read_b128 v[224:227], v177 offset:33792
	global_load_lds_dwordx4 v[228:229], off
	v_lshl_add_u64 v[228:229], v[246:247], 0, s[16:17]
	s_mov_b32 m0, s5
	s_nop 0
	global_load_lds_dwordx4 v[228:229], off
	s_waitcnt lgkmcnt(8)
	s_barrier
	s_waitcnt lgkmcnt(0)
	v_mfma_f32_16x16x32_bf16 v[124:127], v[180:183], v[196:199], v[124:127]
	v_mfma_f32_16x16x32_bf16 v[120:123], v[188:191], v[196:199], v[120:123]
	v_mfma_f32_16x16x32_bf16 v[116:119], v[180:183], v[204:207], v[116:119]
	v_mfma_f32_16x16x32_bf16 v[112:115], v[188:191], v[204:207], v[112:115]
	v_mfma_f32_16x16x32_bf16 v[108:111], v[180:183], v[212:215], v[108:111]
	v_mfma_f32_16x16x32_bf16 v[104:107], v[188:191], v[212:215], v[104:107]
	v_mfma_f32_16x16x32_bf16 v[100:103], v[180:183], v[220:223], v[100:103]
	v_mfma_f32_16x16x32_bf16 v[96:99], v[188:191], v[220:223], v[96:99]
	v_mfma_f32_16x16x32_bf16 v[124:127], v[184:187], v[200:203], v[124:127]
	v_mfma_f32_16x16x32_bf16 v[120:123], v[192:195], v[200:203], v[120:123]
	v_mfma_f32_16x16x32_bf16 v[116:119], v[184:187], v[208:211], v[116:119]
	v_mfma_f32_16x16x32_bf16 v[112:115], v[192:195], v[208:211], v[112:115]
	v_mfma_f32_16x16x32_bf16 v[108:111], v[184:187], v[216:219], v[108:111]
	v_mfma_f32_16x16x32_bf16 v[104:107], v[192:195], v[216:219], v[104:107]
	v_mfma_f32_16x16x32_bf16 v[100:103], v[184:187], v[224:227], v[100:103]
	v_mfma_f32_16x16x32_bf16 v[96:99], v[192:195], v[224:227], v[96:99]
	s_barrier
	v_readfirstlane_b32 s5, v155
	v_add_u32_e32 v165, 0x2000, v155
	v_lshl_add_u64 v[252:253], v[248:249], 0, s[18:19]
	s_mov_b32 m0, s5
	v_readfirstlane_b32 s5, v165
	ds_read_b128 v[228:231], v152
	ds_read_b128 v[232:235], v152 offset:1024
	ds_read_b128 v[236:239], v152 offset:2048
	ds_read_b128 v[240:243], v152 offset:3072
	global_load_lds_dwordx4 v[252:253], off
	v_lshl_add_u64 v[252:253], v[250:251], 0, s[18:19]
	s_mov_b32 m0, s5
	s_nop 0
	global_load_lds_dwordx4 v[252:253], off
	s_barrier
	s_waitcnt lgkmcnt(0)
	v_mfma_f32_16x16x32_bf16 v[92:95], v[228:231], v[196:199], v[92:95]
	v_mfma_f32_16x16x32_bf16 v[88:91], v[236:239], v[196:199], v[88:91]
	v_mfma_f32_16x16x32_bf16 v[84:87], v[228:231], v[204:207], v[84:87]
	v_mfma_f32_16x16x32_bf16 v[80:83], v[236:239], v[204:207], v[80:83]
	v_mfma_f32_16x16x32_bf16 v[76:79], v[228:231], v[212:215], v[76:79]
	v_mfma_f32_16x16x32_bf16 v[72:75], v[236:239], v[212:215], v[72:75]
	v_mfma_f32_16x16x32_bf16 v[68:71], v[228:231], v[220:223], v[68:71]
	v_mfma_f32_16x16x32_bf16 v[64:67], v[236:239], v[220:223], v[64:67]
	v_mfma_f32_16x16x32_bf16 v[92:95], v[232:235], v[200:203], v[92:95]
	v_mfma_f32_16x16x32_bf16 v[88:91], v[240:243], v[200:203], v[88:91]
	v_mfma_f32_16x16x32_bf16 v[84:87], v[232:235], v[208:211], v[84:87]
	v_mfma_f32_16x16x32_bf16 v[80:83], v[240:243], v[208:211], v[80:83]
	v_mfma_f32_16x16x32_bf16 v[76:79], v[232:235], v[216:219], v[76:79]
	v_mfma_f32_16x16x32_bf16 v[72:75], v[240:243], v[216:219], v[72:75]
	v_mfma_f32_16x16x32_bf16 v[68:71], v[232:235], v[224:227], v[68:71]
	v_mfma_f32_16x16x32_bf16 v[64:67], v[240:243], v[224:227], v[64:67]
	v_readfirstlane_b32 s5, v156
	v_lshl_add_u64 v[244:245], v[244:245], 0, s[20:21]
	s_mov_b32 m0, s5
	v_readfirstlane_b32 s5, v157
	s_barrier
	ds_read_b128 v[196:199], v131 offset:49152
	ds_read_b128 v[200:203], v131 offset:50176
	ds_read_b128 v[204:207], v174 offset:49152
	ds_read_b128 v[208:211], v174 offset:50176
	ds_read_b128 v[212:215], v175 offset:49152
	ds_read_b128 v[216:219], v175 offset:50176
	ds_read_b128 v[220:223], v177 offset:49152
	ds_read_b128 v[224:227], v177 offset:50176
	global_load_lds_dwordx4 v[244:245], off
	v_lshl_add_u64 v[244:245], v[246:247], 0, s[20:21]
	s_mov_b32 m0, s5
	s_nop 0
	global_load_lds_dwordx4 v[244:245], off
	s_barrier
; #define STAGE(P,BASE,LD,br,kt) do{long _g=(long)(br)*(LD)+(long)(kt)*BK; \
;     _Pragma("unroll") for(int _i=0;_i<2;++_i){int _b=tid*16+_i*8192;int _r,_c;stage_rc(_b,_r,_c); \
;       __builtin_amdgcn_global_load_lds((const unsigned*)((BASE)+_g+(long)_r*(LD)+_c), \
;         (unsigned*)((char*)(P)+_b),16,0,0);}}while(0)
; #define STAGE(P,BASE,LD,br,kt) do{long _g=(long)(br)*(LD)+(long)(kt)*BK; \
;     _Pragma("unroll") for(int _i=0;_i<2;++_i){int _b=tid*16+_i*8192;int _r,_c;stage_rc(_b,_r,_c); \
;       __builtin_amdgcn_global_load_lds((const unsigned*)((BASE)+_g+(long)_r*(LD)+_c), \
;         (unsigned*)((char*)(P)+_b),16,0,0);}}while(0)
; #define LDA(dst,b,h) _Pragma("unroll") for(int m=0;m<4;++m) _Pragma("unroll") for(int k=0;k<2;++k) \
;     dst[m][k]=*reinterpret_cast<const bf16x8*>((char*)SA(b,h)+lds_byte(wr*64+m*16+fr,k*32+fq*8))
; #define LDB(dst,b,h) _Pragma("unroll") for(int n=0;n<2;++n) _Pragma("unroll") for(int k=0;k<2;++k) \
;     dst[n][k]=*reinterpret_cast<const bf16x8*>((char*)SB(b,h)+lds_byte(wc*32+n*16+fr,k*32+fq*8))
; #define MMA(ai,bj,At_,Bt_) do{__builtin_amdgcn_s_setprio(1); \
;     _Pragma("unroll") for(int m=0;m<4;++m) _Pragma("unroll") for(int n=0;n<2;++n) _Pragma("unroll") for(int k=0;k<2;++k) \
;       acc[ai][bj][m][n]=__builtin_amdgcn_mfma_f32_16x16x32_bf16(Bt_[n][k],At_[m][k],acc[ai][bj][m][n],0,0,0); \
;     __builtin_amdgcn_s_setprio(0);}while(0)
; #define WAIT_V(n) asm volatile("s_waitcnt vmcnt(" #n ")":::"memory")
; #define WAIT_L(n) asm volatile("s_waitcnt lgkmcnt(" #n ")":::"memory")
; #define BAR __builtin_amdgcn_s_barrier()
; #define SCHED __builtin_amdgcn_sched_barrier(0)
; DEVINL void gemm8_mainloop(const u16* A, long lda, const u16* Bt, long ldb, int K, int brow, int bcol, f32x4 (&acc)[2][2][4][2], char* smem, int tid) {
;     ...
;     BAR; WAIT_L(0); MMA(1,0,At,B0); BAR; SCHED;
;     STAGE(SB(1,1),Bt,ldb,bcol+HALF,t+3);
;     WAIT_V(6); BAR; MMA(1,1,At,B1); BAR;
;   }
;   { LDB(B0,0,0); LDA(At,0,0); STAGE(SA(1,1),A,lda,brow+HALF,nt-1);
;     BAR; WAIT_L(0); MMA(0,0,At,B0); BAR;
;     LDB(B1,0,1); BAR; WAIT_L(0); MMA(0,1,At,B1); BAR;
	s_waitcnt lgkmcnt(0)
	v_mfma_f32_16x16x32_bf16 v[60:63], v[180:183], v[196:199], v[60:63]
	v_mfma_f32_16x16x32_bf16 v[56:59], v[188:191], v[196:199], v[56:59]
	v_mfma_f32_16x16x32_bf16 v[52:55], v[180:183], v[204:207], v[52:55]
	v_mfma_f32_16x16x32_bf16 v[48:51], v[188:191], v[204:207], v[48:51]
	v_mfma_f32_16x16x32_bf16 v[44:47], v[180:183], v[212:215], v[44:47]
	v_mfma_f32_16x16x32_bf16 v[40:43], v[188:191], v[212:215], v[40:43]
	v_mfma_f32_16x16x32_bf16 v[36:39], v[180:183], v[220:223], v[36:39]
	v_mfma_f32_16x16x32_bf16 v[32:35], v[188:191], v[220:223], v[32:35]
	v_mfma_f32_16x16x32_bf16 v[60:63], v[184:187], v[200:203], v[60:63]
	v_mfma_f32_16x16x32_bf16 v[56:59], v[192:195], v[200:203], v[56:59]
	v_mfma_f32_16x16x32_bf16 v[52:55], v[184:187], v[208:211], v[52:55]
	v_mfma_f32_16x16x32_bf16 v[48:51], v[192:195], v[208:211], v[48:51]
	v_mfma_f32_16x16x32_bf16 v[44:47], v[184:187], v[216:219], v[44:47]
	v_mfma_f32_16x16x32_bf16 v[40:43], v[192:195], v[216:219], v[40:43]
	v_mfma_f32_16x16x32_bf16 v[36:39], v[184:187], v[224:227], v[36:39]
	v_mfma_f32_16x16x32_bf16 v[32:35], v[192:195], v[224:227], v[32:35]
	s_barrier
	v_readfirstlane_b32 s5, v159
	v_add_u32_e32 v165, 0x2000, v159
	v_lshl_add_u64 v[180:181], v[248:249], 0, s[22:23]
	s_mov_b32 m0, s5
	v_readfirstlane_b32 s5, v165
	global_load_lds_dwordx4 v[180:181], off
	v_lshl_add_u64 v[180:181], v[250:251], 0, s[22:23]
	s_mov_b32 m0, s5
	s_nop 0
	global_load_lds_dwordx4 v[180:181], off
	s_waitcnt vmcnt(6)
	s_barrier
	v_mfma_f32_16x16x32_bf16 v[28:31], v[228:231], v[196:199], v[28:31]
	v_mfma_f32_16x16x32_bf16 v[24:27], v[236:239], v[196:199], v[24:27]
	v_mfma_f32_16x16x32_bf16 v[20:23], v[228:231], v[204:207], v[20:23]
	v_mfma_f32_16x16x32_bf16 v[16:19], v[236:239], v[204:207], v[16:19]
	v_mfma_f32_16x16x32_bf16 v[12:15], v[228:231], v[212:215], v[12:15]
	v_mfma_f32_16x16x32_bf16 v[8:11], v[236:239], v[212:215], v[8:11]
	v_mfma_f32_16x16x32_bf16 v[4:7], v[228:231], v[220:223], v[4:7]
	v_mfma_f32_16x16x32_bf16 v[0:3], v[236:239], v[220:223], v[0:3]
	v_mfma_f32_16x16x32_bf16 v[28:31], v[232:235], v[200:203], v[28:31]
	v_mfma_f32_16x16x32_bf16 v[24:27], v[240:243], v[200:203], v[24:27]
	v_mfma_f32_16x16x32_bf16 v[20:23], v[232:235], v[208:211], v[20:23]
	v_mfma_f32_16x16x32_bf16 v[16:19], v[240:243], v[208:211], v[16:19]
	v_mfma_f32_16x16x32_bf16 v[12:15], v[232:235], v[216:219], v[12:15]
	v_mfma_f32_16x16x32_bf16 v[8:11], v[240:243], v[216:219], v[8:11]
	v_mfma_f32_16x16x32_bf16 v[4:7], v[232:235], v[224:227], v[4:7]
	v_mfma_f32_16x16x32_bf16 v[0:3], v[240:243], v[224:227], v[0:3]
	s_add_i32 s4, s4, 2
	v_lshl_add_u64 v[144:145], v[144:145], 0, s[10:11]
	v_lshl_add_u64 v[146:147], v[146:147], 0, s[10:11]
	v_lshl_add_u64 v[148:149], v[148:149], 0, s[10:11]
	s_cmp_lt_u32 s4, 28
	v_lshl_add_u64 v[150:151], v[150:151], 0, s[10:11]
	s_barrier
	s_cbranch_scc1 .LBB0_1292
	s_or_b32 s4, s36, 0x80
	s_ashr_i32 s5, s4, 31
	s_lshl_b64 s[4:5], s[4:5], 12
	s_add_u32 s4, s90, s4
	s_addc_u32 s5, s91, s5
	v_lshl_add_u64 v[156:157], v[136:137], 1, s[4:5]
	v_lshl_add_u64 v[140:141], v[140:141], 1, v[156:157]
	v_readfirstlane_b32 s1, v178
	v_lshl_add_u64 v[140:141], v[140:141], 0, s[24:25]
	s_mov_b32 m0, s1
	ds_read_b128 v[144:147], v161
	ds_read_b128 v[148:151], v161 offset:1024
	ds_read_b128 v[180:183], v161 offset:2048
	ds_read_b128 v[184:187], v161 offset:3072
	ds_read_b128 v[188:191], v131
	ds_read_b128 v[192:195], v131 offset:1024
	ds_read_b128 v[196:199], v174
	ds_read_b128 v[200:203], v174 offset:1024
	ds_read_b128 v[204:207], v175
	ds_read_b128 v[208:211], v175 offset:1024
	ds_read_b128 v[212:215], v177
	ds_read_b128 v[216:219], v177 offset:1024
	global_load_lds_dwordx4 v[140:141], off
	v_lshl_add_u64 v[140:141], v[138:139], 1, s[4:5]
	v_lshl_add_u64 v[140:141], v[142:143], 1, v[140:141]
	v_readfirstlane_b32 s1, v179
	v_lshl_add_u64 v[140:141], v[140:141], 0, s[24:25]
	s_mov_b32 m0, s1
	s_nop 0
	global_load_lds_dwordx4 v[140:141], off
	s_barrier
	s_waitcnt lgkmcnt(0)
	v_mfma_f32_16x16x32_bf16 v[124:127], v[144:147], v[188:191], v[124:127]
	v_mfma_f32_16x16x32_bf16 v[120:123], v[180:183], v[188:191], v[120:123]
	v_mfma_f32_16x16x32_bf16 v[108:111], v[144:147], v[204:207], v[108:111]
	v_mfma_f32_16x16x32_bf16 v[104:107], v[180:183], v[204:207], v[104:107]
	v_mfma_f32_16x16x32_bf16 v[124:127], v[148:151], v[192:195], v[124:127]
	v_mfma_f32_16x16x32_bf16 v[120:123], v[184:187], v[192:195], v[120:123]
	v_mfma_f32_16x16x32_bf16 v[116:119], v[144:147], v[196:199], v[116:119]
	v_mfma_f32_16x16x32_bf16 v[112:115], v[180:183], v[196:199], v[112:115]
	v_mfma_f32_16x16x32_bf16 v[108:111], v[148:151], v[208:211], v[108:111]
	v_mfma_f32_16x16x32_bf16 v[104:107], v[184:187], v[208:211], v[104:107]
	v_mfma_f32_16x16x32_bf16 v[100:103], v[144:147], v[212:215], v[100:103]
	v_mfma_f32_16x16x32_bf16 v[96:99], v[180:183], v[212:215], v[96:99]
	v_mfma_f32_16x16x32_bf16 v[140:143], v[148:151], v[200:203], v[116:119]
	v_mfma_f32_16x16x32_bf16 v[220:223], v[184:187], v[200:203], v[112:115]
	v_mfma_f32_16x16x32_bf16 v[224:227], v[148:151], v[216:219], v[100:103]
	v_mfma_f32_16x16x32_bf16 v[228:231], v[184:187], v[216:219], v[96:99]
	s_barrier
	s_nop 1
	s_nop 0
	ds_read_b128 v[96:99], v158
	ds_read_b128 v[100:103], v158 offset:1024
	ds_read_b128 v[112:115], v158 offset:2048
	ds_read_b128 v[116:119], v158 offset:3072
	s_barrier
; #define LDA(dst,b,h) _Pragma("unroll") for(int m=0;m<4;++m) _Pragma("unroll") for(int k=0;k<2;++k) \
;     dst[m][k]=*reinterpret_cast<const bf16x8*>((char*)SA(b,h)+lds_byte(wr*64+m*16+fr,k*32+fq*8))
; #define LDB(dst,b,h) _Pragma("unroll") for(int n=0;n<2;++n) _Pragma("unroll") for(int k=0;k<2;++k) \
;     dst[n][k]=*reinterpret_cast<const bf16x8*>((char*)SB(b,h)+lds_byte(wc*32+n*16+fr,k*32+fq*8))
; #define MMA(ai,bj,At_,Bt_) do{__builtin_amdgcn_s_setprio(1); \
;     _Pragma("unroll") for(int m=0;m<4;++m) _Pragma("unroll") for(int n=0;n<2;++n) _Pragma("unroll") for(int k=0;k<2;++k) \
;       acc[ai][bj][m][n]=__builtin_amdgcn_mfma_f32_16x16x32_bf16(Bt_[n][k],At_[m][k],acc[ai][bj][m][n],0,0,0); \
;     __builtin_amdgcn_s_setprio(0);}while(0)
; #define WAIT_V(n) asm volatile("s_waitcnt vmcnt(" #n ")":::"memory")
; #define WAIT_L(n) asm volatile("s_waitcnt lgkmcnt(" #n ")":::"memory")
; #define BAR __builtin_amdgcn_s_barrier()
; DEVINL void gemm8_mainloop(const u16* A, long lda, const u16* Bt, long ldb, int K, int brow, int bcol, f32x4 (&acc)[2][2][4][2], char* smem, int tid) {
;     ...
;     LDB(B1,0,1); BAR; WAIT_L(0); MMA(0,1,At,B1); BAR;
;     LDA(At,0,1); WAIT_V(4); BAR; WAIT_L(0); MMA(1,0,At,B0); MMA(1,1,At,B1); BAR; }
;   { LDB(B0,1,0); LDA(At,1,0); WAIT_V(2); BAR; WAIT_L(0); MMA(0,0,At,B0); BAR;
	s_waitcnt lgkmcnt(0)
	v_mfma_f32_16x16x32_bf16 v[92:95], v[96:99], v[188:191], v[92:95]
	v_mfma_f32_16x16x32_bf16 v[88:91], v[112:115], v[188:191], v[88:91]
	v_mfma_f32_16x16x32_bf16 v[76:79], v[96:99], v[204:207], v[76:79]
	v_mfma_f32_16x16x32_bf16 v[72:75], v[112:115], v[204:207], v[72:75]
	v_mfma_f32_16x16x32_bf16 v[92:95], v[100:103], v[192:195], v[92:95]
	v_mfma_f32_16x16x32_bf16 v[88:91], v[116:119], v[192:195], v[88:91]
	v_mfma_f32_16x16x32_bf16 v[84:87], v[96:99], v[196:199], v[84:87]
	v_mfma_f32_16x16x32_bf16 v[80:83], v[112:115], v[196:199], v[80:83]
	v_mfma_f32_16x16x32_bf16 v[76:79], v[100:103], v[208:211], v[76:79]
	v_mfma_f32_16x16x32_bf16 v[72:75], v[116:119], v[208:211], v[72:75]
	v_mfma_f32_16x16x32_bf16 v[68:71], v[96:99], v[212:215], v[68:71]
	v_mfma_f32_16x16x32_bf16 v[64:67], v[112:115], v[212:215], v[64:67]
	v_mfma_f32_16x16x32_bf16 v[156:159], v[100:103], v[200:203], v[84:87]
	v_mfma_f32_16x16x32_bf16 v[188:191], v[116:119], v[200:203], v[80:83]
	v_mfma_f32_16x16x32_bf16 v[192:195], v[100:103], v[216:219], v[68:71]
	v_mfma_f32_16x16x32_bf16 v[196:199], v[116:119], v[216:219], v[64:67]
	s_barrier
	s_nop 1
	s_nop 0
	ds_read_b128 v[64:67], v131 offset:16384
	ds_read_b128 v[68:71], v131 offset:17408
	ds_read_b128 v[80:83], v174 offset:16384
	ds_read_b128 v[84:87], v174 offset:17408
	ds_read_b128 v[200:203], v175 offset:16384
	ds_read_b128 v[204:207], v175 offset:17408
	ds_read_b128 v[208:211], v177 offset:16384
	ds_read_b128 v[212:215], v177 offset:17408
	s_waitcnt vmcnt(4)
	s_barrier
	s_waitcnt lgkmcnt(0)
	v_mfma_f32_16x16x32_bf16 v[60:63], v[144:147], v[64:67], v[60:63]
	v_mfma_f32_16x16x32_bf16 v[52:55], v[144:147], v[80:83], v[52:55]
	v_mfma_f32_16x16x32_bf16 v[44:47], v[144:147], v[200:203], v[44:47]
	v_mfma_f32_16x16x32_bf16 v[40:43], v[180:183], v[200:203], v[40:43]
	v_mfma_f32_16x16x32_bf16 v[60:63], v[148:151], v[68:71], v[60:63]
	v_mfma_f32_16x16x32_bf16 v[56:59], v[180:183], v[64:67], v[56:59]
	v_mfma_f32_16x16x32_bf16 v[52:55], v[148:151], v[84:87], v[52:55]
	v_mfma_f32_16x16x32_bf16 v[48:51], v[180:183], v[80:83], v[48:51]
	v_mfma_f32_16x16x32_bf16 v[44:47], v[148:151], v[204:207], v[44:47]
	v_mfma_f32_16x16x32_bf16 v[40:43], v[184:187], v[204:207], v[40:43]
	v_mfma_f32_16x16x32_bf16 v[36:39], v[144:147], v[208:211], v[36:39]
	v_mfma_f32_16x16x32_bf16 v[32:35], v[180:183], v[208:211], v[32:35]
	v_mfma_f32_16x16x32_bf16 v[216:219], v[184:187], v[68:71], v[56:59]
	v_mfma_f32_16x16x32_bf16 v[232:235], v[184:187], v[84:87], v[48:51]
	v_mfma_f32_16x16x32_bf16 v[144:147], v[148:151], v[212:215], v[36:39]
	v_mfma_f32_16x16x32_bf16 v[148:151], v[184:187], v[212:215], v[32:35]
	v_mfma_f32_16x16x32_bf16 v[28:31], v[96:99], v[64:67], v[28:31]
	v_mfma_f32_16x16x32_bf16 v[20:23], v[96:99], v[80:83], v[20:23]
	v_mfma_f32_16x16x32_bf16 v[12:15], v[96:99], v[200:203], v[12:15]
	v_mfma_f32_16x16x32_bf16 v[4:7], v[96:99], v[208:211], v[4:7]
	v_mfma_f32_16x16x32_bf16 v[28:31], v[100:103], v[68:71], v[28:31]
	v_mfma_f32_16x16x32_bf16 v[24:27], v[112:115], v[64:67], v[24:27]
	v_mfma_f32_16x16x32_bf16 v[20:23], v[100:103], v[84:87], v[20:23]
	v_mfma_f32_16x16x32_bf16 v[16:19], v[112:115], v[80:83], v[16:19]
	v_mfma_f32_16x16x32_bf16 v[12:15], v[100:103], v[204:207], v[12:15]
	v_mfma_f32_16x16x32_bf16 v[8:11], v[112:115], v[200:203], v[8:11]
	v_mfma_f32_16x16x32_bf16 v[4:7], v[100:103], v[212:215], v[4:7]
	v_mfma_f32_16x16x32_bf16 v[0:3], v[112:115], v[208:211], v[0:3]
	v_mfma_f32_16x16x32_bf16 v[178:181], v[116:119], v[68:71], v[24:27]
	v_mfma_f32_16x16x32_bf16 v[182:185], v[116:119], v[84:87], v[16:19]
	v_mfma_f32_16x16x32_bf16 v[200:203], v[116:119], v[204:207], v[8:11]
	v_mfma_f32_16x16x32_bf16 v[204:207], v[116:119], v[212:215], v[0:3]
	s_barrier
	s_nop 1
	s_nop 0
	ds_read_b128 v[0:3], v154
	ds_read_b128 v[8:11], v154 offset:1024
	ds_read_b128 v[208:211], v154 offset:2048
	ds_read_b128 v[212:215], v154 offset:3072
	ds_read_b128 v[16:19], v131 offset:32768
	ds_read_b128 v[24:27], v131 offset:33792
	ds_read_b128 v[32:35], v174 offset:32768
	ds_read_b128 v[36:39], v174 offset:33792
	ds_read_b128 v[48:51], v175 offset:32768
	ds_read_b128 v[56:59], v175 offset:33792
	ds_read_b128 v[236:239], v177 offset:32768
	ds_read_b128 v[240:243], v177 offset:33792
	s_waitcnt vmcnt(2)
	s_barrier
; #define LDA(dst,b,h) _Pragma("unroll") for(int m=0;m<4;++m) _Pragma("unroll") for(int k=0;k<2;++k) \
;     dst[m][k]=*reinterpret_cast<const bf16x8*>((char*)SA(b,h)+lds_byte(wr*64+m*16+fr,k*32+fq*8))
; #define LDB(dst,b,h) _Pragma("unroll") for(int n=0;n<2;++n) _Pragma("unroll") for(int k=0;k<2;++k) \
;     dst[n][k]=*reinterpret_cast<const bf16x8*>((char*)SB(b,h)+lds_byte(wc*32+n*16+fr,k*32+fq*8))
; #define MMA(ai,bj,At_,Bt_) do{__builtin_amdgcn_s_setprio(1); \
;     _Pragma("unroll") for(int m=0;m<4;++m) _Pragma("unroll") for(int n=0;n<2;++n) _Pragma("unroll") for(int k=0;k<2;++k) \
;       acc[ai][bj][m][n]=__builtin_amdgcn_mfma_f32_16x16x32_bf16(Bt_[n][k],At_[m][k],acc[ai][bj][m][n],0,0,0); \
;     __builtin_amdgcn_s_setprio(0);}while(0)
; #define WAIT_V(n) asm volatile("s_waitcnt vmcnt(" #n ")":::"memory")
; #define WAIT_L(n) asm volatile("s_waitcnt lgkmcnt(" #n ")":::"memory")
; #define BAR __builtin_amdgcn_s_barrier()
; DEVINL void gemm8_mainloop(const u16* A, long lda, const u16* Bt, long ldb, int K, int brow, int bcol, f32x4 (&acc)[2][2][4][2], char* smem, int tid) {
;     ...
;     LDA(At,0,1); WAIT_V(4); BAR; WAIT_L(0); MMA(1,0,At,B0); MMA(1,1,At,B1); BAR; }
;   { LDB(B0,1,0); LDA(At,1,0); WAIT_V(2); BAR; WAIT_L(0); MMA(0,0,At,B0); BAR;
;     LDB(B1,1,1); WAIT_V(0); BAR; WAIT_L(0); MMA(0,1,At,B1); BAR;
;     LDA(At,1,1); BAR; WAIT_L(0); MMA(1,0,At,B0); MMA(1,1,At,B1); BAR; }
;   if(wr==0)BAR;
	s_waitcnt lgkmcnt(0)
	v_mfma_f32_16x16x32_bf16 v[64:67], v[0:3], v[16:19], v[124:127]
	v_mfma_f32_16x16x32_bf16 v[116:119], v[8:11], v[24:27], v[64:67]
	v_mfma_f32_16x16x32_bf16 v[64:67], v[208:211], v[16:19], v[120:123]
	v_mfma_f32_16x16x32_bf16 v[112:115], v[212:215], v[24:27], v[64:67]
	v_mfma_f32_16x16x32_bf16 v[64:67], v[0:3], v[32:35], v[140:143]
	v_mfma_f32_16x16x32_bf16 v[100:103], v[8:11], v[36:39], v[64:67]
	v_mfma_f32_16x16x32_bf16 v[64:67], v[208:211], v[32:35], v[220:223]
	v_mfma_f32_16x16x32_bf16 v[96:99], v[212:215], v[36:39], v[64:67]
	v_mfma_f32_16x16x32_bf16 v[64:67], v[0:3], v[48:51], v[108:111]
	v_mfma_f32_16x16x32_bf16 v[84:87], v[8:11], v[56:59], v[64:67]
	v_mfma_f32_16x16x32_bf16 v[64:67], v[208:211], v[48:51], v[104:107]
	v_mfma_f32_16x16x32_bf16 v[80:83], v[212:215], v[56:59], v[64:67]
	v_mfma_f32_16x16x32_bf16 v[64:67], v[0:3], v[236:239], v[224:227]
	v_mfma_f32_16x16x32_bf16 v[68:71], v[8:11], v[240:243], v[64:67]
	v_mfma_f32_16x16x32_bf16 v[64:67], v[208:211], v[236:239], v[228:231]
	v_mfma_f32_16x16x32_bf16 v[64:67], v[212:215], v[240:243], v[64:67]
	s_barrier
	ds_read_b128 v[140:143], v152
	ds_read_b128 v[220:223], v152 offset:1024
	ds_read_b128 v[224:227], v152 offset:2048
	ds_read_b128 v[152:155], v152 offset:3072
	s_waitcnt vmcnt(0)
	s_barrier
	s_waitcnt lgkmcnt(0)
	v_mfma_f32_16x16x32_bf16 v[92:95], v[140:143], v[16:19], v[92:95]
	v_mfma_f32_16x16x32_bf16 v[16:19], v[224:227], v[16:19], v[88:91]
	v_mfma_f32_16x16x32_bf16 v[120:123], v[152:155], v[24:27], v[16:19]
	v_mfma_f32_16x16x32_bf16 v[16:19], v[140:143], v[32:35], v[156:159]
	v_mfma_f32_16x16x32_bf16 v[104:107], v[220:223], v[36:39], v[16:19]
	v_mfma_f32_16x16x32_bf16 v[16:19], v[224:227], v[32:35], v[188:191]
	v_mfma_f32_16x16x32_bf16 v[108:111], v[152:155], v[36:39], v[16:19]
	v_mfma_f32_16x16x32_bf16 v[16:19], v[140:143], v[48:51], v[76:79]
	v_mfma_f32_16x16x32_bf16 v[124:127], v[220:223], v[24:27], v[92:95]
	v_mfma_f32_16x16x32_bf16 v[92:95], v[220:223], v[56:59], v[16:19]
	v_mfma_f32_16x16x32_bf16 v[16:19], v[224:227], v[48:51], v[72:75]
	v_mfma_f32_16x16x32_bf16 v[88:91], v[152:155], v[56:59], v[16:19]
	v_mfma_f32_16x16x32_bf16 v[16:19], v[140:143], v[236:239], v[192:195]
	v_mfma_f32_16x16x32_bf16 v[72:75], v[220:223], v[240:243], v[16:19]
	v_mfma_f32_16x16x32_bf16 v[16:19], v[224:227], v[236:239], v[196:199]
	v_mfma_f32_16x16x32_bf16 v[76:79], v[152:155], v[240:243], v[16:19]
	s_barrier
	ds_read_b128 v[156:159], v131 offset:49152
	ds_read_b128 v[186:189], v131 offset:50176
	ds_read_b128 v[190:193], v174 offset:49152
	ds_read_b128 v[194:197], v174 offset:50176
	ds_read_b128 v[228:231], v175 offset:49152
	ds_read_b128 v[236:239], v175 offset:50176
	ds_read_b128 v[240:243], v177 offset:49152
	ds_read_b128 v[244:247], v177 offset:50176
	s_barrier
	s_waitcnt lgkmcnt(0)
	v_mfma_f32_16x16x32_bf16 v[16:19], v[0:3], v[156:159], v[60:63]
	v_mfma_f32_16x16x32_bf16 v[56:59], v[8:11], v[186:189], v[16:19]
	v_mfma_f32_16x16x32_bf16 v[16:19], v[208:211], v[156:159], v[216:219]
	v_mfma_f32_16x16x32_bf16 v[48:51], v[212:215], v[186:189], v[16:19]
	v_mfma_f32_16x16x32_bf16 v[16:19], v[0:3], v[190:193], v[52:55]
	v_mfma_f32_16x16x32_bf16 v[36:39], v[8:11], v[194:197], v[16:19]
	v_mfma_f32_16x16x32_bf16 v[16:19], v[208:211], v[190:193], v[232:235]
	v_mfma_f32_16x16x32_bf16 v[32:35], v[212:215], v[194:197], v[16:19]
	v_mfma_f32_16x16x32_bf16 v[16:19], v[0:3], v[228:231], v[44:47]
	v_mfma_f32_16x16x32_bf16 v[0:3], v[0:3], v[240:243], v[144:147]
	v_mfma_f32_16x16x32_bf16 v[24:27], v[8:11], v[236:239], v[16:19]
	v_mfma_f32_16x16x32_bf16 v[16:19], v[208:211], v[228:231], v[40:43]
	v_mfma_f32_16x16x32_bf16 v[8:11], v[8:11], v[244:247], v[0:3]
	v_mfma_f32_16x16x32_bf16 v[0:3], v[208:211], v[240:243], v[148:151]
	v_mfma_f32_16x16x32_bf16 v[16:19], v[212:215], v[236:239], v[16:19]
	v_mfma_f32_16x16x32_bf16 v[0:3], v[212:215], v[244:247], v[0:3]
	v_mfma_f32_16x16x32_bf16 v[28:31], v[140:143], v[156:159], v[28:31]
	v_mfma_f32_16x16x32_bf16 v[60:63], v[220:223], v[186:189], v[28:31]
	v_mfma_f32_16x16x32_bf16 v[28:31], v[224:227], v[156:159], v[178:181]
	v_mfma_f32_16x16x32_bf16 v[20:23], v[140:143], v[190:193], v[20:23]
	v_mfma_f32_16x16x32_bf16 v[12:15], v[140:143], v[228:231], v[12:15]
	v_mfma_f32_16x16x32_bf16 v[52:55], v[152:155], v[186:189], v[28:31]
	v_mfma_f32_16x16x32_bf16 v[40:43], v[220:223], v[194:197], v[20:23]
	v_mfma_f32_16x16x32_bf16 v[20:23], v[224:227], v[190:193], v[182:185]
	v_mfma_f32_16x16x32_bf16 v[28:31], v[220:223], v[236:239], v[12:15]
	v_mfma_f32_16x16x32_bf16 v[12:15], v[224:227], v[228:231], v[200:203]
	v_mfma_f32_16x16x32_bf16 v[4:7], v[140:143], v[240:243], v[4:7]
	v_mfma_f32_16x16x32_bf16 v[44:47], v[152:155], v[194:197], v[20:23]
	v_mfma_f32_16x16x32_bf16 v[20:23], v[152:155], v[236:239], v[12:15]
	v_mfma_f32_16x16x32_bf16 v[12:15], v[220:223], v[244:247], v[4:7]
	v_mfma_f32_16x16x32_bf16 v[4:7], v[224:227], v[240:243], v[204:207]
	v_mfma_f32_16x16x32_bf16 v[4:7], v[152:155], v[244:247], v[4:7]
	s_cmpk_gt_u32 s0, 0xff
	s_barrier
	s_cbranch_scc1 .LBB0_1295
	s_barrier

; #define STAGE(P,BASE,LD,br,kt) do{long _g=(long)(br)*(LD)+(long)(kt)*BK; \
;     _Pragma("unroll") for(int _i=0;_i<2;++_i){int _b=tid*16+_i*8192;int _r,_c;stage_rc(_b,_r,_c); \
;       __builtin_amdgcn_global_load_lds((const unsigned*)((BASE)+_g+(long)_r*(LD)+_c), \
;         (unsigned*)((char*)(P)+_b),16,0,0);}}while(0)
; #define STAGE(P,BASE,LD,br,kt) do{long _g=(long)(br)*(LD)+(long)(kt)*BK; \
;     _Pragma("unroll") for(int _i=0;_i<2;++_i){int _b=tid*16+_i*8192;int _r,_c;stage_rc(_b,_r,_c); \
;       __builtin_amdgcn_global_load_lds((const unsigned*)((BASE)+_g+(long)_r*(LD)+_c), \
;         (unsigned*)((char*)(P)+_b),16,0,0);}}while(0)
; #define LDA(dst,b,h) _Pragma("unroll") for(int m=0;m<4;++m) _Pragma("unroll") for(int k=0;k<2;++k) \
;     dst[m][k]=*reinterpret_cast<const bf16x8*>((char*)SA(b,h)+lds_byte(wr*64+m*16+fr,k*32+fq*8))
; #define LDB(dst,b,h) _Pragma("unroll") for(int n=0;n<2;++n) _Pragma("unroll") for(int k=0;k<2;++k) \
;     dst[n][k]=*reinterpret_cast<const bf16x8*>((char*)SB(b,h)+lds_byte(wc*32+n*16+fr,k*32+fq*8))
; #define MMA(ai,bj,At_,Bt_) do{__builtin_amdgcn_s_setprio(1); \
;     _Pragma("unroll") for(int m=0;m<4;++m) _Pragma("unroll") for(int n=0;n<2;++n) _Pragma("unroll") for(int k=0;k<2;++k) \
;       acc[ai][bj][m][n]=__builtin_amdgcn_mfma_f32_16x16x32_bf16(Bt_[n][k],At_[m][k],acc[ai][bj][m][n],0,0,0); \
;     __builtin_amdgcn_s_setprio(0);}while(0)
; #define WAIT_L(n) asm volatile("s_waitcnt lgkmcnt(" #n ")":::"memory")
; #define BAR __builtin_amdgcn_s_barrier()
; #define SCHED __builtin_amdgcn_sched_barrier(0)
; DEVINL void gemm8_mainloop(const u16* A, long lda, const u16* Bt, long ldb, int K, int brow, int bcol, f32x4 (&acc)[2][2][4][2], char* smem, int tid) {
;     ...
;     LDB(B0,0,0); SCHED; LDA(At,0,0); STAGE(SA(1,1),A,lda,brow+HALF,t+1);
;     WAIT_L(8); BAR; WAIT_L(0); MMA(0,0,At,B0); BAR; SCHED;
;     LDB(B1,0,1); STAGE(SB(0,0),Bt,ldb,bcol,t+2);
;     BAR; WAIT_L(0); MMA(0,1,At,B1); BAR;
;     LDA(At,0,1); STAGE(SA(0,0),A,lda,brow,t+2);
;     BAR; WAIT_L(0); MMA(1,0,At,B0); BAR; SCHED;
.LBB0_1871:
	ds_read_b128 v[178:181], v163
	ds_read_b128 v[182:185], v163 offset:1024
	ds_read_b128 v[186:189], v163 offset:2048
	ds_read_b128 v[190:193], v163 offset:3072
	v_add_u32_e32 v174, 0xc000, v152
	v_lshl_add_u64 v[242:243], s[94:95], 0, v[146:147]
	v_readfirstlane_b32 s27, v174
	v_add_u32_e32 v175, 0xe000, v152
	v_add_u32_e32 v171, s25, v162
	v_add_u32_e32 v172, s37, v162
	v_add_u32_e32 v173, s38, v162
	v_lshl_add_u64 v[164:165], v[242:243], 0, s[2:3]
	s_mov_b32 m0, s27
	v_lshl_add_u64 v[244:245], s[94:95], 0, v[148:149]
	v_readfirstlane_b32 s27, v175
	ds_read_b128 v[166:169], v153
	ds_read_b128 v[194:197], v153 offset:1024
	ds_read_b128 v[198:201], v171
	ds_read_b128 v[202:205], v171 offset:1024
	ds_read_b128 v[206:209], v172
	ds_read_b128 v[210:213], v172 offset:1024
	ds_read_b128 v[214:217], v173
	ds_read_b128 v[218:221], v173 offset:1024
	global_load_lds_dwordx4 v[164:165], off
	v_lshl_add_u64 v[164:165], v[244:245], 0, s[2:3]
	s_mov_b32 m0, s27
	s_nop 0
	global_load_lds_dwordx4 v[164:165], off
	s_waitcnt lgkmcnt(8)
	s_barrier
	s_waitcnt lgkmcnt(0)
	v_mfma_f32_16x16x32_bf16 v[124:127], v[178:181], v[166:169], v[124:127]
	v_mfma_f32_16x16x32_bf16 v[120:123], v[186:189], v[166:169], v[120:123]
	v_mfma_f32_16x16x32_bf16 v[116:119], v[178:181], v[198:201], v[116:119]
	v_mfma_f32_16x16x32_bf16 v[112:115], v[186:189], v[198:201], v[112:115]
	v_mfma_f32_16x16x32_bf16 v[108:111], v[178:181], v[206:209], v[108:111]
	v_mfma_f32_16x16x32_bf16 v[104:107], v[186:189], v[206:209], v[104:107]
	v_mfma_f32_16x16x32_bf16 v[100:103], v[178:181], v[214:217], v[100:103]
	v_mfma_f32_16x16x32_bf16 v[96:99], v[186:189], v[214:217], v[96:99]
	v_mfma_f32_16x16x32_bf16 v[124:127], v[182:185], v[194:197], v[124:127]
	v_mfma_f32_16x16x32_bf16 v[120:123], v[190:193], v[194:197], v[120:123]
	v_mfma_f32_16x16x32_bf16 v[116:119], v[182:185], v[202:205], v[116:119]
	v_mfma_f32_16x16x32_bf16 v[112:115], v[190:193], v[202:205], v[112:115]
	v_mfma_f32_16x16x32_bf16 v[108:111], v[182:185], v[210:213], v[108:111]
	v_mfma_f32_16x16x32_bf16 v[104:107], v[190:193], v[210:213], v[104:107]
	v_mfma_f32_16x16x32_bf16 v[100:103], v[182:185], v[218:221], v[100:103]
	v_mfma_f32_16x16x32_bf16 v[96:99], v[190:193], v[218:221], v[96:99]
	s_barrier
	v_add_u32_e32 v164, s30, v154
	v_lshl_add_u64 v[246:247], s[94:95], 0, v[142:143]
	v_readfirstlane_b32 s27, v164
	v_add_u32_e32 v165, 0x2000, v164
	v_lshl_add_u64 v[238:239], v[246:247], 0, s[4:5]
	s_mov_b32 m0, s27
	v_lshl_add_u64 v[248:249], s[94:95], 0, v[144:145]
	v_readfirstlane_b32 s27, v165
	ds_read_b128 v[222:225], v160
	ds_read_b128 v[226:229], v160 offset:1024
	ds_read_b128 v[230:233], v160 offset:2048
	ds_read_b128 v[234:237], v160 offset:3072
	global_load_lds_dwordx4 v[238:239], off
	v_lshl_add_u64 v[238:239], v[248:249], 0, s[4:5]
	s_mov_b32 m0, s27
	s_nop 0
	global_load_lds_dwordx4 v[238:239], off
	s_barrier
	s_waitcnt lgkmcnt(0)
	v_mfma_f32_16x16x32_bf16 v[92:95], v[222:225], v[166:169], v[92:95]
	v_mfma_f32_16x16x32_bf16 v[88:91], v[230:233], v[166:169], v[88:91]
	v_mfma_f32_16x16x32_bf16 v[84:87], v[222:225], v[198:201], v[84:87]
	v_mfma_f32_16x16x32_bf16 v[80:83], v[230:233], v[198:201], v[80:83]
	v_mfma_f32_16x16x32_bf16 v[76:79], v[222:225], v[206:209], v[76:79]
	v_mfma_f32_16x16x32_bf16 v[72:75], v[230:233], v[206:209], v[72:75]
	v_mfma_f32_16x16x32_bf16 v[68:71], v[222:225], v[214:217], v[68:71]
	v_mfma_f32_16x16x32_bf16 v[64:67], v[230:233], v[214:217], v[64:67]
	v_mfma_f32_16x16x32_bf16 v[92:95], v[226:229], v[194:197], v[92:95]
	v_mfma_f32_16x16x32_bf16 v[88:91], v[234:237], v[194:197], v[88:91]
	v_mfma_f32_16x16x32_bf16 v[84:87], v[226:229], v[202:205], v[84:87]
	v_mfma_f32_16x16x32_bf16 v[80:83], v[234:237], v[202:205], v[80:83]
	v_mfma_f32_16x16x32_bf16 v[76:79], v[226:229], v[210:213], v[76:79]
	v_mfma_f32_16x16x32_bf16 v[72:75], v[234:237], v[210:213], v[72:75]
	v_mfma_f32_16x16x32_bf16 v[68:71], v[226:229], v[218:221], v[68:71]
	v_mfma_f32_16x16x32_bf16 v[64:67], v[234:237], v[218:221], v[64:67]
	v_readfirstlane_b32 s27, v152
	v_lshl_add_u64 v[166:167], v[242:243], 0, s[6:7]
	s_mov_b32 m0, s27
	s_barrier
	ds_read_b128 v[194:197], v153 offset:16384
	ds_read_b128 v[198:201], v153 offset:17408
	ds_read_b128 v[202:205], v171 offset:16384
	ds_read_b128 v[206:209], v171 offset:17408
	ds_read_b128 v[210:213], v172 offset:16384
	ds_read_b128 v[214:217], v172 offset:17408
	ds_read_b128 v[218:221], v173 offset:16384
	ds_read_b128 v[238:241], v173 offset:17408
	global_load_lds_dwordx4 v[166:167], off
	v_add_u32_e32 v166, 0x2000, v152
	v_lshl_add_u64 v[168:169], v[244:245], 0, s[6:7]
	v_readfirstlane_b32 s27, v166
	s_mov_b32 m0, s27
	s_nop 0
	global_load_lds_dwordx4 v[168:169], off
	s_barrier
	s_waitcnt lgkmcnt(0)
	v_mfma_f32_16x16x32_bf16 v[60:63], v[178:181], v[194:197], v[60:63]
	v_mfma_f32_16x16x32_bf16 v[56:59], v[186:189], v[194:197], v[56:59]
	v_mfma_f32_16x16x32_bf16 v[52:55], v[178:181], v[202:205], v[52:55]
	v_mfma_f32_16x16x32_bf16 v[48:51], v[186:189], v[202:205], v[48:51]
	v_mfma_f32_16x16x32_bf16 v[44:47], v[178:181], v[210:213], v[44:47]
	v_mfma_f32_16x16x32_bf16 v[40:43], v[186:189], v[210:213], v[40:43]
	v_mfma_f32_16x16x32_bf16 v[36:39], v[178:181], v[218:221], v[36:39]
	v_mfma_f32_16x16x32_bf16 v[32:35], v[186:189], v[218:221], v[32:35]
	v_mfma_f32_16x16x32_bf16 v[60:63], v[182:185], v[198:201], v[60:63]
	v_mfma_f32_16x16x32_bf16 v[56:59], v[190:193], v[198:201], v[56:59]
	v_mfma_f32_16x16x32_bf16 v[52:55], v[182:185], v[206:209], v[52:55]
	v_mfma_f32_16x16x32_bf16 v[48:51], v[190:193], v[206:209], v[48:51]
	v_mfma_f32_16x16x32_bf16 v[44:47], v[182:185], v[214:217], v[44:47]
	v_mfma_f32_16x16x32_bf16 v[40:43], v[190:193], v[214:217], v[40:43]
	v_mfma_f32_16x16x32_bf16 v[36:39], v[182:185], v[238:241], v[36:39]
	v_mfma_f32_16x16x32_bf16 v[32:35], v[190:193], v[238:241], v[32:35]
	s_barrier
; #define STAGE(P,BASE,LD,br,kt) do{long _g=(long)(br)*(LD)+(long)(kt)*BK; \
;     _Pragma("unroll") for(int _i=0;_i<2;++_i){int _b=tid*16+_i*8192;int _r,_c;stage_rc(_b,_r,_c); \
;       __builtin_amdgcn_global_load_lds((const unsigned*)((BASE)+_g+(long)_r*(LD)+_c), \
;         (unsigned*)((char*)(P)+_b),16,0,0);}}while(0)
; #define STAGE(P,BASE,LD,br,kt) do{long _g=(long)(br)*(LD)+(long)(kt)*BK; \
;     _Pragma("unroll") for(int _i=0;_i<2;++_i){int _b=tid*16+_i*8192;int _r,_c;stage_rc(_b,_r,_c); \
;       __builtin_amdgcn_global_load_lds((const unsigned*)((BASE)+_g+(long)_r*(LD)+_c), \
;         (unsigned*)((char*)(P)+_b),16,0,0);}}while(0)
; #define LDA(dst,b,h) _Pragma("unroll") for(int m=0;m<4;++m) _Pragma("unroll") for(int k=0;k<2;++k) \
;     dst[m][k]=*reinterpret_cast<const bf16x8*>((char*)SA(b,h)+lds_byte(wr*64+m*16+fr,k*32+fq*8))
; #define LDB(dst,b,h) _Pragma("unroll") for(int n=0;n<2;++n) _Pragma("unroll") for(int k=0;k<2;++k) \
;     dst[n][k]=*reinterpret_cast<const bf16x8*>((char*)SB(b,h)+lds_byte(wc*32+n*16+fr,k*32+fq*8))
; #define MMA(ai,bj,At_,Bt_) do{__builtin_amdgcn_s_setprio(1); \
;     _Pragma("unroll") for(int m=0;m<4;++m) _Pragma("unroll") for(int n=0;n<2;++n) _Pragma("unroll") for(int k=0;k<2;++k) \
;       acc[ai][bj][m][n]=__builtin_amdgcn_mfma_f32_16x16x32_bf16(Bt_[n][k],At_[m][k],acc[ai][bj][m][n],0,0,0); \
;     __builtin_amdgcn_s_setprio(0);}while(0)
; #define WAIT_V(n) asm volatile("s_waitcnt vmcnt(" #n ")":::"memory")
; #define WAIT_L(n) asm volatile("s_waitcnt lgkmcnt(" #n ")":::"memory")
; #define BAR __builtin_amdgcn_s_barrier()
; #define SCHED __builtin_amdgcn_sched_barrier(0)
; DEVINL void gemm8_mainloop(const u16* A, long lda, const u16* Bt, long ldb, int K, int brow, int bcol, f32x4 (&acc)[2][2][4][2], char* smem, int tid) {
;     ...
;     STAGE(SB(0,1),Bt,ldb,bcol+HALF,t+2);
;     WAIT_V(6); BAR; MMA(1,1,At,B1); BAR;
;     LDB(B0,1,0); SCHED; LDA(At,1,0); STAGE(SA(0,1),A,lda,brow+HALF,t+2);
;     WAIT_L(8); BAR; WAIT_L(0); MMA(0,0,At,B0); BAR; SCHED;
;     LDB(B1,1,1); STAGE(SB(1,0),Bt,ldb,bcol,t+3);
;     BAR; WAIT_L(0); MMA(0,1,At,B1); BAR;
;     LDA(At,1,1); STAGE(SA(1,0),A,lda,brow,t+3);
	v_add_u32_e32 v167, s31, v154
	v_lshl_add_u64 v[168:169], v[246:247], 0, s[8:9]
	v_readfirstlane_b32 s27, v167
	s_mov_b32 m0, s27
	v_lshl_add_u64 v[178:179], v[248:249], 0, s[8:9]
	global_load_lds_dwordx4 v[168:169], off
	v_add_u32_e32 v168, 0x2000, v167
	s_nop 0
	v_readfirstlane_b32 s27, v168
	s_mov_b32 m0, s27
	s_nop 0
	global_load_lds_dwordx4 v[178:179], off
	s_waitcnt vmcnt(6)
	s_barrier
	v_mfma_f32_16x16x32_bf16 v[28:31], v[222:225], v[194:197], v[28:31]
	v_mfma_f32_16x16x32_bf16 v[24:27], v[230:233], v[194:197], v[24:27]
	v_mfma_f32_16x16x32_bf16 v[20:23], v[222:225], v[202:205], v[20:23]
	v_mfma_f32_16x16x32_bf16 v[16:19], v[230:233], v[202:205], v[16:19]
	v_mfma_f32_16x16x32_bf16 v[12:15], v[222:225], v[210:213], v[12:15]
	v_mfma_f32_16x16x32_bf16 v[8:11], v[230:233], v[210:213], v[8:11]
	v_mfma_f32_16x16x32_bf16 v[4:7], v[222:225], v[218:221], v[4:7]
	v_mfma_f32_16x16x32_bf16 v[0:3], v[230:233], v[218:221], v[0:3]
	v_mfma_f32_16x16x32_bf16 v[28:31], v[226:229], v[198:201], v[28:31]
	v_mfma_f32_16x16x32_bf16 v[24:27], v[234:237], v[198:201], v[24:27]
	v_mfma_f32_16x16x32_bf16 v[20:23], v[226:229], v[206:209], v[20:23]
	v_mfma_f32_16x16x32_bf16 v[16:19], v[234:237], v[206:209], v[16:19]
	v_mfma_f32_16x16x32_bf16 v[12:15], v[226:229], v[214:217], v[12:15]
	v_mfma_f32_16x16x32_bf16 v[8:11], v[234:237], v[214:217], v[8:11]
	v_mfma_f32_16x16x32_bf16 v[4:7], v[226:229], v[238:241], v[4:7]
	v_mfma_f32_16x16x32_bf16 v[0:3], v[234:237], v[238:241], v[0:3]
	s_barrier
	ds_read_b128 v[178:181], v156
	ds_read_b128 v[182:185], v156 offset:1024
	ds_read_b128 v[186:189], v156 offset:2048
	ds_read_b128 v[190:193], v156 offset:3072
	v_add_u32_e32 v169, 0x4000, v152
	v_add_u32_e32 v170, 0x6000, v152
	v_readfirstlane_b32 s27, v169
	v_lshl_add_u64 v[226:227], v[242:243], 0, s[10:11]
	s_mov_b32 m0, s27
	v_readfirstlane_b32 s27, v170
	ds_read_b128 v[194:197], v153 offset:32768
	ds_read_b128 v[198:201], v153 offset:33792
	ds_read_b128 v[202:205], v171 offset:32768
	ds_read_b128 v[206:209], v171 offset:33792
	ds_read_b128 v[210:213], v172 offset:32768
	ds_read_b128 v[214:217], v172 offset:33792
	ds_read_b128 v[218:221], v173 offset:32768
	ds_read_b128 v[222:225], v173 offset:33792
	global_load_lds_dwordx4 v[226:227], off
	v_lshl_add_u64 v[226:227], v[244:245], 0, s[10:11]
	s_mov_b32 m0, s27
	s_nop 0
	global_load_lds_dwordx4 v[226:227], off
	s_waitcnt lgkmcnt(8)
	s_barrier
	s_waitcnt lgkmcnt(0)
	v_mfma_f32_16x16x32_bf16 v[124:127], v[178:181], v[194:197], v[124:127]
	v_mfma_f32_16x16x32_bf16 v[120:123], v[186:189], v[194:197], v[120:123]
	v_mfma_f32_16x16x32_bf16 v[116:119], v[178:181], v[202:205], v[116:119]
	v_mfma_f32_16x16x32_bf16 v[112:115], v[186:189], v[202:205], v[112:115]
	v_mfma_f32_16x16x32_bf16 v[108:111], v[178:181], v[210:213], v[108:111]
	v_mfma_f32_16x16x32_bf16 v[104:107], v[186:189], v[210:213], v[104:107]
	v_mfma_f32_16x16x32_bf16 v[100:103], v[178:181], v[218:221], v[100:103]
	v_mfma_f32_16x16x32_bf16 v[96:99], v[186:189], v[218:221], v[96:99]
	v_mfma_f32_16x16x32_bf16 v[124:127], v[182:185], v[198:201], v[124:127]
	v_mfma_f32_16x16x32_bf16 v[120:123], v[190:193], v[198:201], v[120:123]
	v_mfma_f32_16x16x32_bf16 v[116:119], v[182:185], v[206:209], v[116:119]
	v_mfma_f32_16x16x32_bf16 v[112:115], v[190:193], v[206:209], v[112:115]
	v_mfma_f32_16x16x32_bf16 v[108:111], v[182:185], v[214:217], v[108:111]
	v_mfma_f32_16x16x32_bf16 v[104:107], v[190:193], v[214:217], v[104:107]
	v_mfma_f32_16x16x32_bf16 v[100:103], v[182:185], v[222:225], v[100:103]
	v_mfma_f32_16x16x32_bf16 v[96:99], v[190:193], v[222:225], v[96:99]
	s_barrier
	v_readfirstlane_b32 s27, v157
	v_add_u32_e32 v177, 0x2000, v157
	v_lshl_add_u64 v[250:251], v[246:247], 0, s[12:13]
	s_mov_b32 m0, s27
	v_readfirstlane_b32 s27, v177
	ds_read_b128 v[226:229], v155
	ds_read_b128 v[230:233], v155 offset:1024
	ds_read_b128 v[234:237], v155 offset:2048
	ds_read_b128 v[238:241], v155 offset:3072
	global_load_lds_dwordx4 v[250:251], off
	v_lshl_add_u64 v[250:251], v[248:249], 0, s[12:13]
	s_mov_b32 m0, s27
	s_nop 0
	global_load_lds_dwordx4 v[250:251], off
	s_barrier
	s_waitcnt lgkmcnt(0)
	v_mfma_f32_16x16x32_bf16 v[92:95], v[226:229], v[194:197], v[92:95]
	v_mfma_f32_16x16x32_bf16 v[88:91], v[234:237], v[194:197], v[88:91]
	v_mfma_f32_16x16x32_bf16 v[84:87], v[226:229], v[202:205], v[84:87]
	v_mfma_f32_16x16x32_bf16 v[80:83], v[234:237], v[202:205], v[80:83]
	v_mfma_f32_16x16x32_bf16 v[76:79], v[226:229], v[210:213], v[76:79]
	v_mfma_f32_16x16x32_bf16 v[72:75], v[234:237], v[210:213], v[72:75]
	v_mfma_f32_16x16x32_bf16 v[68:71], v[226:229], v[218:221], v[68:71]
	v_mfma_f32_16x16x32_bf16 v[64:67], v[234:237], v[218:221], v[64:67]
	v_mfma_f32_16x16x32_bf16 v[92:95], v[230:233], v[198:201], v[92:95]
	v_mfma_f32_16x16x32_bf16 v[88:91], v[238:241], v[198:201], v[88:91]
	v_mfma_f32_16x16x32_bf16 v[84:87], v[230:233], v[206:209], v[84:87]
	v_mfma_f32_16x16x32_bf16 v[80:83], v[238:241], v[206:209], v[80:83]
	v_mfma_f32_16x16x32_bf16 v[76:79], v[230:233], v[214:217], v[76:79]
	v_mfma_f32_16x16x32_bf16 v[72:75], v[238:241], v[214:217], v[72:75]
	v_mfma_f32_16x16x32_bf16 v[68:71], v[230:233], v[222:225], v[68:71]
	v_mfma_f32_16x16x32_bf16 v[64:67], v[238:241], v[222:225], v[64:67]
	v_readfirstlane_b32 s27, v158
	v_lshl_add_u64 v[242:243], v[242:243], 0, s[14:15]
	s_mov_b32 m0, s27
	v_readfirstlane_b32 s27, v159
	s_barrier
	ds_read_b128 v[194:197], v153 offset:49152
	ds_read_b128 v[198:201], v153 offset:50176
	ds_read_b128 v[202:205], v171 offset:49152
	ds_read_b128 v[206:209], v171 offset:50176
	ds_read_b128 v[210:213], v172 offset:49152
	ds_read_b128 v[214:217], v172 offset:50176
	ds_read_b128 v[218:221], v173 offset:49152
	ds_read_b128 v[222:225], v173 offset:50176
	global_load_lds_dwordx4 v[242:243], off
	v_lshl_add_u64 v[242:243], v[244:245], 0, s[14:15]
	s_mov_b32 m0, s27
	s_nop 0
	global_load_lds_dwordx4 v[242:243], off
	s_barrier
; #define STAGE(P,BASE,LD,br,kt) do{long _g=(long)(br)*(LD)+(long)(kt)*BK; \
;     _Pragma("unroll") for(int _i=0;_i<2;++_i){int _b=tid*16+_i*8192;int _r,_c;stage_rc(_b,_r,_c); \
;       __builtin_amdgcn_global_load_lds((const unsigned*)((BASE)+_g+(long)_r*(LD)+_c), \
;         (unsigned*)((char*)(P)+_b),16,0,0);}}while(0)
; #define STAGE(P,BASE,LD,br,kt) do{long _g=(long)(br)*(LD)+(long)(kt)*BK; \
;     _Pragma("unroll") for(int _i=0;_i<2;++_i){int _b=tid*16+_i*8192;int _r,_c;stage_rc(_b,_r,_c); \
;       __builtin_amdgcn_global_load_lds((const unsigned*)((BASE)+_g+(long)_r*(LD)+_c), \
;         (unsigned*)((char*)(P)+_b),16,0,0);}}while(0)
; #define LDA(dst,b,h) _Pragma("unroll") for(int m=0;m<4;++m) _Pragma("unroll") for(int k=0;k<2;++k) \
;     dst[m][k]=*reinterpret_cast<const bf16x8*>((char*)SA(b,h)+lds_byte(wr*64+m*16+fr,k*32+fq*8))
; #define LDB(dst,b,h) _Pragma("unroll") for(int n=0;n<2;++n) _Pragma("unroll") for(int k=0;k<2;++k) \
;     dst[n][k]=*reinterpret_cast<const bf16x8*>((char*)SB(b,h)+lds_byte(wc*32+n*16+fr,k*32+fq*8))
; #define MMA(ai,bj,At_,Bt_) do{__builtin_amdgcn_s_setprio(1); \
;     _Pragma("unroll") for(int m=0;m<4;++m) _Pragma("unroll") for(int n=0;n<2;++n) _Pragma("unroll") for(int k=0;k<2;++k) \
;       acc[ai][bj][m][n]=__builtin_amdgcn_mfma_f32_16x16x32_bf16(Bt_[n][k],At_[m][k],acc[ai][bj][m][n],0,0,0); \
;     __builtin_amdgcn_s_setprio(0);}while(0)
; #define WAIT_V(n) asm volatile("s_waitcnt vmcnt(" #n ")":::"memory")
; #define WAIT_L(n) asm volatile("s_waitcnt lgkmcnt(" #n ")":::"memory")
; #define BAR __builtin_amdgcn_s_barrier()
; #define SCHED __builtin_amdgcn_sched_barrier(0)
; DEVINL void gemm8_mainloop(const u16* A, long lda, const u16* Bt, long ldb, int K, int brow, int bcol, f32x4 (&acc)[2][2][4][2], char* smem, int tid) {
;     ...
;     BAR; WAIT_L(0); MMA(1,0,At,B0); BAR; SCHED;
;     STAGE(SB(1,1),Bt,ldb,bcol+HALF,t+3);
;     WAIT_V(6); BAR; MMA(1,1,At,B1); BAR;
;   }
;   { LDB(B0,0,0); LDA(At,0,0); STAGE(SA(1,1),A,lda,brow+HALF,nt-1);
;     BAR; WAIT_L(0); MMA(0,0,At,B0); BAR;
;     LDB(B1,0,1); BAR; WAIT_L(0); MMA(0,1,At,B1); BAR;
	s_waitcnt lgkmcnt(0)
	v_mfma_f32_16x16x32_bf16 v[60:63], v[178:181], v[194:197], v[60:63]
	v_mfma_f32_16x16x32_bf16 v[56:59], v[186:189], v[194:197], v[56:59]
	v_mfma_f32_16x16x32_bf16 v[52:55], v[178:181], v[202:205], v[52:55]
	v_mfma_f32_16x16x32_bf16 v[48:51], v[186:189], v[202:205], v[48:51]
	v_mfma_f32_16x16x32_bf16 v[44:47], v[178:181], v[210:213], v[44:47]
	v_mfma_f32_16x16x32_bf16 v[40:43], v[186:189], v[210:213], v[40:43]
	v_mfma_f32_16x16x32_bf16 v[36:39], v[178:181], v[218:221], v[36:39]
	v_mfma_f32_16x16x32_bf16 v[32:35], v[186:189], v[218:221], v[32:35]
	v_mfma_f32_16x16x32_bf16 v[60:63], v[182:185], v[198:201], v[60:63]
	v_mfma_f32_16x16x32_bf16 v[56:59], v[190:193], v[198:201], v[56:59]
	v_mfma_f32_16x16x32_bf16 v[52:55], v[182:185], v[206:209], v[52:55]
	v_mfma_f32_16x16x32_bf16 v[48:51], v[190:193], v[206:209], v[48:51]
	v_mfma_f32_16x16x32_bf16 v[44:47], v[182:185], v[214:217], v[44:47]
	v_mfma_f32_16x16x32_bf16 v[40:43], v[190:193], v[214:217], v[40:43]
	v_mfma_f32_16x16x32_bf16 v[36:39], v[182:185], v[222:225], v[36:39]
	v_mfma_f32_16x16x32_bf16 v[32:35], v[190:193], v[222:225], v[32:35]
	s_barrier
	v_readfirstlane_b32 s27, v161
	v_add_u32_e32 v177, 0x2000, v161
	v_lshl_add_u64 v[178:179], v[246:247], 0, s[16:17]
	s_mov_b32 m0, s27
	v_readfirstlane_b32 s27, v177
	global_load_lds_dwordx4 v[178:179], off
	v_lshl_add_u64 v[178:179], v[248:249], 0, s[16:17]
	s_mov_b32 m0, s27
	s_nop 0
	global_load_lds_dwordx4 v[178:179], off
	s_waitcnt vmcnt(6)
	s_barrier
	v_mfma_f32_16x16x32_bf16 v[28:31], v[226:229], v[194:197], v[28:31]
	v_mfma_f32_16x16x32_bf16 v[24:27], v[234:237], v[194:197], v[24:27]
	v_mfma_f32_16x16x32_bf16 v[20:23], v[226:229], v[202:205], v[20:23]
	v_mfma_f32_16x16x32_bf16 v[16:19], v[234:237], v[202:205], v[16:19]
	v_mfma_f32_16x16x32_bf16 v[12:15], v[226:229], v[210:213], v[12:15]
	v_mfma_f32_16x16x32_bf16 v[8:11], v[234:237], v[210:213], v[8:11]
	v_mfma_f32_16x16x32_bf16 v[4:7], v[226:229], v[218:221], v[4:7]
	v_mfma_f32_16x16x32_bf16 v[0:3], v[234:237], v[218:221], v[0:3]
	v_mfma_f32_16x16x32_bf16 v[28:31], v[230:233], v[198:201], v[28:31]
	v_mfma_f32_16x16x32_bf16 v[24:27], v[238:241], v[198:201], v[24:27]
	v_mfma_f32_16x16x32_bf16 v[20:23], v[230:233], v[206:209], v[20:23]
	v_mfma_f32_16x16x32_bf16 v[16:19], v[238:241], v[206:209], v[16:19]
	v_mfma_f32_16x16x32_bf16 v[12:15], v[230:233], v[214:217], v[12:15]
	v_mfma_f32_16x16x32_bf16 v[8:11], v[238:241], v[214:217], v[8:11]
	v_mfma_f32_16x16x32_bf16 v[4:7], v[230:233], v[222:225], v[4:7]
	v_mfma_f32_16x16x32_bf16 v[0:3], v[238:241], v[222:225], v[0:3]
	s_add_i32 s26, s26, 2
	v_lshl_add_u64 v[142:143], v[142:143], 0, s[18:19]
	v_lshl_add_u64 v[144:145], v[144:145], 0, s[18:19]
	v_lshl_add_u64 v[146:147], v[146:147], 0, s[18:19]
	s_cmp_lt_u32 s26, 28
	v_lshl_add_u64 v[148:149], v[148:149], 0, s[18:19]
	s_barrier
	s_cbranch_scc1 .LBB0_1871
	s_or_b32 s26, s24, 0x80
	s_ashr_i32 s27, s26, 31
	s_lshl_b64 s[26:27], s[26:27], 12
	s_add_u32 s26, s47, s26
	s_addc_u32 s27, s48, s27
	v_lshl_add_u64 v[158:159], v[134:135], 1, s[26:27]
	v_lshl_add_u64 v[138:139], v[138:139], 1, v[158:159]
	v_readfirstlane_b32 s25, v174
	v_lshl_add_u64 v[138:139], v[138:139], 0, s[20:21]
	s_mov_b32 m0, s25
	ds_read_b128 v[142:145], v163
	ds_read_b128 v[146:149], v163 offset:1024
	ds_read_b128 v[178:181], v163 offset:2048
	ds_read_b128 v[182:185], v163 offset:3072
	ds_read_b128 v[186:189], v153
	ds_read_b128 v[190:193], v153 offset:1024
	ds_read_b128 v[194:197], v171
	ds_read_b128 v[198:201], v171 offset:1024
	ds_read_b128 v[202:205], v172
	ds_read_b128 v[206:209], v172 offset:1024
	ds_read_b128 v[210:213], v173
	ds_read_b128 v[214:217], v173 offset:1024
	global_load_lds_dwordx4 v[138:139], off
	v_lshl_add_u64 v[138:139], v[136:137], 1, s[26:27]
	v_lshl_add_u64 v[138:139], v[140:141], 1, v[138:139]
	v_readfirstlane_b32 s25, v175
	v_lshl_add_u64 v[138:139], v[138:139], 0, s[20:21]
	s_mov_b32 m0, s25
	s_nop 0
	global_load_lds_dwordx4 v[138:139], off
	s_barrier
	s_waitcnt lgkmcnt(0)
	v_mfma_f32_16x16x32_bf16 v[124:127], v[142:145], v[186:189], v[124:127]
	v_mfma_f32_16x16x32_bf16 v[120:123], v[178:181], v[186:189], v[120:123]
	v_mfma_f32_16x16x32_bf16 v[116:119], v[142:145], v[194:197], v[116:119]
	v_mfma_f32_16x16x32_bf16 v[112:115], v[178:181], v[194:197], v[112:115]
	v_mfma_f32_16x16x32_bf16 v[100:103], v[142:145], v[210:213], v[100:103]
	v_mfma_f32_16x16x32_bf16 v[96:99], v[178:181], v[210:213], v[96:99]
	v_mfma_f32_16x16x32_bf16 v[124:127], v[146:149], v[190:193], v[124:127]
	v_mfma_f32_16x16x32_bf16 v[120:123], v[182:185], v[190:193], v[120:123]
	v_mfma_f32_16x16x32_bf16 v[116:119], v[146:149], v[198:201], v[116:119]
	v_mfma_f32_16x16x32_bf16 v[112:115], v[182:185], v[198:201], v[112:115]
	v_mfma_f32_16x16x32_bf16 v[108:111], v[142:145], v[202:205], v[108:111]
	v_mfma_f32_16x16x32_bf16 v[104:107], v[178:181], v[202:205], v[104:107]
	v_mfma_f32_16x16x32_bf16 v[100:103], v[146:149], v[214:217], v[100:103]
	v_mfma_f32_16x16x32_bf16 v[96:99], v[182:185], v[214:217], v[96:99]
	v_mfma_f32_16x16x32_bf16 v[138:141], v[146:149], v[206:209], v[108:111]
	v_mfma_f32_16x16x32_bf16 v[218:221], v[182:185], v[206:209], v[104:107]
	s_barrier
	s_nop 1
	s_nop 0
	ds_read_b128 v[104:107], v160
	ds_read_b128 v[108:111], v160 offset:1024
	ds_read_b128 v[222:225], v160 offset:2048
	ds_read_b128 v[158:161], v160 offset:3072
	s_barrier
; #define LDA(dst,b,h) _Pragma("unroll") for(int m=0;m<4;++m) _Pragma("unroll") for(int k=0;k<2;++k) \
;     dst[m][k]=*reinterpret_cast<const bf16x8*>((char*)SA(b,h)+lds_byte(wr*64+m*16+fr,k*32+fq*8))
; #define LDB(dst,b,h) _Pragma("unroll") for(int n=0;n<2;++n) _Pragma("unroll") for(int k=0;k<2;++k) \
;     dst[n][k]=*reinterpret_cast<const bf16x8*>((char*)SB(b,h)+lds_byte(wc*32+n*16+fr,k*32+fq*8))
; #define MMA(ai,bj,At_,Bt_) do{__builtin_amdgcn_s_setprio(1); \
;     _Pragma("unroll") for(int m=0;m<4;++m) _Pragma("unroll") for(int n=0;n<2;++n) _Pragma("unroll") for(int k=0;k<2;++k) \
;       acc[ai][bj][m][n]=__builtin_amdgcn_mfma_f32_16x16x32_bf16(Bt_[n][k],At_[m][k],acc[ai][bj][m][n],0,0,0); \
;     __builtin_amdgcn_s_setprio(0);}while(0)
; #define WAIT_V(n) asm volatile("s_waitcnt vmcnt(" #n ")":::"memory")
; #define WAIT_L(n) asm volatile("s_waitcnt lgkmcnt(" #n ")":::"memory")
; #define BAR __builtin_amdgcn_s_barrier()
; DEVINL void gemm8_mainloop(const u16* A, long lda, const u16* Bt, long ldb, int K, int brow, int bcol, f32x4 (&acc)[2][2][4][2], char* smem, int tid) {
;     ...
;     LDB(B1,0,1); BAR; WAIT_L(0); MMA(0,1,At,B1); BAR;
;     LDA(At,0,1); WAIT_V(4); BAR; WAIT_L(0); MMA(1,0,At,B0); MMA(1,1,At,B1); BAR; }
;   { LDB(B0,1,0); LDA(At,1,0); WAIT_V(2); BAR; WAIT_L(0); MMA(0,0,At,B0); BAR;
	s_waitcnt lgkmcnt(0)
	v_mfma_f32_16x16x32_bf16 v[84:87], v[104:107], v[194:197], v[84:87]
	v_mfma_f32_16x16x32_bf16 v[80:83], v[222:225], v[194:197], v[80:83]
	v_mfma_f32_16x16x32_bf16 v[68:71], v[104:107], v[210:213], v[68:71]
	v_mfma_f32_16x16x32_bf16 v[92:95], v[104:107], v[186:189], v[92:95]
	v_mfma_f32_16x16x32_bf16 v[88:91], v[222:225], v[186:189], v[88:91]
	v_mfma_f32_16x16x32_bf16 v[84:87], v[108:111], v[198:201], v[84:87]
	v_mfma_f32_16x16x32_bf16 v[80:83], v[158:161], v[198:201], v[80:83]
	v_mfma_f32_16x16x32_bf16 v[76:79], v[104:107], v[202:205], v[76:79]
	v_mfma_f32_16x16x32_bf16 v[72:75], v[222:225], v[202:205], v[72:75]
	v_mfma_f32_16x16x32_bf16 v[68:71], v[108:111], v[214:217], v[68:71]
	v_mfma_f32_16x16x32_bf16 v[64:67], v[222:225], v[210:213], v[64:67]
	v_mfma_f32_16x16x32_bf16 v[226:229], v[108:111], v[190:193], v[92:95]
	v_mfma_f32_16x16x32_bf16 v[186:189], v[158:161], v[190:193], v[88:91]
	v_mfma_f32_16x16x32_bf16 v[190:193], v[108:111], v[206:209], v[76:79]
	v_mfma_f32_16x16x32_bf16 v[194:197], v[158:161], v[206:209], v[72:75]
	v_mfma_f32_16x16x32_bf16 v[198:201], v[158:161], v[214:217], v[64:67]
	s_barrier
	s_nop 0
	s_nop 0
	ds_read_b128 v[64:67], v153 offset:16384
	ds_read_b128 v[72:75], v153 offset:17408
	ds_read_b128 v[76:79], v171 offset:16384
	ds_read_b128 v[88:91], v171 offset:17408
	ds_read_b128 v[92:95], v172 offset:16384
	ds_read_b128 v[202:205], v172 offset:17408
	ds_read_b128 v[206:209], v173 offset:16384
	ds_read_b128 v[210:213], v173 offset:17408
	s_waitcnt vmcnt(4)
	s_barrier
	s_waitcnt lgkmcnt(0)
	v_mfma_f32_16x16x32_bf16 v[60:63], v[142:145], v[64:67], v[60:63]
	v_mfma_f32_16x16x32_bf16 v[56:59], v[178:181], v[64:67], v[56:59]
	v_mfma_f32_16x16x32_bf16 v[52:55], v[142:145], v[76:79], v[52:55]
	v_mfma_f32_16x16x32_bf16 v[48:51], v[178:181], v[76:79], v[48:51]
	v_mfma_f32_16x16x32_bf16 v[36:39], v[142:145], v[206:209], v[36:39]
	v_mfma_f32_16x16x32_bf16 v[32:35], v[178:181], v[206:209], v[32:35]
	v_mfma_f32_16x16x32_bf16 v[60:63], v[146:149], v[72:75], v[60:63]
	v_mfma_f32_16x16x32_bf16 v[56:59], v[182:185], v[72:75], v[56:59]
	v_mfma_f32_16x16x32_bf16 v[52:55], v[146:149], v[88:91], v[52:55]
	v_mfma_f32_16x16x32_bf16 v[48:51], v[182:185], v[88:91], v[48:51]
	v_mfma_f32_16x16x32_bf16 v[44:47], v[142:145], v[92:95], v[44:47]
	v_mfma_f32_16x16x32_bf16 v[40:43], v[178:181], v[92:95], v[40:43]
	v_mfma_f32_16x16x32_bf16 v[36:39], v[146:149], v[210:213], v[36:39]
	v_mfma_f32_16x16x32_bf16 v[32:35], v[182:185], v[210:213], v[32:35]
	v_mfma_f32_16x16x32_bf16 v[214:217], v[146:149], v[202:205], v[44:47]
	v_mfma_f32_16x16x32_bf16 v[230:233], v[182:185], v[202:205], v[40:43]
	v_mfma_f32_16x16x32_bf16 v[20:23], v[104:107], v[76:79], v[20:23]
	v_mfma_f32_16x16x32_bf16 v[16:19], v[222:225], v[76:79], v[16:19]
	v_mfma_f32_16x16x32_bf16 v[4:7], v[104:107], v[206:209], v[4:7]
	v_mfma_f32_16x16x32_bf16 v[28:31], v[104:107], v[64:67], v[28:31]
	v_mfma_f32_16x16x32_bf16 v[24:27], v[222:225], v[64:67], v[24:27]
	v_mfma_f32_16x16x32_bf16 v[20:23], v[108:111], v[88:91], v[20:23]
	v_mfma_f32_16x16x32_bf16 v[16:19], v[158:161], v[88:91], v[16:19]
	v_mfma_f32_16x16x32_bf16 v[12:15], v[104:107], v[92:95], v[12:15]
	v_mfma_f32_16x16x32_bf16 v[8:11], v[222:225], v[92:95], v[8:11]
	v_mfma_f32_16x16x32_bf16 v[4:7], v[108:111], v[210:213], v[4:7]
	v_mfma_f32_16x16x32_bf16 v[0:3], v[222:225], v[206:209], v[0:3]
	v_mfma_f32_16x16x32_bf16 v[142:145], v[108:111], v[72:75], v[28:31]
	v_mfma_f32_16x16x32_bf16 v[146:149], v[158:161], v[72:75], v[24:27]
	v_mfma_f32_16x16x32_bf16 v[178:181], v[108:111], v[202:205], v[12:15]
	v_mfma_f32_16x16x32_bf16 v[182:185], v[158:161], v[202:205], v[8:11]
	v_mfma_f32_16x16x32_bf16 v[158:161], v[158:161], v[210:213], v[0:3]
	s_barrier
	s_nop 0
	s_nop 0
	ds_read_b128 v[0:3], v156
	ds_read_b128 v[8:11], v156 offset:1024
	ds_read_b128 v[202:205], v156 offset:2048
	ds_read_b128 v[206:209], v156 offset:3072
	ds_read_b128 v[12:15], v153 offset:32768
	ds_read_b128 v[24:27], v153 offset:33792
	ds_read_b128 v[28:31], v171 offset:32768
	ds_read_b128 v[40:43], v171 offset:33792
	ds_read_b128 v[44:47], v172 offset:32768
	ds_read_b128 v[64:67], v172 offset:33792
	ds_read_b128 v[210:213], v173 offset:32768
	ds_read_b128 v[222:225], v173 offset:33792
	s_waitcnt vmcnt(2)
	s_barrier
; #define LDA(dst,b,h) _Pragma("unroll") for(int m=0;m<4;++m) _Pragma("unroll") for(int k=0;k<2;++k) \
;     dst[m][k]=*reinterpret_cast<const bf16x8*>((char*)SA(b,h)+lds_byte(wr*64+m*16+fr,k*32+fq*8))
; #define LDB(dst,b,h) _Pragma("unroll") for(int n=0;n<2;++n) _Pragma("unroll") for(int k=0;k<2;++k) \
;     dst[n][k]=*reinterpret_cast<const bf16x8*>((char*)SB(b,h)+lds_byte(wc*32+n*16+fr,k*32+fq*8))
; #define MMA(ai,bj,At_,Bt_) do{__builtin_amdgcn_s_setprio(1); \
;     _Pragma("unroll") for(int m=0;m<4;++m) _Pragma("unroll") for(int n=0;n<2;++n) _Pragma("unroll") for(int k=0;k<2;++k) \
;       acc[ai][bj][m][n]=__builtin_amdgcn_mfma_f32_16x16x32_bf16(Bt_[n][k],At_[m][k],acc[ai][bj][m][n],0,0,0); \
;     __builtin_amdgcn_s_setprio(0);}while(0)
; #define WAIT_V(n) asm volatile("s_waitcnt vmcnt(" #n ")":::"memory")
; #define WAIT_L(n) asm volatile("s_waitcnt lgkmcnt(" #n ")":::"memory")
; #define BAR __builtin_amdgcn_s_barrier()
; DEVINL void gemm8_mainloop(const u16* A, long lda, const u16* Bt, long ldb, int K, int brow, int bcol, f32x4 (&acc)[2][2][4][2], char* smem, int tid) {
;     ...
;     LDA(At,0,1); WAIT_V(4); BAR; WAIT_L(0); MMA(1,0,At,B0); MMA(1,1,At,B1); BAR; }
;   { LDB(B0,1,0); LDA(At,1,0); WAIT_V(2); BAR; WAIT_L(0); MMA(0,0,At,B0); BAR;
;     LDB(B1,1,1); WAIT_V(0); BAR; WAIT_L(0); MMA(0,1,At,B1); BAR;
;     LDA(At,1,1); BAR; WAIT_L(0); MMA(1,0,At,B0); MMA(1,1,At,B1); BAR; }
;   if(wr==0)BAR;
	s_waitcnt lgkmcnt(0)
	v_mfma_f32_16x16x32_bf16 v[72:75], v[0:3], v[12:15], v[124:127]
	v_mfma_f32_16x16x32_bf16 v[124:127], v[8:11], v[24:27], v[72:75]
	v_mfma_f32_16x16x32_bf16 v[72:75], v[202:205], v[12:15], v[120:123]
	v_mfma_f32_16x16x32_bf16 v[120:123], v[206:209], v[24:27], v[72:75]
	v_mfma_f32_16x16x32_bf16 v[72:75], v[0:3], v[28:31], v[116:119]
	v_mfma_f32_16x16x32_bf16 v[108:111], v[8:11], v[40:43], v[72:75]
	v_mfma_f32_16x16x32_bf16 v[72:75], v[202:205], v[28:31], v[112:115]
	v_mfma_f32_16x16x32_bf16 v[104:107], v[206:209], v[40:43], v[72:75]
	v_mfma_f32_16x16x32_bf16 v[72:75], v[0:3], v[44:47], v[138:141]
	v_mfma_f32_16x16x32_bf16 v[92:95], v[8:11], v[64:67], v[72:75]
	v_mfma_f32_16x16x32_bf16 v[72:75], v[202:205], v[44:47], v[218:221]
	v_mfma_f32_16x16x32_bf16 v[88:91], v[206:209], v[64:67], v[72:75]
	v_mfma_f32_16x16x32_bf16 v[72:75], v[0:3], v[210:213], v[100:103]
	v_mfma_f32_16x16x32_bf16 v[76:79], v[8:11], v[222:225], v[72:75]
	v_mfma_f32_16x16x32_bf16 v[72:75], v[202:205], v[210:213], v[96:99]
	v_mfma_f32_16x16x32_bf16 v[72:75], v[206:209], v[222:225], v[72:75]
	s_barrier
	ds_read_b128 v[138:141], v155
	ds_read_b128 v[218:221], v155 offset:1024
	ds_read_b128 v[234:237], v155 offset:2048
	ds_read_b128 v[154:157], v155 offset:3072
	s_waitcnt vmcnt(0)
	s_barrier
	s_waitcnt lgkmcnt(0)
	v_mfma_f32_16x16x32_bf16 v[96:99], v[138:141], v[12:15], v[226:229]
	v_mfma_f32_16x16x32_bf16 v[12:15], v[234:237], v[12:15], v[186:189]
	v_mfma_f32_16x16x32_bf16 v[116:119], v[154:157], v[24:27], v[12:15]
	v_mfma_f32_16x16x32_bf16 v[12:15], v[138:141], v[28:31], v[84:87]
	v_mfma_f32_16x16x32_bf16 v[112:115], v[218:221], v[24:27], v[96:99]
	v_mfma_f32_16x16x32_bf16 v[96:99], v[218:221], v[40:43], v[12:15]
	v_mfma_f32_16x16x32_bf16 v[12:15], v[234:237], v[28:31], v[80:83]
	v_mfma_f32_16x16x32_bf16 v[100:103], v[154:157], v[40:43], v[12:15]
	v_mfma_f32_16x16x32_bf16 v[12:15], v[138:141], v[44:47], v[190:193]
	v_mfma_f32_16x16x32_bf16 v[80:83], v[218:221], v[64:67], v[12:15]
	v_mfma_f32_16x16x32_bf16 v[12:15], v[234:237], v[44:47], v[194:197]
	v_mfma_f32_16x16x32_bf16 v[84:87], v[154:157], v[64:67], v[12:15]
	v_mfma_f32_16x16x32_bf16 v[12:15], v[138:141], v[210:213], v[68:71]
	v_mfma_f32_16x16x32_bf16 v[64:67], v[218:221], v[222:225], v[12:15]
	v_mfma_f32_16x16x32_bf16 v[12:15], v[234:237], v[210:213], v[198:201]
	v_mfma_f32_16x16x32_bf16 v[68:71], v[154:157], v[222:225], v[12:15]
	s_barrier
	ds_read_b128 v[186:189], v153 offset:49152
	ds_read_b128 v[190:193], v153 offset:50176
	ds_read_b128 v[194:197], v171 offset:49152
	ds_read_b128 v[198:201], v171 offset:50176
	ds_read_b128 v[210:213], v172 offset:49152
	ds_read_b128 v[222:225], v172 offset:50176
	ds_read_b128 v[226:229], v173 offset:49152
	ds_read_b128 v[172:175], v173 offset:50176
	s_barrier
	s_waitcnt lgkmcnt(0)
	v_mfma_f32_16x16x32_bf16 v[12:15], v[0:3], v[186:189], v[60:63]
	v_mfma_f32_16x16x32_bf16 v[60:63], v[8:11], v[190:193], v[12:15]
	v_mfma_f32_16x16x32_bf16 v[12:15], v[202:205], v[186:189], v[56:59]
	v_mfma_f32_16x16x32_bf16 v[56:59], v[206:209], v[190:193], v[12:15]
	v_mfma_f32_16x16x32_bf16 v[12:15], v[0:3], v[194:197], v[52:55]
	v_mfma_f32_16x16x32_bf16 v[44:47], v[8:11], v[198:201], v[12:15]
	v_mfma_f32_16x16x32_bf16 v[12:15], v[202:205], v[194:197], v[48:51]
	v_mfma_f32_16x16x32_bf16 v[40:43], v[206:209], v[198:201], v[12:15]
	v_mfma_f32_16x16x32_bf16 v[12:15], v[0:3], v[210:213], v[214:217]
	v_mfma_f32_16x16x32_bf16 v[28:31], v[8:11], v[222:225], v[12:15]
	v_mfma_f32_16x16x32_bf16 v[12:15], v[202:205], v[210:213], v[230:233]
	v_mfma_f32_16x16x32_bf16 v[0:3], v[0:3], v[226:229], v[36:39]
	v_mfma_f32_16x16x32_bf16 v[24:27], v[206:209], v[222:225], v[12:15]
	v_mfma_f32_16x16x32_bf16 v[12:15], v[8:11], v[172:175], v[0:3]
	v_mfma_f32_16x16x32_bf16 v[0:3], v[202:205], v[226:229], v[32:35]
	v_mfma_f32_16x16x32_bf16 v[8:11], v[206:209], v[172:175], v[0:3]
	v_mfma_f32_16x16x32_bf16 v[0:3], v[138:141], v[186:189], v[142:145]
	v_mfma_f32_16x16x32_bf16 v[48:51], v[218:221], v[190:193], v[0:3]
	v_mfma_f32_16x16x32_bf16 v[0:3], v[234:237], v[186:189], v[146:149]
	v_mfma_f32_16x16x32_bf16 v[52:55], v[154:157], v[190:193], v[0:3]
	v_mfma_f32_16x16x32_bf16 v[0:3], v[138:141], v[194:197], v[20:23]
	v_mfma_f32_16x16x32_bf16 v[32:35], v[218:221], v[198:201], v[0:3]
	v_mfma_f32_16x16x32_bf16 v[0:3], v[234:237], v[194:197], v[16:19]
	v_mfma_f32_16x16x32_bf16 v[36:39], v[154:157], v[198:201], v[0:3]
	v_mfma_f32_16x16x32_bf16 v[0:3], v[138:141], v[210:213], v[178:181]
	v_mfma_f32_16x16x32_bf16 v[16:19], v[218:221], v[222:225], v[0:3]
	v_mfma_f32_16x16x32_bf16 v[0:3], v[234:237], v[210:213], v[182:185]
	v_mfma_f32_16x16x32_bf16 v[20:23], v[154:157], v[222:225], v[0:3]
	v_mfma_f32_16x16x32_bf16 v[0:3], v[138:141], v[226:229], v[4:7]
	v_mfma_f32_16x16x32_bf16 v[4:7], v[234:237], v[226:229], v[158:161]
	v_mfma_f32_16x16x32_bf16 v[0:3], v[218:221], v[172:175], v[0:3]
	v_mfma_f32_16x16x32_bf16 v[4:7], v[154:157], v[172:175], v[4:7]
	s_cmpk_gt_u32 s29, 0xff
	s_barrier
	s_cbranch_scc1 .LBB0_1874
	s_barrier

; #define STAGE(P,BASE,LD,br,kt) do{long _g=(long)(br)*(LD)+(long)(kt)*BK; \
;     _Pragma("unroll") for(int _i=0;_i<2;++_i){int _b=tid*16+_i*8192;int _r,_c;stage_rc(_b,_r,_c); \
;       __builtin_amdgcn_global_load_lds((const unsigned*)((BASE)+_g+(long)_r*(LD)+_c), \
;         (unsigned*)((char*)(P)+_b),16,0,0);}}while(0)
; #define STAGE(P,BASE,LD,br,kt) do{long _g=(long)(br)*(LD)+(long)(kt)*BK; \
;     _Pragma("unroll") for(int _i=0;_i<2;++_i){int _b=tid*16+_i*8192;int _r,_c;stage_rc(_b,_r,_c); \
;       __builtin_amdgcn_global_load_lds((const unsigned*)((BASE)+_g+(long)_r*(LD)+_c), \
;         (unsigned*)((char*)(P)+_b),16,0,0);}}while(0)
; #define LDA(dst,b,h) _Pragma("unroll") for(int m=0;m<4;++m) _Pragma("unroll") for(int k=0;k<2;++k) \
;     dst[m][k]=*reinterpret_cast<const bf16x8*>((char*)SA(b,h)+lds_byte(wr*64+m*16+fr,k*32+fq*8))
; #define LDB(dst,b,h) _Pragma("unroll") for(int n=0;n<2;++n) _Pragma("unroll") for(int k=0;k<2;++k) \
;     dst[n][k]=*reinterpret_cast<const bf16x8*>((char*)SB(b,h)+lds_byte(wc*32+n*16+fr,k*32+fq*8))
; #define MMA(ai,bj,At_,Bt_) do{__builtin_amdgcn_s_setprio(1); \
;     _Pragma("unroll") for(int m=0;m<4;++m) _Pragma("unroll") for(int n=0;n<2;++n) _Pragma("unroll") for(int k=0;k<2;++k) \
;       acc[ai][bj][m][n]=__builtin_amdgcn_mfma_f32_16x16x32_bf16(Bt_[n][k],At_[m][k],acc[ai][bj][m][n],0,0,0); \
;     __builtin_amdgcn_s_setprio(0);}while(0)
; #define WAIT_L(n) asm volatile("s_waitcnt lgkmcnt(" #n ")":::"memory")
; #define BAR __builtin_amdgcn_s_barrier()
; #define SCHED __builtin_amdgcn_sched_barrier(0)
; DEVINL void gemm8_mainloop(const u16* A, long lda, const u16* Bt, long ldb, int K, int brow, int bcol, f32x4 (&acc)[2][2][4][2], char* smem, int tid) {
;     ...
;     LDB(B0,0,0); SCHED; LDA(At,0,0); STAGE(SA(1,1),A,lda,brow+HALF,t+1);
;     WAIT_L(8); BAR; WAIT_L(0); MMA(0,0,At,B0); BAR; SCHED;
;     LDB(B1,0,1); STAGE(SB(0,0),Bt,ldb,bcol,t+2);
;     BAR; WAIT_L(0); MMA(0,1,At,B1); BAR;
;     LDA(At,0,1); STAGE(SA(0,0),A,lda,brow,t+2);
;     BAR; WAIT_L(0); MMA(1,0,At,B0); BAR; SCHED;
.LBB0_1938:
	ds_read_b128 v[180:183], v165
	ds_read_b128 v[184:187], v165 offset:1024
	ds_read_b128 v[188:191], v165 offset:2048
	ds_read_b128 v[192:195], v165 offset:3072
	v_add_u32_e32 v177, 0xc000, v154
	v_lshl_add_u64 v[244:245], s[94:95], 0, v[146:147]
	v_readfirstlane_b32 s27, v177
	v_add_u32_e32 v178, 0xe000, v154
	v_add_u32_e32 v173, s23, v164
	v_add_u32_e32 v174, s38, v164
	v_add_u32_e32 v175, s39, v164
	v_lshl_add_u64 v[166:167], v[244:245], 0, s[2:3]
	s_mov_b32 m0, s27
	v_lshl_add_u64 v[246:247], s[94:95], 0, v[148:149]
	v_readfirstlane_b32 s27, v178
	ds_read_b128 v[168:171], v155
	ds_read_b128 v[196:199], v155 offset:1024
	ds_read_b128 v[200:203], v173
	ds_read_b128 v[204:207], v173 offset:1024
	ds_read_b128 v[208:211], v174
	ds_read_b128 v[212:215], v174 offset:1024
	ds_read_b128 v[216:219], v175
	ds_read_b128 v[220:223], v175 offset:1024
	global_load_lds_dwordx4 v[166:167], off
	v_lshl_add_u64 v[166:167], v[246:247], 0, s[2:3]
	s_mov_b32 m0, s27
	s_nop 0
	global_load_lds_dwordx4 v[166:167], off
	s_waitcnt lgkmcnt(8)
	s_barrier
	s_waitcnt lgkmcnt(0)
	v_mfma_f32_16x16x32_bf16 v[124:127], v[180:183], v[168:171], v[124:127]
	v_mfma_f32_16x16x32_bf16 v[120:123], v[188:191], v[168:171], v[120:123]
	v_mfma_f32_16x16x32_bf16 v[116:119], v[180:183], v[200:203], v[116:119]
	v_mfma_f32_16x16x32_bf16 v[112:115], v[188:191], v[200:203], v[112:115]
	v_mfma_f32_16x16x32_bf16 v[108:111], v[180:183], v[208:211], v[108:111]
	v_mfma_f32_16x16x32_bf16 v[104:107], v[188:191], v[208:211], v[104:107]
	v_mfma_f32_16x16x32_bf16 v[100:103], v[180:183], v[216:219], v[100:103]
	v_mfma_f32_16x16x32_bf16 v[96:99], v[188:191], v[216:219], v[96:99]
	v_mfma_f32_16x16x32_bf16 v[124:127], v[184:187], v[196:199], v[124:127]
	v_mfma_f32_16x16x32_bf16 v[120:123], v[192:195], v[196:199], v[120:123]
	v_mfma_f32_16x16x32_bf16 v[116:119], v[184:187], v[204:207], v[116:119]
	v_mfma_f32_16x16x32_bf16 v[112:115], v[192:195], v[204:207], v[112:115]
	v_mfma_f32_16x16x32_bf16 v[108:111], v[184:187], v[212:215], v[108:111]
	v_mfma_f32_16x16x32_bf16 v[104:107], v[192:195], v[212:215], v[104:107]
	v_mfma_f32_16x16x32_bf16 v[100:103], v[184:187], v[220:223], v[100:103]
	v_mfma_f32_16x16x32_bf16 v[96:99], v[192:195], v[220:223], v[96:99]
	s_barrier
	v_add_u32_e32 v166, s28, v157
	v_lshl_add_u64 v[248:249], s[94:95], 0, v[142:143]
	v_readfirstlane_b32 s27, v166
	v_add_u32_e32 v167, 0x2000, v166
	v_lshl_add_u64 v[240:241], v[248:249], 0, s[4:5]
	s_mov_b32 m0, s27
	v_lshl_add_u64 v[250:251], s[94:95], 0, v[144:145]
	v_readfirstlane_b32 s27, v167
	ds_read_b128 v[224:227], v161
	ds_read_b128 v[228:231], v161 offset:1024
	ds_read_b128 v[232:235], v161 offset:2048
	ds_read_b128 v[236:239], v161 offset:3072
	global_load_lds_dwordx4 v[240:241], off
	v_lshl_add_u64 v[240:241], v[250:251], 0, s[4:5]
	s_mov_b32 m0, s27
	s_nop 0
	global_load_lds_dwordx4 v[240:241], off
	s_barrier
	s_waitcnt lgkmcnt(0)
	v_mfma_f32_16x16x32_bf16 v[92:95], v[224:227], v[168:171], v[92:95]
	v_mfma_f32_16x16x32_bf16 v[88:91], v[232:235], v[168:171], v[88:91]
	v_mfma_f32_16x16x32_bf16 v[84:87], v[224:227], v[200:203], v[84:87]
	v_mfma_f32_16x16x32_bf16 v[80:83], v[232:235], v[200:203], v[80:83]
	v_mfma_f32_16x16x32_bf16 v[76:79], v[224:227], v[208:211], v[76:79]
	v_mfma_f32_16x16x32_bf16 v[72:75], v[232:235], v[208:211], v[72:75]
	v_mfma_f32_16x16x32_bf16 v[68:71], v[224:227], v[216:219], v[68:71]
	v_mfma_f32_16x16x32_bf16 v[64:67], v[232:235], v[216:219], v[64:67]
	v_mfma_f32_16x16x32_bf16 v[92:95], v[228:231], v[196:199], v[92:95]
	v_mfma_f32_16x16x32_bf16 v[88:91], v[236:239], v[196:199], v[88:91]
	v_mfma_f32_16x16x32_bf16 v[84:87], v[228:231], v[204:207], v[84:87]
	v_mfma_f32_16x16x32_bf16 v[80:83], v[236:239], v[204:207], v[80:83]
	v_mfma_f32_16x16x32_bf16 v[76:79], v[228:231], v[212:215], v[76:79]
	v_mfma_f32_16x16x32_bf16 v[72:75], v[236:239], v[212:215], v[72:75]
	v_mfma_f32_16x16x32_bf16 v[68:71], v[228:231], v[220:223], v[68:71]
	v_mfma_f32_16x16x32_bf16 v[64:67], v[236:239], v[220:223], v[64:67]
	v_readfirstlane_b32 s27, v154
	v_lshl_add_u64 v[168:169], v[244:245], 0, s[6:7]
	s_mov_b32 m0, s27
	s_barrier
	ds_read_b128 v[196:199], v155 offset:16384
	ds_read_b128 v[200:203], v155 offset:17408
	ds_read_b128 v[204:207], v173 offset:16384
	ds_read_b128 v[208:211], v173 offset:17408
	ds_read_b128 v[212:215], v174 offset:16384
	ds_read_b128 v[216:219], v174 offset:17408
	ds_read_b128 v[220:223], v175 offset:16384
	ds_read_b128 v[240:243], v175 offset:17408
	global_load_lds_dwordx4 v[168:169], off
	v_add_u32_e32 v168, 0x2000, v154
	v_lshl_add_u64 v[170:171], v[246:247], 0, s[6:7]
	v_readfirstlane_b32 s27, v168
	s_mov_b32 m0, s27
	s_nop 0
	global_load_lds_dwordx4 v[170:171], off
	s_barrier
	s_waitcnt lgkmcnt(0)
	v_mfma_f32_16x16x32_bf16 v[60:63], v[180:183], v[196:199], v[60:63]
	v_mfma_f32_16x16x32_bf16 v[56:59], v[188:191], v[196:199], v[56:59]
	v_mfma_f32_16x16x32_bf16 v[52:55], v[180:183], v[204:207], v[52:55]
	v_mfma_f32_16x16x32_bf16 v[48:51], v[188:191], v[204:207], v[48:51]
	v_mfma_f32_16x16x32_bf16 v[44:47], v[180:183], v[212:215], v[44:47]
	v_mfma_f32_16x16x32_bf16 v[40:43], v[188:191], v[212:215], v[40:43]
	v_mfma_f32_16x16x32_bf16 v[36:39], v[180:183], v[220:223], v[36:39]
	v_mfma_f32_16x16x32_bf16 v[32:35], v[188:191], v[220:223], v[32:35]
	v_mfma_f32_16x16x32_bf16 v[60:63], v[184:187], v[200:203], v[60:63]
	v_mfma_f32_16x16x32_bf16 v[56:59], v[192:195], v[200:203], v[56:59]
	v_mfma_f32_16x16x32_bf16 v[52:55], v[184:187], v[208:211], v[52:55]
	v_mfma_f32_16x16x32_bf16 v[48:51], v[192:195], v[208:211], v[48:51]
	v_mfma_f32_16x16x32_bf16 v[44:47], v[184:187], v[216:219], v[44:47]
	v_mfma_f32_16x16x32_bf16 v[40:43], v[192:195], v[216:219], v[40:43]
	v_mfma_f32_16x16x32_bf16 v[36:39], v[184:187], v[240:243], v[36:39]
	v_mfma_f32_16x16x32_bf16 v[32:35], v[192:195], v[240:243], v[32:35]
	s_barrier
; #define STAGE(P,BASE,LD,br,kt) do{long _g=(long)(br)*(LD)+(long)(kt)*BK; \
;     _Pragma("unroll") for(int _i=0;_i<2;++_i){int _b=tid*16+_i*8192;int _r,_c;stage_rc(_b,_r,_c); \
;       __builtin_amdgcn_global_load_lds((const unsigned*)((BASE)+_g+(long)_r*(LD)+_c), \
;         (unsigned*)((char*)(P)+_b),16,0,0);}}while(0)
; #define STAGE(P,BASE,LD,br,kt) do{long _g=(long)(br)*(LD)+(long)(kt)*BK; \
;     _Pragma("unroll") for(int _i=0;_i<2;++_i){int _b=tid*16+_i*8192;int _r,_c;stage_rc(_b,_r,_c); \
;       __builtin_amdgcn_global_load_lds((const unsigned*)((BASE)+_g+(long)_r*(LD)+_c), \
;         (unsigned*)((char*)(P)+_b),16,0,0);}}while(0)
; #define LDA(dst,b,h) _Pragma("unroll") for(int m=0;m<4;++m) _Pragma("unroll") for(int k=0;k<2;++k) \
;     dst[m][k]=*reinterpret_cast<const bf16x8*>((char*)SA(b,h)+lds_byte(wr*64+m*16+fr,k*32+fq*8))
; #define LDB(dst,b,h) _Pragma("unroll") for(int n=0;n<2;++n) _Pragma("unroll") for(int k=0;k<2;++k) \
;     dst[n][k]=*reinterpret_cast<const bf16x8*>((char*)SB(b,h)+lds_byte(wc*32+n*16+fr,k*32+fq*8))
; #define MMA(ai,bj,At_,Bt_) do{__builtin_amdgcn_s_setprio(1); \
;     _Pragma("unroll") for(int m=0;m<4;++m) _Pragma("unroll") for(int n=0;n<2;++n) _Pragma("unroll") for(int k=0;k<2;++k) \
;       acc[ai][bj][m][n]=__builtin_amdgcn_mfma_f32_16x16x32_bf16(Bt_[n][k],At_[m][k],acc[ai][bj][m][n],0,0,0); \
;     __builtin_amdgcn_s_setprio(0);}while(0)
; #define WAIT_V(n) asm volatile("s_waitcnt vmcnt(" #n ")":::"memory")
; #define WAIT_L(n) asm volatile("s_waitcnt lgkmcnt(" #n ")":::"memory")
; #define BAR __builtin_amdgcn_s_barrier()
; #define SCHED __builtin_amdgcn_sched_barrier(0)
; DEVINL void gemm8_mainloop(const u16* A, long lda, const u16* Bt, long ldb, int K, int brow, int bcol, f32x4 (&acc)[2][2][4][2], char* smem, int tid) {
;     ...
;     STAGE(SB(0,1),Bt,ldb,bcol+HALF,t+2);
;     WAIT_V(6); BAR; MMA(1,1,At,B1); BAR;
;     LDB(B0,1,0); SCHED; LDA(At,1,0); STAGE(SA(0,1),A,lda,brow+HALF,t+2);
;     WAIT_L(8); BAR; WAIT_L(0); MMA(0,0,At,B0); BAR; SCHED;
;     LDB(B1,1,1); STAGE(SB(1,0),Bt,ldb,bcol,t+3);
;     BAR; WAIT_L(0); MMA(0,1,At,B1); BAR;
;     LDA(At,1,1); STAGE(SA(1,0),A,lda,brow,t+3);
	v_add_u32_e32 v169, s29, v157
	v_lshl_add_u64 v[170:171], v[248:249], 0, s[8:9]
	v_readfirstlane_b32 s27, v169
	s_mov_b32 m0, s27
	v_lshl_add_u64 v[180:181], v[250:251], 0, s[8:9]
	global_load_lds_dwordx4 v[170:171], off
	v_add_u32_e32 v170, 0x2000, v169
	s_nop 0
	v_readfirstlane_b32 s27, v170
	s_mov_b32 m0, s27
	s_nop 0
	global_load_lds_dwordx4 v[180:181], off
	s_waitcnt vmcnt(6)
	s_barrier
	v_mfma_f32_16x16x32_bf16 v[28:31], v[224:227], v[196:199], v[28:31]
	v_mfma_f32_16x16x32_bf16 v[24:27], v[232:235], v[196:199], v[24:27]
	v_mfma_f32_16x16x32_bf16 v[20:23], v[224:227], v[204:207], v[20:23]
	v_mfma_f32_16x16x32_bf16 v[16:19], v[232:235], v[204:207], v[16:19]
	v_mfma_f32_16x16x32_bf16 v[12:15], v[224:227], v[212:215], v[12:15]
	v_mfma_f32_16x16x32_bf16 v[8:11], v[232:235], v[212:215], v[8:11]
	v_mfma_f32_16x16x32_bf16 v[4:7], v[224:227], v[220:223], v[4:7]
	v_mfma_f32_16x16x32_bf16 v[0:3], v[232:235], v[220:223], v[0:3]
	v_mfma_f32_16x16x32_bf16 v[28:31], v[228:231], v[200:203], v[28:31]
	v_mfma_f32_16x16x32_bf16 v[24:27], v[236:239], v[200:203], v[24:27]
	v_mfma_f32_16x16x32_bf16 v[20:23], v[228:231], v[208:211], v[20:23]
	v_mfma_f32_16x16x32_bf16 v[16:19], v[236:239], v[208:211], v[16:19]
	v_mfma_f32_16x16x32_bf16 v[12:15], v[228:231], v[216:219], v[12:15]
	v_mfma_f32_16x16x32_bf16 v[8:11], v[236:239], v[216:219], v[8:11]
	v_mfma_f32_16x16x32_bf16 v[4:7], v[228:231], v[240:243], v[4:7]
	v_mfma_f32_16x16x32_bf16 v[0:3], v[236:239], v[240:243], v[0:3]
	s_barrier
	ds_read_b128 v[180:183], v158
	ds_read_b128 v[184:187], v158 offset:1024
	ds_read_b128 v[188:191], v158 offset:2048
	ds_read_b128 v[192:195], v158 offset:3072
	v_add_u32_e32 v171, 0x4000, v154
	v_add_u32_e32 v172, 0x6000, v154
	v_readfirstlane_b32 s27, v171
	v_lshl_add_u64 v[228:229], v[244:245], 0, s[10:11]
	s_mov_b32 m0, s27
	v_readfirstlane_b32 s27, v172
	ds_read_b128 v[196:199], v155 offset:32768
	ds_read_b128 v[200:203], v155 offset:33792
	ds_read_b128 v[204:207], v173 offset:32768
	ds_read_b128 v[208:211], v173 offset:33792
	ds_read_b128 v[212:215], v174 offset:32768
	ds_read_b128 v[216:219], v174 offset:33792
	ds_read_b128 v[220:223], v175 offset:32768
	ds_read_b128 v[224:227], v175 offset:33792
	global_load_lds_dwordx4 v[228:229], off
	v_lshl_add_u64 v[228:229], v[246:247], 0, s[10:11]
	s_mov_b32 m0, s27
	s_nop 0
	global_load_lds_dwordx4 v[228:229], off
	s_waitcnt lgkmcnt(8)
	s_barrier
	s_waitcnt lgkmcnt(0)
	v_mfma_f32_16x16x32_bf16 v[124:127], v[180:183], v[196:199], v[124:127]
	v_mfma_f32_16x16x32_bf16 v[120:123], v[188:191], v[196:199], v[120:123]
	v_mfma_f32_16x16x32_bf16 v[116:119], v[180:183], v[204:207], v[116:119]
	v_mfma_f32_16x16x32_bf16 v[112:115], v[188:191], v[204:207], v[112:115]
	v_mfma_f32_16x16x32_bf16 v[108:111], v[180:183], v[212:215], v[108:111]
	v_mfma_f32_16x16x32_bf16 v[104:107], v[188:191], v[212:215], v[104:107]
	v_mfma_f32_16x16x32_bf16 v[100:103], v[180:183], v[220:223], v[100:103]
	v_mfma_f32_16x16x32_bf16 v[96:99], v[188:191], v[220:223], v[96:99]
	v_mfma_f32_16x16x32_bf16 v[124:127], v[184:187], v[200:203], v[124:127]
	v_mfma_f32_16x16x32_bf16 v[120:123], v[192:195], v[200:203], v[120:123]
	v_mfma_f32_16x16x32_bf16 v[116:119], v[184:187], v[208:211], v[116:119]
	v_mfma_f32_16x16x32_bf16 v[112:115], v[192:195], v[208:211], v[112:115]
	v_mfma_f32_16x16x32_bf16 v[108:111], v[184:187], v[216:219], v[108:111]
	v_mfma_f32_16x16x32_bf16 v[104:107], v[192:195], v[216:219], v[104:107]
	v_mfma_f32_16x16x32_bf16 v[100:103], v[184:187], v[224:227], v[100:103]
	v_mfma_f32_16x16x32_bf16 v[96:99], v[192:195], v[224:227], v[96:99]
	s_barrier
	v_readfirstlane_b32 s27, v159
	v_add_u32_e32 v179, 0x2000, v159
	v_lshl_add_u64 v[252:253], v[248:249], 0, s[12:13]
	s_mov_b32 m0, s27
	v_readfirstlane_b32 s27, v179
	ds_read_b128 v[228:231], v156
	ds_read_b128 v[232:235], v156 offset:1024
	ds_read_b128 v[236:239], v156 offset:2048
	ds_read_b128 v[240:243], v156 offset:3072
	global_load_lds_dwordx4 v[252:253], off
	v_lshl_add_u64 v[252:253], v[250:251], 0, s[12:13]
	s_mov_b32 m0, s27
	s_nop 0
	global_load_lds_dwordx4 v[252:253], off
	s_barrier
	s_waitcnt lgkmcnt(0)
	v_mfma_f32_16x16x32_bf16 v[92:95], v[228:231], v[196:199], v[92:95]
	v_mfma_f32_16x16x32_bf16 v[88:91], v[236:239], v[196:199], v[88:91]
	v_mfma_f32_16x16x32_bf16 v[84:87], v[228:231], v[204:207], v[84:87]
	v_mfma_f32_16x16x32_bf16 v[80:83], v[236:239], v[204:207], v[80:83]
	v_mfma_f32_16x16x32_bf16 v[76:79], v[228:231], v[212:215], v[76:79]
	v_mfma_f32_16x16x32_bf16 v[72:75], v[236:239], v[212:215], v[72:75]
	v_mfma_f32_16x16x32_bf16 v[68:71], v[228:231], v[220:223], v[68:71]
	v_mfma_f32_16x16x32_bf16 v[64:67], v[236:239], v[220:223], v[64:67]
	v_mfma_f32_16x16x32_bf16 v[92:95], v[232:235], v[200:203], v[92:95]
	v_mfma_f32_16x16x32_bf16 v[88:91], v[240:243], v[200:203], v[88:91]
	v_mfma_f32_16x16x32_bf16 v[84:87], v[232:235], v[208:211], v[84:87]
	v_mfma_f32_16x16x32_bf16 v[80:83], v[240:243], v[208:211], v[80:83]
	v_mfma_f32_16x16x32_bf16 v[76:79], v[232:235], v[216:219], v[76:79]
	v_mfma_f32_16x16x32_bf16 v[72:75], v[240:243], v[216:219], v[72:75]
	v_mfma_f32_16x16x32_bf16 v[68:71], v[232:235], v[224:227], v[68:71]
	v_mfma_f32_16x16x32_bf16 v[64:67], v[240:243], v[224:227], v[64:67]
	v_readfirstlane_b32 s27, v160
	v_lshl_add_u64 v[244:245], v[244:245], 0, s[14:15]
	s_mov_b32 m0, s27
	v_readfirstlane_b32 s27, v162
	s_barrier
	ds_read_b128 v[196:199], v155 offset:49152
	ds_read_b128 v[200:203], v155 offset:50176
	ds_read_b128 v[204:207], v173 offset:49152
	ds_read_b128 v[208:211], v173 offset:50176
	ds_read_b128 v[212:215], v174 offset:49152
	ds_read_b128 v[216:219], v174 offset:50176
	ds_read_b128 v[220:223], v175 offset:49152
	ds_read_b128 v[224:227], v175 offset:50176
	global_load_lds_dwordx4 v[244:245], off
	v_lshl_add_u64 v[244:245], v[246:247], 0, s[14:15]
	s_mov_b32 m0, s27
	s_nop 0
	global_load_lds_dwordx4 v[244:245], off
	s_barrier
; #define STAGE(P,BASE,LD,br,kt) do{long _g=(long)(br)*(LD)+(long)(kt)*BK; \
;     _Pragma("unroll") for(int _i=0;_i<2;++_i){int _b=tid*16+_i*8192;int _r,_c;stage_rc(_b,_r,_c); \
;       __builtin_amdgcn_global_load_lds((const unsigned*)((BASE)+_g+(long)_r*(LD)+_c), \
;         (unsigned*)((char*)(P)+_b),16,0,0);}}while(0)
; #define STAGE(P,BASE,LD,br,kt) do{long _g=(long)(br)*(LD)+(long)(kt)*BK; \
;     _Pragma("unroll") for(int _i=0;_i<2;++_i){int _b=tid*16+_i*8192;int _r,_c;stage_rc(_b,_r,_c); \
;       __builtin_amdgcn_global_load_lds((const unsigned*)((BASE)+_g+(long)_r*(LD)+_c), \
;         (unsigned*)((char*)(P)+_b),16,0,0);}}while(0)
; #define LDA(dst,b,h) _Pragma("unroll") for(int m=0;m<4;++m) _Pragma("unroll") for(int k=0;k<2;++k) \
;     dst[m][k]=*reinterpret_cast<const bf16x8*>((char*)SA(b,h)+lds_byte(wr*64+m*16+fr,k*32+fq*8))
; #define LDB(dst,b,h) _Pragma("unroll") for(int n=0;n<2;++n) _Pragma("unroll") for(int k=0;k<2;++k) \
;     dst[n][k]=*reinterpret_cast<const bf16x8*>((char*)SB(b,h)+lds_byte(wc*32+n*16+fr,k*32+fq*8))
; #define MMA(ai,bj,At_,Bt_) do{__builtin_amdgcn_s_setprio(1); \
;     _Pragma("unroll") for(int m=0;m<4;++m) _Pragma("unroll") for(int n=0;n<2;++n) _Pragma("unroll") for(int k=0;k<2;++k) \
;       acc[ai][bj][m][n]=__builtin_amdgcn_mfma_f32_16x16x32_bf16(Bt_[n][k],At_[m][k],acc[ai][bj][m][n],0,0,0); \
;     __builtin_amdgcn_s_setprio(0);}while(0)
; #define WAIT_V(n) asm volatile("s_waitcnt vmcnt(" #n ")":::"memory")
; #define WAIT_L(n) asm volatile("s_waitcnt lgkmcnt(" #n ")":::"memory")
; #define BAR __builtin_amdgcn_s_barrier()
; #define SCHED __builtin_amdgcn_sched_barrier(0)
; DEVINL void gemm8_mainloop(const u16* A, long lda, const u16* Bt, long ldb, int K, int brow, int bcol, f32x4 (&acc)[2][2][4][2], char* smem, int tid) {
;     ...
;     BAR; WAIT_L(0); MMA(1,0,At,B0); BAR; SCHED;
;     STAGE(SB(1,1),Bt,ldb,bcol+HALF,t+3);
;     WAIT_V(6); BAR; MMA(1,1,At,B1); BAR;
;   }
;   { LDB(B0,0,0); LDA(At,0,0); STAGE(SA(1,1),A,lda,brow+HALF,nt-1);
;     BAR; WAIT_L(0); MMA(0,0,At,B0); BAR;
;     LDB(B1,0,1); BAR; WAIT_L(0); MMA(0,1,At,B1); BAR;
	s_waitcnt lgkmcnt(0)
	v_mfma_f32_16x16x32_bf16 v[60:63], v[180:183], v[196:199], v[60:63]
	v_mfma_f32_16x16x32_bf16 v[56:59], v[188:191], v[196:199], v[56:59]
	v_mfma_f32_16x16x32_bf16 v[52:55], v[180:183], v[204:207], v[52:55]
	v_mfma_f32_16x16x32_bf16 v[48:51], v[188:191], v[204:207], v[48:51]
	v_mfma_f32_16x16x32_bf16 v[44:47], v[180:183], v[212:215], v[44:47]
	v_mfma_f32_16x16x32_bf16 v[40:43], v[188:191], v[212:215], v[40:43]
	v_mfma_f32_16x16x32_bf16 v[36:39], v[180:183], v[220:223], v[36:39]
	v_mfma_f32_16x16x32_bf16 v[32:35], v[188:191], v[220:223], v[32:35]
	v_mfma_f32_16x16x32_bf16 v[60:63], v[184:187], v[200:203], v[60:63]
	v_mfma_f32_16x16x32_bf16 v[56:59], v[192:195], v[200:203], v[56:59]
	v_mfma_f32_16x16x32_bf16 v[52:55], v[184:187], v[208:211], v[52:55]
	v_mfma_f32_16x16x32_bf16 v[48:51], v[192:195], v[208:211], v[48:51]
	v_mfma_f32_16x16x32_bf16 v[44:47], v[184:187], v[216:219], v[44:47]
	v_mfma_f32_16x16x32_bf16 v[40:43], v[192:195], v[216:219], v[40:43]
	v_mfma_f32_16x16x32_bf16 v[36:39], v[184:187], v[224:227], v[36:39]
	v_mfma_f32_16x16x32_bf16 v[32:35], v[192:195], v[224:227], v[32:35]
	s_barrier
	v_readfirstlane_b32 s27, v163
	v_add_u32_e32 v179, 0x2000, v163
	v_lshl_add_u64 v[180:181], v[248:249], 0, s[16:17]
	s_mov_b32 m0, s27
	v_readfirstlane_b32 s27, v179
	global_load_lds_dwordx4 v[180:181], off
	v_lshl_add_u64 v[180:181], v[250:251], 0, s[16:17]
	s_mov_b32 m0, s27
	s_nop 0
	global_load_lds_dwordx4 v[180:181], off
	s_waitcnt vmcnt(6)
	s_barrier
	v_mfma_f32_16x16x32_bf16 v[28:31], v[228:231], v[196:199], v[28:31]
	v_mfma_f32_16x16x32_bf16 v[24:27], v[236:239], v[196:199], v[24:27]
	v_mfma_f32_16x16x32_bf16 v[20:23], v[228:231], v[204:207], v[20:23]
	v_mfma_f32_16x16x32_bf16 v[16:19], v[236:239], v[204:207], v[16:19]
	v_mfma_f32_16x16x32_bf16 v[12:15], v[228:231], v[212:215], v[12:15]
	v_mfma_f32_16x16x32_bf16 v[8:11], v[236:239], v[212:215], v[8:11]
	v_mfma_f32_16x16x32_bf16 v[4:7], v[228:231], v[220:223], v[4:7]
	v_mfma_f32_16x16x32_bf16 v[0:3], v[236:239], v[220:223], v[0:3]
	v_mfma_f32_16x16x32_bf16 v[28:31], v[232:235], v[200:203], v[28:31]
	v_mfma_f32_16x16x32_bf16 v[24:27], v[240:243], v[200:203], v[24:27]
	v_mfma_f32_16x16x32_bf16 v[20:23], v[232:235], v[208:211], v[20:23]
	v_mfma_f32_16x16x32_bf16 v[16:19], v[240:243], v[208:211], v[16:19]
	v_mfma_f32_16x16x32_bf16 v[12:15], v[232:235], v[216:219], v[12:15]
	v_mfma_f32_16x16x32_bf16 v[8:11], v[240:243], v[216:219], v[8:11]
	v_mfma_f32_16x16x32_bf16 v[4:7], v[232:235], v[224:227], v[4:7]
	v_mfma_f32_16x16x32_bf16 v[0:3], v[240:243], v[224:227], v[0:3]
	s_add_i32 s26, s26, 2
	v_lshl_add_u64 v[142:143], v[142:143], 0, s[18:19]
	v_lshl_add_u64 v[144:145], v[144:145], 0, s[18:19]
	v_lshl_add_u64 v[146:147], v[146:147], 0, s[18:19]
	s_cmp_lt_u32 s26, 28
	v_lshl_add_u64 v[148:149], v[148:149], 0, s[18:19]
	s_barrier
	s_cbranch_scc1 .LBB0_1938
	s_or_b32 s26, s22, 0x80
	s_ashr_i32 s27, s26, 31
	s_lshl_b64 s[26:27], s[26:27], 12
	s_add_u32 s26, s90, s26
	s_addc_u32 s27, s91, s27
	v_lshl_add_u64 v[216:217], v[134:135], 1, s[26:27]
	v_lshl_add_u64 v[138:139], v[138:139], 1, v[216:217]
	v_readfirstlane_b32 s23, v177
	v_lshl_add_u64 v[138:139], v[138:139], 0, s[20:21]
	s_mov_b32 m0, s23
	ds_read_b128 v[142:145], v165
	ds_read_b128 v[146:149], v165 offset:1024
	ds_read_b128 v[180:183], v165 offset:2048
	ds_read_b128 v[162:165], v165 offset:3072
	ds_read_b128 v[184:187], v155
	ds_read_b128 v[188:191], v155 offset:1024
	ds_read_b128 v[192:195], v173
	ds_read_b128 v[196:199], v173 offset:1024
	ds_read_b128 v[200:203], v174
	ds_read_b128 v[204:207], v174 offset:1024
	ds_read_b128 v[208:211], v175
	ds_read_b128 v[212:215], v175 offset:1024
	global_load_lds_dwordx4 v[138:139], off
	v_lshl_add_u64 v[138:139], v[136:137], 1, s[26:27]
	v_lshl_add_u64 v[138:139], v[140:141], 1, v[138:139]
	v_readfirstlane_b32 s23, v178
	v_lshl_add_u64 v[138:139], v[138:139], 0, s[20:21]
	s_mov_b32 m0, s23
	s_nop 0
	global_load_lds_dwordx4 v[138:139], off
	s_barrier
	s_waitcnt lgkmcnt(0)
	v_mfma_f32_16x16x32_bf16 v[124:127], v[142:145], v[184:187], v[124:127]
	v_mfma_f32_16x16x32_bf16 v[120:123], v[180:183], v[184:187], v[120:123]
	v_mfma_f32_16x16x32_bf16 v[116:119], v[142:145], v[192:195], v[116:119]
	v_mfma_f32_16x16x32_bf16 v[112:115], v[180:183], v[192:195], v[112:115]
	v_mfma_f32_16x16x32_bf16 v[104:107], v[180:183], v[200:203], v[104:107]
	v_mfma_f32_16x16x32_bf16 v[96:99], v[180:183], v[208:211], v[96:99]
	v_mfma_f32_16x16x32_bf16 v[124:127], v[146:149], v[188:191], v[124:127]
	v_mfma_f32_16x16x32_bf16 v[120:123], v[162:165], v[188:191], v[120:123]
	v_mfma_f32_16x16x32_bf16 v[116:119], v[146:149], v[196:199], v[116:119]
	v_mfma_f32_16x16x32_bf16 v[112:115], v[162:165], v[196:199], v[112:115]
	v_mfma_f32_16x16x32_bf16 v[108:111], v[142:145], v[200:203], v[108:111]
	v_mfma_f32_16x16x32_bf16 v[104:107], v[162:165], v[204:207], v[104:107]
	v_mfma_f32_16x16x32_bf16 v[100:103], v[142:145], v[208:211], v[100:103]
	v_mfma_f32_16x16x32_bf16 v[96:99], v[162:165], v[212:215], v[96:99]
	v_mfma_f32_16x16x32_bf16 v[138:141], v[146:149], v[204:207], v[108:111]
	v_mfma_f32_16x16x32_bf16 v[216:219], v[146:149], v[212:215], v[100:103]
	s_barrier
	s_nop 2
	s_nop 0
	ds_read_b128 v[100:103], v161
	ds_read_b128 v[108:111], v161 offset:1024
	ds_read_b128 v[220:223], v161 offset:2048
	ds_read_b128 v[224:227], v161 offset:3072
	s_barrier
; #define LDA(dst,b,h) _Pragma("unroll") for(int m=0;m<4;++m) _Pragma("unroll") for(int k=0;k<2;++k) \
;     dst[m][k]=*reinterpret_cast<const bf16x8*>((char*)SA(b,h)+lds_byte(wr*64+m*16+fr,k*32+fq*8))
; #define LDB(dst,b,h) _Pragma("unroll") for(int n=0;n<2;++n) _Pragma("unroll") for(int k=0;k<2;++k) \
;     dst[n][k]=*reinterpret_cast<const bf16x8*>((char*)SB(b,h)+lds_byte(wc*32+n*16+fr,k*32+fq*8))
; #define MMA(ai,bj,At_,Bt_) do{__builtin_amdgcn_s_setprio(1); \
;     _Pragma("unroll") for(int m=0;m<4;++m) _Pragma("unroll") for(int n=0;n<2;++n) _Pragma("unroll") for(int k=0;k<2;++k) \
;       acc[ai][bj][m][n]=__builtin_amdgcn_mfma_f32_16x16x32_bf16(Bt_[n][k],At_[m][k],acc[ai][bj][m][n],0,0,0); \
;     __builtin_amdgcn_s_setprio(0);}while(0)
; #define WAIT_V(n) asm volatile("s_waitcnt vmcnt(" #n ")":::"memory")
; #define WAIT_L(n) asm volatile("s_waitcnt lgkmcnt(" #n ")":::"memory")
; #define BAR __builtin_amdgcn_s_barrier()
; DEVINL void gemm8_mainloop(const u16* A, long lda, const u16* Bt, long ldb, int K, int brow, int bcol, f32x4 (&acc)[2][2][4][2], char* smem, int tid) {
;     ...
;     LDB(B1,0,1); BAR; WAIT_L(0); MMA(0,1,At,B1); BAR;
;     LDA(At,0,1); WAIT_V(4); BAR; WAIT_L(0); MMA(1,0,At,B0); MMA(1,1,At,B1); BAR; }
;   { LDB(B0,1,0); LDA(At,1,0); WAIT_V(2); BAR; WAIT_L(0); MMA(0,0,At,B0); BAR;
	s_waitcnt lgkmcnt(0)
	v_mfma_f32_16x16x32_bf16 v[88:91], v[220:223], v[184:187], v[88:91]
	v_mfma_f32_16x16x32_bf16 v[80:83], v[220:223], v[192:195], v[80:83]
	v_mfma_f32_16x16x32_bf16 v[72:75], v[220:223], v[200:203], v[72:75]
	v_mfma_f32_16x16x32_bf16 v[64:67], v[220:223], v[208:211], v[64:67]
	v_mfma_f32_16x16x32_bf16 v[92:95], v[100:103], v[184:187], v[92:95]
	v_mfma_f32_16x16x32_bf16 v[88:91], v[224:227], v[188:191], v[88:91]
	v_mfma_f32_16x16x32_bf16 v[84:87], v[100:103], v[192:195], v[84:87]
	v_mfma_f32_16x16x32_bf16 v[80:83], v[224:227], v[196:199], v[80:83]
	v_mfma_f32_16x16x32_bf16 v[76:79], v[100:103], v[200:203], v[76:79]
	v_mfma_f32_16x16x32_bf16 v[72:75], v[224:227], v[204:207], v[72:75]
	v_mfma_f32_16x16x32_bf16 v[68:71], v[100:103], v[208:211], v[68:71]
	v_mfma_f32_16x16x32_bf16 v[64:67], v[224:227], v[212:215], v[64:67]
	v_mfma_f32_16x16x32_bf16 v[228:231], v[108:111], v[188:191], v[92:95]
	v_mfma_f32_16x16x32_bf16 v[184:187], v[108:111], v[196:199], v[84:87]
	v_mfma_f32_16x16x32_bf16 v[188:191], v[108:111], v[204:207], v[76:79]
	v_mfma_f32_16x16x32_bf16 v[192:195], v[108:111], v[212:215], v[68:71]
	s_barrier
	s_nop 0
	s_nop 0
	ds_read_b128 v[68:71], v155 offset:16384
	ds_read_b128 v[76:79], v155 offset:17408
	ds_read_b128 v[84:87], v173 offset:16384
	ds_read_b128 v[92:95], v173 offset:17408
	ds_read_b128 v[196:199], v174 offset:16384
	ds_read_b128 v[200:203], v174 offset:17408
	ds_read_b128 v[204:207], v175 offset:16384
	ds_read_b128 v[208:211], v175 offset:17408
	s_waitcnt vmcnt(4)
	s_barrier
	s_waitcnt lgkmcnt(0)
	v_mfma_f32_16x16x32_bf16 v[60:63], v[142:145], v[68:71], v[60:63]
	v_mfma_f32_16x16x32_bf16 v[56:59], v[180:183], v[68:71], v[56:59]
	v_mfma_f32_16x16x32_bf16 v[48:51], v[180:183], v[84:87], v[48:51]
	v_mfma_f32_16x16x32_bf16 v[40:43], v[180:183], v[196:199], v[40:43]
	v_mfma_f32_16x16x32_bf16 v[32:35], v[180:183], v[204:207], v[32:35]
	v_mfma_f32_16x16x32_bf16 v[60:63], v[146:149], v[76:79], v[60:63]
	v_mfma_f32_16x16x32_bf16 v[56:59], v[162:165], v[76:79], v[56:59]
	v_mfma_f32_16x16x32_bf16 v[52:55], v[142:145], v[84:87], v[52:55]
	v_mfma_f32_16x16x32_bf16 v[48:51], v[162:165], v[92:95], v[48:51]
	v_mfma_f32_16x16x32_bf16 v[44:47], v[142:145], v[196:199], v[44:47]
	v_mfma_f32_16x16x32_bf16 v[40:43], v[162:165], v[200:203], v[40:43]
	v_mfma_f32_16x16x32_bf16 v[36:39], v[142:145], v[204:207], v[36:39]
	v_mfma_f32_16x16x32_bf16 v[32:35], v[162:165], v[208:211], v[32:35]
	v_mfma_f32_16x16x32_bf16 v[212:215], v[146:149], v[92:95], v[52:55]
	v_mfma_f32_16x16x32_bf16 v[232:235], v[146:149], v[200:203], v[44:47]
	v_mfma_f32_16x16x32_bf16 v[142:145], v[146:149], v[208:211], v[36:39]
	v_mfma_f32_16x16x32_bf16 v[24:27], v[220:223], v[68:71], v[24:27]
	v_mfma_f32_16x16x32_bf16 v[16:19], v[220:223], v[84:87], v[16:19]
	v_mfma_f32_16x16x32_bf16 v[4:7], v[100:103], v[204:207], v[4:7]
	v_mfma_f32_16x16x32_bf16 v[0:3], v[220:223], v[204:207], v[0:3]
	v_mfma_f32_16x16x32_bf16 v[28:31], v[100:103], v[68:71], v[28:31]
	v_mfma_f32_16x16x32_bf16 v[24:27], v[224:227], v[76:79], v[24:27]
	v_mfma_f32_16x16x32_bf16 v[20:23], v[100:103], v[84:87], v[20:23]
	v_mfma_f32_16x16x32_bf16 v[16:19], v[224:227], v[92:95], v[16:19]
	v_mfma_f32_16x16x32_bf16 v[12:15], v[100:103], v[196:199], v[12:15]
	v_mfma_f32_16x16x32_bf16 v[8:11], v[220:223], v[196:199], v[8:11]
	v_mfma_f32_16x16x32_bf16 v[4:7], v[108:111], v[208:211], v[4:7]
	v_mfma_f32_16x16x32_bf16 v[0:3], v[224:227], v[208:211], v[0:3]
	v_mfma_f32_16x16x32_bf16 v[146:149], v[108:111], v[76:79], v[28:31]
	v_mfma_f32_16x16x32_bf16 v[160:163], v[108:111], v[92:95], v[20:23]
	v_mfma_f32_16x16x32_bf16 v[178:181], v[108:111], v[200:203], v[12:15]
	v_mfma_f32_16x16x32_bf16 v[196:199], v[224:227], v[200:203], v[8:11]
	s_barrier
	s_nop 0
	s_nop 0
	ds_read_b128 v[8:11], v158
	ds_read_b128 v[12:15], v158 offset:1024
	ds_read_b128 v[200:203], v158 offset:2048
	ds_read_b128 v[204:207], v158 offset:3072
	ds_read_b128 v[20:23], v155 offset:32768
	ds_read_b128 v[28:31], v155 offset:33792
	ds_read_b128 v[36:39], v173 offset:32768
	ds_read_b128 v[44:47], v173 offset:33792
	ds_read_b128 v[52:55], v174 offset:32768
	ds_read_b128 v[208:211], v174 offset:33792
	ds_read_b128 v[220:223], v175 offset:32768
	ds_read_b128 v[224:227], v175 offset:33792
	s_waitcnt vmcnt(2)
	s_barrier
; #define LDA(dst,b,h) _Pragma("unroll") for(int m=0;m<4;++m) _Pragma("unroll") for(int k=0;k<2;++k) \
;     dst[m][k]=*reinterpret_cast<const bf16x8*>((char*)SA(b,h)+lds_byte(wr*64+m*16+fr,k*32+fq*8))
; #define LDB(dst,b,h) _Pragma("unroll") for(int n=0;n<2;++n) _Pragma("unroll") for(int k=0;k<2;++k) \
;     dst[n][k]=*reinterpret_cast<const bf16x8*>((char*)SB(b,h)+lds_byte(wc*32+n*16+fr,k*32+fq*8))
; #define MMA(ai,bj,At_,Bt_) do{__builtin_amdgcn_s_setprio(1); \
;     _Pragma("unroll") for(int m=0;m<4;++m) _Pragma("unroll") for(int n=0;n<2;++n) _Pragma("unroll") for(int k=0;k<2;++k) \
;       acc[ai][bj][m][n]=__builtin_amdgcn_mfma_f32_16x16x32_bf16(Bt_[n][k],At_[m][k],acc[ai][bj][m][n],0,0,0); \
;     __builtin_amdgcn_s_setprio(0);}while(0)
; #define WAIT_V(n) asm volatile("s_waitcnt vmcnt(" #n ")":::"memory")
; #define WAIT_L(n) asm volatile("s_waitcnt lgkmcnt(" #n ")":::"memory")
; #define BAR __builtin_amdgcn_s_barrier()
; DEVINL void gemm8_mainloop(const u16* A, long lda, const u16* Bt, long ldb, int K, int brow, int bcol, f32x4 (&acc)[2][2][4][2], char* smem, int tid) {
;     ...
;     LDA(At,0,1); WAIT_V(4); BAR; WAIT_L(0); MMA(1,0,At,B0); MMA(1,1,At,B1); BAR; }
;   { LDB(B0,1,0); LDA(At,1,0); WAIT_V(2); BAR; WAIT_L(0); MMA(0,0,At,B0); BAR;
;     LDB(B1,1,1); WAIT_V(0); BAR; WAIT_L(0); MMA(0,1,At,B1); BAR;
;     LDA(At,1,1); BAR; WAIT_L(0); MMA(1,0,At,B0); MMA(1,1,At,B1); BAR; }
;   if(wr==0)BAR;
	s_waitcnt lgkmcnt(0)
	v_mfma_f32_16x16x32_bf16 v[68:71], v[8:11], v[20:23], v[124:127]
	v_mfma_f32_16x16x32_bf16 v[124:127], v[12:15], v[28:31], v[68:71]
	v_mfma_f32_16x16x32_bf16 v[68:71], v[200:203], v[20:23], v[120:123]
	v_mfma_f32_16x16x32_bf16 v[120:123], v[204:207], v[28:31], v[68:71]
	v_mfma_f32_16x16x32_bf16 v[68:71], v[8:11], v[36:39], v[116:119]
	v_mfma_f32_16x16x32_bf16 v[108:111], v[12:15], v[44:47], v[68:71]
	v_mfma_f32_16x16x32_bf16 v[68:71], v[200:203], v[36:39], v[112:115]
	v_mfma_f32_16x16x32_bf16 v[100:103], v[204:207], v[44:47], v[68:71]
	v_mfma_f32_16x16x32_bf16 v[68:71], v[8:11], v[52:55], v[138:141]
	v_mfma_f32_16x16x32_bf16 v[92:95], v[12:15], v[208:211], v[68:71]
	v_mfma_f32_16x16x32_bf16 v[68:71], v[200:203], v[52:55], v[104:107]
	v_mfma_f32_16x16x32_bf16 v[84:87], v[204:207], v[208:211], v[68:71]
	v_mfma_f32_16x16x32_bf16 v[68:71], v[8:11], v[220:223], v[216:219]
	v_mfma_f32_16x16x32_bf16 v[76:79], v[12:15], v[224:227], v[68:71]
	v_mfma_f32_16x16x32_bf16 v[68:71], v[200:203], v[220:223], v[96:99]
	v_mfma_f32_16x16x32_bf16 v[68:71], v[204:207], v[224:227], v[68:71]
	s_barrier
	ds_read_b128 v[138:141], v156
	ds_read_b128 v[216:219], v156 offset:1024
	ds_read_b128 v[236:239], v156 offset:2048
	ds_read_b128 v[156:159], v156 offset:3072
	s_waitcnt vmcnt(0)
	s_barrier
	s_waitcnt lgkmcnt(0)
	v_mfma_f32_16x16x32_bf16 v[96:99], v[138:141], v[20:23], v[228:231]
	v_mfma_f32_16x16x32_bf16 v[20:23], v[236:239], v[20:23], v[88:91]
	v_mfma_f32_16x16x32_bf16 v[112:115], v[156:159], v[28:31], v[20:23]
	v_mfma_f32_16x16x32_bf16 v[20:23], v[138:141], v[36:39], v[184:187]
	v_mfma_f32_16x16x32_bf16 v[104:107], v[216:219], v[44:47], v[20:23]
	v_mfma_f32_16x16x32_bf16 v[20:23], v[236:239], v[36:39], v[80:83]
	v_mfma_f32_16x16x32_bf16 v[116:119], v[216:219], v[28:31], v[96:99]
	v_mfma_f32_16x16x32_bf16 v[96:99], v[156:159], v[44:47], v[20:23]
	v_mfma_f32_16x16x32_bf16 v[20:23], v[138:141], v[52:55], v[188:191]
	v_mfma_f32_16x16x32_bf16 v[88:91], v[216:219], v[208:211], v[20:23]
	v_mfma_f32_16x16x32_bf16 v[20:23], v[236:239], v[52:55], v[72:75]
	v_mfma_f32_16x16x32_bf16 v[80:83], v[156:159], v[208:211], v[20:23]
	v_mfma_f32_16x16x32_bf16 v[20:23], v[138:141], v[220:223], v[192:195]
	v_mfma_f32_16x16x32_bf16 v[72:75], v[216:219], v[224:227], v[20:23]
	v_mfma_f32_16x16x32_bf16 v[20:23], v[236:239], v[220:223], v[64:67]
	v_mfma_f32_16x16x32_bf16 v[64:67], v[156:159], v[224:227], v[20:23]
	s_barrier
	ds_read_b128 v[182:185], v155 offset:49152
	ds_read_b128 v[186:189], v155 offset:50176
	ds_read_b128 v[190:193], v173 offset:49152
	ds_read_b128 v[208:211], v173 offset:50176
	ds_read_b128 v[220:223], v174 offset:49152
	ds_read_b128 v[224:227], v174 offset:50176
	ds_read_b128 v[228:231], v175 offset:49152
	ds_read_b128 v[240:243], v175 offset:50176
	s_barrier
	s_waitcnt lgkmcnt(0)
	v_mfma_f32_16x16x32_bf16 v[20:23], v[8:11], v[182:185], v[60:63]
	v_mfma_f32_16x16x32_bf16 v[60:63], v[12:15], v[186:189], v[20:23]
	v_mfma_f32_16x16x32_bf16 v[20:23], v[200:203], v[182:185], v[56:59]
	v_mfma_f32_16x16x32_bf16 v[52:55], v[204:207], v[186:189], v[20:23]
	v_mfma_f32_16x16x32_bf16 v[20:23], v[8:11], v[190:193], v[212:215]
	v_mfma_f32_16x16x32_bf16 v[44:47], v[12:15], v[208:211], v[20:23]
	v_mfma_f32_16x16x32_bf16 v[20:23], v[200:203], v[190:193], v[48:51]
	v_mfma_f32_16x16x32_bf16 v[36:39], v[204:207], v[208:211], v[20:23]
	v_mfma_f32_16x16x32_bf16 v[20:23], v[8:11], v[220:223], v[232:235]
	v_mfma_f32_16x16x32_bf16 v[8:11], v[8:11], v[228:231], v[142:145]
	v_mfma_f32_16x16x32_bf16 v[28:31], v[12:15], v[224:227], v[20:23]
	v_mfma_f32_16x16x32_bf16 v[20:23], v[200:203], v[220:223], v[40:43]
	v_mfma_f32_16x16x32_bf16 v[12:15], v[12:15], v[240:243], v[8:11]
	v_mfma_f32_16x16x32_bf16 v[8:11], v[200:203], v[228:231], v[32:35]
	v_mfma_f32_16x16x32_bf16 v[20:23], v[204:207], v[224:227], v[20:23]
	v_mfma_f32_16x16x32_bf16 v[8:11], v[204:207], v[240:243], v[8:11]
	v_mfma_f32_16x16x32_bf16 v[32:35], v[138:141], v[182:185], v[146:149]
	v_mfma_f32_16x16x32_bf16 v[24:27], v[236:239], v[182:185], v[24:27]
	v_mfma_f32_16x16x32_bf16 v[16:19], v[236:239], v[190:193], v[16:19]
	v_mfma_f32_16x16x32_bf16 v[56:59], v[216:219], v[186:189], v[32:35]
	v_mfma_f32_16x16x32_bf16 v[48:51], v[156:159], v[186:189], v[24:27]
	v_mfma_f32_16x16x32_bf16 v[24:27], v[138:141], v[190:193], v[160:163]
	v_mfma_f32_16x16x32_bf16 v[32:35], v[156:159], v[208:211], v[16:19]
	v_mfma_f32_16x16x32_bf16 v[16:19], v[138:141], v[220:223], v[178:181]
	v_mfma_f32_16x16x32_bf16 v[40:43], v[216:219], v[208:211], v[24:27]
	v_mfma_f32_16x16x32_bf16 v[24:27], v[216:219], v[224:227], v[16:19]
	v_mfma_f32_16x16x32_bf16 v[16:19], v[236:239], v[220:223], v[196:199]
	v_mfma_f32_16x16x32_bf16 v[4:7], v[138:141], v[228:231], v[4:7]
	v_mfma_f32_16x16x32_bf16 v[0:3], v[236:239], v[228:231], v[0:3]
	v_mfma_f32_16x16x32_bf16 v[16:19], v[156:159], v[224:227], v[16:19]
	v_mfma_f32_16x16x32_bf16 v[4:7], v[216:219], v[240:243], v[4:7]
	v_mfma_f32_16x16x32_bf16 v[0:3], v[156:159], v[240:243], v[0:3]
	s_cmpk_gt_u32 s37, 0xff
	s_barrier
	s_cbranch_scc1 .LBB0_1941
	s_barrier

; #define STAGE(P,BASE,LD,br,kt) do{long _g=(long)(br)*(LD)+(long)(kt)*BK; \
;     _Pragma("unroll") for(int _i=0;_i<2;++_i){int _b=tid*16+_i*8192;int _r,_c;stage_rc(_b,_r,_c); \
;       __builtin_amdgcn_global_load_lds((const unsigned*)((BASE)+_g+(long)_r*(LD)+_c), \
;         (unsigned*)((char*)(P)+_b),16,0,0);}}while(0)
; #define STAGE(P,BASE,LD,br,kt) do{long _g=(long)(br)*(LD)+(long)(kt)*BK; \
;     _Pragma("unroll") for(int _i=0;_i<2;++_i){int _b=tid*16+_i*8192;int _r,_c;stage_rc(_b,_r,_c); \
;       __builtin_amdgcn_global_load_lds((const unsigned*)((BASE)+_g+(long)_r*(LD)+_c), \
;         (unsigned*)((char*)(P)+_b),16,0,0);}}while(0)
; #define LDA(dst,b,h) _Pragma("unroll") for(int m=0;m<4;++m) _Pragma("unroll") for(int k=0;k<2;++k) \
;     dst[m][k]=*reinterpret_cast<const bf16x8*>((char*)SA(b,h)+lds_byte(wr*64+m*16+fr,k*32+fq*8))
; #define LDB(dst,b,h) _Pragma("unroll") for(int n=0;n<2;++n) _Pragma("unroll") for(int k=0;k<2;++k) \
;     dst[n][k]=*reinterpret_cast<const bf16x8*>((char*)SB(b,h)+lds_byte(wc*32+n*16+fr,k*32+fq*8))
; #define MMA(ai,bj,At_,Bt_) do{__builtin_amdgcn_s_setprio(1); \
;     _Pragma("unroll") for(int m=0;m<4;++m) _Pragma("unroll") for(int n=0;n<2;++n) _Pragma("unroll") for(int k=0;k<2;++k) \
;       acc[ai][bj][m][n]=__builtin_amdgcn_mfma_f32_16x16x32_bf16(Bt_[n][k],At_[m][k],acc[ai][bj][m][n],0,0,0); \
;     __builtin_amdgcn_s_setprio(0);}while(0)
; #define WAIT_L(n) asm volatile("s_waitcnt lgkmcnt(" #n ")":::"memory")
; #define BAR __builtin_amdgcn_s_barrier()
; #define SCHED __builtin_amdgcn_sched_barrier(0)
; DEVINL void gemm8_mainloop(const u16* A, long lda, const u16* Bt, long ldb, int K, int brow, int bcol, f32x4 (&acc)[2][2][4][2], char* smem, int tid) {
;     ...
;     LDB(B0,0,0); SCHED; LDA(At,0,0); STAGE(SA(1,1),A,lda,brow+HALF,t+1);
;     WAIT_L(8); BAR; WAIT_L(0); MMA(0,0,At,B0); BAR; SCHED;
;     LDB(B1,0,1); STAGE(SB(0,0),Bt,ldb,bcol,t+2);
;     BAR; WAIT_L(0); MMA(0,1,At,B1); BAR;
;     LDA(At,0,1); STAGE(SA(0,0),A,lda,brow,t+2);
;     BAR; WAIT_L(0); MMA(1,0,At,B0); BAR; SCHED;
.LBB0_1987:
	ds_read_b128 v[178:181], v163
	ds_read_b128 v[182:185], v163 offset:1024
	ds_read_b128 v[186:189], v163 offset:2048
	ds_read_b128 v[190:193], v163 offset:3072
	v_add_u32_e32 v174, 0xc000, v152
	v_lshl_add_u64 v[242:243], s[94:95], 0, v[146:147]
	v_readfirstlane_b32 s25, v174
	v_add_u32_e32 v175, 0xe000, v152
	v_add_u32_e32 v171, s23, v162
	v_add_u32_e32 v172, s34, v162
	v_add_u32_e32 v173, s35, v162
	v_lshl_add_u64 v[164:165], v[242:243], 0, s[2:3]
	s_mov_b32 m0, s25
	v_lshl_add_u64 v[244:245], s[94:95], 0, v[148:149]
	v_readfirstlane_b32 s25, v175
	ds_read_b128 v[166:169], v153
	ds_read_b128 v[194:197], v153 offset:1024
	ds_read_b128 v[198:201], v171
	ds_read_b128 v[202:205], v171 offset:1024
	ds_read_b128 v[206:209], v172
	ds_read_b128 v[210:213], v172 offset:1024
	ds_read_b128 v[214:217], v173
	ds_read_b128 v[218:221], v173 offset:1024
	global_load_lds_dwordx4 v[164:165], off
	v_lshl_add_u64 v[164:165], v[244:245], 0, s[2:3]
	s_mov_b32 m0, s25
	s_nop 0
	global_load_lds_dwordx4 v[164:165], off
	s_waitcnt lgkmcnt(8)
	s_barrier
	s_waitcnt lgkmcnt(0)
	v_mfma_f32_16x16x32_bf16 v[124:127], v[178:181], v[166:169], v[124:127]
	v_mfma_f32_16x16x32_bf16 v[120:123], v[186:189], v[166:169], v[120:123]
	v_mfma_f32_16x16x32_bf16 v[116:119], v[178:181], v[198:201], v[116:119]
	v_mfma_f32_16x16x32_bf16 v[112:115], v[186:189], v[198:201], v[112:115]
	v_mfma_f32_16x16x32_bf16 v[108:111], v[178:181], v[206:209], v[108:111]
	v_mfma_f32_16x16x32_bf16 v[104:107], v[186:189], v[206:209], v[104:107]
	v_mfma_f32_16x16x32_bf16 v[100:103], v[178:181], v[214:217], v[100:103]
	v_mfma_f32_16x16x32_bf16 v[96:99], v[186:189], v[214:217], v[96:99]
	v_mfma_f32_16x16x32_bf16 v[124:127], v[182:185], v[194:197], v[124:127]
	v_mfma_f32_16x16x32_bf16 v[120:123], v[190:193], v[194:197], v[120:123]
	v_mfma_f32_16x16x32_bf16 v[116:119], v[182:185], v[202:205], v[116:119]
	v_mfma_f32_16x16x32_bf16 v[112:115], v[190:193], v[202:205], v[112:115]
	v_mfma_f32_16x16x32_bf16 v[108:111], v[182:185], v[210:213], v[108:111]
	v_mfma_f32_16x16x32_bf16 v[104:107], v[190:193], v[210:213], v[104:107]
	v_mfma_f32_16x16x32_bf16 v[100:103], v[182:185], v[218:221], v[100:103]
	v_mfma_f32_16x16x32_bf16 v[96:99], v[190:193], v[218:221], v[96:99]
	s_barrier
	v_add_u32_e32 v164, s28, v154
	v_lshl_add_u64 v[246:247], s[94:95], 0, v[142:143]
	v_readfirstlane_b32 s25, v164
	v_add_u32_e32 v165, 0x2000, v164
	v_lshl_add_u64 v[238:239], v[246:247], 0, s[4:5]
	s_mov_b32 m0, s25
	v_lshl_add_u64 v[248:249], s[94:95], 0, v[144:145]
	v_readfirstlane_b32 s25, v165
	ds_read_b128 v[222:225], v160
	ds_read_b128 v[226:229], v160 offset:1024
	ds_read_b128 v[230:233], v160 offset:2048
	ds_read_b128 v[234:237], v160 offset:3072
	global_load_lds_dwordx4 v[238:239], off
	v_lshl_add_u64 v[238:239], v[248:249], 0, s[4:5]
	s_mov_b32 m0, s25
	s_nop 0
	global_load_lds_dwordx4 v[238:239], off
	s_barrier
	s_waitcnt lgkmcnt(0)
	v_mfma_f32_16x16x32_bf16 v[92:95], v[222:225], v[166:169], v[92:95]
	v_mfma_f32_16x16x32_bf16 v[88:91], v[230:233], v[166:169], v[88:91]
	v_mfma_f32_16x16x32_bf16 v[84:87], v[222:225], v[198:201], v[84:87]
	v_mfma_f32_16x16x32_bf16 v[80:83], v[230:233], v[198:201], v[80:83]
	v_mfma_f32_16x16x32_bf16 v[76:79], v[222:225], v[206:209], v[76:79]
	v_mfma_f32_16x16x32_bf16 v[72:75], v[230:233], v[206:209], v[72:75]
	v_mfma_f32_16x16x32_bf16 v[68:71], v[222:225], v[214:217], v[68:71]
	v_mfma_f32_16x16x32_bf16 v[64:67], v[230:233], v[214:217], v[64:67]
	v_mfma_f32_16x16x32_bf16 v[92:95], v[226:229], v[194:197], v[92:95]
	v_mfma_f32_16x16x32_bf16 v[88:91], v[234:237], v[194:197], v[88:91]
	v_mfma_f32_16x16x32_bf16 v[84:87], v[226:229], v[202:205], v[84:87]
	v_mfma_f32_16x16x32_bf16 v[80:83], v[234:237], v[202:205], v[80:83]
	v_mfma_f32_16x16x32_bf16 v[76:79], v[226:229], v[210:213], v[76:79]
	v_mfma_f32_16x16x32_bf16 v[72:75], v[234:237], v[210:213], v[72:75]
	v_mfma_f32_16x16x32_bf16 v[68:71], v[226:229], v[218:221], v[68:71]
	v_mfma_f32_16x16x32_bf16 v[64:67], v[234:237], v[218:221], v[64:67]
	v_readfirstlane_b32 s25, v152
	v_lshl_add_u64 v[166:167], v[242:243], 0, s[6:7]
	s_mov_b32 m0, s25
	s_barrier
	ds_read_b128 v[194:197], v153 offset:16384
	ds_read_b128 v[198:201], v153 offset:17408
	ds_read_b128 v[202:205], v171 offset:16384
	ds_read_b128 v[206:209], v171 offset:17408
	ds_read_b128 v[210:213], v172 offset:16384
	ds_read_b128 v[214:217], v172 offset:17408
	ds_read_b128 v[218:221], v173 offset:16384
	ds_read_b128 v[238:241], v173 offset:17408
	global_load_lds_dwordx4 v[166:167], off
	v_add_u32_e32 v166, 0x2000, v152
	v_lshl_add_u64 v[168:169], v[244:245], 0, s[6:7]
	v_readfirstlane_b32 s25, v166
	s_mov_b32 m0, s25
	s_nop 0
	global_load_lds_dwordx4 v[168:169], off
	s_barrier
	s_waitcnt lgkmcnt(0)
	v_mfma_f32_16x16x32_bf16 v[60:63], v[178:181], v[194:197], v[60:63]
	v_mfma_f32_16x16x32_bf16 v[56:59], v[186:189], v[194:197], v[56:59]
	v_mfma_f32_16x16x32_bf16 v[52:55], v[178:181], v[202:205], v[52:55]
	v_mfma_f32_16x16x32_bf16 v[48:51], v[186:189], v[202:205], v[48:51]
	v_mfma_f32_16x16x32_bf16 v[44:47], v[178:181], v[210:213], v[44:47]
	v_mfma_f32_16x16x32_bf16 v[40:43], v[186:189], v[210:213], v[40:43]
	v_mfma_f32_16x16x32_bf16 v[36:39], v[178:181], v[218:221], v[36:39]
	v_mfma_f32_16x16x32_bf16 v[32:35], v[186:189], v[218:221], v[32:35]
	v_mfma_f32_16x16x32_bf16 v[60:63], v[182:185], v[198:201], v[60:63]
	v_mfma_f32_16x16x32_bf16 v[56:59], v[190:193], v[198:201], v[56:59]
	v_mfma_f32_16x16x32_bf16 v[52:55], v[182:185], v[206:209], v[52:55]
	v_mfma_f32_16x16x32_bf16 v[48:51], v[190:193], v[206:209], v[48:51]
	v_mfma_f32_16x16x32_bf16 v[44:47], v[182:185], v[214:217], v[44:47]
	v_mfma_f32_16x16x32_bf16 v[40:43], v[190:193], v[214:217], v[40:43]
	v_mfma_f32_16x16x32_bf16 v[36:39], v[182:185], v[238:241], v[36:39]
	v_mfma_f32_16x16x32_bf16 v[32:35], v[190:193], v[238:241], v[32:35]
	s_barrier
; #define STAGE(P,BASE,LD,br,kt) do{long _g=(long)(br)*(LD)+(long)(kt)*BK; \
;     _Pragma("unroll") for(int _i=0;_i<2;++_i){int _b=tid*16+_i*8192;int _r,_c;stage_rc(_b,_r,_c); \
;       __builtin_amdgcn_global_load_lds((const unsigned*)((BASE)+_g+(long)_r*(LD)+_c), \
;         (unsigned*)((char*)(P)+_b),16,0,0);}}while(0)
; #define STAGE(P,BASE,LD,br,kt) do{long _g=(long)(br)*(LD)+(long)(kt)*BK; \
;     _Pragma("unroll") for(int _i=0;_i<2;++_i){int _b=tid*16+_i*8192;int _r,_c;stage_rc(_b,_r,_c); \
;       __builtin_amdgcn_global_load_lds((const unsigned*)((BASE)+_g+(long)_r*(LD)+_c), \
;         (unsigned*)((char*)(P)+_b),16,0,0);}}while(0)
; #define LDA(dst,b,h) _Pragma("unroll") for(int m=0;m<4;++m) _Pragma("unroll") for(int k=0;k<2;++k) \
;     dst[m][k]=*reinterpret_cast<const bf16x8*>((char*)SA(b,h)+lds_byte(wr*64+m*16+fr,k*32+fq*8))
; #define LDB(dst,b,h) _Pragma("unroll") for(int n=0;n<2;++n) _Pragma("unroll") for(int k=0;k<2;++k) \
;     dst[n][k]=*reinterpret_cast<const bf16x8*>((char*)SB(b,h)+lds_byte(wc*32+n*16+fr,k*32+fq*8))
; #define MMA(ai,bj,At_,Bt_) do{__builtin_amdgcn_s_setprio(1); \
;     _Pragma("unroll") for(int m=0;m<4;++m) _Pragma("unroll") for(int n=0;n<2;++n) _Pragma("unroll") for(int k=0;k<2;++k) \
;       acc[ai][bj][m][n]=__builtin_amdgcn_mfma_f32_16x16x32_bf16(Bt_[n][k],At_[m][k],acc[ai][bj][m][n],0,0,0); \
;     __builtin_amdgcn_s_setprio(0);}while(0)
; #define WAIT_V(n) asm volatile("s_waitcnt vmcnt(" #n ")":::"memory")
; #define WAIT_L(n) asm volatile("s_waitcnt lgkmcnt(" #n ")":::"memory")
; #define BAR __builtin_amdgcn_s_barrier()
; #define SCHED __builtin_amdgcn_sched_barrier(0)
; DEVINL void gemm8_mainloop(const u16* A, long lda, const u16* Bt, long ldb, int K, int brow, int bcol, f32x4 (&acc)[2][2][4][2], char* smem, int tid) {
;     ...
;     STAGE(SB(0,1),Bt,ldb,bcol+HALF,t+2);
;     WAIT_V(6); BAR; MMA(1,1,At,B1); BAR;
;     LDB(B0,1,0); SCHED; LDA(At,1,0); STAGE(SA(0,1),A,lda,brow+HALF,t+2);
;     WAIT_L(8); BAR; WAIT_L(0); MMA(0,0,At,B0); BAR; SCHED;
;     LDB(B1,1,1); STAGE(SB(1,0),Bt,ldb,bcol,t+3);
;     BAR; WAIT_L(0); MMA(0,1,At,B1); BAR;
;     LDA(At,1,1); STAGE(SA(1,0),A,lda,brow,t+3);
	v_add_u32_e32 v167, s29, v154
	v_lshl_add_u64 v[168:169], v[246:247], 0, s[8:9]
	v_readfirstlane_b32 s25, v167
	s_mov_b32 m0, s25
	v_lshl_add_u64 v[178:179], v[248:249], 0, s[8:9]
	global_load_lds_dwordx4 v[168:169], off
	v_add_u32_e32 v168, 0x2000, v167
	s_nop 0
	v_readfirstlane_b32 s25, v168
	s_mov_b32 m0, s25
	s_nop 0
	global_load_lds_dwordx4 v[178:179], off
	s_waitcnt vmcnt(6)
	s_barrier
	v_mfma_f32_16x16x32_bf16 v[28:31], v[222:225], v[194:197], v[28:31]
	v_mfma_f32_16x16x32_bf16 v[24:27], v[230:233], v[194:197], v[24:27]
	v_mfma_f32_16x16x32_bf16 v[20:23], v[222:225], v[202:205], v[20:23]
	v_mfma_f32_16x16x32_bf16 v[16:19], v[230:233], v[202:205], v[16:19]
	v_mfma_f32_16x16x32_bf16 v[12:15], v[222:225], v[210:213], v[12:15]
	v_mfma_f32_16x16x32_bf16 v[8:11], v[230:233], v[210:213], v[8:11]
	v_mfma_f32_16x16x32_bf16 v[4:7], v[222:225], v[218:221], v[4:7]
	v_mfma_f32_16x16x32_bf16 v[0:3], v[230:233], v[218:221], v[0:3]
	v_mfma_f32_16x16x32_bf16 v[28:31], v[226:229], v[198:201], v[28:31]
	v_mfma_f32_16x16x32_bf16 v[24:27], v[234:237], v[198:201], v[24:27]
	v_mfma_f32_16x16x32_bf16 v[20:23], v[226:229], v[206:209], v[20:23]
	v_mfma_f32_16x16x32_bf16 v[16:19], v[234:237], v[206:209], v[16:19]
	v_mfma_f32_16x16x32_bf16 v[12:15], v[226:229], v[214:217], v[12:15]
	v_mfma_f32_16x16x32_bf16 v[8:11], v[234:237], v[214:217], v[8:11]
	v_mfma_f32_16x16x32_bf16 v[4:7], v[226:229], v[238:241], v[4:7]
	v_mfma_f32_16x16x32_bf16 v[0:3], v[234:237], v[238:241], v[0:3]
	s_barrier
	ds_read_b128 v[178:181], v156
	ds_read_b128 v[182:185], v156 offset:1024
	ds_read_b128 v[186:189], v156 offset:2048
	ds_read_b128 v[190:193], v156 offset:3072
	v_add_u32_e32 v169, 0x4000, v152
	v_add_u32_e32 v170, 0x6000, v152
	v_readfirstlane_b32 s25, v169
	v_lshl_add_u64 v[226:227], v[242:243], 0, s[10:11]
	s_mov_b32 m0, s25
	v_readfirstlane_b32 s25, v170
	ds_read_b128 v[194:197], v153 offset:32768
	ds_read_b128 v[198:201], v153 offset:33792
	ds_read_b128 v[202:205], v171 offset:32768
	ds_read_b128 v[206:209], v171 offset:33792
	ds_read_b128 v[210:213], v172 offset:32768
	ds_read_b128 v[214:217], v172 offset:33792
	ds_read_b128 v[218:221], v173 offset:32768
	ds_read_b128 v[222:225], v173 offset:33792
	global_load_lds_dwordx4 v[226:227], off
	v_lshl_add_u64 v[226:227], v[244:245], 0, s[10:11]
	s_mov_b32 m0, s25
	s_nop 0
	global_load_lds_dwordx4 v[226:227], off
	s_waitcnt lgkmcnt(8)
	s_barrier
	s_waitcnt lgkmcnt(0)
	v_mfma_f32_16x16x32_bf16 v[124:127], v[178:181], v[194:197], v[124:127]
	v_mfma_f32_16x16x32_bf16 v[120:123], v[186:189], v[194:197], v[120:123]
	v_mfma_f32_16x16x32_bf16 v[116:119], v[178:181], v[202:205], v[116:119]
	v_mfma_f32_16x16x32_bf16 v[112:115], v[186:189], v[202:205], v[112:115]
	v_mfma_f32_16x16x32_bf16 v[108:111], v[178:181], v[210:213], v[108:111]
	v_mfma_f32_16x16x32_bf16 v[104:107], v[186:189], v[210:213], v[104:107]
	v_mfma_f32_16x16x32_bf16 v[100:103], v[178:181], v[218:221], v[100:103]
	v_mfma_f32_16x16x32_bf16 v[96:99], v[186:189], v[218:221], v[96:99]
	v_mfma_f32_16x16x32_bf16 v[124:127], v[182:185], v[198:201], v[124:127]
	v_mfma_f32_16x16x32_bf16 v[120:123], v[190:193], v[198:201], v[120:123]
	v_mfma_f32_16x16x32_bf16 v[116:119], v[182:185], v[206:209], v[116:119]
	v_mfma_f32_16x16x32_bf16 v[112:115], v[190:193], v[206:209], v[112:115]
	v_mfma_f32_16x16x32_bf16 v[108:111], v[182:185], v[214:217], v[108:111]
	v_mfma_f32_16x16x32_bf16 v[104:107], v[190:193], v[214:217], v[104:107]
	v_mfma_f32_16x16x32_bf16 v[100:103], v[182:185], v[222:225], v[100:103]
	v_mfma_f32_16x16x32_bf16 v[96:99], v[190:193], v[222:225], v[96:99]
	s_barrier
	v_readfirstlane_b32 s25, v157
	v_add_u32_e32 v177, 0x2000, v157
	v_lshl_add_u64 v[250:251], v[246:247], 0, s[12:13]
	s_mov_b32 m0, s25
	v_readfirstlane_b32 s25, v177
	ds_read_b128 v[226:229], v155
	ds_read_b128 v[230:233], v155 offset:1024
	ds_read_b128 v[234:237], v155 offset:2048
	ds_read_b128 v[238:241], v155 offset:3072
	global_load_lds_dwordx4 v[250:251], off
	v_lshl_add_u64 v[250:251], v[248:249], 0, s[12:13]
	s_mov_b32 m0, s25
	s_nop 0
	global_load_lds_dwordx4 v[250:251], off
	s_barrier
	s_waitcnt lgkmcnt(0)
	v_mfma_f32_16x16x32_bf16 v[92:95], v[226:229], v[194:197], v[92:95]
	v_mfma_f32_16x16x32_bf16 v[88:91], v[234:237], v[194:197], v[88:91]
	v_mfma_f32_16x16x32_bf16 v[84:87], v[226:229], v[202:205], v[84:87]
	v_mfma_f32_16x16x32_bf16 v[80:83], v[234:237], v[202:205], v[80:83]
	v_mfma_f32_16x16x32_bf16 v[76:79], v[226:229], v[210:213], v[76:79]
	v_mfma_f32_16x16x32_bf16 v[72:75], v[234:237], v[210:213], v[72:75]
	v_mfma_f32_16x16x32_bf16 v[68:71], v[226:229], v[218:221], v[68:71]
	v_mfma_f32_16x16x32_bf16 v[64:67], v[234:237], v[218:221], v[64:67]
	v_mfma_f32_16x16x32_bf16 v[92:95], v[230:233], v[198:201], v[92:95]
	v_mfma_f32_16x16x32_bf16 v[88:91], v[238:241], v[198:201], v[88:91]
	v_mfma_f32_16x16x32_bf16 v[84:87], v[230:233], v[206:209], v[84:87]
	v_mfma_f32_16x16x32_bf16 v[80:83], v[238:241], v[206:209], v[80:83]
	v_mfma_f32_16x16x32_bf16 v[76:79], v[230:233], v[214:217], v[76:79]
	v_mfma_f32_16x16x32_bf16 v[72:75], v[238:241], v[214:217], v[72:75]
	v_mfma_f32_16x16x32_bf16 v[68:71], v[230:233], v[222:225], v[68:71]
	v_mfma_f32_16x16x32_bf16 v[64:67], v[238:241], v[222:225], v[64:67]
	v_readfirstlane_b32 s25, v158
	v_lshl_add_u64 v[242:243], v[242:243], 0, s[14:15]
	s_mov_b32 m0, s25
	v_readfirstlane_b32 s25, v159
	s_barrier
	ds_read_b128 v[194:197], v153 offset:49152
	ds_read_b128 v[198:201], v153 offset:50176
	ds_read_b128 v[202:205], v171 offset:49152
	ds_read_b128 v[206:209], v171 offset:50176
	ds_read_b128 v[210:213], v172 offset:49152
	ds_read_b128 v[214:217], v172 offset:50176
	ds_read_b128 v[218:221], v173 offset:49152
	ds_read_b128 v[222:225], v173 offset:50176
	global_load_lds_dwordx4 v[242:243], off
	v_lshl_add_u64 v[242:243], v[244:245], 0, s[14:15]
	s_mov_b32 m0, s25
	s_nop 0
	global_load_lds_dwordx4 v[242:243], off
	s_barrier
; #define STAGE(P,BASE,LD,br,kt) do{long _g=(long)(br)*(LD)+(long)(kt)*BK; \
;     _Pragma("unroll") for(int _i=0;_i<2;++_i){int _b=tid*16+_i*8192;int _r,_c;stage_rc(_b,_r,_c); \
;       __builtin_amdgcn_global_load_lds((const unsigned*)((BASE)+_g+(long)_r*(LD)+_c), \
;         (unsigned*)((char*)(P)+_b),16,0,0);}}while(0)
; #define STAGE(P,BASE,LD,br,kt) do{long _g=(long)(br)*(LD)+(long)(kt)*BK; \
;     _Pragma("unroll") for(int _i=0;_i<2;++_i){int _b=tid*16+_i*8192;int _r,_c;stage_rc(_b,_r,_c); \
;       __builtin_amdgcn_global_load_lds((const unsigned*)((BASE)+_g+(long)_r*(LD)+_c), \
;         (unsigned*)((char*)(P)+_b),16,0,0);}}while(0)
; #define LDA(dst,b,h) _Pragma("unroll") for(int m=0;m<4;++m) _Pragma("unroll") for(int k=0;k<2;++k) \
;     dst[m][k]=*reinterpret_cast<const bf16x8*>((char*)SA(b,h)+lds_byte(wr*64+m*16+fr,k*32+fq*8))
; #define LDB(dst,b,h) _Pragma("unroll") for(int n=0;n<2;++n) _Pragma("unroll") for(int k=0;k<2;++k) \
;     dst[n][k]=*reinterpret_cast<const bf16x8*>((char*)SB(b,h)+lds_byte(wc*32+n*16+fr,k*32+fq*8))
; #define MMA(ai,bj,At_,Bt_) do{__builtin_amdgcn_s_setprio(1); \
;     _Pragma("unroll") for(int m=0;m<4;++m) _Pragma("unroll") for(int n=0;n<2;++n) _Pragma("unroll") for(int k=0;k<2;++k) \
;       acc[ai][bj][m][n]=__builtin_amdgcn_mfma_f32_16x16x32_bf16(Bt_[n][k],At_[m][k],acc[ai][bj][m][n],0,0,0); \
;     __builtin_amdgcn_s_setprio(0);}while(0)
; #define WAIT_V(n) asm volatile("s_waitcnt vmcnt(" #n ")":::"memory")
; #define WAIT_L(n) asm volatile("s_waitcnt lgkmcnt(" #n ")":::"memory")
; #define BAR __builtin_amdgcn_s_barrier()
; #define SCHED __builtin_amdgcn_sched_barrier(0)
; DEVINL void gemm8_mainloop(const u16* A, long lda, const u16* Bt, long ldb, int K, int brow, int bcol, f32x4 (&acc)[2][2][4][2], char* smem, int tid) {
;     ...
;     BAR; WAIT_L(0); MMA(1,0,At,B0); BAR; SCHED;
;     STAGE(SB(1,1),Bt,ldb,bcol+HALF,t+3);
;     WAIT_V(6); BAR; MMA(1,1,At,B1); BAR;
;   }
;   { LDB(B0,0,0); LDA(At,0,0); STAGE(SA(1,1),A,lda,brow+HALF,nt-1);
;     BAR; WAIT_L(0); MMA(0,0,At,B0); BAR;
;     LDB(B1,0,1); BAR; WAIT_L(0); MMA(0,1,At,B1); BAR;
	s_waitcnt lgkmcnt(0)
	v_mfma_f32_16x16x32_bf16 v[60:63], v[178:181], v[194:197], v[60:63]
	v_mfma_f32_16x16x32_bf16 v[56:59], v[186:189], v[194:197], v[56:59]
	v_mfma_f32_16x16x32_bf16 v[52:55], v[178:181], v[202:205], v[52:55]
	v_mfma_f32_16x16x32_bf16 v[48:51], v[186:189], v[202:205], v[48:51]
	v_mfma_f32_16x16x32_bf16 v[44:47], v[178:181], v[210:213], v[44:47]
	v_mfma_f32_16x16x32_bf16 v[40:43], v[186:189], v[210:213], v[40:43]
	v_mfma_f32_16x16x32_bf16 v[36:39], v[178:181], v[218:221], v[36:39]
	v_mfma_f32_16x16x32_bf16 v[32:35], v[186:189], v[218:221], v[32:35]
	v_mfma_f32_16x16x32_bf16 v[60:63], v[182:185], v[198:201], v[60:63]
	v_mfma_f32_16x16x32_bf16 v[56:59], v[190:193], v[198:201], v[56:59]
	v_mfma_f32_16x16x32_bf16 v[52:55], v[182:185], v[206:209], v[52:55]
	v_mfma_f32_16x16x32_bf16 v[48:51], v[190:193], v[206:209], v[48:51]
	v_mfma_f32_16x16x32_bf16 v[44:47], v[182:185], v[214:217], v[44:47]
	v_mfma_f32_16x16x32_bf16 v[40:43], v[190:193], v[214:217], v[40:43]
	v_mfma_f32_16x16x32_bf16 v[36:39], v[182:185], v[222:225], v[36:39]
	v_mfma_f32_16x16x32_bf16 v[32:35], v[190:193], v[222:225], v[32:35]
	s_barrier
	v_readfirstlane_b32 s25, v161
	v_add_u32_e32 v177, 0x2000, v161
	v_lshl_add_u64 v[178:179], v[246:247], 0, s[16:17]
	s_mov_b32 m0, s25
	v_readfirstlane_b32 s25, v177
	global_load_lds_dwordx4 v[178:179], off
	v_lshl_add_u64 v[178:179], v[248:249], 0, s[16:17]
	s_mov_b32 m0, s25
	s_nop 0
	global_load_lds_dwordx4 v[178:179], off
	s_waitcnt vmcnt(6)
	s_barrier
	v_mfma_f32_16x16x32_bf16 v[28:31], v[226:229], v[194:197], v[28:31]
	v_mfma_f32_16x16x32_bf16 v[24:27], v[234:237], v[194:197], v[24:27]
	v_mfma_f32_16x16x32_bf16 v[20:23], v[226:229], v[202:205], v[20:23]
	v_mfma_f32_16x16x32_bf16 v[16:19], v[234:237], v[202:205], v[16:19]
	v_mfma_f32_16x16x32_bf16 v[12:15], v[226:229], v[210:213], v[12:15]
	v_mfma_f32_16x16x32_bf16 v[8:11], v[234:237], v[210:213], v[8:11]
	v_mfma_f32_16x16x32_bf16 v[4:7], v[226:229], v[218:221], v[4:7]
	v_mfma_f32_16x16x32_bf16 v[0:3], v[234:237], v[218:221], v[0:3]
	v_mfma_f32_16x16x32_bf16 v[28:31], v[230:233], v[198:201], v[28:31]
	v_mfma_f32_16x16x32_bf16 v[24:27], v[238:241], v[198:201], v[24:27]
	v_mfma_f32_16x16x32_bf16 v[20:23], v[230:233], v[206:209], v[20:23]
	v_mfma_f32_16x16x32_bf16 v[16:19], v[238:241], v[206:209], v[16:19]
	v_mfma_f32_16x16x32_bf16 v[12:15], v[230:233], v[214:217], v[12:15]
	v_mfma_f32_16x16x32_bf16 v[8:11], v[238:241], v[214:217], v[8:11]
	v_mfma_f32_16x16x32_bf16 v[4:7], v[230:233], v[222:225], v[4:7]
	v_mfma_f32_16x16x32_bf16 v[0:3], v[238:241], v[222:225], v[0:3]
	s_add_i32 s24, s24, 2
	v_lshl_add_u64 v[142:143], v[142:143], 0, s[18:19]
	v_lshl_add_u64 v[144:145], v[144:145], 0, s[18:19]
	v_lshl_add_u64 v[146:147], v[146:147], 0, s[18:19]
	s_cmpk_lt_u32 s24, 0x7c
	v_lshl_add_u64 v[148:149], v[148:149], 0, s[18:19]
	s_barrier
	s_cbranch_scc1 .LBB0_1987
	s_or_b32 s24, s22, 0x80
	s_ashr_i32 s25, s24, 31
	s_lshl_b64 s[24:25], s[24:25], 14
	s_add_u32 s23, s62, s24
	s_addc_u32 s25, s63, s25
	s_add_u32 s24, s23, 0x3f80
	s_addc_u32 s25, s25, 0
	v_lshl_add_u64 v[158:159], v[134:135], 1, s[24:25]
	v_readfirstlane_b32 s23, v174
	v_lshl_add_u64 v[138:139], v[138:139], 1, v[158:159]
	s_mov_b32 m0, s23
	ds_read_b128 v[142:145], v163
	ds_read_b128 v[146:149], v163 offset:1024
	ds_read_b128 v[178:181], v163 offset:2048
	ds_read_b128 v[182:185], v163 offset:3072
	ds_read_b128 v[186:189], v153
	ds_read_b128 v[190:193], v153 offset:1024
	ds_read_b128 v[194:197], v171
	ds_read_b128 v[198:201], v171 offset:1024
	ds_read_b128 v[202:205], v172
	ds_read_b128 v[206:209], v172 offset:1024
	ds_read_b128 v[210:213], v173
	ds_read_b128 v[214:217], v173 offset:1024
	global_load_lds_dwordx4 v[138:139], off
	v_lshl_add_u64 v[138:139], v[136:137], 1, s[24:25]
	v_readfirstlane_b32 s23, v175
	v_lshl_add_u64 v[138:139], v[140:141], 1, v[138:139]
	s_mov_b32 m0, s23
	s_nop 0
	global_load_lds_dwordx4 v[138:139], off
	s_barrier
	s_waitcnt lgkmcnt(0)
	v_mfma_f32_16x16x32_bf16 v[124:127], v[142:145], v[186:189], v[124:127]
	v_mfma_f32_16x16x32_bf16 v[120:123], v[178:181], v[186:189], v[120:123]
	v_mfma_f32_16x16x32_bf16 v[116:119], v[142:145], v[194:197], v[116:119]
	v_mfma_f32_16x16x32_bf16 v[112:115], v[178:181], v[194:197], v[112:115]
	v_mfma_f32_16x16x32_bf16 v[100:103], v[142:145], v[210:213], v[100:103]
	v_mfma_f32_16x16x32_bf16 v[96:99], v[178:181], v[210:213], v[96:99]
	v_mfma_f32_16x16x32_bf16 v[124:127], v[146:149], v[190:193], v[124:127]
	v_mfma_f32_16x16x32_bf16 v[120:123], v[182:185], v[190:193], v[120:123]
	v_mfma_f32_16x16x32_bf16 v[116:119], v[146:149], v[198:201], v[116:119]
	v_mfma_f32_16x16x32_bf16 v[112:115], v[182:185], v[198:201], v[112:115]
	v_mfma_f32_16x16x32_bf16 v[108:111], v[142:145], v[202:205], v[108:111]
	v_mfma_f32_16x16x32_bf16 v[104:107], v[178:181], v[202:205], v[104:107]
	v_mfma_f32_16x16x32_bf16 v[100:103], v[146:149], v[214:217], v[100:103]
	v_mfma_f32_16x16x32_bf16 v[96:99], v[182:185], v[214:217], v[96:99]
	v_mfma_f32_16x16x32_bf16 v[138:141], v[146:149], v[206:209], v[108:111]
	v_mfma_f32_16x16x32_bf16 v[218:221], v[182:185], v[206:209], v[104:107]
	s_barrier
	s_nop 1
	s_nop 0
	ds_read_b128 v[104:107], v160
	ds_read_b128 v[108:111], v160 offset:1024
	ds_read_b128 v[222:225], v160 offset:2048
	ds_read_b128 v[158:161], v160 offset:3072
	s_barrier
; #define LDA(dst,b,h) _Pragma("unroll") for(int m=0;m<4;++m) _Pragma("unroll") for(int k=0;k<2;++k) \
;     dst[m][k]=*reinterpret_cast<const bf16x8*>((char*)SA(b,h)+lds_byte(wr*64+m*16+fr,k*32+fq*8))
; #define LDB(dst,b,h) _Pragma("unroll") for(int n=0;n<2;++n) _Pragma("unroll") for(int k=0;k<2;++k) \
;     dst[n][k]=*reinterpret_cast<const bf16x8*>((char*)SB(b,h)+lds_byte(wc*32+n*16+fr,k*32+fq*8))
; #define MMA(ai,bj,At_,Bt_) do{__builtin_amdgcn_s_setprio(1); \
;     _Pragma("unroll") for(int m=0;m<4;++m) _Pragma("unroll") for(int n=0;n<2;++n) _Pragma("unroll") for(int k=0;k<2;++k) \
;       acc[ai][bj][m][n]=__builtin_amdgcn_mfma_f32_16x16x32_bf16(Bt_[n][k],At_[m][k],acc[ai][bj][m][n],0,0,0); \
;     __builtin_amdgcn_s_setprio(0);}while(0)
; #define WAIT_V(n) asm volatile("s_waitcnt vmcnt(" #n ")":::"memory")
; #define WAIT_L(n) asm volatile("s_waitcnt lgkmcnt(" #n ")":::"memory")
; #define BAR __builtin_amdgcn_s_barrier()
; DEVINL void gemm8_mainloop(const u16* A, long lda, const u16* Bt, long ldb, int K, int brow, int bcol, f32x4 (&acc)[2][2][4][2], char* smem, int tid) {
;     ...
;     LDB(B1,0,1); BAR; WAIT_L(0); MMA(0,1,At,B1); BAR;
;     LDA(At,0,1); WAIT_V(4); BAR; WAIT_L(0); MMA(1,0,At,B0); MMA(1,1,At,B1); BAR; }
;   { LDB(B0,1,0); LDA(At,1,0); WAIT_V(2); BAR; WAIT_L(0); MMA(0,0,At,B0); BAR;
	s_waitcnt lgkmcnt(0)
	v_mfma_f32_16x16x32_bf16 v[84:87], v[104:107], v[194:197], v[84:87]
	v_mfma_f32_16x16x32_bf16 v[80:83], v[222:225], v[194:197], v[80:83]
	v_mfma_f32_16x16x32_bf16 v[68:71], v[104:107], v[210:213], v[68:71]
	v_mfma_f32_16x16x32_bf16 v[92:95], v[104:107], v[186:189], v[92:95]
	v_mfma_f32_16x16x32_bf16 v[88:91], v[222:225], v[186:189], v[88:91]
	v_mfma_f32_16x16x32_bf16 v[84:87], v[108:111], v[198:201], v[84:87]
	v_mfma_f32_16x16x32_bf16 v[80:83], v[158:161], v[198:201], v[80:83]
	v_mfma_f32_16x16x32_bf16 v[76:79], v[104:107], v[202:205], v[76:79]
	v_mfma_f32_16x16x32_bf16 v[72:75], v[222:225], v[202:205], v[72:75]
	v_mfma_f32_16x16x32_bf16 v[68:71], v[108:111], v[214:217], v[68:71]
	v_mfma_f32_16x16x32_bf16 v[64:67], v[222:225], v[210:213], v[64:67]
	v_mfma_f32_16x16x32_bf16 v[226:229], v[108:111], v[190:193], v[92:95]
	v_mfma_f32_16x16x32_bf16 v[186:189], v[158:161], v[190:193], v[88:91]
	v_mfma_f32_16x16x32_bf16 v[190:193], v[108:111], v[206:209], v[76:79]
	v_mfma_f32_16x16x32_bf16 v[194:197], v[158:161], v[206:209], v[72:75]
	v_mfma_f32_16x16x32_bf16 v[198:201], v[158:161], v[214:217], v[64:67]
	s_barrier
	s_nop 0
	s_nop 0
	ds_read_b128 v[64:67], v153 offset:16384
	ds_read_b128 v[72:75], v153 offset:17408
	ds_read_b128 v[76:79], v171 offset:16384
	ds_read_b128 v[88:91], v171 offset:17408
	ds_read_b128 v[92:95], v172 offset:16384
	ds_read_b128 v[202:205], v172 offset:17408
	ds_read_b128 v[206:209], v173 offset:16384
	ds_read_b128 v[210:213], v173 offset:17408
	s_waitcnt vmcnt(4)
	s_barrier
	s_waitcnt lgkmcnt(0)
	v_mfma_f32_16x16x32_bf16 v[60:63], v[142:145], v[64:67], v[60:63]
	v_mfma_f32_16x16x32_bf16 v[56:59], v[178:181], v[64:67], v[56:59]
	v_mfma_f32_16x16x32_bf16 v[52:55], v[142:145], v[76:79], v[52:55]
	v_mfma_f32_16x16x32_bf16 v[48:51], v[178:181], v[76:79], v[48:51]
	v_mfma_f32_16x16x32_bf16 v[36:39], v[142:145], v[206:209], v[36:39]
	v_mfma_f32_16x16x32_bf16 v[32:35], v[178:181], v[206:209], v[32:35]
	v_mfma_f32_16x16x32_bf16 v[60:63], v[146:149], v[72:75], v[60:63]
	v_mfma_f32_16x16x32_bf16 v[56:59], v[182:185], v[72:75], v[56:59]
	v_mfma_f32_16x16x32_bf16 v[52:55], v[146:149], v[88:91], v[52:55]
	v_mfma_f32_16x16x32_bf16 v[48:51], v[182:185], v[88:91], v[48:51]
	v_mfma_f32_16x16x32_bf16 v[44:47], v[142:145], v[92:95], v[44:47]
	v_mfma_f32_16x16x32_bf16 v[40:43], v[178:181], v[92:95], v[40:43]
	v_mfma_f32_16x16x32_bf16 v[36:39], v[146:149], v[210:213], v[36:39]
	v_mfma_f32_16x16x32_bf16 v[32:35], v[182:185], v[210:213], v[32:35]
	v_mfma_f32_16x16x32_bf16 v[214:217], v[146:149], v[202:205], v[44:47]
	v_mfma_f32_16x16x32_bf16 v[230:233], v[182:185], v[202:205], v[40:43]
	v_mfma_f32_16x16x32_bf16 v[20:23], v[104:107], v[76:79], v[20:23]
	v_mfma_f32_16x16x32_bf16 v[16:19], v[222:225], v[76:79], v[16:19]
	v_mfma_f32_16x16x32_bf16 v[4:7], v[104:107], v[206:209], v[4:7]
	v_mfma_f32_16x16x32_bf16 v[28:31], v[104:107], v[64:67], v[28:31]
	v_mfma_f32_16x16x32_bf16 v[24:27], v[222:225], v[64:67], v[24:27]
	v_mfma_f32_16x16x32_bf16 v[20:23], v[108:111], v[88:91], v[20:23]
	v_mfma_f32_16x16x32_bf16 v[16:19], v[158:161], v[88:91], v[16:19]
	v_mfma_f32_16x16x32_bf16 v[12:15], v[104:107], v[92:95], v[12:15]
	v_mfma_f32_16x16x32_bf16 v[8:11], v[222:225], v[92:95], v[8:11]
	v_mfma_f32_16x16x32_bf16 v[4:7], v[108:111], v[210:213], v[4:7]
	v_mfma_f32_16x16x32_bf16 v[0:3], v[222:225], v[206:209], v[0:3]
	v_mfma_f32_16x16x32_bf16 v[142:145], v[108:111], v[72:75], v[28:31]
	v_mfma_f32_16x16x32_bf16 v[146:149], v[158:161], v[72:75], v[24:27]
	v_mfma_f32_16x16x32_bf16 v[178:181], v[108:111], v[202:205], v[12:15]
	v_mfma_f32_16x16x32_bf16 v[182:185], v[158:161], v[202:205], v[8:11]
	v_mfma_f32_16x16x32_bf16 v[158:161], v[158:161], v[210:213], v[0:3]
	s_barrier
	s_nop 0
	s_nop 0
	ds_read_b128 v[0:3], v156
	ds_read_b128 v[8:11], v156 offset:1024
	ds_read_b128 v[202:205], v156 offset:2048
	ds_read_b128 v[206:209], v156 offset:3072
	ds_read_b128 v[12:15], v153 offset:32768
	ds_read_b128 v[24:27], v153 offset:33792
	ds_read_b128 v[28:31], v171 offset:32768
	ds_read_b128 v[40:43], v171 offset:33792
	ds_read_b128 v[44:47], v172 offset:32768
	ds_read_b128 v[64:67], v172 offset:33792
	ds_read_b128 v[210:213], v173 offset:32768
	ds_read_b128 v[222:225], v173 offset:33792
	s_waitcnt vmcnt(2)
	s_barrier
; #define LDA(dst,b,h) _Pragma("unroll") for(int m=0;m<4;++m) _Pragma("unroll") for(int k=0;k<2;++k) \
;     dst[m][k]=*reinterpret_cast<const bf16x8*>((char*)SA(b,h)+lds_byte(wr*64+m*16+fr,k*32+fq*8))
; #define LDB(dst,b,h) _Pragma("unroll") for(int n=0;n<2;++n) _Pragma("unroll") for(int k=0;k<2;++k) \
;     dst[n][k]=*reinterpret_cast<const bf16x8*>((char*)SB(b,h)+lds_byte(wc*32+n*16+fr,k*32+fq*8))
; #define MMA(ai,bj,At_,Bt_) do{__builtin_amdgcn_s_setprio(1); \
;     _Pragma("unroll") for(int m=0;m<4;++m) _Pragma("unroll") for(int n=0;n<2;++n) _Pragma("unroll") for(int k=0;k<2;++k) \
;       acc[ai][bj][m][n]=__builtin_amdgcn_mfma_f32_16x16x32_bf16(Bt_[n][k],At_[m][k],acc[ai][bj][m][n],0,0,0); \
;     __builtin_amdgcn_s_setprio(0);}while(0)
; #define WAIT_V(n) asm volatile("s_waitcnt vmcnt(" #n ")":::"memory")
; #define WAIT_L(n) asm volatile("s_waitcnt lgkmcnt(" #n ")":::"memory")
; #define BAR __builtin_amdgcn_s_barrier()
; DEVINL void gemm8_mainloop(const u16* A, long lda, const u16* Bt, long ldb, int K, int brow, int bcol, f32x4 (&acc)[2][2][4][2], char* smem, int tid) {
;     ...
;     LDA(At,0,1); WAIT_V(4); BAR; WAIT_L(0); MMA(1,0,At,B0); MMA(1,1,At,B1); BAR; }
;   { LDB(B0,1,0); LDA(At,1,0); WAIT_V(2); BAR; WAIT_L(0); MMA(0,0,At,B0); BAR;
;     LDB(B1,1,1); WAIT_V(0); BAR; WAIT_L(0); MMA(0,1,At,B1); BAR;
;     LDA(At,1,1); BAR; WAIT_L(0); MMA(1,0,At,B0); MMA(1,1,At,B1); BAR; }
;   if(wr==0)BAR;
	s_waitcnt lgkmcnt(0)
	v_mfma_f32_16x16x32_bf16 v[72:75], v[0:3], v[12:15], v[124:127]
	v_mfma_f32_16x16x32_bf16 v[124:127], v[8:11], v[24:27], v[72:75]
	v_mfma_f32_16x16x32_bf16 v[72:75], v[202:205], v[12:15], v[120:123]
	v_mfma_f32_16x16x32_bf16 v[120:123], v[206:209], v[24:27], v[72:75]
	v_mfma_f32_16x16x32_bf16 v[72:75], v[0:3], v[28:31], v[116:119]
	v_mfma_f32_16x16x32_bf16 v[108:111], v[8:11], v[40:43], v[72:75]
	v_mfma_f32_16x16x32_bf16 v[72:75], v[202:205], v[28:31], v[112:115]
	v_mfma_f32_16x16x32_bf16 v[104:107], v[206:209], v[40:43], v[72:75]
	v_mfma_f32_16x16x32_bf16 v[72:75], v[0:3], v[44:47], v[138:141]
	v_mfma_f32_16x16x32_bf16 v[92:95], v[8:11], v[64:67], v[72:75]
	v_mfma_f32_16x16x32_bf16 v[72:75], v[202:205], v[44:47], v[218:221]
	v_mfma_f32_16x16x32_bf16 v[88:91], v[206:209], v[64:67], v[72:75]
	v_mfma_f32_16x16x32_bf16 v[72:75], v[0:3], v[210:213], v[100:103]
	v_mfma_f32_16x16x32_bf16 v[76:79], v[8:11], v[222:225], v[72:75]
	v_mfma_f32_16x16x32_bf16 v[72:75], v[202:205], v[210:213], v[96:99]
	v_mfma_f32_16x16x32_bf16 v[72:75], v[206:209], v[222:225], v[72:75]
	s_barrier
	ds_read_b128 v[138:141], v155
	ds_read_b128 v[218:221], v155 offset:1024
	ds_read_b128 v[234:237], v155 offset:2048
	ds_read_b128 v[154:157], v155 offset:3072
	s_waitcnt vmcnt(0)
	s_barrier
	s_waitcnt lgkmcnt(0)
	v_mfma_f32_16x16x32_bf16 v[96:99], v[138:141], v[12:15], v[226:229]
	v_mfma_f32_16x16x32_bf16 v[12:15], v[234:237], v[12:15], v[186:189]
	v_mfma_f32_16x16x32_bf16 v[116:119], v[154:157], v[24:27], v[12:15]
	v_mfma_f32_16x16x32_bf16 v[12:15], v[138:141], v[28:31], v[84:87]
	v_mfma_f32_16x16x32_bf16 v[112:115], v[218:221], v[24:27], v[96:99]
	v_mfma_f32_16x16x32_bf16 v[96:99], v[218:221], v[40:43], v[12:15]
	v_mfma_f32_16x16x32_bf16 v[12:15], v[234:237], v[28:31], v[80:83]
	v_mfma_f32_16x16x32_bf16 v[100:103], v[154:157], v[40:43], v[12:15]
	v_mfma_f32_16x16x32_bf16 v[12:15], v[138:141], v[44:47], v[190:193]
	v_mfma_f32_16x16x32_bf16 v[80:83], v[218:221], v[64:67], v[12:15]
	v_mfma_f32_16x16x32_bf16 v[12:15], v[234:237], v[44:47], v[194:197]
	v_mfma_f32_16x16x32_bf16 v[84:87], v[154:157], v[64:67], v[12:15]
	v_mfma_f32_16x16x32_bf16 v[12:15], v[138:141], v[210:213], v[68:71]
	v_mfma_f32_16x16x32_bf16 v[64:67], v[218:221], v[222:225], v[12:15]
	v_mfma_f32_16x16x32_bf16 v[12:15], v[234:237], v[210:213], v[198:201]
	v_mfma_f32_16x16x32_bf16 v[68:71], v[154:157], v[222:225], v[12:15]
	s_barrier
	ds_read_b128 v[186:189], v153 offset:49152
	ds_read_b128 v[190:193], v153 offset:50176
	ds_read_b128 v[194:197], v171 offset:49152
	ds_read_b128 v[198:201], v171 offset:50176
	ds_read_b128 v[210:213], v172 offset:49152
	ds_read_b128 v[222:225], v172 offset:50176
	ds_read_b128 v[226:229], v173 offset:49152
	ds_read_b128 v[172:175], v173 offset:50176
	s_barrier
	s_waitcnt lgkmcnt(0)
	v_mfma_f32_16x16x32_bf16 v[12:15], v[0:3], v[186:189], v[60:63]
	v_mfma_f32_16x16x32_bf16 v[60:63], v[8:11], v[190:193], v[12:15]
	v_mfma_f32_16x16x32_bf16 v[12:15], v[202:205], v[186:189], v[56:59]
	v_mfma_f32_16x16x32_bf16 v[56:59], v[206:209], v[190:193], v[12:15]
	v_mfma_f32_16x16x32_bf16 v[12:15], v[0:3], v[194:197], v[52:55]
	v_mfma_f32_16x16x32_bf16 v[44:47], v[8:11], v[198:201], v[12:15]
	v_mfma_f32_16x16x32_bf16 v[12:15], v[202:205], v[194:197], v[48:51]
	v_mfma_f32_16x16x32_bf16 v[40:43], v[206:209], v[198:201], v[12:15]
	v_mfma_f32_16x16x32_bf16 v[12:15], v[0:3], v[210:213], v[214:217]
	v_mfma_f32_16x16x32_bf16 v[28:31], v[8:11], v[222:225], v[12:15]
	v_mfma_f32_16x16x32_bf16 v[12:15], v[202:205], v[210:213], v[230:233]
	v_mfma_f32_16x16x32_bf16 v[0:3], v[0:3], v[226:229], v[36:39]
	v_mfma_f32_16x16x32_bf16 v[24:27], v[206:209], v[222:225], v[12:15]
	v_mfma_f32_16x16x32_bf16 v[12:15], v[8:11], v[172:175], v[0:3]
	v_mfma_f32_16x16x32_bf16 v[0:3], v[202:205], v[226:229], v[32:35]
	v_mfma_f32_16x16x32_bf16 v[8:11], v[206:209], v[172:175], v[0:3]
	v_mfma_f32_16x16x32_bf16 v[0:3], v[138:141], v[186:189], v[142:145]
	v_mfma_f32_16x16x32_bf16 v[48:51], v[218:221], v[190:193], v[0:3]
	v_mfma_f32_16x16x32_bf16 v[0:3], v[234:237], v[186:189], v[146:149]
	v_mfma_f32_16x16x32_bf16 v[52:55], v[154:157], v[190:193], v[0:3]
	v_mfma_f32_16x16x32_bf16 v[0:3], v[138:141], v[194:197], v[20:23]
	v_mfma_f32_16x16x32_bf16 v[32:35], v[218:221], v[198:201], v[0:3]
	v_mfma_f32_16x16x32_bf16 v[0:3], v[234:237], v[194:197], v[16:19]
	v_mfma_f32_16x16x32_bf16 v[36:39], v[154:157], v[198:201], v[0:3]
	v_mfma_f32_16x16x32_bf16 v[0:3], v[138:141], v[210:213], v[178:181]
	v_mfma_f32_16x16x32_bf16 v[16:19], v[218:221], v[222:225], v[0:3]
	v_mfma_f32_16x16x32_bf16 v[0:3], v[234:237], v[210:213], v[182:185]
	v_mfma_f32_16x16x32_bf16 v[20:23], v[154:157], v[222:225], v[0:3]
	v_mfma_f32_16x16x32_bf16 v[0:3], v[138:141], v[226:229], v[4:7]
	v_mfma_f32_16x16x32_bf16 v[4:7], v[234:237], v[226:229], v[158:161]
	v_mfma_f32_16x16x32_bf16 v[0:3], v[218:221], v[172:175], v[0:3]
	v_mfma_f32_16x16x32_bf16 v[4:7], v[154:157], v[172:175], v[4:7]
	s_cmpk_gt_u32 s27, 0xff
	s_barrier
	s_cbranch_scc1 .LBB0_1990
	s_barrier
